# GEMM epilogues: one dwordx4 per lane plus cross-lane add instead of four broadcast loads of the row sum-of-squares partials (12 sites), on top of line-efficient dil units
# speedup vs baseline: 1.0154x; 1.0154x over previous
.LBB0_166:
	v_lshl_add_u32 v146, s6, 8, v148
	v_ashrrev_i32_e32 v147, 31, v146
	v_lshlrev_b64 v[144:145], 6, v[146:147]
	v_lshl_add_u64 v[144:145], s[10:11], 0, v[144:145]
	v_bfe_u32 v164, v206, 4, 2
	v_lshlrev_b32_e32 v164, 4, v164
	v_mov_b32_e32 v165, 0
	v_lshl_add_u64 v[160:161], v[144:145], 0, v[164:165]
	global_load_dwordx4 v[156:159], v[160:161], off
	v_or_b32_e32 v172, 16, v146
	v_ashrrev_i32_e32 v173, 31, v172
	s_lshr_b32 s17, s7, 31
	v_lshlrev_b64 v[144:145], 6, v[172:173]
	s_add_i32 s17, s7, s17
	v_lshl_add_u64 v[176:177], s[10:11], 0, v[144:145]
	s_ashr_i32 s24, s17, 1
	s_ashr_i32 s25, s24, 31
	s_lshl_b32 s6, s7, 8
	s_lshl_b64 s[26:27], s[24:25], 25
	s_add_u32 s26, s43, s26
	s_addc_u32 s27, s44, s27
	s_lshl_b32 s17, s24, 9
	s_lshl_b32 s7, 1, s7
	s_sub_i32 s6, s6, s17
	s_and_b32 s7, s7, 0xc3
	s_cmp_eq_u32 s7, 0
	v_or_b32_e32 v144, s6, v150
	s_cselect_b64 s[6:7], -1, 0
	v_lshlrev_b64 v[174:175], 10, v[146:147]
	v_cndmask_b32_e64 v147, v155, 1.0, s[6:7]
	s_waitcnt vmcnt(0)
	v_add_f32_e32 v160, v156, v157
	v_add_f32_e32 v161, v158, v159
	v_add_f32_e32 v160, v160, v161
	ds_swizzle_b32 v161, v160 offset:swizzle(SWAP,16)
	s_waitcnt lgkmcnt(0)
	v_add_f32_e32 v160, v160, v161
	v_mov_b32_e32 v161, v160
	s_nop 1
	v_permlane32_swap_b32_e32 v160, v161
	v_add_f32_e32 v168, v160, v161
	s_nop 0
	s_nop 0
	v_mov_b32_e32 v145, v168
	v_fmamk_f32 v145, v145, 0x3a800000, v154
	v_mul_f32_e32 v156, 0x4b800000, v145
	v_cmp_gt_f32_e32 vcc, s50, v145
	s_nop 1
	v_cndmask_b32_e32 v145, v145, v156, vcc
	v_rsq_f32_e32 v158, v145
	v_ashrrev_i32_e32 v145, 31, v144
	v_lshl_add_u64 v[144:145], v[144:145], 1, s[26:27]
	v_lshl_add_u64 v[156:157], v[144:145], 0, v[174:175]
	v_mul_f32_e32 v159, 0x45800000, v158
	v_cndmask_b32_e32 v158, v158, v159, vcc
	v_mul_f32_e32 v158, v147, v158
	v_pk_mul_f32 v[126:127], v[126:127], v[158:159] op_sel_hi:[1,0]
	v_pk_mul_f32 v[124:125], v[124:125], v[158:159] op_sel_hi:[1,0]
	v_pk_mul_f32 v[122:123], v[122:123], v[158:159] op_sel_hi:[1,0]
	v_pk_mul_f32 v[120:121], v[120:121], v[158:159] op_sel_hi:[1,0]
	v_pk_mul_f32 v[118:119], v[118:119], v[158:159] op_sel_hi:[1,0]
	v_pk_mul_f32 v[116:117], v[116:117], v[158:159] op_sel_hi:[1,0]
	v_pk_mul_f32 v[160:161], v[114:115], v[158:159] op_sel_hi:[1,0]
	v_pk_mul_f32 v[158:159], v[112:113], v[158:159] op_sel_hi:[1,0]
	v_cvt_pk_bf16_f32 v112, v124, v125
	v_cvt_pk_bf16_f32 v113, v126, v127
	v_cvt_pk_bf16_f32 v114, v120, v121
	v_cvt_pk_bf16_f32 v115, v122, v123
	global_store_dwordx4 v[156:157], v[112:115], off
	s_nop 1
	v_cvt_pk_bf16_f32 v112, v116, v117
	v_cvt_pk_bf16_f32 v113, v118, v119
	v_cvt_pk_bf16_f32 v114, v158, v159
	v_cvt_pk_bf16_f32 v115, v160, v161
	global_store_dwordx4 v[156:157], v[112:115], off offset:256
	v_bfe_u32 v120, v206, 4, 2
	v_lshlrev_b32_e32 v120, 4, v120
	v_mov_b32_e32 v121, 0
	v_lshl_add_u64 v[116:117], v[176:177], 0, v[120:121]
	global_load_dwordx4 v[112:115], v[116:117], off
	s_nop 0
	v_or_b32_e32 v156, 32, v146
	v_ashrrev_i32_e32 v157, 31, v156
	v_lshlrev_b64 v[158:159], 10, v[172:173]
	s_waitcnt vmcnt(0)
	v_add_f32_e32 v116, v112, v113
	v_add_f32_e32 v117, v114, v115
	v_add_f32_e32 v116, v116, v117
	ds_swizzle_b32 v117, v116 offset:swizzle(SWAP,16)
	s_waitcnt lgkmcnt(0)
	v_add_f32_e32 v116, v116, v117
	v_mov_b32_e32 v117, v116
	s_nop 1
	v_permlane32_swap_b32_e32 v116, v117
	v_add_f32_e32 v124, v116, v117
	s_nop 0
	v_lshl_add_u64 v[114:115], v[144:145], 0, v[158:159]
	v_mov_b32_e32 v112, v124
	v_fmamk_f32 v112, v112, 0x3a800000, v154
	v_mul_f32_e32 v113, 0x4b800000, v112
	v_cmp_gt_f32_e32 vcc, s50, v112
	s_nop 1
	v_cndmask_b32_e32 v112, v112, v113, vcc
	v_rsq_f32_e32 v116, v112
	v_lshlrev_b64 v[112:113], 6, v[156:157]
	v_lshl_add_u64 v[112:113], s[10:11], 0, v[112:113]
	v_mul_f32_e32 v117, 0x45800000, v116
	v_cndmask_b32_e32 v116, v116, v117, vcc
	v_mul_f32_e32 v116, v147, v116
	v_pk_mul_f32 v[110:111], v[110:111], v[116:117] op_sel_hi:[1,0]
	v_pk_mul_f32 v[108:109], v[108:109], v[116:117] op_sel_hi:[1,0]
	v_pk_mul_f32 v[106:107], v[106:107], v[116:117] op_sel_hi:[1,0]
	v_pk_mul_f32 v[104:105], v[104:105], v[116:117] op_sel_hi:[1,0]
	v_pk_mul_f32 v[102:103], v[102:103], v[116:117] op_sel_hi:[1,0]
	v_pk_mul_f32 v[100:101], v[100:101], v[116:117] op_sel_hi:[1,0]
	v_pk_mul_f32 v[118:119], v[98:99], v[116:117] op_sel_hi:[1,0]
	v_pk_mul_f32 v[116:117], v[96:97], v[116:117] op_sel_hi:[1,0]
	v_cvt_pk_bf16_f32 v96, v108, v109
	v_cvt_pk_bf16_f32 v97, v110, v111
	v_cvt_pk_bf16_f32 v98, v104, v105
	v_cvt_pk_bf16_f32 v99, v106, v107
	global_store_dwordx4 v[114:115], v[96:99], off
	s_nop 1
	v_cvt_pk_bf16_f32 v96, v100, v101
	v_cvt_pk_bf16_f32 v97, v102, v103
	v_cvt_pk_bf16_f32 v98, v116, v117
	v_cvt_pk_bf16_f32 v99, v118, v119
	global_store_dwordx4 v[114:115], v[96:99], off offset:256
	v_bfe_u32 v104, v206, 4, 2
	v_lshlrev_b32_e32 v104, 4, v104
	v_mov_b32_e32 v105, 0
	v_lshl_add_u64 v[100:101], v[112:113], 0, v[104:105]
	global_load_dwordx4 v[96:99], v[100:101], off
	s_nop 0
	v_or_b32_e32 v112, 48, v146
	v_ashrrev_i32_e32 v113, 31, v112
	v_lshlrev_b64 v[114:115], 10, v[156:157]
	s_waitcnt vmcnt(0)
	v_add_f32_e32 v100, v96, v97
	v_add_f32_e32 v101, v98, v99
	v_add_f32_e32 v100, v100, v101
	ds_swizzle_b32 v101, v100 offset:swizzle(SWAP,16)
	s_waitcnt lgkmcnt(0)
	v_add_f32_e32 v100, v100, v101
	v_mov_b32_e32 v101, v100
	s_nop 1
	v_permlane32_swap_b32_e32 v100, v101
	v_add_f32_e32 v108, v100, v101
	s_nop 0
	v_lshl_add_u64 v[98:99], v[144:145], 0, v[114:115]
	v_mov_b32_e32 v96, v108
	v_fmamk_f32 v96, v96, 0x3a800000, v154
	v_mul_f32_e32 v97, 0x4b800000, v96
	v_cmp_gt_f32_e32 vcc, s50, v96
	s_nop 1
	v_cndmask_b32_e32 v96, v96, v97, vcc
	v_rsq_f32_e32 v100, v96
	v_lshlrev_b64 v[96:97], 6, v[112:113]
	v_lshl_add_u64 v[96:97], s[10:11], 0, v[96:97]
	v_mul_f32_e32 v101, 0x45800000, v100
	v_cndmask_b32_e32 v100, v100, v101, vcc
	v_mul_f32_e32 v100, v147, v100
	v_pk_mul_f32 v[94:95], v[94:95], v[100:101] op_sel_hi:[1,0]
	v_pk_mul_f32 v[92:93], v[92:93], v[100:101] op_sel_hi:[1,0]
	v_pk_mul_f32 v[90:91], v[90:91], v[100:101] op_sel_hi:[1,0]
	v_pk_mul_f32 v[88:89], v[88:89], v[100:101] op_sel_hi:[1,0]
	v_pk_mul_f32 v[86:87], v[86:87], v[100:101] op_sel_hi:[1,0]
	v_pk_mul_f32 v[84:85], v[84:85], v[100:101] op_sel_hi:[1,0]
	v_pk_mul_f32 v[102:103], v[82:83], v[100:101] op_sel_hi:[1,0]
	v_pk_mul_f32 v[100:101], v[80:81], v[100:101] op_sel_hi:[1,0]
	v_cvt_pk_bf16_f32 v80, v92, v93
	v_cvt_pk_bf16_f32 v81, v94, v95
	v_cvt_pk_bf16_f32 v82, v88, v89
	v_cvt_pk_bf16_f32 v83, v90, v91
	global_store_dwordx4 v[98:99], v[80:83], off
	s_nop 1
	v_cvt_pk_bf16_f32 v80, v84, v85
	v_cvt_pk_bf16_f32 v81, v86, v87
	v_cvt_pk_bf16_f32 v82, v100, v101
	v_cvt_pk_bf16_f32 v83, v102, v103
	global_store_dwordx4 v[98:99], v[80:83], off offset:256
	v_bfe_u32 v88, v206, 4, 2
	v_lshlrev_b32_e32 v88, 4, v88
	v_mov_b32_e32 v89, 0
	v_lshl_add_u64 v[84:85], v[96:97], 0, v[88:89]
	global_load_dwordx4 v[80:83], v[84:85], off
	s_nop 0
	v_add_u32_e32 v96, 0x80, v146
	v_ashrrev_i32_e32 v97, 31, v96
	v_lshlrev_b64 v[98:99], 10, v[112:113]
	s_waitcnt vmcnt(0)
	v_add_f32_e32 v84, v80, v81
	v_add_f32_e32 v85, v82, v83
	v_add_f32_e32 v84, v84, v85
	ds_swizzle_b32 v85, v84 offset:swizzle(SWAP,16)
	s_waitcnt lgkmcnt(0)
	v_add_f32_e32 v84, v84, v85
	v_mov_b32_e32 v85, v84
	s_nop 1
	v_permlane32_swap_b32_e32 v84, v85
	v_add_f32_e32 v92, v84, v85
	s_nop 0
	v_lshl_add_u64 v[82:83], v[144:145], 0, v[98:99]
	v_mov_b32_e32 v80, v92
	v_fmamk_f32 v80, v80, 0x3a800000, v154
	v_mul_f32_e32 v81, 0x4b800000, v80
	v_cmp_gt_f32_e32 vcc, s50, v80
	s_nop 1
	v_cndmask_b32_e32 v80, v80, v81, vcc
	v_rsq_f32_e32 v84, v80
	v_lshlrev_b64 v[80:81], 6, v[96:97]
	v_lshl_add_u64 v[80:81], s[10:11], 0, v[80:81]
	v_mul_f32_e32 v85, 0x45800000, v84
	v_cndmask_b32_e32 v84, v84, v85, vcc
	v_mul_f32_e32 v84, v147, v84
	v_pk_mul_f32 v[78:79], v[78:79], v[84:85] op_sel_hi:[1,0]
	v_pk_mul_f32 v[76:77], v[76:77], v[84:85] op_sel_hi:[1,0]
	v_pk_mul_f32 v[74:75], v[74:75], v[84:85] op_sel_hi:[1,0]
	v_pk_mul_f32 v[72:73], v[72:73], v[84:85] op_sel_hi:[1,0]
	v_pk_mul_f32 v[70:71], v[70:71], v[84:85] op_sel_hi:[1,0]
	v_pk_mul_f32 v[68:69], v[68:69], v[84:85] op_sel_hi:[1,0]
	v_pk_mul_f32 v[86:87], v[66:67], v[84:85] op_sel_hi:[1,0]
	v_pk_mul_f32 v[84:85], v[64:65], v[84:85] op_sel_hi:[1,0]
	v_cvt_pk_bf16_f32 v64, v76, v77
	v_cvt_pk_bf16_f32 v65, v78, v79
	v_cvt_pk_bf16_f32 v66, v72, v73
	v_cvt_pk_bf16_f32 v67, v74, v75
	global_store_dwordx4 v[82:83], v[64:67], off
	s_nop 1
	v_cvt_pk_bf16_f32 v64, v68, v69
	v_cvt_pk_bf16_f32 v65, v70, v71
	v_cvt_pk_bf16_f32 v66, v84, v85
	v_cvt_pk_bf16_f32 v67, v86, v87
	global_store_dwordx4 v[82:83], v[64:67], off offset:256
	v_bfe_u32 v72, v206, 4, 2
	v_lshlrev_b32_e32 v72, 4, v72
	v_mov_b32_e32 v73, 0
	v_lshl_add_u64 v[68:69], v[80:81], 0, v[72:73]
	global_load_dwordx4 v[64:67], v[68:69], off
	s_nop 0
	v_add_u32_e32 v80, 0x90, v146
	v_ashrrev_i32_e32 v81, 31, v80
	v_lshlrev_b64 v[82:83], 10, v[96:97]
	s_waitcnt vmcnt(0)
	v_add_f32_e32 v68, v64, v65
	v_add_f32_e32 v69, v66, v67
	v_add_f32_e32 v68, v68, v69
	ds_swizzle_b32 v69, v68 offset:swizzle(SWAP,16)
	s_waitcnt lgkmcnt(0)
	v_add_f32_e32 v68, v68, v69
	v_mov_b32_e32 v69, v68
	s_nop 1
	v_permlane32_swap_b32_e32 v68, v69
	v_add_f32_e32 v76, v68, v69
	s_nop 0
	v_lshl_add_u64 v[66:67], v[144:145], 0, v[82:83]
	v_mov_b32_e32 v64, v76
	v_fmamk_f32 v64, v64, 0x3a800000, v154
	v_mul_f32_e32 v65, 0x4b800000, v64
	v_cmp_gt_f32_e32 vcc, s50, v64
	s_nop 1
	v_cndmask_b32_e32 v64, v64, v65, vcc
	v_rsq_f32_e32 v68, v64
	v_lshlrev_b64 v[64:65], 6, v[80:81]
	v_lshl_add_u64 v[64:65], s[10:11], 0, v[64:65]
	v_mul_f32_e32 v69, 0x45800000, v68
	v_cndmask_b32_e32 v68, v68, v69, vcc
	v_mul_f32_e32 v68, v147, v68
	v_pk_mul_f32 v[62:63], v[62:63], v[68:69] op_sel_hi:[1,0]
	v_pk_mul_f32 v[60:61], v[60:61], v[68:69] op_sel_hi:[1,0]
	v_pk_mul_f32 v[58:59], v[58:59], v[68:69] op_sel_hi:[1,0]
	v_pk_mul_f32 v[56:57], v[56:57], v[68:69] op_sel_hi:[1,0]
	v_pk_mul_f32 v[54:55], v[54:55], v[68:69] op_sel_hi:[1,0]
	v_pk_mul_f32 v[52:53], v[52:53], v[68:69] op_sel_hi:[1,0]
	v_pk_mul_f32 v[70:71], v[50:51], v[68:69] op_sel_hi:[1,0]
	v_pk_mul_f32 v[68:69], v[48:49], v[68:69] op_sel_hi:[1,0]
	v_cvt_pk_bf16_f32 v48, v60, v61
	v_cvt_pk_bf16_f32 v49, v62, v63
	v_cvt_pk_bf16_f32 v50, v56, v57
	v_cvt_pk_bf16_f32 v51, v58, v59
	global_store_dwordx4 v[66:67], v[48:51], off
	s_nop 1
	v_cvt_pk_bf16_f32 v48, v52, v53
	v_cvt_pk_bf16_f32 v49, v54, v55
	v_cvt_pk_bf16_f32 v50, v68, v69
	v_cvt_pk_bf16_f32 v51, v70, v71
	global_store_dwordx4 v[66:67], v[48:51], off offset:256
	v_bfe_u32 v56, v206, 4, 2
	v_lshlrev_b32_e32 v56, 4, v56
	v_mov_b32_e32 v57, 0
	v_lshl_add_u64 v[52:53], v[64:65], 0, v[56:57]
	global_load_dwordx4 v[48:51], v[52:53], off
	s_nop 0
	v_add_u32_e32 v64, 0xa0, v146
	v_ashrrev_i32_e32 v65, 31, v64
	v_lshlrev_b64 v[66:67], 10, v[80:81]
	s_waitcnt vmcnt(0)
	v_add_f32_e32 v52, v48, v49
	v_add_f32_e32 v53, v50, v51
	v_add_f32_e32 v52, v52, v53
	ds_swizzle_b32 v53, v52 offset:swizzle(SWAP,16)
	s_waitcnt lgkmcnt(0)
	v_add_f32_e32 v52, v52, v53
	v_mov_b32_e32 v53, v52
	s_nop 1
	v_permlane32_swap_b32_e32 v52, v53
	v_add_f32_e32 v60, v52, v53
	s_nop 0
	v_lshl_add_u64 v[50:51], v[144:145], 0, v[66:67]
	v_mov_b32_e32 v48, v60
	v_fmamk_f32 v48, v48, 0x3a800000, v154
	v_mul_f32_e32 v49, 0x4b800000, v48
	v_cmp_gt_f32_e32 vcc, s50, v48
	s_nop 1
	v_cndmask_b32_e32 v48, v48, v49, vcc
	v_rsq_f32_e32 v52, v48
	v_lshlrev_b64 v[48:49], 6, v[64:65]
	v_lshl_add_u64 v[48:49], s[10:11], 0, v[48:49]
	v_mul_f32_e32 v53, 0x45800000, v52
	v_cndmask_b32_e32 v52, v52, v53, vcc
	v_mul_f32_e32 v52, v147, v52
	v_pk_mul_f32 v[46:47], v[46:47], v[52:53] op_sel_hi:[1,0]
	v_pk_mul_f32 v[44:45], v[44:45], v[52:53] op_sel_hi:[1,0]
	v_pk_mul_f32 v[42:43], v[42:43], v[52:53] op_sel_hi:[1,0]
	v_pk_mul_f32 v[40:41], v[40:41], v[52:53] op_sel_hi:[1,0]
	v_pk_mul_f32 v[38:39], v[38:39], v[52:53] op_sel_hi:[1,0]
	v_pk_mul_f32 v[36:37], v[36:37], v[52:53] op_sel_hi:[1,0]
	v_pk_mul_f32 v[54:55], v[34:35], v[52:53] op_sel_hi:[1,0]
	v_pk_mul_f32 v[52:53], v[32:33], v[52:53] op_sel_hi:[1,0]
	v_cvt_pk_bf16_f32 v32, v44, v45
	v_cvt_pk_bf16_f32 v33, v46, v47
	v_cvt_pk_bf16_f32 v34, v40, v41
	v_cvt_pk_bf16_f32 v35, v42, v43
	global_store_dwordx4 v[50:51], v[32:35], off
	s_nop 1
	v_cvt_pk_bf16_f32 v32, v36, v37
	v_cvt_pk_bf16_f32 v33, v38, v39
	v_cvt_pk_bf16_f32 v34, v52, v53
	v_cvt_pk_bf16_f32 v35, v54, v55
	global_store_dwordx4 v[50:51], v[32:35], off offset:256
	v_bfe_u32 v40, v206, 4, 2
	v_lshlrev_b32_e32 v40, 4, v40
	v_mov_b32_e32 v41, 0
	v_lshl_add_u64 v[36:37], v[48:49], 0, v[40:41]
	global_load_dwordx4 v[32:35], v[36:37], off
	s_nop 0
	v_add_u32_e32 v48, 0xb0, v146
	v_ashrrev_i32_e32 v49, 31, v48
	v_lshlrev_b64 v[50:51], 10, v[64:65]
	s_waitcnt vmcnt(0)
	v_add_f32_e32 v36, v32, v33
	v_add_f32_e32 v37, v34, v35
	v_add_f32_e32 v36, v36, v37
	ds_swizzle_b32 v37, v36 offset:swizzle(SWAP,16)
	s_waitcnt lgkmcnt(0)
	v_add_f32_e32 v36, v36, v37
	v_mov_b32_e32 v37, v36
	s_nop 1
	v_permlane32_swap_b32_e32 v36, v37
	v_add_f32_e32 v44, v36, v37
	s_nop 0
	v_lshl_add_u64 v[34:35], v[144:145], 0, v[50:51]
	v_mov_b32_e32 v32, v44
	v_fmamk_f32 v32, v32, 0x3a800000, v154
	v_mul_f32_e32 v33, 0x4b800000, v32
	v_cmp_gt_f32_e32 vcc, s50, v32
	s_nop 1
	v_cndmask_b32_e32 v32, v32, v33, vcc
	v_rsq_f32_e32 v36, v32
	v_lshlrev_b64 v[32:33], 6, v[48:49]
	v_lshl_add_u64 v[32:33], s[10:11], 0, v[32:33]
	v_mul_f32_e32 v37, 0x45800000, v36
	v_cndmask_b32_e32 v36, v36, v37, vcc
	v_mul_f32_e32 v36, v147, v36
	v_pk_mul_f32 v[30:31], v[30:31], v[36:37] op_sel_hi:[1,0]
	v_pk_mul_f32 v[28:29], v[28:29], v[36:37] op_sel_hi:[1,0]
	v_pk_mul_f32 v[26:27], v[26:27], v[36:37] op_sel_hi:[1,0]
	v_pk_mul_f32 v[24:25], v[24:25], v[36:37] op_sel_hi:[1,0]
	v_pk_mul_f32 v[22:23], v[22:23], v[36:37] op_sel_hi:[1,0]
	v_pk_mul_f32 v[20:21], v[20:21], v[36:37] op_sel_hi:[1,0]
	v_pk_mul_f32 v[38:39], v[18:19], v[36:37] op_sel_hi:[1,0]
	v_pk_mul_f32 v[36:37], v[16:17], v[36:37] op_sel_hi:[1,0]
	v_cvt_pk_bf16_f32 v16, v28, v29
	v_cvt_pk_bf16_f32 v17, v30, v31
	v_cvt_pk_bf16_f32 v18, v24, v25
	v_cvt_pk_bf16_f32 v19, v26, v27
	global_store_dwordx4 v[34:35], v[16:19], off
	s_andn2_b64 vcc, exec, s[4:5]
	s_mov_b64 s[4:5], -1
	v_cvt_pk_bf16_f32 v16, v20, v21
	v_cvt_pk_bf16_f32 v17, v22, v23
	v_cvt_pk_bf16_f32 v18, v36, v37
	v_cvt_pk_bf16_f32 v19, v38, v39
	global_store_dwordx4 v[34:35], v[16:19], off offset:256
	v_bfe_u32 v24, v206, 4, 2
	v_lshlrev_b32_e32 v24, 4, v24
	v_mov_b32_e32 v25, 0
	v_lshl_add_u64 v[20:21], v[32:33], 0, v[24:25]
	global_load_dwordx4 v[16:19], v[20:21], off
	s_nop 0
	s_waitcnt vmcnt(0)
	v_add_f32_e32 v20, v16, v17
	v_add_f32_e32 v21, v18, v19
	v_add_f32_e32 v20, v20, v21
	ds_swizzle_b32 v21, v20 offset:swizzle(SWAP,16)
	s_waitcnt lgkmcnt(0)
	v_add_f32_e32 v20, v20, v21
	v_mov_b32_e32 v21, v20
	s_nop 1
	v_permlane32_swap_b32_e32 v20, v21
	v_add_f32_e32 v28, v20, v21
	s_nop 0
	s_nop 0
	v_mov_b32_e32 v16, v28
	v_fmamk_f32 v16, v16, 0x3a800000, v154
	v_mul_f32_e32 v17, 0x4b800000, v16
	v_cmp_gt_f32_e64 s[6:7], s50, v16
	s_nop 1
	v_cndmask_b32_e64 v16, v16, v17, s[6:7]
	v_rsq_f32_e32 v18, v16
	v_lshlrev_b64 v[16:17], 10, v[48:49]
	v_lshl_add_u64 v[16:17], v[144:145], 0, v[16:17]
	v_mul_f32_e32 v19, 0x45800000, v18
	v_cndmask_b32_e64 v18, v18, v19, s[6:7]
	v_mul_f32_e32 v18, v147, v18
	v_pk_mul_f32 v[14:15], v[14:15], v[18:19] op_sel_hi:[1,0]
	v_pk_mul_f32 v[12:13], v[12:13], v[18:19] op_sel_hi:[1,0]
	v_pk_mul_f32 v[10:11], v[10:11], v[18:19] op_sel_hi:[1,0]
	v_pk_mul_f32 v[8:9], v[8:9], v[18:19] op_sel_hi:[1,0]
	v_pk_mul_f32 v[6:7], v[6:7], v[18:19] op_sel_hi:[1,0]
	v_pk_mul_f32 v[4:5], v[4:5], v[18:19] op_sel_hi:[1,0]
	v_pk_mul_f32 v[20:21], v[2:3], v[18:19] op_sel_hi:[1,0]
	v_pk_mul_f32 v[18:19], v[0:1], v[18:19] op_sel_hi:[1,0]
	v_cvt_pk_bf16_f32 v0, v12, v13
	v_cvt_pk_bf16_f32 v1, v14, v15
	v_cvt_pk_bf16_f32 v2, v8, v9
	v_cvt_pk_bf16_f32 v3, v10, v11
	global_store_dwordx4 v[16:17], v[0:3], off
	s_nop 1
	v_cvt_pk_bf16_f32 v0, v4, v5
	v_cvt_pk_bf16_f32 v1, v6, v7
	v_cvt_pk_bf16_f32 v2, v18, v19
	v_cvt_pk_bf16_f32 v3, v20, v21
	global_store_dwordx4 v[16:17], v[0:3], off offset:256
	s_cbranch_vccnz .LBB0_159
	s_andn2_b64 vcc, exec, s[2:3]
	s_cbranch_vccnz .LBB0_158
	s_barrier
	s_branch .LBB0_158

.LBB0_702:
	v_lshl_add_u32 v146, s6, 8, v148
	v_ashrrev_i32_e32 v147, 31, v146
	v_lshlrev_b64 v[144:145], 6, v[146:147]
	v_lshl_add_u64 v[144:145], s[10:11], 0, v[144:145]
	v_bfe_u32 v164, v206, 4, 2
	v_lshlrev_b32_e32 v164, 4, v164
	v_mov_b32_e32 v165, 0
	v_lshl_add_u64 v[160:161], v[144:145], 0, v[164:165]
	global_load_dwordx4 v[156:159], v[160:161], off
	v_lshlrev_b64 v[174:175], 13, v[146:147]
	v_lshl_or_b32 v144, s7, 8, v150
	v_ashrrev_i32_e32 v145, 31, v144
	v_or_b32_e32 v172, 16, v146
	v_lshl_add_u64 v[144:145], v[144:145], 1, s[12:13]
	v_ashrrev_i32_e32 v173, 31, v172
	s_waitcnt vmcnt(0)
	v_add_f32_e32 v160, v156, v157
	v_add_f32_e32 v161, v158, v159
	v_add_f32_e32 v160, v160, v161
	ds_swizzle_b32 v161, v160 offset:swizzle(SWAP,16)
	s_waitcnt lgkmcnt(0)
	v_add_f32_e32 v160, v160, v161
	v_mov_b32_e32 v161, v160
	s_nop 1
	v_permlane32_swap_b32_e32 v160, v161
	v_add_f32_e32 v168, v160, v161
	s_nop 0
	v_lshlrev_b64 v[158:159], 6, v[172:173]
	v_mov_b32_e32 v147, v168
	v_fmamk_f32 v147, v147, 0x3a800000, v154
	v_mul_f32_e32 v155, 0x4b800000, v147
	v_cmp_gt_f32_e32 vcc, s48, v147
	v_lshl_add_u64 v[156:157], v[144:145], 0, v[174:175]
	v_lshl_add_u64 v[158:159], s[10:11], 0, v[158:159]
	v_cndmask_b32_e32 v147, v147, v155, vcc
	v_rsq_f32_e32 v147, v147
	s_nop 0
	v_mul_f32_e32 v155, 0x45800000, v147
	v_cndmask_b32_e32 v160, v147, v155, vcc
	v_pk_mul_f32 v[126:127], v[126:127], v[160:161] op_sel_hi:[1,0]
	v_pk_mul_f32 v[124:125], v[124:125], v[160:161] op_sel_hi:[1,0]
	v_pk_mul_f32 v[122:123], v[122:123], v[160:161] op_sel_hi:[1,0]
	v_pk_mul_f32 v[120:121], v[120:121], v[160:161] op_sel_hi:[1,0]
	v_pk_mul_f32 v[114:115], v[114:115], v[160:161] op_sel_hi:[1,0]
	v_pk_mul_f32 v[112:113], v[112:113], v[160:161] op_sel_hi:[1,0]
	v_pk_mul_f32 v[118:119], v[118:119], v[160:161] op_sel_hi:[1,0]
	v_pk_mul_f32 v[116:117], v[116:117], v[160:161] op_sel_hi:[1,0]
	v_max_f32_e32 v124, 0, v124
	v_max_f32_e32 v120, 0, v120
	v_max_f32_e32 v125, 0, v125
	v_max_f32_e32 v121, 0, v121
	v_max_f32_e32 v126, 0, v126
	v_max_f32_e32 v122, 0, v122
	v_max_f32_e32 v127, 0, v127
	v_max_f32_e32 v123, 0, v123
	v_max_f32_e32 v112, 0, v112
	v_max_f32_e32 v113, 0, v113
	v_max_f32_e32 v114, 0, v114
	v_max_f32_e32 v115, 0, v115
	v_max_f32_e32 v116, 0, v116
	v_max_f32_e32 v117, 0, v117
	v_max_f32_e32 v118, 0, v118
	v_max_f32_e32 v119, 0, v119
	v_mul_f32_e32 v124, v124, v124
	v_mul_f32_e32 v120, v120, v120
	v_mul_f32_e32 v125, v125, v125
	v_mul_f32_e32 v121, v121, v121
	v_mul_f32_e32 v126, v126, v126
	v_mul_f32_e32 v122, v122, v122
	v_mul_f32_e32 v127, v127, v127
	v_mul_f32_e32 v123, v123, v123
	v_mul_f32_e32 v147, v112, v112
	v_mul_f32_e32 v155, v113, v113
	v_mul_f32_e32 v160, v114, v114
	v_mul_f32_e32 v161, v115, v115
	v_cvt_pk_bf16_f32 v112, v124, v125
	v_cvt_pk_bf16_f32 v113, v126, v127
	v_cvt_pk_bf16_f32 v114, v120, v121
	v_cvt_pk_bf16_f32 v115, v122, v123
	v_mul_f32_e32 v116, v116, v116
	v_mul_f32_e32 v117, v117, v117
	v_mul_f32_e32 v118, v118, v118
	v_mul_f32_e32 v119, v119, v119
	global_store_dwordx4 v[156:157], v[112:115], off
	s_nop 1
	v_cvt_pk_bf16_f32 v112, v116, v117
	v_cvt_pk_bf16_f32 v113, v118, v119
	v_cvt_pk_bf16_f32 v114, v147, v155
	v_cvt_pk_bf16_f32 v115, v160, v161
	global_store_dwordx4 v[156:157], v[112:115], off offset:256
	v_bfe_u32 v120, v206, 4, 2
	v_lshlrev_b32_e32 v120, 4, v120
	v_mov_b32_e32 v121, 0
	v_lshl_add_u64 v[116:117], v[158:159], 0, v[120:121]
	global_load_dwordx4 v[112:115], v[116:117], off
	s_nop 0
	v_or_b32_e32 v156, 32, v146
	v_ashrrev_i32_e32 v157, 31, v156
	v_lshlrev_b64 v[158:159], 13, v[172:173]
	s_waitcnt vmcnt(0)
	v_add_f32_e32 v116, v112, v113
	v_add_f32_e32 v117, v114, v115
	v_add_f32_e32 v116, v116, v117
	ds_swizzle_b32 v117, v116 offset:swizzle(SWAP,16)
	s_waitcnt lgkmcnt(0)
	v_add_f32_e32 v116, v116, v117
	v_mov_b32_e32 v117, v116
	s_nop 1
	v_permlane32_swap_b32_e32 v116, v117
	v_add_f32_e32 v124, v116, v117
	s_nop 0
	v_lshl_add_u64 v[114:115], v[144:145], 0, v[158:159]
	v_mov_b32_e32 v112, v124
	v_fmamk_f32 v112, v112, 0x3a800000, v154
	v_mul_f32_e32 v113, 0x4b800000, v112
	v_cmp_gt_f32_e32 vcc, s48, v112
	s_nop 1
	v_cndmask_b32_e32 v112, v112, v113, vcc
	v_rsq_f32_e32 v116, v112
	v_lshlrev_b64 v[112:113], 6, v[156:157]
	v_lshl_add_u64 v[112:113], s[10:11], 0, v[112:113]
	v_mul_f32_e32 v117, 0x45800000, v116
	v_cndmask_b32_e32 v116, v116, v117, vcc
	v_pk_mul_f32 v[110:111], v[110:111], v[116:117] op_sel_hi:[1,0]
	v_pk_mul_f32 v[108:109], v[108:109], v[116:117] op_sel_hi:[1,0]
	v_pk_mul_f32 v[106:107], v[106:107], v[116:117] op_sel_hi:[1,0]
	v_pk_mul_f32 v[104:105], v[104:105], v[116:117] op_sel_hi:[1,0]
	v_pk_mul_f32 v[98:99], v[98:99], v[116:117] op_sel_hi:[1,0]
	v_pk_mul_f32 v[96:97], v[96:97], v[116:117] op_sel_hi:[1,0]
	v_pk_mul_f32 v[102:103], v[102:103], v[116:117] op_sel_hi:[1,0]
	v_pk_mul_f32 v[100:101], v[100:101], v[116:117] op_sel_hi:[1,0]
	v_max_f32_e32 v108, 0, v108
	v_max_f32_e32 v104, 0, v104
	v_max_f32_e32 v109, 0, v109
	v_max_f32_e32 v105, 0, v105
	v_max_f32_e32 v110, 0, v110
	v_max_f32_e32 v106, 0, v106
	v_max_f32_e32 v111, 0, v111
	v_max_f32_e32 v107, 0, v107
	v_max_f32_e32 v96, 0, v96
	v_max_f32_e32 v97, 0, v97
	v_max_f32_e32 v98, 0, v98
	v_max_f32_e32 v99, 0, v99
	v_max_f32_e32 v100, 0, v100
	v_max_f32_e32 v101, 0, v101
	v_max_f32_e32 v102, 0, v102
	v_max_f32_e32 v103, 0, v103
	v_mul_f32_e32 v108, v108, v108
	v_mul_f32_e32 v104, v104, v104
	v_mul_f32_e32 v109, v109, v109
	v_mul_f32_e32 v105, v105, v105
	v_mul_f32_e32 v110, v110, v110
	v_mul_f32_e32 v106, v106, v106
	v_mul_f32_e32 v111, v111, v111
	v_mul_f32_e32 v107, v107, v107
	v_mul_f32_e32 v116, v96, v96
	v_mul_f32_e32 v117, v97, v97
	v_mul_f32_e32 v118, v98, v98
	v_mul_f32_e32 v119, v99, v99
	v_cvt_pk_bf16_f32 v96, v108, v109
	v_cvt_pk_bf16_f32 v97, v110, v111
	v_cvt_pk_bf16_f32 v98, v104, v105
	v_cvt_pk_bf16_f32 v99, v106, v107
	v_mul_f32_e32 v100, v100, v100
	v_mul_f32_e32 v101, v101, v101
	v_mul_f32_e32 v102, v102, v102
	v_mul_f32_e32 v103, v103, v103
	global_store_dwordx4 v[114:115], v[96:99], off
	s_nop 1
	v_cvt_pk_bf16_f32 v96, v100, v101
	v_cvt_pk_bf16_f32 v97, v102, v103
	v_cvt_pk_bf16_f32 v98, v116, v117
	v_cvt_pk_bf16_f32 v99, v118, v119
	global_store_dwordx4 v[114:115], v[96:99], off offset:256
	v_bfe_u32 v104, v206, 4, 2
	v_lshlrev_b32_e32 v104, 4, v104
	v_mov_b32_e32 v105, 0
	v_lshl_add_u64 v[100:101], v[112:113], 0, v[104:105]
	global_load_dwordx4 v[96:99], v[100:101], off
	s_nop 0
	v_or_b32_e32 v112, 48, v146
	v_ashrrev_i32_e32 v113, 31, v112
	v_lshlrev_b64 v[114:115], 13, v[156:157]
	s_waitcnt vmcnt(0)
	v_add_f32_e32 v100, v96, v97
	v_add_f32_e32 v101, v98, v99
	v_add_f32_e32 v100, v100, v101
	ds_swizzle_b32 v101, v100 offset:swizzle(SWAP,16)
	s_waitcnt lgkmcnt(0)
	v_add_f32_e32 v100, v100, v101
	v_mov_b32_e32 v101, v100
	s_nop 1
	v_permlane32_swap_b32_e32 v100, v101
	v_add_f32_e32 v108, v100, v101
	s_nop 0
	v_lshl_add_u64 v[98:99], v[144:145], 0, v[114:115]
	v_mov_b32_e32 v96, v108
	v_fmamk_f32 v96, v96, 0x3a800000, v154
	v_mul_f32_e32 v97, 0x4b800000, v96
	v_cmp_gt_f32_e32 vcc, s48, v96
	s_nop 1
	v_cndmask_b32_e32 v96, v96, v97, vcc
	v_rsq_f32_e32 v100, v96
	v_lshlrev_b64 v[96:97], 6, v[112:113]
	v_lshl_add_u64 v[96:97], s[10:11], 0, v[96:97]
	v_mul_f32_e32 v101, 0x45800000, v100
	v_cndmask_b32_e32 v100, v100, v101, vcc
	v_pk_mul_f32 v[94:95], v[94:95], v[100:101] op_sel_hi:[1,0]
	v_pk_mul_f32 v[92:93], v[92:93], v[100:101] op_sel_hi:[1,0]
	v_pk_mul_f32 v[90:91], v[90:91], v[100:101] op_sel_hi:[1,0]
	v_pk_mul_f32 v[88:89], v[88:89], v[100:101] op_sel_hi:[1,0]
	v_pk_mul_f32 v[82:83], v[82:83], v[100:101] op_sel_hi:[1,0]
	v_pk_mul_f32 v[80:81], v[80:81], v[100:101] op_sel_hi:[1,0]
	v_pk_mul_f32 v[86:87], v[86:87], v[100:101] op_sel_hi:[1,0]
	v_pk_mul_f32 v[84:85], v[84:85], v[100:101] op_sel_hi:[1,0]
	v_max_f32_e32 v92, 0, v92
	v_max_f32_e32 v88, 0, v88
	v_max_f32_e32 v93, 0, v93
	v_max_f32_e32 v89, 0, v89
	v_max_f32_e32 v94, 0, v94
	v_max_f32_e32 v90, 0, v90
	v_max_f32_e32 v95, 0, v95
	v_max_f32_e32 v91, 0, v91
	v_max_f32_e32 v80, 0, v80
	v_max_f32_e32 v81, 0, v81
	v_max_f32_e32 v82, 0, v82
	v_max_f32_e32 v83, 0, v83
	v_max_f32_e32 v84, 0, v84
	v_max_f32_e32 v85, 0, v85
	v_max_f32_e32 v86, 0, v86
	v_max_f32_e32 v87, 0, v87
	v_mul_f32_e32 v92, v92, v92
	v_mul_f32_e32 v88, v88, v88
	v_mul_f32_e32 v93, v93, v93
	v_mul_f32_e32 v89, v89, v89
	v_mul_f32_e32 v94, v94, v94
	v_mul_f32_e32 v90, v90, v90
	v_mul_f32_e32 v95, v95, v95
	v_mul_f32_e32 v91, v91, v91
	v_mul_f32_e32 v100, v80, v80
	v_mul_f32_e32 v101, v81, v81
	v_mul_f32_e32 v102, v82, v82
	v_mul_f32_e32 v103, v83, v83
	v_cvt_pk_bf16_f32 v80, v92, v93
	v_cvt_pk_bf16_f32 v81, v94, v95
	v_cvt_pk_bf16_f32 v82, v88, v89
	v_cvt_pk_bf16_f32 v83, v90, v91
	v_mul_f32_e32 v84, v84, v84
	v_mul_f32_e32 v85, v85, v85
	v_mul_f32_e32 v86, v86, v86
	v_mul_f32_e32 v87, v87, v87
	global_store_dwordx4 v[98:99], v[80:83], off
	s_nop 1
	v_cvt_pk_bf16_f32 v80, v84, v85
	v_cvt_pk_bf16_f32 v81, v86, v87
	v_cvt_pk_bf16_f32 v82, v100, v101
	v_cvt_pk_bf16_f32 v83, v102, v103
	global_store_dwordx4 v[98:99], v[80:83], off offset:256
	v_bfe_u32 v88, v206, 4, 2
	v_lshlrev_b32_e32 v88, 4, v88
	v_mov_b32_e32 v89, 0
	v_lshl_add_u64 v[84:85], v[96:97], 0, v[88:89]
	global_load_dwordx4 v[80:83], v[84:85], off
	s_nop 0
	v_add_u32_e32 v96, 0x80, v146
	v_ashrrev_i32_e32 v97, 31, v96
	v_lshlrev_b64 v[98:99], 13, v[112:113]
	s_waitcnt vmcnt(0)
	v_add_f32_e32 v84, v80, v81
	v_add_f32_e32 v85, v82, v83
	v_add_f32_e32 v84, v84, v85
	ds_swizzle_b32 v85, v84 offset:swizzle(SWAP,16)
	s_waitcnt lgkmcnt(0)
	v_add_f32_e32 v84, v84, v85
	v_mov_b32_e32 v85, v84
	s_nop 1
	v_permlane32_swap_b32_e32 v84, v85
	v_add_f32_e32 v92, v84, v85
	s_nop 0
	v_lshl_add_u64 v[82:83], v[144:145], 0, v[98:99]
	v_mov_b32_e32 v80, v92
	v_fmamk_f32 v80, v80, 0x3a800000, v154
	v_mul_f32_e32 v81, 0x4b800000, v80
	v_cmp_gt_f32_e32 vcc, s48, v80
	s_nop 1
	v_cndmask_b32_e32 v80, v80, v81, vcc
	v_rsq_f32_e32 v84, v80
	v_lshlrev_b64 v[80:81], 6, v[96:97]
	v_lshl_add_u64 v[80:81], s[10:11], 0, v[80:81]
	v_mul_f32_e32 v85, 0x45800000, v84
	v_cndmask_b32_e32 v84, v84, v85, vcc
	v_pk_mul_f32 v[78:79], v[78:79], v[84:85] op_sel_hi:[1,0]
	v_pk_mul_f32 v[76:77], v[76:77], v[84:85] op_sel_hi:[1,0]
	v_pk_mul_f32 v[74:75], v[74:75], v[84:85] op_sel_hi:[1,0]
	v_pk_mul_f32 v[72:73], v[72:73], v[84:85] op_sel_hi:[1,0]
	v_pk_mul_f32 v[66:67], v[66:67], v[84:85] op_sel_hi:[1,0]
	v_pk_mul_f32 v[64:65], v[64:65], v[84:85] op_sel_hi:[1,0]
	v_pk_mul_f32 v[70:71], v[70:71], v[84:85] op_sel_hi:[1,0]
	v_pk_mul_f32 v[68:69], v[68:69], v[84:85] op_sel_hi:[1,0]
	v_max_f32_e32 v76, 0, v76
	v_max_f32_e32 v72, 0, v72
	v_max_f32_e32 v77, 0, v77
	v_max_f32_e32 v73, 0, v73
	v_max_f32_e32 v78, 0, v78
	v_max_f32_e32 v74, 0, v74
	v_max_f32_e32 v79, 0, v79
	v_max_f32_e32 v75, 0, v75
	v_max_f32_e32 v64, 0, v64
	v_max_f32_e32 v65, 0, v65
	v_max_f32_e32 v66, 0, v66
	v_max_f32_e32 v67, 0, v67
	v_max_f32_e32 v68, 0, v68
	v_max_f32_e32 v69, 0, v69
	v_max_f32_e32 v70, 0, v70
	v_max_f32_e32 v71, 0, v71
	v_mul_f32_e32 v76, v76, v76
	v_mul_f32_e32 v72, v72, v72
	v_mul_f32_e32 v77, v77, v77
	v_mul_f32_e32 v73, v73, v73
	v_mul_f32_e32 v78, v78, v78
	v_mul_f32_e32 v74, v74, v74
	v_mul_f32_e32 v79, v79, v79
	v_mul_f32_e32 v75, v75, v75
	v_mul_f32_e32 v84, v64, v64
	v_mul_f32_e32 v85, v65, v65
	v_mul_f32_e32 v86, v66, v66
	v_mul_f32_e32 v87, v67, v67
	v_cvt_pk_bf16_f32 v64, v76, v77
	v_cvt_pk_bf16_f32 v65, v78, v79
	v_cvt_pk_bf16_f32 v66, v72, v73
	v_cvt_pk_bf16_f32 v67, v74, v75
	v_mul_f32_e32 v68, v68, v68
	v_mul_f32_e32 v69, v69, v69
	v_mul_f32_e32 v70, v70, v70
	v_mul_f32_e32 v71, v71, v71
	global_store_dwordx4 v[82:83], v[64:67], off
	s_nop 1
	v_cvt_pk_bf16_f32 v64, v68, v69
	v_cvt_pk_bf16_f32 v65, v70, v71
	v_cvt_pk_bf16_f32 v66, v84, v85
	v_cvt_pk_bf16_f32 v67, v86, v87
	global_store_dwordx4 v[82:83], v[64:67], off offset:256
	v_bfe_u32 v72, v206, 4, 2
	v_lshlrev_b32_e32 v72, 4, v72
	v_mov_b32_e32 v73, 0
	v_lshl_add_u64 v[68:69], v[80:81], 0, v[72:73]
	global_load_dwordx4 v[64:67], v[68:69], off
	s_nop 0
	v_add_u32_e32 v80, 0x90, v146
	v_ashrrev_i32_e32 v81, 31, v80
	v_lshlrev_b64 v[82:83], 13, v[96:97]
	s_waitcnt vmcnt(0)
	v_add_f32_e32 v68, v64, v65
	v_add_f32_e32 v69, v66, v67
	v_add_f32_e32 v68, v68, v69
	ds_swizzle_b32 v69, v68 offset:swizzle(SWAP,16)
	s_waitcnt lgkmcnt(0)
	v_add_f32_e32 v68, v68, v69
	v_mov_b32_e32 v69, v68
	s_nop 1
	v_permlane32_swap_b32_e32 v68, v69
	v_add_f32_e32 v76, v68, v69
	s_nop 0
	v_lshl_add_u64 v[66:67], v[144:145], 0, v[82:83]
	v_mov_b32_e32 v64, v76
	v_fmamk_f32 v64, v64, 0x3a800000, v154
	v_mul_f32_e32 v65, 0x4b800000, v64
	v_cmp_gt_f32_e32 vcc, s48, v64
	s_nop 1
	v_cndmask_b32_e32 v64, v64, v65, vcc
	v_rsq_f32_e32 v68, v64
	v_lshlrev_b64 v[64:65], 6, v[80:81]
	v_lshl_add_u64 v[64:65], s[10:11], 0, v[64:65]
	v_mul_f32_e32 v69, 0x45800000, v68
	v_cndmask_b32_e32 v68, v68, v69, vcc
	v_pk_mul_f32 v[62:63], v[62:63], v[68:69] op_sel_hi:[1,0]
	v_pk_mul_f32 v[60:61], v[60:61], v[68:69] op_sel_hi:[1,0]
	v_pk_mul_f32 v[58:59], v[58:59], v[68:69] op_sel_hi:[1,0]
	v_pk_mul_f32 v[56:57], v[56:57], v[68:69] op_sel_hi:[1,0]
	v_pk_mul_f32 v[50:51], v[50:51], v[68:69] op_sel_hi:[1,0]
	v_pk_mul_f32 v[48:49], v[48:49], v[68:69] op_sel_hi:[1,0]
	v_pk_mul_f32 v[54:55], v[54:55], v[68:69] op_sel_hi:[1,0]
	v_pk_mul_f32 v[52:53], v[52:53], v[68:69] op_sel_hi:[1,0]
	v_max_f32_e32 v60, 0, v60
	v_max_f32_e32 v56, 0, v56
	v_max_f32_e32 v61, 0, v61
	v_max_f32_e32 v57, 0, v57
	v_max_f32_e32 v62, 0, v62
	v_max_f32_e32 v58, 0, v58
	v_max_f32_e32 v63, 0, v63
	v_max_f32_e32 v59, 0, v59
	v_max_f32_e32 v48, 0, v48
	v_max_f32_e32 v49, 0, v49
	v_max_f32_e32 v50, 0, v50
	v_max_f32_e32 v51, 0, v51
	v_max_f32_e32 v52, 0, v52
	v_max_f32_e32 v53, 0, v53
	v_max_f32_e32 v54, 0, v54
	v_max_f32_e32 v55, 0, v55
	v_mul_f32_e32 v60, v60, v60
	v_mul_f32_e32 v56, v56, v56
	v_mul_f32_e32 v61, v61, v61
	v_mul_f32_e32 v57, v57, v57
	v_mul_f32_e32 v62, v62, v62
	v_mul_f32_e32 v58, v58, v58
	v_mul_f32_e32 v63, v63, v63
	v_mul_f32_e32 v59, v59, v59
	v_mul_f32_e32 v68, v48, v48
	v_mul_f32_e32 v69, v49, v49
	v_mul_f32_e32 v70, v50, v50
	v_mul_f32_e32 v71, v51, v51
	v_cvt_pk_bf16_f32 v48, v60, v61
	v_cvt_pk_bf16_f32 v49, v62, v63
	v_cvt_pk_bf16_f32 v50, v56, v57
	v_cvt_pk_bf16_f32 v51, v58, v59
	v_mul_f32_e32 v52, v52, v52
	v_mul_f32_e32 v53, v53, v53
	v_mul_f32_e32 v54, v54, v54
	v_mul_f32_e32 v55, v55, v55
	global_store_dwordx4 v[66:67], v[48:51], off
	s_nop 1
	v_cvt_pk_bf16_f32 v48, v52, v53
	v_cvt_pk_bf16_f32 v49, v54, v55
	v_cvt_pk_bf16_f32 v50, v68, v69
	v_cvt_pk_bf16_f32 v51, v70, v71
	global_store_dwordx4 v[66:67], v[48:51], off offset:256
	v_bfe_u32 v56, v206, 4, 2
	v_lshlrev_b32_e32 v56, 4, v56
	v_mov_b32_e32 v57, 0
	v_lshl_add_u64 v[52:53], v[64:65], 0, v[56:57]
	global_load_dwordx4 v[48:51], v[52:53], off
	s_nop 0
	v_add_u32_e32 v64, 0xa0, v146
	v_ashrrev_i32_e32 v65, 31, v64
	v_lshlrev_b64 v[66:67], 13, v[80:81]
	s_waitcnt vmcnt(0)
	v_add_f32_e32 v52, v48, v49
	v_add_f32_e32 v53, v50, v51
	v_add_f32_e32 v52, v52, v53
	ds_swizzle_b32 v53, v52 offset:swizzle(SWAP,16)
	s_waitcnt lgkmcnt(0)
	v_add_f32_e32 v52, v52, v53
	v_mov_b32_e32 v53, v52
	s_nop 1
	v_permlane32_swap_b32_e32 v52, v53
	v_add_f32_e32 v60, v52, v53
	s_nop 0
	v_lshl_add_u64 v[50:51], v[144:145], 0, v[66:67]
	v_mov_b32_e32 v48, v60
	v_fmamk_f32 v48, v48, 0x3a800000, v154
	v_mul_f32_e32 v49, 0x4b800000, v48
	v_cmp_gt_f32_e32 vcc, s48, v48
	s_nop 1
	v_cndmask_b32_e32 v48, v48, v49, vcc
	v_rsq_f32_e32 v52, v48
	v_lshlrev_b64 v[48:49], 6, v[64:65]
	v_lshl_add_u64 v[48:49], s[10:11], 0, v[48:49]
	v_mul_f32_e32 v53, 0x45800000, v52
	v_cndmask_b32_e32 v52, v52, v53, vcc
	v_pk_mul_f32 v[46:47], v[46:47], v[52:53] op_sel_hi:[1,0]
	v_pk_mul_f32 v[44:45], v[44:45], v[52:53] op_sel_hi:[1,0]
	v_pk_mul_f32 v[42:43], v[42:43], v[52:53] op_sel_hi:[1,0]
	v_pk_mul_f32 v[40:41], v[40:41], v[52:53] op_sel_hi:[1,0]
	v_pk_mul_f32 v[34:35], v[34:35], v[52:53] op_sel_hi:[1,0]
	v_pk_mul_f32 v[32:33], v[32:33], v[52:53] op_sel_hi:[1,0]
	v_pk_mul_f32 v[38:39], v[38:39], v[52:53] op_sel_hi:[1,0]
	v_pk_mul_f32 v[36:37], v[36:37], v[52:53] op_sel_hi:[1,0]
	v_max_f32_e32 v44, 0, v44
	v_max_f32_e32 v40, 0, v40
	v_max_f32_e32 v45, 0, v45
	v_max_f32_e32 v41, 0, v41
	v_max_f32_e32 v46, 0, v46
	v_max_f32_e32 v42, 0, v42
	v_max_f32_e32 v47, 0, v47
	v_max_f32_e32 v43, 0, v43
	v_max_f32_e32 v32, 0, v32
	v_max_f32_e32 v33, 0, v33
	v_max_f32_e32 v34, 0, v34
	v_max_f32_e32 v35, 0, v35
	v_max_f32_e32 v36, 0, v36
	v_max_f32_e32 v37, 0, v37
	v_max_f32_e32 v38, 0, v38
	v_max_f32_e32 v39, 0, v39
	v_mul_f32_e32 v44, v44, v44
	v_mul_f32_e32 v40, v40, v40
	v_mul_f32_e32 v45, v45, v45
	v_mul_f32_e32 v41, v41, v41
	v_mul_f32_e32 v46, v46, v46
	v_mul_f32_e32 v42, v42, v42
	v_mul_f32_e32 v47, v47, v47
	v_mul_f32_e32 v43, v43, v43
	v_mul_f32_e32 v52, v32, v32
	v_mul_f32_e32 v53, v33, v33
	v_mul_f32_e32 v54, v34, v34
	v_mul_f32_e32 v55, v35, v35
	v_cvt_pk_bf16_f32 v32, v44, v45
	v_cvt_pk_bf16_f32 v33, v46, v47
	v_cvt_pk_bf16_f32 v34, v40, v41
	v_cvt_pk_bf16_f32 v35, v42, v43
	v_mul_f32_e32 v36, v36, v36
	v_mul_f32_e32 v37, v37, v37
	v_mul_f32_e32 v38, v38, v38
	v_mul_f32_e32 v39, v39, v39
	global_store_dwordx4 v[50:51], v[32:35], off
	s_nop 1
	v_cvt_pk_bf16_f32 v32, v36, v37
	v_cvt_pk_bf16_f32 v33, v38, v39
	v_cvt_pk_bf16_f32 v34, v52, v53
	v_cvt_pk_bf16_f32 v35, v54, v55
	global_store_dwordx4 v[50:51], v[32:35], off offset:256
	v_bfe_u32 v40, v206, 4, 2
	v_lshlrev_b32_e32 v40, 4, v40
	v_mov_b32_e32 v41, 0
	v_lshl_add_u64 v[36:37], v[48:49], 0, v[40:41]
	global_load_dwordx4 v[32:35], v[36:37], off
	s_nop 0
	v_add_u32_e32 v48, 0xb0, v146
	v_ashrrev_i32_e32 v49, 31, v48
	v_lshlrev_b64 v[50:51], 13, v[64:65]
	s_waitcnt vmcnt(0)
	v_add_f32_e32 v36, v32, v33
	v_add_f32_e32 v37, v34, v35
	v_add_f32_e32 v36, v36, v37
	ds_swizzle_b32 v37, v36 offset:swizzle(SWAP,16)
	s_waitcnt lgkmcnt(0)
	v_add_f32_e32 v36, v36, v37
	v_mov_b32_e32 v37, v36
	s_nop 1
	v_permlane32_swap_b32_e32 v36, v37
	v_add_f32_e32 v44, v36, v37
	s_nop 0
	v_lshl_add_u64 v[34:35], v[144:145], 0, v[50:51]
	v_mov_b32_e32 v32, v44
	v_fmamk_f32 v32, v32, 0x3a800000, v154
	v_mul_f32_e32 v33, 0x4b800000, v32
	v_cmp_gt_f32_e32 vcc, s48, v32
	s_nop 1
	v_cndmask_b32_e32 v32, v32, v33, vcc
	v_rsq_f32_e32 v36, v32
	v_lshlrev_b64 v[32:33], 6, v[48:49]
	v_lshl_add_u64 v[32:33], s[10:11], 0, v[32:33]
	v_mul_f32_e32 v37, 0x45800000, v36
	v_cndmask_b32_e32 v36, v36, v37, vcc
	v_pk_mul_f32 v[30:31], v[30:31], v[36:37] op_sel_hi:[1,0]
	v_pk_mul_f32 v[28:29], v[28:29], v[36:37] op_sel_hi:[1,0]
	v_pk_mul_f32 v[26:27], v[26:27], v[36:37] op_sel_hi:[1,0]
	v_pk_mul_f32 v[24:25], v[24:25], v[36:37] op_sel_hi:[1,0]
	v_pk_mul_f32 v[18:19], v[18:19], v[36:37] op_sel_hi:[1,0]
	v_pk_mul_f32 v[16:17], v[16:17], v[36:37] op_sel_hi:[1,0]
	v_pk_mul_f32 v[22:23], v[22:23], v[36:37] op_sel_hi:[1,0]
	v_pk_mul_f32 v[20:21], v[20:21], v[36:37] op_sel_hi:[1,0]
	v_max_f32_e32 v28, 0, v28
	v_max_f32_e32 v24, 0, v24
	v_max_f32_e32 v29, 0, v29
	v_max_f32_e32 v25, 0, v25
	v_max_f32_e32 v30, 0, v30
	v_max_f32_e32 v26, 0, v26
	v_max_f32_e32 v31, 0, v31
	v_max_f32_e32 v27, 0, v27
	v_max_f32_e32 v16, 0, v16
	v_max_f32_e32 v17, 0, v17
	v_max_f32_e32 v18, 0, v18
	v_max_f32_e32 v19, 0, v19
	v_max_f32_e32 v20, 0, v20
	v_max_f32_e32 v21, 0, v21
	v_max_f32_e32 v22, 0, v22
	v_max_f32_e32 v23, 0, v23
	v_mul_f32_e32 v28, v28, v28
	v_mul_f32_e32 v24, v24, v24
	v_mul_f32_e32 v29, v29, v29
	v_mul_f32_e32 v25, v25, v25
	v_mul_f32_e32 v30, v30, v30
	v_mul_f32_e32 v26, v26, v26
	v_mul_f32_e32 v31, v31, v31
	v_mul_f32_e32 v27, v27, v27
	v_mul_f32_e32 v36, v16, v16
	v_mul_f32_e32 v37, v17, v17
	v_mul_f32_e32 v38, v18, v18
	v_mul_f32_e32 v39, v19, v19
	v_cvt_pk_bf16_f32 v16, v28, v29
	v_cvt_pk_bf16_f32 v17, v30, v31
	v_cvt_pk_bf16_f32 v18, v24, v25
	v_cvt_pk_bf16_f32 v19, v26, v27
	v_mul_f32_e32 v20, v20, v20
	v_mul_f32_e32 v21, v21, v21
	v_mul_f32_e32 v22, v22, v22
	v_mul_f32_e32 v23, v23, v23
	global_store_dwordx4 v[34:35], v[16:19], off
	s_andn2_b64 vcc, exec, s[4:5]
	s_mov_b64 s[4:5], -1
	v_cvt_pk_bf16_f32 v16, v20, v21
	v_cvt_pk_bf16_f32 v17, v22, v23
	v_cvt_pk_bf16_f32 v18, v36, v37
	v_cvt_pk_bf16_f32 v19, v38, v39
	global_store_dwordx4 v[34:35], v[16:19], off offset:256
	v_bfe_u32 v24, v206, 4, 2
	v_lshlrev_b32_e32 v24, 4, v24
	v_mov_b32_e32 v25, 0
	v_lshl_add_u64 v[20:21], v[32:33], 0, v[24:25]
	global_load_dwordx4 v[16:19], v[20:21], off
	s_nop 0
	s_waitcnt vmcnt(0)
	v_add_f32_e32 v20, v16, v17
	v_add_f32_e32 v21, v18, v19
	v_add_f32_e32 v20, v20, v21
	ds_swizzle_b32 v21, v20 offset:swizzle(SWAP,16)
	s_waitcnt lgkmcnt(0)
	v_add_f32_e32 v20, v20, v21
	v_mov_b32_e32 v21, v20
	s_nop 1
	v_permlane32_swap_b32_e32 v20, v21
	v_add_f32_e32 v28, v20, v21
	s_nop 0
	s_nop 0
	v_mov_b32_e32 v16, v28
	v_fmamk_f32 v16, v16, 0x3a800000, v154
	v_mul_f32_e32 v17, 0x4b800000, v16
	v_cmp_gt_f32_e64 s[6:7], s48, v16
	s_nop 1
	v_cndmask_b32_e64 v16, v16, v17, s[6:7]
	v_rsq_f32_e32 v18, v16
	v_lshlrev_b64 v[16:17], 13, v[48:49]
	v_lshl_add_u64 v[16:17], v[144:145], 0, v[16:17]
	v_mul_f32_e32 v19, 0x45800000, v18
	v_cndmask_b32_e64 v18, v18, v19, s[6:7]
	v_pk_mul_f32 v[14:15], v[14:15], v[18:19] op_sel_hi:[1,0]
	v_pk_mul_f32 v[12:13], v[12:13], v[18:19] op_sel_hi:[1,0]
	v_pk_mul_f32 v[10:11], v[10:11], v[18:19] op_sel_hi:[1,0]
	v_pk_mul_f32 v[8:9], v[8:9], v[18:19] op_sel_hi:[1,0]
	v_pk_mul_f32 v[2:3], v[2:3], v[18:19] op_sel_hi:[1,0]
	v_pk_mul_f32 v[0:1], v[0:1], v[18:19] op_sel_hi:[1,0]
	v_pk_mul_f32 v[6:7], v[6:7], v[18:19] op_sel_hi:[1,0]
	v_pk_mul_f32 v[4:5], v[4:5], v[18:19] op_sel_hi:[1,0]
	v_max_f32_e32 v12, 0, v12
	v_max_f32_e32 v8, 0, v8
	v_max_f32_e32 v13, 0, v13
	v_max_f32_e32 v9, 0, v9
	v_max_f32_e32 v14, 0, v14
	v_max_f32_e32 v10, 0, v10
	v_max_f32_e32 v15, 0, v15
	v_max_f32_e32 v11, 0, v11
	v_max_f32_e32 v0, 0, v0
	v_max_f32_e32 v1, 0, v1
	v_max_f32_e32 v2, 0, v2
	v_max_f32_e32 v3, 0, v3
	v_max_f32_e32 v4, 0, v4
	v_max_f32_e32 v5, 0, v5
	v_max_f32_e32 v6, 0, v6
	v_max_f32_e32 v7, 0, v7
	v_mul_f32_e32 v12, v12, v12
	v_mul_f32_e32 v8, v8, v8
	v_mul_f32_e32 v13, v13, v13
	v_mul_f32_e32 v9, v9, v9
	v_mul_f32_e32 v14, v14, v14
	v_mul_f32_e32 v10, v10, v10
	v_mul_f32_e32 v15, v15, v15
	v_mul_f32_e32 v11, v11, v11
	v_mul_f32_e32 v18, v0, v0
	v_mul_f32_e32 v19, v1, v1
	v_mul_f32_e32 v20, v2, v2
	v_mul_f32_e32 v21, v3, v3
	v_cvt_pk_bf16_f32 v0, v12, v13
	v_cvt_pk_bf16_f32 v1, v14, v15
	v_cvt_pk_bf16_f32 v2, v8, v9
	v_cvt_pk_bf16_f32 v3, v10, v11
	v_mul_f32_e32 v4, v4, v4
	v_mul_f32_e32 v5, v5, v5
	v_mul_f32_e32 v6, v6, v6
	v_mul_f32_e32 v7, v7, v7
	global_store_dwordx4 v[16:17], v[0:3], off
	s_nop 1
	v_cvt_pk_bf16_f32 v0, v4, v5
	v_cvt_pk_bf16_f32 v1, v6, v7
	v_cvt_pk_bf16_f32 v2, v18, v19
	v_cvt_pk_bf16_f32 v3, v20, v21
	global_store_dwordx4 v[16:17], v[0:3], off offset:256
	s_cbranch_vccnz .LBB0_691
	s_andn2_b64 vcc, exec, s[2:3]
	s_cbranch_vccnz .LBB0_690
	s_barrier
	s_branch .LBB0_690

.LBB0_898:
	v_lshl_add_u32 v142, s12, 8, v150
	v_ashrrev_i32_e32 v143, 31, v142
	v_lshlrev_b64 v[144:145], 6, v[142:143]
	v_lshl_add_u64 v[146:147], s[10:11], 0, v[144:145]
	v_bfe_u32 v166, v206, 4, 2
	v_lshlrev_b32_e32 v166, 4, v166
	v_mov_b32_e32 v167, 0
	v_lshl_add_u64 v[162:163], v[146:147], 0, v[166:167]
	global_load_dwordx4 v[158:161], v[162:163], off
	v_lshl_or_b32 v140, s2, 8, v152
	v_ashrrev_i32_e32 v141, 31, v140
	v_lshlrev_b64 v[146:147], 10, v[142:143]
	v_lshl_add_u64 v[146:147], v[146:147], 0, v[140:141]
	v_lshlrev_b64 v[146:147], 1, v[146:147]
	v_lshl_add_u64 v[148:149], s[20:21], 0, v[146:147]
	global_load_dwordx2 v[174:175], v[148:149], off
	v_lshl_add_u64 v[148:149], s[8:9], 0, v[146:147]
	global_load_dwordx2 v[176:177], v[148:149], off
	v_lshl_add_u64 v[178:179], s[16:17], 0, v[146:147]
	v_or_b32_e32 v180, 32, v146
	v_mov_b32_e32 v181, v147
	s_lshl_b32 s36, s2, 2
	s_ashr_i32 s37, s36, 31
	s_waitcnt vmcnt(0)
	v_add_f32_e32 v162, v158, v159
	v_add_f32_e32 v163, v160, v161
	v_add_f32_e32 v162, v162, v163
	ds_swizzle_b32 v163, v162 offset:swizzle(SWAP,16)
	s_waitcnt lgkmcnt(0)
	v_add_f32_e32 v162, v162, v163
	v_mov_b32_e32 v163, v162
	s_nop 1
	v_permlane32_swap_b32_e32 v162, v163
	v_add_f32_e32 v170, v162, v163
	v_lshlrev_b32_e32 v164, 16, v175
	v_lshlrev_b32_e32 v160, 16, v174
	v_mov_b32_e32 v143, v170
	v_fmamk_f32 v143, v143, 0x3a800000, v156
	v_mul_f32_e32 v157, 0x4b800000, v143
	v_cmp_gt_f32_e32 vcc, s56, v143
	v_and_b32_e32 v161, 0xffff0000, v174
	v_and_b32_e32 v165, 0xffff0000, v175
	v_cndmask_b32_e32 v143, v143, v157, vcc
	v_rsq_f32_e32 v143, v143
	v_lshlrev_b32_e32 v158, 16, v176
	v_and_b32_e32 v159, 0xffff0000, v176
	v_lshlrev_b32_e32 v162, 16, v177
	v_mul_f32_e32 v157, 0x45800000, v143
	v_cndmask_b32_e32 v143, v143, v157, vcc
	v_mul_f32_e32 v124, v124, v143
	v_mul_f32_e32 v125, v125, v143
	v_mul_f32_e32 v126, v126, v143
	v_mul_f32_e32 v127, v127, v143
	v_mul_f32_e32 v124, 0xbfb8aa3b, v124
	v_mul_f32_e32 v125, 0xbfb8aa3b, v125
	v_mul_f32_e32 v126, 0xbfb8aa3b, v126
	v_mul_f32_e32 v127, 0xbfb8aa3b, v127
	v_exp_f32_e32 v124, v124
	v_exp_f32_e32 v125, v125
	v_exp_f32_e32 v126, v126
	v_exp_f32_e32 v127, v127
	v_add_f32_e32 v124, 1.0, v124
	v_add_f32_e32 v157, 1.0, v125
	v_add_f32_e32 v125, 1.0, v126
	v_add_f32_e32 v127, 1.0, v127
	v_rcp_f32_e32 v126, v124
	v_rcp_f32_e32 v124, v125
	v_rcp_f32_e32 v125, v127
	v_rcp_f32_e32 v127, v157
	v_and_b32_e32 v163, 0xffff0000, v177
	v_mul_f32_e32 v120, v120, v143
	v_pk_fma_f32 v[124:125], v[124:125], v[164:165], v[162:163]
	v_pk_fma_f32 v[126:127], v[126:127], v[160:161], v[158:159]
	v_lshl_add_u64 v[162:163], s[20:21], 0, v[180:181]
	v_cvt_pk_bf16_f32 v158, v126, v127
	v_cvt_pk_bf16_f32 v159, v124, v125
	global_store_dwordx2 v[178:179], v[158:159], off
	global_load_dwordx2 v[160:161], v[148:149], off offset:32
	v_mul_f32_e32 v121, v121, v143
	global_load_dwordx2 v[158:159], v[162:163], off
	v_mul_f32_e32 v122, v122, v143
	v_mul_f32_e32 v123, v123, v143
	v_mul_f32_e32 v120, 0xbfb8aa3b, v120
	v_mul_f32_e32 v121, 0xbfb8aa3b, v121
	v_mul_f32_e32 v122, 0xbfb8aa3b, v122
	v_mul_f32_e32 v123, 0xbfb8aa3b, v123
	v_exp_f32_e32 v120, v120
	v_exp_f32_e32 v121, v121
	v_exp_f32_e32 v122, v122
	v_exp_f32_e32 v123, v123
	v_add_f32_e32 v120, 1.0, v120
	v_add_f32_e32 v121, 1.0, v121
	v_add_f32_e32 v122, 1.0, v122
	v_add_f32_e32 v123, 1.0, v123
	v_rcp_f32_e32 v120, v120
	v_rcp_f32_e32 v121, v121
	v_rcp_f32_e32 v122, v122
	v_rcp_f32_e32 v123, v123
	v_or_b32_e32 v162, 0x100, v146
	v_mov_b32_e32 v163, v147
	v_mul_f32_e32 v118, v118, v143
	v_mul_f32_e32 v119, v119, v143
	v_mul_f32_e32 v116, v116, v143
	v_mul_f32_e32 v117, v117, v143
	v_mul_f32_e32 v118, 0xbfb8aa3b, v118
	v_mul_f32_e32 v119, 0xbfb8aa3b, v119
	v_mul_f32_e32 v116, 0xbfb8aa3b, v116
	v_mul_f32_e32 v117, 0xbfb8aa3b, v117
	v_exp_f32_e32 v118, v118
	v_exp_f32_e32 v119, v119
	v_exp_f32_e32 v116, v116
	v_exp_f32_e32 v117, v117
	v_add_f32_e32 v118, 1.0, v118
	v_add_f32_e32 v119, 1.0, v119
	v_add_f32_e32 v116, 1.0, v116
	v_add_f32_e32 v117, 1.0, v117
	v_rcp_f32_e32 v118, v118
	v_rcp_f32_e32 v119, v119
	v_rcp_f32_e32 v116, v116
	v_rcp_f32_e32 v117, v117
	v_or_b32_e32 v146, 0x120, v146
	v_mul_f32_e32 v112, v112, v143
	v_mul_f32_e32 v113, v113, v143
	v_mul_f32_e32 v114, v114, v143
	v_mul_f32_e32 v115, v115, v143
	v_mul_f32_e32 v112, 0xbfb8aa3b, v112
	v_mul_f32_e32 v113, 0xbfb8aa3b, v113
	v_mul_f32_e32 v114, 0xbfb8aa3b, v114
	v_mul_f32_e32 v115, 0xbfb8aa3b, v115
	v_exp_f32_e32 v112, v112
	v_exp_f32_e32 v113, v113
	v_exp_f32_e32 v114, v114
	v_exp_f32_e32 v115, v115
	v_add_f32_e32 v112, 1.0, v112
	v_add_f32_e32 v113, 1.0, v113
	v_add_f32_e32 v114, 1.0, v114
	v_add_f32_e32 v115, 1.0, v115
	v_mul_f32_e32 v127, v127, v127
	v_mul_f32_e32 v125, v125, v125
	v_rcp_f32_e32 v112, v112
	v_rcp_f32_e32 v113, v113
	v_rcp_f32_e32 v114, v114
	v_rcp_f32_e32 v115, v115
	v_fmac_f32_e32 v127, v126, v126
	v_fmac_f32_e32 v125, v124, v124
	v_add_f32_e32 v124, v127, v125
	s_waitcnt vmcnt(1)
	v_lshlrev_b32_e32 v164, 16, v160
	v_and_b32_e32 v165, 0xffff0000, v160
	s_waitcnt vmcnt(0)
	v_lshlrev_b32_e32 v166, 16, v158
	v_and_b32_e32 v167, 0xffff0000, v158
	v_lshlrev_b32_e32 v160, 16, v161
	v_and_b32_e32 v161, 0xffff0000, v161
	v_lshlrev_b32_e32 v158, 16, v159
	v_and_b32_e32 v159, 0xffff0000, v159
	v_pk_fma_f32 v[120:121], v[120:121], v[166:167], v[164:165]
	v_lshl_add_u64 v[164:165], s[16:17], 0, v[180:181]
	v_pk_fma_f32 v[122:123], v[122:123], v[158:159], v[160:161]
	v_cvt_pk_bf16_f32 v158, v120, v121
	v_lshl_add_u64 v[166:167], s[20:21], 0, v[162:163]
	v_cvt_pk_bf16_f32 v159, v122, v123
	global_store_dwordx2 v[164:165], v[158:159], off
	global_load_dwordx2 v[160:161], v[148:149], off offset:256
	v_mul_f32_e32 v121, v121, v121
	global_load_dwordx2 v[158:159], v[166:167], off
	v_mul_f32_e32 v123, v123, v123
	v_fmac_f32_e32 v121, v120, v120
	v_fmac_f32_e32 v123, v122, v122
	v_add_f32_e32 v120, v121, v123
	v_add_f32_e32 v120, v124, v120
	s_waitcnt vmcnt(1)
	v_lshlrev_b32_e32 v164, 16, v160
	v_and_b32_e32 v165, 0xffff0000, v160
	v_lshlrev_b32_e32 v160, 16, v161
	v_and_b32_e32 v161, 0xffff0000, v161
	s_waitcnt vmcnt(0)
	v_lshlrev_b32_e32 v166, 16, v158
	v_and_b32_e32 v167, 0xffff0000, v158
	v_lshlrev_b32_e32 v158, 16, v159
	v_and_b32_e32 v159, 0xffff0000, v159
	v_pk_fma_f32 v[118:119], v[118:119], v[158:159], v[160:161]
	v_lshl_add_u64 v[160:161], s[16:17], 0, v[162:163]
	v_pk_fma_f32 v[116:117], v[116:117], v[166:167], v[164:165]
	v_lshl_add_u64 v[162:163], s[20:21], 0, v[146:147]
	v_cvt_pk_bf16_f32 v158, v116, v117
	v_cvt_pk_bf16_f32 v159, v118, v119
	global_store_dwordx2 v[160:161], v[158:159], off
	global_load_dwordx2 v[148:149], v[148:149], off offset:288
	v_mul_f32_e32 v117, v117, v117
	global_load_dwordx2 v[158:159], v[162:163], off
	v_mul_f32_e32 v119, v119, v119
	v_fmac_f32_e32 v117, v116, v116
	v_fmac_f32_e32 v119, v118, v118
	v_add_f32_e32 v116, v117, v119
	v_add_f32_e32 v124, v116, v120
	s_waitcnt vmcnt(1)
	v_lshlrev_b32_e32 v116, 16, v148
	v_and_b32_e32 v117, 0xffff0000, v148
	v_lshlrev_b32_e32 v118, 16, v149
	v_and_b32_e32 v119, 0xffff0000, v149
	s_waitcnt vmcnt(0)
	v_lshlrev_b32_e32 v120, 16, v158
	v_and_b32_e32 v121, 0xffff0000, v158
	v_lshlrev_b32_e32 v122, 16, v159
	v_and_b32_e32 v123, 0xffff0000, v159
	v_pk_fma_f32 v[114:115], v[114:115], v[122:123], v[118:119]
	v_pk_fma_f32 v[112:113], v[112:113], v[120:121], v[116:117]
	v_mul_f32_e32 v117, v115, v115
	v_mul_f32_e32 v116, v113, v113
	v_fmac_f32_e32 v116, v112, v112
	v_fmac_f32_e32 v117, v114, v114
	v_add_f32_e32 v116, v116, v117
	v_add_f32_e32 v118, v124, v116
	ds_swizzle_b32 v119, v118 offset:swizzle(SWAP,16)
	v_lshl_add_u64 v[116:117], s[16:17], 0, v[146:147]
	v_cvt_pk_bf16_f32 v112, v112, v113
	v_cvt_pk_bf16_f32 v113, v114, v115
	global_store_dwordx2 v[116:117], v[112:113], off
	s_waitcnt lgkmcnt(0)
	v_add_f32_e32 v112, v118, v119
	v_mov_b32_e32 v113, v112
	s_nop 1
	v_permlane32_swap_b32_e32 v112, v113
	s_and_saveexec_b64 s[2:3], s[4:5]
	s_cbranch_execz .LBB0_900
	v_add_f32_e32 v114, v112, v113
	v_lshl_add_u64 v[112:113], s[18:19], 0, v[144:145]
	v_lshl_add_u64 v[112:113], s[36:37], 2, v[112:113]
	s_lshl_b32 s12, s50, 2
	v_lshl_add_u64 v[112:113], v[112:113], 0, s[12:13]
	global_store_dword v[112:113], v114, off
.LBB0_900:
	s_or_b64 exec, exec, s[2:3]
	v_or_b32_e32 v114, 16, v142
	v_ashrrev_i32_e32 v115, 31, v114
	v_lshlrev_b64 v[112:113], 6, v[114:115]
	v_lshl_add_u64 v[116:117], s[10:11], 0, v[112:113]
	v_bfe_u32 v144, v206, 4, 2
	v_lshlrev_b32_e32 v144, 4, v144
	v_mov_b32_e32 v145, 0
	v_lshl_add_u64 v[122:123], v[116:117], 0, v[144:145]
	global_load_dwordx4 v[118:121], v[122:123], off
	v_lshlrev_b64 v[114:115], 10, v[114:115]
	v_lshl_add_u64 v[114:115], v[114:115], 0, v[140:141]
	v_lshlrev_b64 v[114:115], 1, v[114:115]
	v_lshl_add_u64 v[116:117], s[20:21], 0, v[114:115]
	global_load_dwordx2 v[126:127], v[116:117], off
	v_lshl_add_u64 v[116:117], s[8:9], 0, v[114:115]
	global_load_dwordx2 v[148:149], v[116:117], off
	v_lshl_add_u64 v[162:163], s[16:17], 0, v[114:115]
	v_or_b32_e32 v164, 32, v114
	v_mov_b32_e32 v165, v115
	s_waitcnt vmcnt(0)
	v_add_f32_e32 v122, v118, v119
	v_add_f32_e32 v123, v120, v121
	v_add_f32_e32 v122, v122, v123
	ds_swizzle_b32 v123, v122 offset:swizzle(SWAP,16)
	s_waitcnt lgkmcnt(0)
	v_add_f32_e32 v122, v122, v123
	v_mov_b32_e32 v123, v122
	s_nop 1
	v_permlane32_swap_b32_e32 v122, v123
	v_add_f32_e32 v158, v122, v123
	v_lshlrev_b32_e32 v124, 16, v127
	v_lshlrev_b32_e32 v120, 16, v126
	v_mov_b32_e32 v118, v158
	v_fmamk_f32 v118, v118, 0x3a800000, v156
	v_mul_f32_e32 v119, 0x4b800000, v118
	v_cmp_gt_f32_e32 vcc, s56, v118
	v_and_b32_e32 v121, 0xffff0000, v126
	v_and_b32_e32 v125, 0xffff0000, v127
	v_cndmask_b32_e32 v118, v118, v119, vcc
	v_rsq_f32_e32 v122, v118
	s_waitcnt vmcnt(0)
	v_lshlrev_b32_e32 v118, 16, v148
	v_and_b32_e32 v119, 0xffff0000, v148
	v_mul_f32_e32 v123, 0x45800000, v122
	v_cndmask_b32_e32 v143, v122, v123, vcc
	v_mul_f32_e32 v108, v108, v143
	v_mul_f32_e32 v109, v109, v143
	v_mul_f32_e32 v110, v110, v143
	v_mul_f32_e32 v111, v111, v143
	v_mul_f32_e32 v108, 0xbfb8aa3b, v108
	v_mul_f32_e32 v109, 0xbfb8aa3b, v109
	v_mul_f32_e32 v110, 0xbfb8aa3b, v110
	v_mul_f32_e32 v111, 0xbfb8aa3b, v111
	v_exp_f32_e32 v108, v108
	v_exp_f32_e32 v109, v109
	v_exp_f32_e32 v110, v110
	v_exp_f32_e32 v111, v111
	v_add_f32_e32 v108, 1.0, v108
	v_add_f32_e32 v122, 1.0, v109
	v_add_f32_e32 v109, 1.0, v110
	v_add_f32_e32 v111, 1.0, v111
	v_rcp_f32_e32 v110, v108
	v_rcp_f32_e32 v108, v109
	v_rcp_f32_e32 v109, v111
	v_rcp_f32_e32 v111, v122
	v_lshlrev_b32_e32 v122, 16, v149
	v_and_b32_e32 v123, 0xffff0000, v149
	v_pk_fma_f32 v[108:109], v[108:109], v[124:125], v[122:123]
	v_pk_fma_f32 v[110:111], v[110:111], v[120:121], v[118:119]
	v_lshl_add_u64 v[122:123], s[20:21], 0, v[164:165]
	v_cvt_pk_bf16_f32 v118, v110, v111
	v_cvt_pk_bf16_f32 v119, v108, v109
	global_store_dwordx2 v[162:163], v[118:119], off
	global_load_dwordx2 v[120:121], v[116:117], off offset:32
	v_mul_f32_e32 v104, v104, v143
	global_load_dwordx2 v[118:119], v[122:123], off
	v_mul_f32_e32 v105, v105, v143
	v_mul_f32_e32 v106, v106, v143
	v_mul_f32_e32 v107, v107, v143
	v_mul_f32_e32 v104, 0xbfb8aa3b, v104
	v_mul_f32_e32 v105, 0xbfb8aa3b, v105
	v_mul_f32_e32 v106, 0xbfb8aa3b, v106
	v_mul_f32_e32 v107, 0xbfb8aa3b, v107
	v_exp_f32_e32 v104, v104
	v_exp_f32_e32 v105, v105
	v_exp_f32_e32 v106, v106
	v_exp_f32_e32 v107, v107
	v_add_f32_e32 v104, 1.0, v104
	v_add_f32_e32 v105, 1.0, v105
	v_add_f32_e32 v106, 1.0, v106
	v_add_f32_e32 v107, 1.0, v107
	v_rcp_f32_e32 v104, v104
	v_rcp_f32_e32 v105, v105
	v_rcp_f32_e32 v106, v106
	v_rcp_f32_e32 v107, v107
	v_or_b32_e32 v122, 0x100, v114
	v_mov_b32_e32 v123, v115
	v_mul_f32_e32 v102, v102, v143
	v_mul_f32_e32 v103, v103, v143
	v_mul_f32_e32 v100, v100, v143
	v_mul_f32_e32 v101, v101, v143
	v_mul_f32_e32 v102, 0xbfb8aa3b, v102
	v_mul_f32_e32 v103, 0xbfb8aa3b, v103
	v_mul_f32_e32 v100, 0xbfb8aa3b, v100
	v_mul_f32_e32 v101, 0xbfb8aa3b, v101
	v_exp_f32_e32 v102, v102
	v_exp_f32_e32 v103, v103
	v_exp_f32_e32 v100, v100
	v_exp_f32_e32 v101, v101
	v_add_f32_e32 v102, 1.0, v102
	v_add_f32_e32 v103, 1.0, v103
	v_add_f32_e32 v100, 1.0, v100
	v_add_f32_e32 v101, 1.0, v101
	v_rcp_f32_e32 v102, v102
	v_rcp_f32_e32 v103, v103
	v_rcp_f32_e32 v100, v100
	v_rcp_f32_e32 v101, v101
	v_or_b32_e32 v114, 0x120, v114
	v_mul_f32_e32 v96, v96, v143
	v_mul_f32_e32 v97, v97, v143
	v_mul_f32_e32 v98, v98, v143
	v_mul_f32_e32 v99, v99, v143
	v_mul_f32_e32 v96, 0xbfb8aa3b, v96
	v_mul_f32_e32 v97, 0xbfb8aa3b, v97
	v_mul_f32_e32 v98, 0xbfb8aa3b, v98
	v_mul_f32_e32 v99, 0xbfb8aa3b, v99
	v_exp_f32_e32 v96, v96
	v_exp_f32_e32 v97, v97
	v_exp_f32_e32 v98, v98
	v_exp_f32_e32 v99, v99
	v_add_f32_e32 v96, 1.0, v96
	v_add_f32_e32 v97, 1.0, v97
	v_add_f32_e32 v98, 1.0, v98
	v_add_f32_e32 v99, 1.0, v99
	v_mul_f32_e32 v111, v111, v111
	v_mul_f32_e32 v109, v109, v109
	v_rcp_f32_e32 v96, v96
	v_rcp_f32_e32 v97, v97
	v_rcp_f32_e32 v98, v98
	v_rcp_f32_e32 v99, v99
	v_fmac_f32_e32 v111, v110, v110
	v_fmac_f32_e32 v109, v108, v108
	v_add_f32_e32 v108, v111, v109
	s_waitcnt vmcnt(1)
	v_lshlrev_b32_e32 v124, 16, v120
	v_and_b32_e32 v125, 0xffff0000, v120
	s_waitcnt vmcnt(0)
	v_lshlrev_b32_e32 v126, 16, v118
	v_and_b32_e32 v127, 0xffff0000, v118
	v_lshlrev_b32_e32 v120, 16, v121
	v_and_b32_e32 v121, 0xffff0000, v121
	v_lshlrev_b32_e32 v118, 16, v119
	v_and_b32_e32 v119, 0xffff0000, v119
	v_pk_fma_f32 v[104:105], v[104:105], v[126:127], v[124:125]
	v_lshl_add_u64 v[124:125], s[16:17], 0, v[164:165]
	v_pk_fma_f32 v[106:107], v[106:107], v[118:119], v[120:121]
	v_cvt_pk_bf16_f32 v118, v104, v105
	v_lshl_add_u64 v[126:127], s[20:21], 0, v[122:123]
	v_cvt_pk_bf16_f32 v119, v106, v107
	global_store_dwordx2 v[124:125], v[118:119], off
	global_load_dwordx2 v[120:121], v[116:117], off offset:256
	v_mul_f32_e32 v105, v105, v105
	global_load_dwordx2 v[118:119], v[126:127], off
	v_mul_f32_e32 v107, v107, v107
	v_fmac_f32_e32 v105, v104, v104
	v_fmac_f32_e32 v107, v106, v106
	v_add_f32_e32 v104, v105, v107
	v_add_f32_e32 v104, v108, v104
	s_waitcnt vmcnt(1)
	v_lshlrev_b32_e32 v124, 16, v120
	v_and_b32_e32 v125, 0xffff0000, v120
	v_lshlrev_b32_e32 v120, 16, v121
	v_and_b32_e32 v121, 0xffff0000, v121
	s_waitcnt vmcnt(0)
	v_lshlrev_b32_e32 v126, 16, v118
	v_and_b32_e32 v127, 0xffff0000, v118
	v_lshlrev_b32_e32 v118, 16, v119
	v_and_b32_e32 v119, 0xffff0000, v119
	v_pk_fma_f32 v[102:103], v[102:103], v[118:119], v[120:121]
	v_lshl_add_u64 v[120:121], s[16:17], 0, v[122:123]
	v_pk_fma_f32 v[100:101], v[100:101], v[126:127], v[124:125]
	v_lshl_add_u64 v[122:123], s[20:21], 0, v[114:115]
	v_cvt_pk_bf16_f32 v118, v100, v101
	v_cvt_pk_bf16_f32 v119, v102, v103
	global_store_dwordx2 v[120:121], v[118:119], off
	global_load_dwordx2 v[116:117], v[116:117], off offset:288
	v_mul_f32_e32 v101, v101, v101
	global_load_dwordx2 v[118:119], v[122:123], off
	v_mul_f32_e32 v103, v103, v103
	v_fmac_f32_e32 v101, v100, v100
	v_fmac_f32_e32 v103, v102, v102
	v_add_f32_e32 v100, v101, v103
	v_add_f32_e32 v108, v100, v104
	s_waitcnt vmcnt(1)
	v_lshlrev_b32_e32 v100, 16, v116
	v_and_b32_e32 v101, 0xffff0000, v116
	v_lshlrev_b32_e32 v102, 16, v117
	v_and_b32_e32 v103, 0xffff0000, v117
	s_waitcnt vmcnt(0)
	v_lshlrev_b32_e32 v104, 16, v118
	v_and_b32_e32 v105, 0xffff0000, v118
	v_lshlrev_b32_e32 v106, 16, v119
	v_and_b32_e32 v107, 0xffff0000, v119
	v_pk_fma_f32 v[98:99], v[98:99], v[106:107], v[102:103]
	v_pk_fma_f32 v[96:97], v[96:97], v[104:105], v[100:101]
	v_mul_f32_e32 v101, v99, v99
	v_mul_f32_e32 v100, v97, v97
	v_fmac_f32_e32 v100, v96, v96
	v_fmac_f32_e32 v101, v98, v98
	v_add_f32_e32 v100, v100, v101
	v_add_f32_e32 v102, v108, v100
	ds_swizzle_b32 v103, v102 offset:swizzle(SWAP,16)
	v_lshl_add_u64 v[100:101], s[16:17], 0, v[114:115]
	v_cvt_pk_bf16_f32 v96, v96, v97
	v_cvt_pk_bf16_f32 v97, v98, v99
	global_store_dwordx2 v[100:101], v[96:97], off
	s_waitcnt lgkmcnt(0)
	v_add_f32_e32 v96, v102, v103
	v_mov_b32_e32 v97, v96
	s_nop 1
	v_permlane32_swap_b32_e32 v96, v97
	s_and_saveexec_b64 s[2:3], s[4:5]
	s_cbranch_execz .LBB0_902
	v_add_f32_e32 v98, v96, v97
	v_lshl_add_u64 v[96:97], s[18:19], 0, v[112:113]
	v_lshl_add_u64 v[96:97], s[36:37], 2, v[96:97]
	s_lshl_b32 s12, s50, 2
	v_lshl_add_u64 v[96:97], v[96:97], 0, s[12:13]
	global_store_dword v[96:97], v98, off
.LBB0_902:
	s_or_b64 exec, exec, s[2:3]
	v_or_b32_e32 v98, 32, v142
	v_ashrrev_i32_e32 v99, 31, v98
	v_lshlrev_b64 v[96:97], 6, v[98:99]
	v_lshl_add_u64 v[100:101], s[10:11], 0, v[96:97]
	v_bfe_u32 v110, v206, 4, 2
	v_lshlrev_b32_e32 v110, 4, v110
	v_mov_b32_e32 v111, 0
	v_lshl_add_u64 v[106:107], v[100:101], 0, v[110:111]
	global_load_dwordx4 v[102:105], v[106:107], off
	v_lshlrev_b64 v[98:99], 10, v[98:99]
	v_lshl_add_u64 v[98:99], v[98:99], 0, v[140:141]
	v_lshlrev_b64 v[98:99], 1, v[98:99]
	v_lshl_add_u64 v[100:101], s[20:21], 0, v[98:99]
	global_load_dwordx2 v[118:119], v[100:101], off
	v_lshl_add_u64 v[100:101], s[8:9], 0, v[98:99]
	global_load_dwordx2 v[120:121], v[100:101], off
	v_lshl_add_u64 v[122:123], s[16:17], 0, v[98:99]
	v_or_b32_e32 v124, 32, v98
	v_mov_b32_e32 v125, v99
	s_waitcnt vmcnt(0)
	v_add_f32_e32 v106, v102, v103
	v_add_f32_e32 v107, v104, v105
	v_add_f32_e32 v106, v106, v107
	ds_swizzle_b32 v107, v106 offset:swizzle(SWAP,16)
	s_waitcnt lgkmcnt(0)
	v_add_f32_e32 v106, v106, v107
	v_mov_b32_e32 v107, v106
	s_nop 1
	v_permlane32_swap_b32_e32 v106, v107
	v_add_f32_e32 v114, v106, v107
	v_lshlrev_b32_e32 v108, 16, v119
	v_lshlrev_b32_e32 v104, 16, v118
	v_mov_b32_e32 v102, v114
	v_fmamk_f32 v102, v102, 0x3a800000, v156
	v_mul_f32_e32 v103, 0x4b800000, v102
	v_cmp_gt_f32_e32 vcc, s56, v102
	v_and_b32_e32 v105, 0xffff0000, v118
	v_and_b32_e32 v109, 0xffff0000, v119
	v_cndmask_b32_e32 v102, v102, v103, vcc
	v_rsq_f32_e32 v106, v102
	s_waitcnt vmcnt(0)
	v_lshlrev_b32_e32 v102, 16, v120
	v_and_b32_e32 v103, 0xffff0000, v120
	v_mul_f32_e32 v107, 0x45800000, v106
	v_cndmask_b32_e32 v112, v106, v107, vcc
	v_mul_f32_e32 v92, v92, v112
	v_mul_f32_e32 v93, v93, v112
	v_mul_f32_e32 v94, v94, v112
	v_mul_f32_e32 v95, v95, v112
	v_mul_f32_e32 v92, 0xbfb8aa3b, v92
	v_mul_f32_e32 v93, 0xbfb8aa3b, v93
	v_mul_f32_e32 v94, 0xbfb8aa3b, v94
	v_mul_f32_e32 v95, 0xbfb8aa3b, v95
	v_exp_f32_e32 v92, v92
	v_exp_f32_e32 v93, v93
	v_exp_f32_e32 v94, v94
	v_exp_f32_e32 v95, v95
	v_add_f32_e32 v92, 1.0, v92
	v_add_f32_e32 v106, 1.0, v93
	v_add_f32_e32 v93, 1.0, v94
	v_add_f32_e32 v95, 1.0, v95
	v_rcp_f32_e32 v94, v92
	v_rcp_f32_e32 v92, v93
	v_rcp_f32_e32 v93, v95
	v_rcp_f32_e32 v95, v106
	v_lshlrev_b32_e32 v106, 16, v121
	v_and_b32_e32 v107, 0xffff0000, v121
	v_pk_fma_f32 v[92:93], v[92:93], v[108:109], v[106:107]
	v_pk_fma_f32 v[94:95], v[94:95], v[104:105], v[102:103]
	v_lshl_add_u64 v[106:107], s[20:21], 0, v[124:125]
	v_cvt_pk_bf16_f32 v102, v94, v95
	v_cvt_pk_bf16_f32 v103, v92, v93
	global_store_dwordx2 v[122:123], v[102:103], off
	global_load_dwordx2 v[104:105], v[100:101], off offset:32
	v_mul_f32_e32 v88, v88, v112
	global_load_dwordx2 v[102:103], v[106:107], off
	v_mul_f32_e32 v89, v89, v112
	v_mul_f32_e32 v90, v90, v112
	v_mul_f32_e32 v91, v91, v112
	v_mul_f32_e32 v88, 0xbfb8aa3b, v88
	v_mul_f32_e32 v89, 0xbfb8aa3b, v89
	v_mul_f32_e32 v90, 0xbfb8aa3b, v90
	v_mul_f32_e32 v91, 0xbfb8aa3b, v91
	v_exp_f32_e32 v88, v88
	v_exp_f32_e32 v89, v89
	v_exp_f32_e32 v90, v90
	v_exp_f32_e32 v91, v91
	v_add_f32_e32 v88, 1.0, v88
	v_add_f32_e32 v89, 1.0, v89
	v_add_f32_e32 v90, 1.0, v90
	v_add_f32_e32 v91, 1.0, v91
	v_rcp_f32_e32 v88, v88
	v_rcp_f32_e32 v89, v89
	v_rcp_f32_e32 v90, v90
	v_rcp_f32_e32 v91, v91
	v_or_b32_e32 v106, 0x100, v98
	v_mov_b32_e32 v107, v99
	v_mul_f32_e32 v86, v86, v112
	v_mul_f32_e32 v87, v87, v112
	v_mul_f32_e32 v84, v84, v112
	v_mul_f32_e32 v85, v85, v112
	v_mul_f32_e32 v86, 0xbfb8aa3b, v86
	v_mul_f32_e32 v87, 0xbfb8aa3b, v87
	v_mul_f32_e32 v84, 0xbfb8aa3b, v84
	v_mul_f32_e32 v85, 0xbfb8aa3b, v85
	v_exp_f32_e32 v86, v86
	v_exp_f32_e32 v87, v87
	v_exp_f32_e32 v84, v84
	v_exp_f32_e32 v85, v85
	v_add_f32_e32 v86, 1.0, v86
	v_add_f32_e32 v87, 1.0, v87
	v_add_f32_e32 v84, 1.0, v84
	v_add_f32_e32 v85, 1.0, v85
	v_rcp_f32_e32 v86, v86
	v_rcp_f32_e32 v87, v87
	v_rcp_f32_e32 v84, v84
	v_rcp_f32_e32 v85, v85
	v_or_b32_e32 v98, 0x120, v98
	v_mul_f32_e32 v80, v80, v112
	v_mul_f32_e32 v81, v81, v112
	v_mul_f32_e32 v82, v82, v112
	v_mul_f32_e32 v83, v83, v112
	v_mul_f32_e32 v80, 0xbfb8aa3b, v80
	v_mul_f32_e32 v81, 0xbfb8aa3b, v81
	v_mul_f32_e32 v82, 0xbfb8aa3b, v82
	v_mul_f32_e32 v83, 0xbfb8aa3b, v83
	v_exp_f32_e32 v80, v80
	v_exp_f32_e32 v81, v81
	v_exp_f32_e32 v82, v82
	v_exp_f32_e32 v83, v83
	v_add_f32_e32 v80, 1.0, v80
	v_add_f32_e32 v81, 1.0, v81
	v_add_f32_e32 v82, 1.0, v82
	v_add_f32_e32 v83, 1.0, v83
	v_mul_f32_e32 v95, v95, v95
	v_mul_f32_e32 v93, v93, v93
	v_rcp_f32_e32 v80, v80
	v_rcp_f32_e32 v81, v81
	v_rcp_f32_e32 v82, v82
	v_rcp_f32_e32 v83, v83
	v_fmac_f32_e32 v95, v94, v94
	v_fmac_f32_e32 v93, v92, v92
	v_add_f32_e32 v92, v95, v93
	s_waitcnt vmcnt(1)
	v_lshlrev_b32_e32 v108, 16, v104
	v_and_b32_e32 v109, 0xffff0000, v104
	s_waitcnt vmcnt(0)
	v_lshlrev_b32_e32 v110, 16, v102
	v_and_b32_e32 v111, 0xffff0000, v102
	v_lshlrev_b32_e32 v104, 16, v105
	v_and_b32_e32 v105, 0xffff0000, v105
	v_lshlrev_b32_e32 v102, 16, v103
	v_and_b32_e32 v103, 0xffff0000, v103
	v_pk_fma_f32 v[88:89], v[88:89], v[110:111], v[108:109]
	v_lshl_add_u64 v[108:109], s[16:17], 0, v[124:125]
	v_pk_fma_f32 v[90:91], v[90:91], v[102:103], v[104:105]
	v_cvt_pk_bf16_f32 v102, v88, v89
	v_lshl_add_u64 v[110:111], s[20:21], 0, v[106:107]
	v_cvt_pk_bf16_f32 v103, v90, v91
	global_store_dwordx2 v[108:109], v[102:103], off
	global_load_dwordx2 v[104:105], v[100:101], off offset:256
	v_mul_f32_e32 v89, v89, v89
	global_load_dwordx2 v[102:103], v[110:111], off
	v_mul_f32_e32 v91, v91, v91
	v_fmac_f32_e32 v89, v88, v88
	v_fmac_f32_e32 v91, v90, v90
	v_add_f32_e32 v88, v89, v91
	v_add_f32_e32 v88, v92, v88
	s_waitcnt vmcnt(1)
	v_lshlrev_b32_e32 v108, 16, v104
	v_and_b32_e32 v109, 0xffff0000, v104
	v_lshlrev_b32_e32 v104, 16, v105
	v_and_b32_e32 v105, 0xffff0000, v105
	s_waitcnt vmcnt(0)
	v_lshlrev_b32_e32 v110, 16, v102
	v_and_b32_e32 v111, 0xffff0000, v102
	v_lshlrev_b32_e32 v102, 16, v103
	v_and_b32_e32 v103, 0xffff0000, v103
	v_pk_fma_f32 v[86:87], v[86:87], v[102:103], v[104:105]
	v_lshl_add_u64 v[104:105], s[16:17], 0, v[106:107]
	v_pk_fma_f32 v[84:85], v[84:85], v[110:111], v[108:109]
	v_lshl_add_u64 v[106:107], s[20:21], 0, v[98:99]
	v_cvt_pk_bf16_f32 v102, v84, v85
	v_cvt_pk_bf16_f32 v103, v86, v87
	global_store_dwordx2 v[104:105], v[102:103], off
	global_load_dwordx2 v[100:101], v[100:101], off offset:288
	v_mul_f32_e32 v85, v85, v85
	global_load_dwordx2 v[102:103], v[106:107], off
	v_mul_f32_e32 v87, v87, v87
	v_fmac_f32_e32 v85, v84, v84
	v_fmac_f32_e32 v87, v86, v86
	v_add_f32_e32 v84, v85, v87
	v_add_f32_e32 v92, v84, v88
	s_waitcnt vmcnt(1)
	v_lshlrev_b32_e32 v84, 16, v100
	v_and_b32_e32 v85, 0xffff0000, v100
	v_lshlrev_b32_e32 v86, 16, v101
	v_and_b32_e32 v87, 0xffff0000, v101
	s_waitcnt vmcnt(0)
	v_lshlrev_b32_e32 v88, 16, v102
	v_and_b32_e32 v89, 0xffff0000, v102
	v_lshlrev_b32_e32 v90, 16, v103
	v_and_b32_e32 v91, 0xffff0000, v103
	v_pk_fma_f32 v[82:83], v[82:83], v[90:91], v[86:87]
	v_pk_fma_f32 v[80:81], v[80:81], v[88:89], v[84:85]
	v_mul_f32_e32 v85, v83, v83
	v_mul_f32_e32 v84, v81, v81
	v_fmac_f32_e32 v84, v80, v80
	v_fmac_f32_e32 v85, v82, v82
	v_add_f32_e32 v84, v84, v85
	v_add_f32_e32 v86, v92, v84
	ds_swizzle_b32 v87, v86 offset:swizzle(SWAP,16)
	v_lshl_add_u64 v[84:85], s[16:17], 0, v[98:99]
	v_cvt_pk_bf16_f32 v80, v80, v81
	v_cvt_pk_bf16_f32 v81, v82, v83
	global_store_dwordx2 v[84:85], v[80:81], off
	s_waitcnt lgkmcnt(0)
	v_add_f32_e32 v80, v86, v87
	v_mov_b32_e32 v81, v80
	s_nop 1
	v_permlane32_swap_b32_e32 v80, v81
	s_and_saveexec_b64 s[2:3], s[4:5]
	s_cbranch_execz .LBB0_904
	v_add_f32_e32 v82, v80, v81
	v_lshl_add_u64 v[80:81], s[18:19], 0, v[96:97]
	v_lshl_add_u64 v[80:81], s[36:37], 2, v[80:81]
	s_lshl_b32 s12, s50, 2
	v_lshl_add_u64 v[80:81], v[80:81], 0, s[12:13]
	global_store_dword v[80:81], v82, off
.LBB0_904:
	s_or_b64 exec, exec, s[2:3]
	v_or_b32_e32 v82, 48, v142
	v_ashrrev_i32_e32 v83, 31, v82
	v_lshlrev_b64 v[80:81], 6, v[82:83]
	v_lshl_add_u64 v[84:85], s[10:11], 0, v[80:81]
	v_bfe_u32 v94, v206, 4, 2
	v_lshlrev_b32_e32 v94, 4, v94
	v_mov_b32_e32 v95, 0
	v_lshl_add_u64 v[90:91], v[84:85], 0, v[94:95]
	global_load_dwordx4 v[86:89], v[90:91], off
	v_lshlrev_b64 v[82:83], 10, v[82:83]
	v_lshl_add_u64 v[82:83], v[82:83], 0, v[140:141]
	v_lshlrev_b64 v[82:83], 1, v[82:83]
	v_lshl_add_u64 v[84:85], s[20:21], 0, v[82:83]
	global_load_dwordx2 v[102:103], v[84:85], off
	v_lshl_add_u64 v[84:85], s[8:9], 0, v[82:83]
	global_load_dwordx2 v[104:105], v[84:85], off
	v_lshl_add_u64 v[106:107], s[16:17], 0, v[82:83]
	v_or_b32_e32 v108, 32, v82
	v_mov_b32_e32 v109, v83
	s_waitcnt vmcnt(0)
	v_add_f32_e32 v90, v86, v87
	v_add_f32_e32 v91, v88, v89
	v_add_f32_e32 v90, v90, v91
	ds_swizzle_b32 v91, v90 offset:swizzle(SWAP,16)
	s_waitcnt lgkmcnt(0)
	v_add_f32_e32 v90, v90, v91
	v_mov_b32_e32 v91, v90
	s_nop 1
	v_permlane32_swap_b32_e32 v90, v91
	v_add_f32_e32 v98, v90, v91
	v_lshlrev_b32_e32 v92, 16, v103
	v_lshlrev_b32_e32 v88, 16, v102
	v_mov_b32_e32 v86, v98
	v_fmamk_f32 v86, v86, 0x3a800000, v156
	v_mul_f32_e32 v87, 0x4b800000, v86
	v_cmp_gt_f32_e32 vcc, s56, v86
	v_and_b32_e32 v89, 0xffff0000, v102
	v_and_b32_e32 v93, 0xffff0000, v103
	v_cndmask_b32_e32 v86, v86, v87, vcc
	v_rsq_f32_e32 v90, v86
	s_waitcnt vmcnt(0)
	v_lshlrev_b32_e32 v86, 16, v104
	v_and_b32_e32 v87, 0xffff0000, v104
	v_mul_f32_e32 v91, 0x45800000, v90
	v_cndmask_b32_e32 v96, v90, v91, vcc
	v_mul_f32_e32 v76, v76, v96
	v_mul_f32_e32 v77, v77, v96
	v_mul_f32_e32 v78, v78, v96
	v_mul_f32_e32 v79, v79, v96
	v_mul_f32_e32 v76, 0xbfb8aa3b, v76
	v_mul_f32_e32 v77, 0xbfb8aa3b, v77
	v_mul_f32_e32 v78, 0xbfb8aa3b, v78
	v_mul_f32_e32 v79, 0xbfb8aa3b, v79
	v_exp_f32_e32 v76, v76
	v_exp_f32_e32 v77, v77
	v_exp_f32_e32 v78, v78
	v_exp_f32_e32 v79, v79
	v_add_f32_e32 v76, 1.0, v76
	v_add_f32_e32 v90, 1.0, v77
	v_add_f32_e32 v77, 1.0, v78
	v_add_f32_e32 v79, 1.0, v79
	v_rcp_f32_e32 v78, v76
	v_rcp_f32_e32 v76, v77
	v_rcp_f32_e32 v77, v79
	v_rcp_f32_e32 v79, v90
	v_lshlrev_b32_e32 v90, 16, v105
	v_and_b32_e32 v91, 0xffff0000, v105
	v_pk_fma_f32 v[76:77], v[76:77], v[92:93], v[90:91]
	v_pk_fma_f32 v[78:79], v[78:79], v[88:89], v[86:87]
	v_lshl_add_u64 v[90:91], s[20:21], 0, v[108:109]
	v_cvt_pk_bf16_f32 v86, v78, v79
	v_cvt_pk_bf16_f32 v87, v76, v77
	global_store_dwordx2 v[106:107], v[86:87], off
	global_load_dwordx2 v[88:89], v[84:85], off offset:32
	v_mul_f32_e32 v72, v72, v96
	global_load_dwordx2 v[86:87], v[90:91], off
	v_mul_f32_e32 v73, v73, v96
	v_mul_f32_e32 v74, v74, v96
	v_mul_f32_e32 v75, v75, v96
	v_mul_f32_e32 v72, 0xbfb8aa3b, v72
	v_mul_f32_e32 v73, 0xbfb8aa3b, v73
	v_mul_f32_e32 v74, 0xbfb8aa3b, v74
	v_mul_f32_e32 v75, 0xbfb8aa3b, v75
	v_exp_f32_e32 v72, v72
	v_exp_f32_e32 v73, v73
	v_exp_f32_e32 v74, v74
	v_exp_f32_e32 v75, v75
	v_add_f32_e32 v72, 1.0, v72
	v_add_f32_e32 v73, 1.0, v73
	v_add_f32_e32 v74, 1.0, v74
	v_add_f32_e32 v75, 1.0, v75
	v_rcp_f32_e32 v72, v72
	v_rcp_f32_e32 v73, v73
	v_rcp_f32_e32 v74, v74
	v_rcp_f32_e32 v75, v75
	v_or_b32_e32 v90, 0x100, v82
	v_mov_b32_e32 v91, v83
	v_mul_f32_e32 v70, v70, v96
	v_mul_f32_e32 v71, v71, v96
	v_mul_f32_e32 v68, v68, v96
	v_mul_f32_e32 v69, v69, v96
	v_mul_f32_e32 v70, 0xbfb8aa3b, v70
	v_mul_f32_e32 v71, 0xbfb8aa3b, v71
	v_mul_f32_e32 v68, 0xbfb8aa3b, v68
	v_mul_f32_e32 v69, 0xbfb8aa3b, v69
	v_exp_f32_e32 v70, v70
	v_exp_f32_e32 v71, v71
	v_exp_f32_e32 v68, v68
	v_exp_f32_e32 v69, v69
	v_add_f32_e32 v70, 1.0, v70
	v_add_f32_e32 v71, 1.0, v71
	v_add_f32_e32 v68, 1.0, v68
	v_add_f32_e32 v69, 1.0, v69
	v_rcp_f32_e32 v70, v70
	v_rcp_f32_e32 v71, v71
	v_rcp_f32_e32 v68, v68
	v_rcp_f32_e32 v69, v69
	v_or_b32_e32 v82, 0x120, v82
	v_mul_f32_e32 v64, v64, v96
	v_mul_f32_e32 v65, v65, v96
	v_mul_f32_e32 v66, v66, v96
	v_mul_f32_e32 v67, v67, v96
	v_mul_f32_e32 v64, 0xbfb8aa3b, v64
	v_mul_f32_e32 v65, 0xbfb8aa3b, v65
	v_mul_f32_e32 v66, 0xbfb8aa3b, v66
	v_mul_f32_e32 v67, 0xbfb8aa3b, v67
	v_exp_f32_e32 v64, v64
	v_exp_f32_e32 v65, v65
	v_exp_f32_e32 v66, v66
	v_exp_f32_e32 v67, v67
	v_add_f32_e32 v64, 1.0, v64
	v_add_f32_e32 v65, 1.0, v65
	v_add_f32_e32 v66, 1.0, v66
	v_add_f32_e32 v67, 1.0, v67
	v_mul_f32_e32 v79, v79, v79
	v_mul_f32_e32 v77, v77, v77
	v_rcp_f32_e32 v64, v64
	v_rcp_f32_e32 v65, v65
	v_rcp_f32_e32 v66, v66
	v_rcp_f32_e32 v67, v67
	v_fmac_f32_e32 v79, v78, v78
	v_fmac_f32_e32 v77, v76, v76
	v_add_f32_e32 v76, v79, v77
	s_waitcnt vmcnt(1)
	v_lshlrev_b32_e32 v92, 16, v88
	v_and_b32_e32 v93, 0xffff0000, v88
	s_waitcnt vmcnt(0)
	v_lshlrev_b32_e32 v94, 16, v86
	v_and_b32_e32 v95, 0xffff0000, v86
	v_lshlrev_b32_e32 v88, 16, v89
	v_and_b32_e32 v89, 0xffff0000, v89
	v_lshlrev_b32_e32 v86, 16, v87
	v_and_b32_e32 v87, 0xffff0000, v87
	v_pk_fma_f32 v[72:73], v[72:73], v[94:95], v[92:93]
	v_lshl_add_u64 v[92:93], s[16:17], 0, v[108:109]
	v_pk_fma_f32 v[74:75], v[74:75], v[86:87], v[88:89]
	v_cvt_pk_bf16_f32 v86, v72, v73
	v_lshl_add_u64 v[94:95], s[20:21], 0, v[90:91]
	v_cvt_pk_bf16_f32 v87, v74, v75
	global_store_dwordx2 v[92:93], v[86:87], off
	global_load_dwordx2 v[88:89], v[84:85], off offset:256
	v_mul_f32_e32 v73, v73, v73
	global_load_dwordx2 v[86:87], v[94:95], off
	v_mul_f32_e32 v75, v75, v75
	v_fmac_f32_e32 v73, v72, v72
	v_fmac_f32_e32 v75, v74, v74
	v_add_f32_e32 v72, v73, v75
	v_add_f32_e32 v72, v76, v72
	s_waitcnt vmcnt(1)
	v_lshlrev_b32_e32 v92, 16, v88
	v_and_b32_e32 v93, 0xffff0000, v88
	v_lshlrev_b32_e32 v88, 16, v89
	v_and_b32_e32 v89, 0xffff0000, v89
	s_waitcnt vmcnt(0)
	v_lshlrev_b32_e32 v94, 16, v86
	v_and_b32_e32 v95, 0xffff0000, v86
	v_lshlrev_b32_e32 v86, 16, v87
	v_and_b32_e32 v87, 0xffff0000, v87
	v_pk_fma_f32 v[70:71], v[70:71], v[86:87], v[88:89]
	v_lshl_add_u64 v[88:89], s[16:17], 0, v[90:91]
	v_pk_fma_f32 v[68:69], v[68:69], v[94:95], v[92:93]
	v_lshl_add_u64 v[90:91], s[20:21], 0, v[82:83]
	v_cvt_pk_bf16_f32 v86, v68, v69
	v_cvt_pk_bf16_f32 v87, v70, v71
	global_store_dwordx2 v[88:89], v[86:87], off
	global_load_dwordx2 v[84:85], v[84:85], off offset:288
	v_mul_f32_e32 v69, v69, v69
	global_load_dwordx2 v[86:87], v[90:91], off
	v_mul_f32_e32 v71, v71, v71
	v_fmac_f32_e32 v69, v68, v68
	v_fmac_f32_e32 v71, v70, v70
	v_add_f32_e32 v68, v69, v71
	v_add_f32_e32 v76, v68, v72
	s_waitcnt vmcnt(1)
	v_lshlrev_b32_e32 v68, 16, v84
	v_and_b32_e32 v69, 0xffff0000, v84
	v_lshlrev_b32_e32 v70, 16, v85
	v_and_b32_e32 v71, 0xffff0000, v85
	s_waitcnt vmcnt(0)
	v_lshlrev_b32_e32 v72, 16, v86
	v_and_b32_e32 v73, 0xffff0000, v86
	v_lshlrev_b32_e32 v74, 16, v87
	v_and_b32_e32 v75, 0xffff0000, v87
	v_pk_fma_f32 v[66:67], v[66:67], v[74:75], v[70:71]
	v_pk_fma_f32 v[64:65], v[64:65], v[72:73], v[68:69]
	v_mul_f32_e32 v69, v67, v67
	v_mul_f32_e32 v68, v65, v65
	v_fmac_f32_e32 v68, v64, v64
	v_fmac_f32_e32 v69, v66, v66
	v_add_f32_e32 v68, v68, v69
	v_add_f32_e32 v70, v76, v68
	ds_swizzle_b32 v71, v70 offset:swizzle(SWAP,16)
	v_lshl_add_u64 v[68:69], s[16:17], 0, v[82:83]
	v_cvt_pk_bf16_f32 v64, v64, v65
	v_cvt_pk_bf16_f32 v65, v66, v67
	global_store_dwordx2 v[68:69], v[64:65], off
	s_waitcnt lgkmcnt(0)
	v_add_f32_e32 v64, v70, v71
	v_mov_b32_e32 v65, v64
	s_nop 1
	v_permlane32_swap_b32_e32 v64, v65
	s_and_saveexec_b64 s[2:3], s[4:5]
	s_cbranch_execz .LBB0_906
	v_add_f32_e32 v66, v64, v65
	v_lshl_add_u64 v[64:65], s[18:19], 0, v[80:81]
	v_lshl_add_u64 v[64:65], s[36:37], 2, v[64:65]
	s_lshl_b32 s12, s50, 2
	v_lshl_add_u64 v[64:65], v[64:65], 0, s[12:13]
	global_store_dword v[64:65], v66, off
.LBB0_906:
	s_or_b64 exec, exec, s[2:3]
	v_add_u32_e32 v66, 0x80, v142
	v_ashrrev_i32_e32 v67, 31, v66
	v_lshlrev_b64 v[64:65], 6, v[66:67]
	v_lshl_add_u64 v[68:69], s[10:11], 0, v[64:65]
	v_bfe_u32 v78, v206, 4, 2
	v_lshlrev_b32_e32 v78, 4, v78
	v_mov_b32_e32 v79, 0
	v_lshl_add_u64 v[74:75], v[68:69], 0, v[78:79]
	global_load_dwordx4 v[70:73], v[74:75], off
	v_lshlrev_b64 v[66:67], 10, v[66:67]
	v_lshl_add_u64 v[66:67], v[66:67], 0, v[140:141]
	v_lshlrev_b64 v[66:67], 1, v[66:67]
	v_lshl_add_u64 v[68:69], s[20:21], 0, v[66:67]
	global_load_dwordx2 v[86:87], v[68:69], off
	v_lshl_add_u64 v[68:69], s[8:9], 0, v[66:67]
	global_load_dwordx2 v[88:89], v[68:69], off
	v_lshl_add_u64 v[90:91], s[16:17], 0, v[66:67]
	v_or_b32_e32 v92, 32, v66
	v_mov_b32_e32 v93, v67
	s_waitcnt vmcnt(0)
	v_add_f32_e32 v74, v70, v71
	v_add_f32_e32 v75, v72, v73
	v_add_f32_e32 v74, v74, v75
	ds_swizzle_b32 v75, v74 offset:swizzle(SWAP,16)
	s_waitcnt lgkmcnt(0)
	v_add_f32_e32 v74, v74, v75
	v_mov_b32_e32 v75, v74
	s_nop 1
	v_permlane32_swap_b32_e32 v74, v75
	v_add_f32_e32 v82, v74, v75
	v_lshlrev_b32_e32 v76, 16, v87
	v_lshlrev_b32_e32 v72, 16, v86
	v_mov_b32_e32 v70, v82
	v_fmamk_f32 v70, v70, 0x3a800000, v156
	v_mul_f32_e32 v71, 0x4b800000, v70
	v_cmp_gt_f32_e32 vcc, s56, v70
	v_and_b32_e32 v73, 0xffff0000, v86
	v_and_b32_e32 v77, 0xffff0000, v87
	v_cndmask_b32_e32 v70, v70, v71, vcc
	v_rsq_f32_e32 v74, v70
	s_waitcnt vmcnt(0)
	v_lshlrev_b32_e32 v70, 16, v88
	v_and_b32_e32 v71, 0xffff0000, v88
	v_mul_f32_e32 v75, 0x45800000, v74
	v_cndmask_b32_e32 v80, v74, v75, vcc
	v_mul_f32_e32 v60, v60, v80
	v_mul_f32_e32 v61, v61, v80
	v_mul_f32_e32 v62, v62, v80
	v_mul_f32_e32 v63, v63, v80
	v_mul_f32_e32 v60, 0xbfb8aa3b, v60
	v_mul_f32_e32 v61, 0xbfb8aa3b, v61
	v_mul_f32_e32 v62, 0xbfb8aa3b, v62
	v_mul_f32_e32 v63, 0xbfb8aa3b, v63
	v_exp_f32_e32 v60, v60
	v_exp_f32_e32 v61, v61
	v_exp_f32_e32 v62, v62
	v_exp_f32_e32 v63, v63
	v_add_f32_e32 v60, 1.0, v60
	v_add_f32_e32 v74, 1.0, v61
	v_add_f32_e32 v61, 1.0, v62
	v_add_f32_e32 v63, 1.0, v63
	v_rcp_f32_e32 v62, v60
	v_rcp_f32_e32 v60, v61
	v_rcp_f32_e32 v61, v63
	v_rcp_f32_e32 v63, v74
	v_lshlrev_b32_e32 v74, 16, v89
	v_and_b32_e32 v75, 0xffff0000, v89
	v_pk_fma_f32 v[60:61], v[60:61], v[76:77], v[74:75]
	v_pk_fma_f32 v[62:63], v[62:63], v[72:73], v[70:71]
	v_lshl_add_u64 v[74:75], s[20:21], 0, v[92:93]
	v_cvt_pk_bf16_f32 v70, v62, v63
	v_cvt_pk_bf16_f32 v71, v60, v61
	global_store_dwordx2 v[90:91], v[70:71], off
	global_load_dwordx2 v[72:73], v[68:69], off offset:32
	v_mul_f32_e32 v56, v56, v80
	global_load_dwordx2 v[70:71], v[74:75], off
	v_mul_f32_e32 v57, v57, v80
	v_mul_f32_e32 v58, v58, v80
	v_mul_f32_e32 v59, v59, v80
	v_mul_f32_e32 v56, 0xbfb8aa3b, v56
	v_mul_f32_e32 v57, 0xbfb8aa3b, v57
	v_mul_f32_e32 v58, 0xbfb8aa3b, v58
	v_mul_f32_e32 v59, 0xbfb8aa3b, v59
	v_exp_f32_e32 v56, v56
	v_exp_f32_e32 v57, v57
	v_exp_f32_e32 v58, v58
	v_exp_f32_e32 v59, v59
	v_add_f32_e32 v56, 1.0, v56
	v_add_f32_e32 v57, 1.0, v57
	v_add_f32_e32 v58, 1.0, v58
	v_add_f32_e32 v59, 1.0, v59
	v_rcp_f32_e32 v56, v56
	v_rcp_f32_e32 v57, v57
	v_rcp_f32_e32 v58, v58
	v_rcp_f32_e32 v59, v59
	v_or_b32_e32 v74, 0x100, v66
	v_mov_b32_e32 v75, v67
	v_mul_f32_e32 v54, v54, v80
	v_mul_f32_e32 v55, v55, v80
	v_mul_f32_e32 v52, v52, v80
	v_mul_f32_e32 v53, v53, v80
	v_mul_f32_e32 v54, 0xbfb8aa3b, v54
	v_mul_f32_e32 v55, 0xbfb8aa3b, v55
	v_mul_f32_e32 v52, 0xbfb8aa3b, v52
	v_mul_f32_e32 v53, 0xbfb8aa3b, v53
	v_exp_f32_e32 v54, v54
	v_exp_f32_e32 v55, v55
	v_exp_f32_e32 v52, v52
	v_exp_f32_e32 v53, v53
	v_add_f32_e32 v54, 1.0, v54
	v_add_f32_e32 v55, 1.0, v55
	v_add_f32_e32 v52, 1.0, v52
	v_add_f32_e32 v53, 1.0, v53
	v_rcp_f32_e32 v54, v54
	v_rcp_f32_e32 v55, v55
	v_rcp_f32_e32 v52, v52
	v_rcp_f32_e32 v53, v53
	v_or_b32_e32 v66, 0x120, v66
	v_mul_f32_e32 v48, v48, v80
	v_mul_f32_e32 v49, v49, v80
	v_mul_f32_e32 v50, v50, v80
	v_mul_f32_e32 v51, v51, v80
	v_mul_f32_e32 v48, 0xbfb8aa3b, v48
	v_mul_f32_e32 v49, 0xbfb8aa3b, v49
	v_mul_f32_e32 v50, 0xbfb8aa3b, v50
	v_mul_f32_e32 v51, 0xbfb8aa3b, v51
	v_exp_f32_e32 v48, v48
	v_exp_f32_e32 v49, v49
	v_exp_f32_e32 v50, v50
	v_exp_f32_e32 v51, v51
	v_add_f32_e32 v48, 1.0, v48
	v_add_f32_e32 v49, 1.0, v49
	v_add_f32_e32 v50, 1.0, v50
	v_add_f32_e32 v51, 1.0, v51
	v_mul_f32_e32 v63, v63, v63
	v_mul_f32_e32 v61, v61, v61
	v_rcp_f32_e32 v48, v48
	v_rcp_f32_e32 v49, v49
	v_rcp_f32_e32 v50, v50
	v_rcp_f32_e32 v51, v51
	v_fmac_f32_e32 v63, v62, v62
	v_fmac_f32_e32 v61, v60, v60
	v_add_f32_e32 v60, v63, v61
	s_waitcnt vmcnt(1)
	v_lshlrev_b32_e32 v76, 16, v72
	v_and_b32_e32 v77, 0xffff0000, v72
	s_waitcnt vmcnt(0)
	v_lshlrev_b32_e32 v78, 16, v70
	v_and_b32_e32 v79, 0xffff0000, v70
	v_lshlrev_b32_e32 v72, 16, v73
	v_and_b32_e32 v73, 0xffff0000, v73
	v_lshlrev_b32_e32 v70, 16, v71
	v_and_b32_e32 v71, 0xffff0000, v71
	v_pk_fma_f32 v[56:57], v[56:57], v[78:79], v[76:77]
	v_lshl_add_u64 v[76:77], s[16:17], 0, v[92:93]
	v_pk_fma_f32 v[58:59], v[58:59], v[70:71], v[72:73]
	v_cvt_pk_bf16_f32 v70, v56, v57
	v_lshl_add_u64 v[78:79], s[20:21], 0, v[74:75]
	v_cvt_pk_bf16_f32 v71, v58, v59
	global_store_dwordx2 v[76:77], v[70:71], off
	global_load_dwordx2 v[72:73], v[68:69], off offset:256
	v_mul_f32_e32 v57, v57, v57
	global_load_dwordx2 v[70:71], v[78:79], off
	v_mul_f32_e32 v59, v59, v59
	v_fmac_f32_e32 v57, v56, v56
	v_fmac_f32_e32 v59, v58, v58
	v_add_f32_e32 v56, v57, v59
	v_add_f32_e32 v56, v60, v56
	s_waitcnt vmcnt(1)
	v_lshlrev_b32_e32 v76, 16, v72
	v_and_b32_e32 v77, 0xffff0000, v72
	v_lshlrev_b32_e32 v72, 16, v73
	v_and_b32_e32 v73, 0xffff0000, v73
	s_waitcnt vmcnt(0)
	v_lshlrev_b32_e32 v78, 16, v70
	v_and_b32_e32 v79, 0xffff0000, v70
	v_lshlrev_b32_e32 v70, 16, v71
	v_and_b32_e32 v71, 0xffff0000, v71
	v_pk_fma_f32 v[54:55], v[54:55], v[70:71], v[72:73]
	v_lshl_add_u64 v[72:73], s[16:17], 0, v[74:75]
	v_pk_fma_f32 v[52:53], v[52:53], v[78:79], v[76:77]
	v_lshl_add_u64 v[74:75], s[20:21], 0, v[66:67]
	v_cvt_pk_bf16_f32 v70, v52, v53
	v_cvt_pk_bf16_f32 v71, v54, v55
	global_store_dwordx2 v[72:73], v[70:71], off
	global_load_dwordx2 v[68:69], v[68:69], off offset:288
	v_mul_f32_e32 v53, v53, v53
	global_load_dwordx2 v[70:71], v[74:75], off
	v_mul_f32_e32 v55, v55, v55
	v_fmac_f32_e32 v53, v52, v52
	v_fmac_f32_e32 v55, v54, v54
	v_add_f32_e32 v52, v53, v55
	v_add_f32_e32 v60, v52, v56
	s_waitcnt vmcnt(1)
	v_lshlrev_b32_e32 v52, 16, v68
	v_and_b32_e32 v53, 0xffff0000, v68
	v_lshlrev_b32_e32 v54, 16, v69
	v_and_b32_e32 v55, 0xffff0000, v69
	s_waitcnt vmcnt(0)
	v_lshlrev_b32_e32 v56, 16, v70
	v_and_b32_e32 v57, 0xffff0000, v70
	v_lshlrev_b32_e32 v58, 16, v71
	v_and_b32_e32 v59, 0xffff0000, v71
	v_pk_fma_f32 v[50:51], v[50:51], v[58:59], v[54:55]
	v_pk_fma_f32 v[48:49], v[48:49], v[56:57], v[52:53]
	v_mul_f32_e32 v53, v51, v51
	v_mul_f32_e32 v52, v49, v49
	v_fmac_f32_e32 v52, v48, v48
	v_fmac_f32_e32 v53, v50, v50
	v_add_f32_e32 v52, v52, v53
	v_add_f32_e32 v54, v60, v52
	ds_swizzle_b32 v55, v54 offset:swizzle(SWAP,16)
	v_lshl_add_u64 v[52:53], s[16:17], 0, v[66:67]
	v_cvt_pk_bf16_f32 v48, v48, v49
	v_cvt_pk_bf16_f32 v49, v50, v51
	global_store_dwordx2 v[52:53], v[48:49], off
	s_waitcnt lgkmcnt(0)
	v_add_f32_e32 v48, v54, v55
	v_mov_b32_e32 v49, v48
	s_nop 1
	v_permlane32_swap_b32_e32 v48, v49
	s_and_saveexec_b64 s[2:3], s[4:5]
	s_cbranch_execz .LBB0_908
	v_add_f32_e32 v50, v48, v49
	v_lshl_add_u64 v[48:49], s[18:19], 0, v[64:65]
	v_lshl_add_u64 v[48:49], s[36:37], 2, v[48:49]
	s_lshl_b32 s12, s50, 2
	v_lshl_add_u64 v[48:49], v[48:49], 0, s[12:13]
	global_store_dword v[48:49], v50, off
.LBB0_908:
	s_or_b64 exec, exec, s[2:3]
	v_add_u32_e32 v50, 0x90, v142
	v_ashrrev_i32_e32 v51, 31, v50
	v_lshlrev_b64 v[48:49], 6, v[50:51]
	v_lshl_add_u64 v[52:53], s[10:11], 0, v[48:49]
	v_bfe_u32 v62, v206, 4, 2
	v_lshlrev_b32_e32 v62, 4, v62
	v_mov_b32_e32 v63, 0
	v_lshl_add_u64 v[58:59], v[52:53], 0, v[62:63]
	global_load_dwordx4 v[54:57], v[58:59], off
	v_lshlrev_b64 v[50:51], 10, v[50:51]
	v_lshl_add_u64 v[50:51], v[50:51], 0, v[140:141]
	v_lshlrev_b64 v[50:51], 1, v[50:51]
	v_lshl_add_u64 v[52:53], s[20:21], 0, v[50:51]
	global_load_dwordx2 v[70:71], v[52:53], off
	v_lshl_add_u64 v[52:53], s[8:9], 0, v[50:51]
	global_load_dwordx2 v[72:73], v[52:53], off
	v_lshl_add_u64 v[74:75], s[16:17], 0, v[50:51]
	v_or_b32_e32 v76, 32, v50
	v_mov_b32_e32 v77, v51
	s_waitcnt vmcnt(0)
	v_add_f32_e32 v58, v54, v55
	v_add_f32_e32 v59, v56, v57
	v_add_f32_e32 v58, v58, v59
	ds_swizzle_b32 v59, v58 offset:swizzle(SWAP,16)
	s_waitcnt lgkmcnt(0)
	v_add_f32_e32 v58, v58, v59
	v_mov_b32_e32 v59, v58
	s_nop 1
	v_permlane32_swap_b32_e32 v58, v59
	v_add_f32_e32 v66, v58, v59
	v_lshlrev_b32_e32 v60, 16, v71
	v_lshlrev_b32_e32 v56, 16, v70
	v_mov_b32_e32 v54, v66
	v_fmamk_f32 v54, v54, 0x3a800000, v156
	v_mul_f32_e32 v55, 0x4b800000, v54
	v_cmp_gt_f32_e32 vcc, s56, v54
	v_and_b32_e32 v57, 0xffff0000, v70
	v_and_b32_e32 v61, 0xffff0000, v71
	v_cndmask_b32_e32 v54, v54, v55, vcc
	v_rsq_f32_e32 v58, v54
	s_waitcnt vmcnt(0)
	v_lshlrev_b32_e32 v54, 16, v72
	v_and_b32_e32 v55, 0xffff0000, v72
	v_mul_f32_e32 v59, 0x45800000, v58
	v_cndmask_b32_e32 v64, v58, v59, vcc
	v_mul_f32_e32 v44, v44, v64
	v_mul_f32_e32 v45, v45, v64
	v_mul_f32_e32 v46, v46, v64
	v_mul_f32_e32 v47, v47, v64
	v_mul_f32_e32 v44, 0xbfb8aa3b, v44
	v_mul_f32_e32 v45, 0xbfb8aa3b, v45
	v_mul_f32_e32 v46, 0xbfb8aa3b, v46
	v_mul_f32_e32 v47, 0xbfb8aa3b, v47
	v_exp_f32_e32 v44, v44
	v_exp_f32_e32 v45, v45
	v_exp_f32_e32 v46, v46
	v_exp_f32_e32 v47, v47
	v_add_f32_e32 v44, 1.0, v44
	v_add_f32_e32 v58, 1.0, v45
	v_add_f32_e32 v45, 1.0, v46
	v_add_f32_e32 v47, 1.0, v47
	v_rcp_f32_e32 v46, v44
	v_rcp_f32_e32 v44, v45
	v_rcp_f32_e32 v45, v47
	v_rcp_f32_e32 v47, v58
	v_lshlrev_b32_e32 v58, 16, v73
	v_and_b32_e32 v59, 0xffff0000, v73
	v_pk_fma_f32 v[44:45], v[44:45], v[60:61], v[58:59]
	v_pk_fma_f32 v[46:47], v[46:47], v[56:57], v[54:55]
	v_lshl_add_u64 v[58:59], s[20:21], 0, v[76:77]
	v_cvt_pk_bf16_f32 v54, v46, v47
	v_cvt_pk_bf16_f32 v55, v44, v45
	global_store_dwordx2 v[74:75], v[54:55], off
	global_load_dwordx2 v[56:57], v[52:53], off offset:32
	v_mul_f32_e32 v40, v40, v64
	global_load_dwordx2 v[54:55], v[58:59], off
	v_mul_f32_e32 v41, v41, v64
	v_mul_f32_e32 v42, v42, v64
	v_mul_f32_e32 v43, v43, v64
	v_mul_f32_e32 v40, 0xbfb8aa3b, v40
	v_mul_f32_e32 v41, 0xbfb8aa3b, v41
	v_mul_f32_e32 v42, 0xbfb8aa3b, v42
	v_mul_f32_e32 v43, 0xbfb8aa3b, v43
	v_exp_f32_e32 v40, v40
	v_exp_f32_e32 v41, v41
	v_exp_f32_e32 v42, v42
	v_exp_f32_e32 v43, v43
	v_add_f32_e32 v40, 1.0, v40
	v_add_f32_e32 v41, 1.0, v41
	v_add_f32_e32 v42, 1.0, v42
	v_add_f32_e32 v43, 1.0, v43
	v_rcp_f32_e32 v40, v40
	v_rcp_f32_e32 v41, v41
	v_rcp_f32_e32 v42, v42
	v_rcp_f32_e32 v43, v43
	v_or_b32_e32 v58, 0x100, v50
	v_mov_b32_e32 v59, v51
	v_mul_f32_e32 v38, v38, v64
	v_mul_f32_e32 v39, v39, v64
	v_mul_f32_e32 v36, v36, v64
	v_mul_f32_e32 v37, v37, v64
	v_mul_f32_e32 v38, 0xbfb8aa3b, v38
	v_mul_f32_e32 v39, 0xbfb8aa3b, v39
	v_mul_f32_e32 v36, 0xbfb8aa3b, v36
	v_mul_f32_e32 v37, 0xbfb8aa3b, v37
	v_exp_f32_e32 v38, v38
	v_exp_f32_e32 v39, v39
	v_exp_f32_e32 v36, v36
	v_exp_f32_e32 v37, v37
	v_add_f32_e32 v38, 1.0, v38
	v_add_f32_e32 v39, 1.0, v39
	v_add_f32_e32 v36, 1.0, v36
	v_add_f32_e32 v37, 1.0, v37
	v_rcp_f32_e32 v38, v38
	v_rcp_f32_e32 v39, v39
	v_rcp_f32_e32 v36, v36
	v_rcp_f32_e32 v37, v37
	v_or_b32_e32 v50, 0x120, v50
	v_mul_f32_e32 v32, v32, v64
	v_mul_f32_e32 v33, v33, v64
	v_mul_f32_e32 v34, v34, v64
	v_mul_f32_e32 v35, v35, v64
	v_mul_f32_e32 v32, 0xbfb8aa3b, v32
	v_mul_f32_e32 v33, 0xbfb8aa3b, v33
	v_mul_f32_e32 v34, 0xbfb8aa3b, v34
	v_mul_f32_e32 v35, 0xbfb8aa3b, v35
	v_exp_f32_e32 v32, v32
	v_exp_f32_e32 v33, v33
	v_exp_f32_e32 v34, v34
	v_exp_f32_e32 v35, v35
	v_add_f32_e32 v32, 1.0, v32
	v_add_f32_e32 v33, 1.0, v33
	v_add_f32_e32 v34, 1.0, v34
	v_add_f32_e32 v35, 1.0, v35
	v_mul_f32_e32 v47, v47, v47
	v_mul_f32_e32 v45, v45, v45
	v_rcp_f32_e32 v32, v32
	v_rcp_f32_e32 v33, v33
	v_rcp_f32_e32 v34, v34
	v_rcp_f32_e32 v35, v35
	v_fmac_f32_e32 v47, v46, v46
	v_fmac_f32_e32 v45, v44, v44
	v_add_f32_e32 v44, v47, v45
	s_waitcnt vmcnt(1)
	v_lshlrev_b32_e32 v60, 16, v56
	v_and_b32_e32 v61, 0xffff0000, v56
	s_waitcnt vmcnt(0)
	v_lshlrev_b32_e32 v62, 16, v54
	v_and_b32_e32 v63, 0xffff0000, v54
	v_lshlrev_b32_e32 v56, 16, v57
	v_and_b32_e32 v57, 0xffff0000, v57
	v_lshlrev_b32_e32 v54, 16, v55
	v_and_b32_e32 v55, 0xffff0000, v55
	v_pk_fma_f32 v[40:41], v[40:41], v[62:63], v[60:61]
	v_lshl_add_u64 v[60:61], s[16:17], 0, v[76:77]
	v_pk_fma_f32 v[42:43], v[42:43], v[54:55], v[56:57]
	v_cvt_pk_bf16_f32 v54, v40, v41
	v_lshl_add_u64 v[62:63], s[20:21], 0, v[58:59]
	v_cvt_pk_bf16_f32 v55, v42, v43
	global_store_dwordx2 v[60:61], v[54:55], off
	global_load_dwordx2 v[56:57], v[52:53], off offset:256
	v_mul_f32_e32 v41, v41, v41
	global_load_dwordx2 v[54:55], v[62:63], off
	v_mul_f32_e32 v43, v43, v43
	v_fmac_f32_e32 v41, v40, v40
	v_fmac_f32_e32 v43, v42, v42
	v_add_f32_e32 v40, v41, v43
	v_add_f32_e32 v40, v44, v40
	s_waitcnt vmcnt(1)
	v_lshlrev_b32_e32 v60, 16, v56
	v_and_b32_e32 v61, 0xffff0000, v56
	v_lshlrev_b32_e32 v56, 16, v57
	v_and_b32_e32 v57, 0xffff0000, v57
	s_waitcnt vmcnt(0)
	v_lshlrev_b32_e32 v62, 16, v54
	v_and_b32_e32 v63, 0xffff0000, v54
	v_lshlrev_b32_e32 v54, 16, v55
	v_and_b32_e32 v55, 0xffff0000, v55
	v_pk_fma_f32 v[38:39], v[38:39], v[54:55], v[56:57]
	v_lshl_add_u64 v[56:57], s[16:17], 0, v[58:59]
	v_pk_fma_f32 v[36:37], v[36:37], v[62:63], v[60:61]
	v_lshl_add_u64 v[58:59], s[20:21], 0, v[50:51]
	v_cvt_pk_bf16_f32 v54, v36, v37
	v_cvt_pk_bf16_f32 v55, v38, v39
	global_store_dwordx2 v[56:57], v[54:55], off
	global_load_dwordx2 v[52:53], v[52:53], off offset:288
	v_mul_f32_e32 v37, v37, v37
	global_load_dwordx2 v[54:55], v[58:59], off
	v_mul_f32_e32 v39, v39, v39
	v_fmac_f32_e32 v37, v36, v36
	v_fmac_f32_e32 v39, v38, v38
	v_add_f32_e32 v36, v37, v39
	v_add_f32_e32 v44, v36, v40
	s_waitcnt vmcnt(1)
	v_lshlrev_b32_e32 v36, 16, v52
	v_and_b32_e32 v37, 0xffff0000, v52
	v_lshlrev_b32_e32 v38, 16, v53
	v_and_b32_e32 v39, 0xffff0000, v53
	s_waitcnt vmcnt(0)
	v_lshlrev_b32_e32 v40, 16, v54
	v_and_b32_e32 v41, 0xffff0000, v54
	v_lshlrev_b32_e32 v42, 16, v55
	v_and_b32_e32 v43, 0xffff0000, v55
	v_pk_fma_f32 v[34:35], v[34:35], v[42:43], v[38:39]
	v_pk_fma_f32 v[32:33], v[32:33], v[40:41], v[36:37]
	v_mul_f32_e32 v37, v35, v35
	v_mul_f32_e32 v36, v33, v33
	v_fmac_f32_e32 v36, v32, v32
	v_fmac_f32_e32 v37, v34, v34
	v_add_f32_e32 v36, v36, v37
	v_add_f32_e32 v38, v44, v36
	ds_swizzle_b32 v39, v38 offset:swizzle(SWAP,16)
	v_lshl_add_u64 v[36:37], s[16:17], 0, v[50:51]
	v_cvt_pk_bf16_f32 v32, v32, v33
	v_cvt_pk_bf16_f32 v33, v34, v35
	global_store_dwordx2 v[36:37], v[32:33], off
	s_waitcnt lgkmcnt(0)
	v_add_f32_e32 v32, v38, v39
	v_mov_b32_e32 v33, v32
	s_nop 1
	v_permlane32_swap_b32_e32 v32, v33
	s_and_saveexec_b64 s[2:3], s[4:5]
	s_cbranch_execz .LBB0_910
	v_add_f32_e32 v34, v32, v33
	v_lshl_add_u64 v[32:33], s[18:19], 0, v[48:49]
	v_lshl_add_u64 v[32:33], s[36:37], 2, v[32:33]
	s_lshl_b32 s12, s50, 2
	v_lshl_add_u64 v[32:33], v[32:33], 0, s[12:13]
	global_store_dword v[32:33], v34, off
.LBB0_910:
	s_or_b64 exec, exec, s[2:3]
	v_add_u32_e32 v34, 0xa0, v142
	v_ashrrev_i32_e32 v35, 31, v34
	v_lshlrev_b64 v[32:33], 6, v[34:35]
	v_lshl_add_u64 v[36:37], s[10:11], 0, v[32:33]
	v_bfe_u32 v46, v206, 4, 2
	v_lshlrev_b32_e32 v46, 4, v46
	v_mov_b32_e32 v47, 0
	v_lshl_add_u64 v[42:43], v[36:37], 0, v[46:47]
	global_load_dwordx4 v[38:41], v[42:43], off
	v_lshlrev_b64 v[34:35], 10, v[34:35]
	v_lshl_add_u64 v[34:35], v[34:35], 0, v[140:141]
	v_lshlrev_b64 v[34:35], 1, v[34:35]
	v_lshl_add_u64 v[36:37], s[20:21], 0, v[34:35]
	global_load_dwordx2 v[54:55], v[36:37], off
	v_lshl_add_u64 v[36:37], s[8:9], 0, v[34:35]
	global_load_dwordx2 v[56:57], v[36:37], off
	v_lshl_add_u64 v[58:59], s[16:17], 0, v[34:35]
	v_or_b32_e32 v60, 32, v34
	v_mov_b32_e32 v61, v35
	s_waitcnt vmcnt(0)
	v_add_f32_e32 v42, v38, v39
	v_add_f32_e32 v43, v40, v41
	v_add_f32_e32 v42, v42, v43
	ds_swizzle_b32 v43, v42 offset:swizzle(SWAP,16)
	s_waitcnt lgkmcnt(0)
	v_add_f32_e32 v42, v42, v43
	v_mov_b32_e32 v43, v42
	s_nop 1
	v_permlane32_swap_b32_e32 v42, v43
	v_add_f32_e32 v50, v42, v43
	v_lshlrev_b32_e32 v44, 16, v55
	v_lshlrev_b32_e32 v40, 16, v54
	v_mov_b32_e32 v38, v50
	v_fmamk_f32 v38, v38, 0x3a800000, v156
	v_mul_f32_e32 v39, 0x4b800000, v38
	v_cmp_gt_f32_e32 vcc, s56, v38
	v_and_b32_e32 v41, 0xffff0000, v54
	v_and_b32_e32 v45, 0xffff0000, v55
	v_cndmask_b32_e32 v38, v38, v39, vcc
	v_rsq_f32_e32 v42, v38
	s_waitcnt vmcnt(0)
	v_lshlrev_b32_e32 v38, 16, v56
	v_and_b32_e32 v39, 0xffff0000, v56
	v_mul_f32_e32 v43, 0x45800000, v42
	v_cndmask_b32_e32 v48, v42, v43, vcc
	v_mul_f32_e32 v28, v28, v48
	v_mul_f32_e32 v29, v29, v48
	v_mul_f32_e32 v30, v30, v48
	v_mul_f32_e32 v31, v31, v48
	v_mul_f32_e32 v28, 0xbfb8aa3b, v28
	v_mul_f32_e32 v29, 0xbfb8aa3b, v29
	v_mul_f32_e32 v30, 0xbfb8aa3b, v30
	v_mul_f32_e32 v31, 0xbfb8aa3b, v31
	v_exp_f32_e32 v28, v28
	v_exp_f32_e32 v29, v29
	v_exp_f32_e32 v30, v30
	v_exp_f32_e32 v31, v31
	v_add_f32_e32 v28, 1.0, v28
	v_add_f32_e32 v42, 1.0, v29
	v_add_f32_e32 v29, 1.0, v30
	v_add_f32_e32 v31, 1.0, v31
	v_rcp_f32_e32 v30, v28
	v_rcp_f32_e32 v28, v29
	v_rcp_f32_e32 v29, v31
	v_rcp_f32_e32 v31, v42
	v_lshlrev_b32_e32 v42, 16, v57
	v_and_b32_e32 v43, 0xffff0000, v57
	v_pk_fma_f32 v[28:29], v[28:29], v[44:45], v[42:43]
	v_pk_fma_f32 v[30:31], v[30:31], v[40:41], v[38:39]
	v_lshl_add_u64 v[42:43], s[20:21], 0, v[60:61]
	v_cvt_pk_bf16_f32 v38, v30, v31
	v_cvt_pk_bf16_f32 v39, v28, v29
	global_store_dwordx2 v[58:59], v[38:39], off
	global_load_dwordx2 v[40:41], v[36:37], off offset:32
	v_mul_f32_e32 v24, v24, v48
	global_load_dwordx2 v[38:39], v[42:43], off
	v_mul_f32_e32 v25, v25, v48
	v_mul_f32_e32 v26, v26, v48
	v_mul_f32_e32 v27, v27, v48
	v_mul_f32_e32 v24, 0xbfb8aa3b, v24
	v_mul_f32_e32 v25, 0xbfb8aa3b, v25
	v_mul_f32_e32 v26, 0xbfb8aa3b, v26
	v_mul_f32_e32 v27, 0xbfb8aa3b, v27
	v_exp_f32_e32 v24, v24
	v_exp_f32_e32 v25, v25
	v_exp_f32_e32 v26, v26
	v_exp_f32_e32 v27, v27
	v_add_f32_e32 v24, 1.0, v24
	v_add_f32_e32 v25, 1.0, v25
	v_add_f32_e32 v26, 1.0, v26
	v_add_f32_e32 v27, 1.0, v27
	v_rcp_f32_e32 v24, v24
	v_rcp_f32_e32 v25, v25
	v_rcp_f32_e32 v26, v26
	v_rcp_f32_e32 v27, v27
	v_or_b32_e32 v42, 0x100, v34
	v_mov_b32_e32 v43, v35
	v_mul_f32_e32 v22, v22, v48
	v_mul_f32_e32 v23, v23, v48
	v_mul_f32_e32 v20, v20, v48
	v_mul_f32_e32 v21, v21, v48
	v_mul_f32_e32 v22, 0xbfb8aa3b, v22
	v_mul_f32_e32 v23, 0xbfb8aa3b, v23
	v_mul_f32_e32 v20, 0xbfb8aa3b, v20
	v_mul_f32_e32 v21, 0xbfb8aa3b, v21
	v_exp_f32_e32 v22, v22
	v_exp_f32_e32 v23, v23
	v_exp_f32_e32 v20, v20
	v_exp_f32_e32 v21, v21
	v_add_f32_e32 v22, 1.0, v22
	v_add_f32_e32 v23, 1.0, v23
	v_add_f32_e32 v20, 1.0, v20
	v_add_f32_e32 v21, 1.0, v21
	v_rcp_f32_e32 v22, v22
	v_rcp_f32_e32 v23, v23
	v_rcp_f32_e32 v20, v20
	v_rcp_f32_e32 v21, v21
	v_or_b32_e32 v34, 0x120, v34
	v_mul_f32_e32 v16, v16, v48
	v_mul_f32_e32 v17, v17, v48
	v_mul_f32_e32 v18, v18, v48
	v_mul_f32_e32 v19, v19, v48
	v_mul_f32_e32 v16, 0xbfb8aa3b, v16
	v_mul_f32_e32 v17, 0xbfb8aa3b, v17
	v_mul_f32_e32 v18, 0xbfb8aa3b, v18
	v_mul_f32_e32 v19, 0xbfb8aa3b, v19
	v_exp_f32_e32 v16, v16
	v_exp_f32_e32 v17, v17
	v_exp_f32_e32 v18, v18
	v_exp_f32_e32 v19, v19
	v_add_f32_e32 v16, 1.0, v16
	v_add_f32_e32 v17, 1.0, v17
	v_add_f32_e32 v18, 1.0, v18
	v_add_f32_e32 v19, 1.0, v19
	v_mul_f32_e32 v31, v31, v31
	v_mul_f32_e32 v29, v29, v29
	v_rcp_f32_e32 v16, v16
	v_rcp_f32_e32 v17, v17
	v_rcp_f32_e32 v18, v18
	v_rcp_f32_e32 v19, v19
	v_fmac_f32_e32 v31, v30, v30
	v_fmac_f32_e32 v29, v28, v28
	v_add_f32_e32 v28, v31, v29
	s_waitcnt vmcnt(1)
	v_lshlrev_b32_e32 v44, 16, v40
	v_and_b32_e32 v45, 0xffff0000, v40
	s_waitcnt vmcnt(0)
	v_lshlrev_b32_e32 v46, 16, v38
	v_and_b32_e32 v47, 0xffff0000, v38
	v_lshlrev_b32_e32 v40, 16, v41
	v_and_b32_e32 v41, 0xffff0000, v41
	v_lshlrev_b32_e32 v38, 16, v39
	v_and_b32_e32 v39, 0xffff0000, v39
	v_pk_fma_f32 v[24:25], v[24:25], v[46:47], v[44:45]
	v_lshl_add_u64 v[44:45], s[16:17], 0, v[60:61]
	v_pk_fma_f32 v[26:27], v[26:27], v[38:39], v[40:41]
	v_cvt_pk_bf16_f32 v38, v24, v25
	v_lshl_add_u64 v[46:47], s[20:21], 0, v[42:43]
	v_cvt_pk_bf16_f32 v39, v26, v27
	global_store_dwordx2 v[44:45], v[38:39], off
	global_load_dwordx2 v[40:41], v[36:37], off offset:256
	v_mul_f32_e32 v25, v25, v25
	global_load_dwordx2 v[38:39], v[46:47], off
	v_mul_f32_e32 v27, v27, v27
	v_fmac_f32_e32 v25, v24, v24
	v_fmac_f32_e32 v27, v26, v26
	v_add_f32_e32 v24, v25, v27
	v_add_f32_e32 v24, v28, v24
	s_waitcnt vmcnt(1)
	v_lshlrev_b32_e32 v44, 16, v40
	v_and_b32_e32 v45, 0xffff0000, v40
	v_lshlrev_b32_e32 v40, 16, v41
	v_and_b32_e32 v41, 0xffff0000, v41
	s_waitcnt vmcnt(0)
	v_lshlrev_b32_e32 v46, 16, v38
	v_and_b32_e32 v47, 0xffff0000, v38
	v_lshlrev_b32_e32 v38, 16, v39
	v_and_b32_e32 v39, 0xffff0000, v39
	v_pk_fma_f32 v[22:23], v[22:23], v[38:39], v[40:41]
	v_lshl_add_u64 v[40:41], s[16:17], 0, v[42:43]
	v_pk_fma_f32 v[20:21], v[20:21], v[46:47], v[44:45]
	v_lshl_add_u64 v[42:43], s[20:21], 0, v[34:35]
	v_cvt_pk_bf16_f32 v38, v20, v21
	v_cvt_pk_bf16_f32 v39, v22, v23
	global_store_dwordx2 v[40:41], v[38:39], off
	global_load_dwordx2 v[36:37], v[36:37], off offset:288
	v_mul_f32_e32 v21, v21, v21
	global_load_dwordx2 v[38:39], v[42:43], off
	v_mul_f32_e32 v23, v23, v23
	v_fmac_f32_e32 v21, v20, v20
	v_fmac_f32_e32 v23, v22, v22
	v_add_f32_e32 v20, v21, v23
	v_add_f32_e32 v28, v20, v24
	s_waitcnt vmcnt(1)
	v_lshlrev_b32_e32 v20, 16, v36
	v_and_b32_e32 v21, 0xffff0000, v36
	v_lshlrev_b32_e32 v22, 16, v37
	v_and_b32_e32 v23, 0xffff0000, v37
	s_waitcnt vmcnt(0)
	v_lshlrev_b32_e32 v24, 16, v38
	v_and_b32_e32 v25, 0xffff0000, v38
	v_lshlrev_b32_e32 v26, 16, v39
	v_and_b32_e32 v27, 0xffff0000, v39
	v_pk_fma_f32 v[18:19], v[18:19], v[26:27], v[22:23]
	v_pk_fma_f32 v[16:17], v[16:17], v[24:25], v[20:21]
	v_mul_f32_e32 v21, v19, v19
	v_mul_f32_e32 v20, v17, v17
	v_fmac_f32_e32 v20, v16, v16
	v_fmac_f32_e32 v21, v18, v18
	v_add_f32_e32 v20, v20, v21
	v_add_f32_e32 v22, v28, v20
	ds_swizzle_b32 v23, v22 offset:swizzle(SWAP,16)
	v_lshl_add_u64 v[20:21], s[16:17], 0, v[34:35]
	v_cvt_pk_bf16_f32 v16, v16, v17
	v_cvt_pk_bf16_f32 v17, v18, v19
	global_store_dwordx2 v[20:21], v[16:17], off
	s_waitcnt lgkmcnt(0)
	v_add_f32_e32 v16, v22, v23
	v_mov_b32_e32 v17, v16
	s_nop 1
	v_permlane32_swap_b32_e32 v16, v17
	s_and_saveexec_b64 s[2:3], s[4:5]
	s_cbranch_execz .LBB0_912
	v_add_f32_e32 v18, v16, v17
	v_lshl_add_u64 v[16:17], s[18:19], 0, v[32:33]
	v_lshl_add_u64 v[16:17], s[36:37], 2, v[16:17]
	s_lshl_b32 s12, s50, 2
	v_lshl_add_u64 v[16:17], v[16:17], 0, s[12:13]
	global_store_dword v[16:17], v18, off
.LBB0_912:
	s_or_b64 exec, exec, s[2:3]
	v_add_u32_e32 v18, 0xb0, v142
	v_ashrrev_i32_e32 v19, 31, v18
	v_lshlrev_b64 v[16:17], 6, v[18:19]
	v_lshl_add_u64 v[20:21], s[10:11], 0, v[16:17]
	v_bfe_u32 v30, v206, 4, 2
	v_lshlrev_b32_e32 v30, 4, v30
	v_mov_b32_e32 v31, 0
	v_lshl_add_u64 v[26:27], v[20:21], 0, v[30:31]
	global_load_dwordx4 v[22:25], v[26:27], off
	v_lshlrev_b64 v[18:19], 10, v[18:19]
	v_lshl_add_u64 v[18:19], v[18:19], 0, v[140:141]
	v_lshlrev_b64 v[18:19], 1, v[18:19]
	v_lshl_add_u64 v[20:21], s[20:21], 0, v[18:19]
	global_load_dwordx2 v[38:39], v[20:21], off
	v_lshl_add_u64 v[20:21], s[8:9], 0, v[18:19]
	global_load_dwordx2 v[40:41], v[20:21], off
	v_lshl_add_u64 v[42:43], s[16:17], 0, v[18:19]
	v_or_b32_e32 v44, 32, v18
	v_mov_b32_e32 v45, v19
	s_waitcnt vmcnt(0)
	v_add_f32_e32 v26, v22, v23
	v_add_f32_e32 v27, v24, v25
	v_add_f32_e32 v26, v26, v27
	ds_swizzle_b32 v27, v26 offset:swizzle(SWAP,16)
	s_waitcnt lgkmcnt(0)
	v_add_f32_e32 v26, v26, v27
	v_mov_b32_e32 v27, v26
	s_nop 1
	v_permlane32_swap_b32_e32 v26, v27
	v_add_f32_e32 v34, v26, v27
	v_lshlrev_b32_e32 v28, 16, v39
	v_lshlrev_b32_e32 v24, 16, v38
	v_mov_b32_e32 v22, v34
	v_fmamk_f32 v22, v22, 0x3a800000, v156
	v_mul_f32_e32 v23, 0x4b800000, v22
	v_cmp_gt_f32_e32 vcc, s56, v22
	v_and_b32_e32 v25, 0xffff0000, v38
	v_and_b32_e32 v29, 0xffff0000, v39
	v_cndmask_b32_e32 v22, v22, v23, vcc
	v_rsq_f32_e32 v26, v22
	s_waitcnt vmcnt(0)
	v_lshlrev_b32_e32 v22, 16, v40
	v_and_b32_e32 v23, 0xffff0000, v40
	v_mul_f32_e32 v27, 0x45800000, v26
	v_cndmask_b32_e32 v32, v26, v27, vcc
	v_mul_f32_e32 v12, v12, v32
	v_mul_f32_e32 v13, v13, v32
	v_mul_f32_e32 v14, v14, v32
	v_mul_f32_e32 v15, v15, v32
	v_mul_f32_e32 v12, 0xbfb8aa3b, v12
	v_mul_f32_e32 v13, 0xbfb8aa3b, v13
	v_mul_f32_e32 v14, 0xbfb8aa3b, v14
	v_mul_f32_e32 v15, 0xbfb8aa3b, v15
	v_exp_f32_e32 v12, v12
	v_exp_f32_e32 v13, v13
	v_exp_f32_e32 v14, v14
	v_exp_f32_e32 v15, v15
	v_add_f32_e32 v12, 1.0, v12
	v_add_f32_e32 v26, 1.0, v13
	v_add_f32_e32 v13, 1.0, v14
	v_add_f32_e32 v15, 1.0, v15
	v_rcp_f32_e32 v14, v12
	v_rcp_f32_e32 v12, v13
	v_rcp_f32_e32 v13, v15
	v_rcp_f32_e32 v15, v26
	v_lshlrev_b32_e32 v26, 16, v41
	v_and_b32_e32 v27, 0xffff0000, v41
	v_pk_fma_f32 v[12:13], v[12:13], v[28:29], v[26:27]
	v_pk_fma_f32 v[14:15], v[14:15], v[24:25], v[22:23]
	v_lshl_add_u64 v[26:27], s[20:21], 0, v[44:45]
	v_cvt_pk_bf16_f32 v22, v14, v15
	v_cvt_pk_bf16_f32 v23, v12, v13
	global_store_dwordx2 v[42:43], v[22:23], off
	global_load_dwordx2 v[24:25], v[20:21], off offset:32
	v_mul_f32_e32 v8, v8, v32
	global_load_dwordx2 v[22:23], v[26:27], off
	v_mul_f32_e32 v9, v9, v32
	v_mul_f32_e32 v10, v10, v32
	v_mul_f32_e32 v11, v11, v32
	v_mul_f32_e32 v8, 0xbfb8aa3b, v8
	v_mul_f32_e32 v9, 0xbfb8aa3b, v9
	v_mul_f32_e32 v10, 0xbfb8aa3b, v10
	v_mul_f32_e32 v11, 0xbfb8aa3b, v11
	v_exp_f32_e32 v8, v8
	v_exp_f32_e32 v9, v9
	v_exp_f32_e32 v10, v10
	v_exp_f32_e32 v11, v11
	v_add_f32_e32 v8, 1.0, v8
	v_add_f32_e32 v9, 1.0, v9
	v_add_f32_e32 v10, 1.0, v10
	v_add_f32_e32 v11, 1.0, v11
	v_rcp_f32_e32 v8, v8
	v_rcp_f32_e32 v9, v9
	v_rcp_f32_e32 v10, v10
	v_rcp_f32_e32 v11, v11
	v_or_b32_e32 v26, 0x100, v18
	v_mov_b32_e32 v27, v19
	v_mul_f32_e32 v6, v6, v32
	v_mul_f32_e32 v7, v7, v32
	v_mul_f32_e32 v4, v4, v32
	v_mul_f32_e32 v5, v5, v32
	v_mul_f32_e32 v6, 0xbfb8aa3b, v6
	v_mul_f32_e32 v7, 0xbfb8aa3b, v7
	v_mul_f32_e32 v4, 0xbfb8aa3b, v4
	v_mul_f32_e32 v5, 0xbfb8aa3b, v5
	v_exp_f32_e32 v6, v6
	v_exp_f32_e32 v7, v7
	v_exp_f32_e32 v4, v4
	v_exp_f32_e32 v5, v5
	v_add_f32_e32 v6, 1.0, v6
	v_add_f32_e32 v7, 1.0, v7
	v_add_f32_e32 v4, 1.0, v4
	v_add_f32_e32 v5, 1.0, v5
	v_rcp_f32_e32 v6, v6
	v_rcp_f32_e32 v7, v7
	v_rcp_f32_e32 v4, v4
	v_rcp_f32_e32 v5, v5
	v_or_b32_e32 v18, 0x120, v18
	v_mul_f32_e32 v0, v0, v32
	v_mul_f32_e32 v1, v1, v32
	v_mul_f32_e32 v2, v2, v32
	v_mul_f32_e32 v3, v3, v32
	v_mul_f32_e32 v0, 0xbfb8aa3b, v0
	v_mul_f32_e32 v1, 0xbfb8aa3b, v1
	v_mul_f32_e32 v2, 0xbfb8aa3b, v2
	v_mul_f32_e32 v3, 0xbfb8aa3b, v3
	v_exp_f32_e32 v0, v0
	v_exp_f32_e32 v1, v1
	v_exp_f32_e32 v2, v2
	v_exp_f32_e32 v3, v3
	v_add_f32_e32 v0, 1.0, v0
	v_add_f32_e32 v1, 1.0, v1
	v_add_f32_e32 v2, 1.0, v2
	v_add_f32_e32 v3, 1.0, v3
	v_mul_f32_e32 v15, v15, v15
	v_mul_f32_e32 v13, v13, v13
	v_rcp_f32_e32 v0, v0
	v_rcp_f32_e32 v1, v1
	v_rcp_f32_e32 v2, v2
	v_rcp_f32_e32 v3, v3
	v_fmac_f32_e32 v15, v14, v14
	v_fmac_f32_e32 v13, v12, v12
	v_add_f32_e32 v12, v15, v13
	s_waitcnt vmcnt(1)
	v_lshlrev_b32_e32 v28, 16, v24
	v_and_b32_e32 v29, 0xffff0000, v24
	s_waitcnt vmcnt(0)
	v_lshlrev_b32_e32 v30, 16, v22
	v_and_b32_e32 v31, 0xffff0000, v22
	v_lshlrev_b32_e32 v24, 16, v25
	v_and_b32_e32 v25, 0xffff0000, v25
	v_lshlrev_b32_e32 v22, 16, v23
	v_and_b32_e32 v23, 0xffff0000, v23
	v_pk_fma_f32 v[8:9], v[8:9], v[30:31], v[28:29]
	v_lshl_add_u64 v[28:29], s[16:17], 0, v[44:45]
	v_pk_fma_f32 v[10:11], v[10:11], v[22:23], v[24:25]
	v_cvt_pk_bf16_f32 v22, v8, v9
	v_lshl_add_u64 v[30:31], s[20:21], 0, v[26:27]
	v_cvt_pk_bf16_f32 v23, v10, v11
	global_store_dwordx2 v[28:29], v[22:23], off
	global_load_dwordx2 v[24:25], v[20:21], off offset:256
	v_mul_f32_e32 v9, v9, v9
	global_load_dwordx2 v[22:23], v[30:31], off
	v_mul_f32_e32 v11, v11, v11
	v_fmac_f32_e32 v9, v8, v8
	v_fmac_f32_e32 v11, v10, v10
	v_add_f32_e32 v8, v9, v11
	v_add_f32_e32 v8, v12, v8
	s_waitcnt vmcnt(1)
	v_lshlrev_b32_e32 v28, 16, v24
	v_and_b32_e32 v29, 0xffff0000, v24
	v_lshlrev_b32_e32 v24, 16, v25
	v_and_b32_e32 v25, 0xffff0000, v25
	s_waitcnt vmcnt(0)
	v_lshlrev_b32_e32 v30, 16, v22
	v_and_b32_e32 v31, 0xffff0000, v22
	v_lshlrev_b32_e32 v22, 16, v23
	v_and_b32_e32 v23, 0xffff0000, v23
	v_pk_fma_f32 v[6:7], v[6:7], v[22:23], v[24:25]
	v_lshl_add_u64 v[24:25], s[16:17], 0, v[26:27]
	v_pk_fma_f32 v[4:5], v[4:5], v[30:31], v[28:29]
	v_lshl_add_u64 v[26:27], s[20:21], 0, v[18:19]
	v_cvt_pk_bf16_f32 v22, v4, v5
	v_cvt_pk_bf16_f32 v23, v6, v7
	global_store_dwordx2 v[24:25], v[22:23], off
	global_load_dwordx2 v[20:21], v[20:21], off offset:288
	v_mul_f32_e32 v5, v5, v5
	global_load_dwordx2 v[22:23], v[26:27], off
	v_mul_f32_e32 v7, v7, v7
	v_fmac_f32_e32 v5, v4, v4
	v_fmac_f32_e32 v7, v6, v6
	v_add_f32_e32 v4, v5, v7
	v_add_f32_e32 v12, v4, v8
	s_waitcnt vmcnt(1)
	v_lshlrev_b32_e32 v4, 16, v20
	v_and_b32_e32 v5, 0xffff0000, v20
	v_lshlrev_b32_e32 v6, 16, v21
	v_and_b32_e32 v7, 0xffff0000, v21
	s_waitcnt vmcnt(0)
	v_lshlrev_b32_e32 v8, 16, v22
	v_and_b32_e32 v9, 0xffff0000, v22
	v_lshlrev_b32_e32 v10, 16, v23
	v_and_b32_e32 v11, 0xffff0000, v23
	v_pk_fma_f32 v[2:3], v[2:3], v[10:11], v[6:7]
	v_pk_fma_f32 v[0:1], v[0:1], v[8:9], v[4:5]
	v_mul_f32_e32 v5, v3, v3
	v_mul_f32_e32 v4, v1, v1
	v_fmac_f32_e32 v4, v0, v0
	v_fmac_f32_e32 v5, v2, v2
	v_add_f32_e32 v4, v4, v5
	v_add_f32_e32 v6, v12, v4
	ds_swizzle_b32 v7, v6 offset:swizzle(SWAP,16)
	v_lshl_add_u64 v[4:5], s[16:17], 0, v[18:19]
	v_cvt_pk_bf16_f32 v0, v0, v1
	v_cvt_pk_bf16_f32 v1, v2, v3
	global_store_dwordx2 v[4:5], v[0:1], off
	s_waitcnt lgkmcnt(0)
	v_add_f32_e32 v0, v6, v7
	v_mov_b32_e32 v1, v0
	s_nop 1
	v_permlane32_swap_b32_e32 v0, v1
	s_and_saveexec_b64 s[2:3], s[4:5]
	s_cbranch_execz .LBB0_914
	v_add_f32_e32 v2, v0, v1
	v_lshl_add_u64 v[0:1], s[18:19], 0, v[16:17]
	v_lshl_add_u64 v[0:1], s[36:37], 2, v[0:1]
	s_lshl_b32 s12, s50, 2
	v_lshl_add_u64 v[0:1], v[0:1], 0, s[12:13]
	global_store_dword v[0:1], v2, off

.LBB0_991:
	v_lshl_add_u32 v146, s24, 8, v148
	v_ashrrev_i32_e32 v147, 31, v146
	v_lshlrev_b64 v[144:145], 6, v[146:147]
	v_lshl_add_u64 v[144:145], s[10:11], 0, v[144:145]
	v_bfe_u32 v164, v206, 4, 2
	v_lshlrev_b32_e32 v164, 4, v164
	v_mov_b32_e32 v165, 0
	v_lshl_add_u64 v[160:161], v[144:145], 0, v[164:165]
	global_load_dwordx4 v[156:159], v[160:161], off
	v_lshlrev_b64 v[174:175], 12, v[146:147]
	v_lshl_or_b32 v144, s48, 8, v150
	v_ashrrev_i32_e32 v145, 31, v144
	v_or_b32_e32 v172, 16, v146
	v_lshl_add_u64 v[144:145], v[144:145], 1, s[8:9]
	v_ashrrev_i32_e32 v173, 31, v172
	s_waitcnt vmcnt(0)
	v_add_f32_e32 v160, v156, v157
	v_add_f32_e32 v161, v158, v159
	v_add_f32_e32 v160, v160, v161
	ds_swizzle_b32 v161, v160 offset:swizzle(SWAP,16)
	s_waitcnt lgkmcnt(0)
	v_add_f32_e32 v160, v160, v161
	v_mov_b32_e32 v161, v160
	s_nop 1
	v_permlane32_swap_b32_e32 v160, v161
	v_add_f32_e32 v168, v160, v161
	s_nop 0
	v_lshlrev_b64 v[158:159], 6, v[172:173]
	v_mov_b32_e32 v147, v168
	v_fmamk_f32 v147, v147, 0x3a800000, v154
	v_mul_f32_e32 v155, 0x4b800000, v147
	v_cmp_gt_f32_e32 vcc, s47, v147
	v_lshl_add_u64 v[156:157], v[144:145], 0, v[174:175]
	v_lshl_add_u64 v[158:159], s[10:11], 0, v[158:159]
	v_cndmask_b32_e32 v147, v147, v155, vcc
	v_rsq_f32_e32 v147, v147
	s_nop 0
	v_mul_f32_e32 v155, 0x45800000, v147
	v_cndmask_b32_e32 v160, v147, v155, vcc
	v_pk_mul_f32 v[126:127], v[126:127], v[160:161] op_sel_hi:[1,0]
	v_pk_mul_f32 v[124:125], v[124:125], v[160:161] op_sel_hi:[1,0]
	v_pk_mul_f32 v[122:123], v[122:123], v[160:161] op_sel_hi:[1,0]
	v_pk_mul_f32 v[120:121], v[120:121], v[160:161] op_sel_hi:[1,0]
	v_pk_mul_f32 v[118:119], v[118:119], v[160:161] op_sel_hi:[1,0]
	v_pk_mul_f32 v[116:117], v[116:117], v[160:161] op_sel_hi:[1,0]
	v_pk_mul_f32 v[162:163], v[114:115], v[160:161] op_sel_hi:[1,0]
	v_pk_mul_f32 v[160:161], v[112:113], v[160:161] op_sel_hi:[1,0]
	v_cvt_pk_bf16_f32 v112, v124, v125
	v_cvt_pk_bf16_f32 v113, v126, v127
	v_cvt_pk_bf16_f32 v114, v120, v121
	v_cvt_pk_bf16_f32 v115, v122, v123
	global_store_dwordx4 v[156:157], v[112:115], off
	s_nop 1
	v_cvt_pk_bf16_f32 v112, v116, v117
	v_cvt_pk_bf16_f32 v113, v118, v119
	v_cvt_pk_bf16_f32 v114, v160, v161
	v_cvt_pk_bf16_f32 v115, v162, v163
	global_store_dwordx4 v[156:157], v[112:115], off offset:256
	v_bfe_u32 v120, v206, 4, 2
	v_lshlrev_b32_e32 v120, 4, v120
	v_mov_b32_e32 v121, 0
	v_lshl_add_u64 v[116:117], v[158:159], 0, v[120:121]
	global_load_dwordx4 v[112:115], v[116:117], off
	s_nop 0
	v_or_b32_e32 v156, 32, v146
	v_ashrrev_i32_e32 v157, 31, v156
	v_lshlrev_b64 v[158:159], 12, v[172:173]
	s_waitcnt vmcnt(0)
	v_add_f32_e32 v116, v112, v113
	v_add_f32_e32 v117, v114, v115
	v_add_f32_e32 v116, v116, v117
	ds_swizzle_b32 v117, v116 offset:swizzle(SWAP,16)
	s_waitcnt lgkmcnt(0)
	v_add_f32_e32 v116, v116, v117
	v_mov_b32_e32 v117, v116
	s_nop 1
	v_permlane32_swap_b32_e32 v116, v117
	v_add_f32_e32 v124, v116, v117
	s_nop 0
	v_lshl_add_u64 v[114:115], v[144:145], 0, v[158:159]
	v_mov_b32_e32 v112, v124
	v_fmamk_f32 v112, v112, 0x3a800000, v154
	v_mul_f32_e32 v113, 0x4b800000, v112
	v_cmp_gt_f32_e32 vcc, s47, v112
	s_nop 1
	v_cndmask_b32_e32 v112, v112, v113, vcc
	v_rsq_f32_e32 v116, v112
	v_lshlrev_b64 v[112:113], 6, v[156:157]
	v_lshl_add_u64 v[112:113], s[10:11], 0, v[112:113]
	v_mul_f32_e32 v117, 0x45800000, v116
	v_cndmask_b32_e32 v116, v116, v117, vcc
	v_pk_mul_f32 v[110:111], v[110:111], v[116:117] op_sel_hi:[1,0]
	v_pk_mul_f32 v[108:109], v[108:109], v[116:117] op_sel_hi:[1,0]
	v_pk_mul_f32 v[106:107], v[106:107], v[116:117] op_sel_hi:[1,0]
	v_pk_mul_f32 v[104:105], v[104:105], v[116:117] op_sel_hi:[1,0]
	v_pk_mul_f32 v[102:103], v[102:103], v[116:117] op_sel_hi:[1,0]
	v_pk_mul_f32 v[100:101], v[100:101], v[116:117] op_sel_hi:[1,0]
	v_pk_mul_f32 v[118:119], v[98:99], v[116:117] op_sel_hi:[1,0]
	v_pk_mul_f32 v[116:117], v[96:97], v[116:117] op_sel_hi:[1,0]
	v_cvt_pk_bf16_f32 v96, v108, v109
	v_cvt_pk_bf16_f32 v97, v110, v111
	v_cvt_pk_bf16_f32 v98, v104, v105
	v_cvt_pk_bf16_f32 v99, v106, v107
	global_store_dwordx4 v[114:115], v[96:99], off
	s_nop 1
	v_cvt_pk_bf16_f32 v96, v100, v101
	v_cvt_pk_bf16_f32 v97, v102, v103
	v_cvt_pk_bf16_f32 v98, v116, v117
	v_cvt_pk_bf16_f32 v99, v118, v119
	global_store_dwordx4 v[114:115], v[96:99], off offset:256
	v_bfe_u32 v104, v206, 4, 2
	v_lshlrev_b32_e32 v104, 4, v104
	v_mov_b32_e32 v105, 0
	v_lshl_add_u64 v[100:101], v[112:113], 0, v[104:105]
	global_load_dwordx4 v[96:99], v[100:101], off
	s_nop 0
	v_or_b32_e32 v112, 48, v146
	v_ashrrev_i32_e32 v113, 31, v112
	v_lshlrev_b64 v[114:115], 12, v[156:157]
	s_waitcnt vmcnt(0)
	v_add_f32_e32 v100, v96, v97
	v_add_f32_e32 v101, v98, v99
	v_add_f32_e32 v100, v100, v101
	ds_swizzle_b32 v101, v100 offset:swizzle(SWAP,16)
	s_waitcnt lgkmcnt(0)
	v_add_f32_e32 v100, v100, v101
	v_mov_b32_e32 v101, v100
	s_nop 1
	v_permlane32_swap_b32_e32 v100, v101
	v_add_f32_e32 v108, v100, v101
	s_nop 0
	v_lshl_add_u64 v[98:99], v[144:145], 0, v[114:115]
	v_mov_b32_e32 v96, v108
	v_fmamk_f32 v96, v96, 0x3a800000, v154
	v_mul_f32_e32 v97, 0x4b800000, v96
	v_cmp_gt_f32_e32 vcc, s47, v96
	s_nop 1
	v_cndmask_b32_e32 v96, v96, v97, vcc
	v_rsq_f32_e32 v100, v96
	v_lshlrev_b64 v[96:97], 6, v[112:113]
	v_lshl_add_u64 v[96:97], s[10:11], 0, v[96:97]
	v_mul_f32_e32 v101, 0x45800000, v100
	v_cndmask_b32_e32 v100, v100, v101, vcc
	v_pk_mul_f32 v[94:95], v[94:95], v[100:101] op_sel_hi:[1,0]
	v_pk_mul_f32 v[92:93], v[92:93], v[100:101] op_sel_hi:[1,0]
	v_pk_mul_f32 v[90:91], v[90:91], v[100:101] op_sel_hi:[1,0]
	v_pk_mul_f32 v[88:89], v[88:89], v[100:101] op_sel_hi:[1,0]
	v_pk_mul_f32 v[86:87], v[86:87], v[100:101] op_sel_hi:[1,0]
	v_pk_mul_f32 v[84:85], v[84:85], v[100:101] op_sel_hi:[1,0]
	v_pk_mul_f32 v[102:103], v[82:83], v[100:101] op_sel_hi:[1,0]
	v_pk_mul_f32 v[100:101], v[80:81], v[100:101] op_sel_hi:[1,0]
	v_cvt_pk_bf16_f32 v80, v92, v93
	v_cvt_pk_bf16_f32 v81, v94, v95
	v_cvt_pk_bf16_f32 v82, v88, v89
	v_cvt_pk_bf16_f32 v83, v90, v91
	global_store_dwordx4 v[98:99], v[80:83], off
	s_nop 1
	v_cvt_pk_bf16_f32 v80, v84, v85
	v_cvt_pk_bf16_f32 v81, v86, v87
	v_cvt_pk_bf16_f32 v82, v100, v101
	v_cvt_pk_bf16_f32 v83, v102, v103
	global_store_dwordx4 v[98:99], v[80:83], off offset:256
	v_bfe_u32 v88, v206, 4, 2
	v_lshlrev_b32_e32 v88, 4, v88
	v_mov_b32_e32 v89, 0
	v_lshl_add_u64 v[84:85], v[96:97], 0, v[88:89]
	global_load_dwordx4 v[80:83], v[84:85], off
	s_nop 0
	v_add_u32_e32 v96, 0x80, v146
	v_ashrrev_i32_e32 v97, 31, v96
	v_lshlrev_b64 v[98:99], 12, v[112:113]
	s_waitcnt vmcnt(0)
	v_add_f32_e32 v84, v80, v81
	v_add_f32_e32 v85, v82, v83
	v_add_f32_e32 v84, v84, v85
	ds_swizzle_b32 v85, v84 offset:swizzle(SWAP,16)
	s_waitcnt lgkmcnt(0)
	v_add_f32_e32 v84, v84, v85
	v_mov_b32_e32 v85, v84
	s_nop 1
	v_permlane32_swap_b32_e32 v84, v85
	v_add_f32_e32 v92, v84, v85
	s_nop 0
	v_lshl_add_u64 v[82:83], v[144:145], 0, v[98:99]
	v_mov_b32_e32 v80, v92
	v_fmamk_f32 v80, v80, 0x3a800000, v154
	v_mul_f32_e32 v81, 0x4b800000, v80
	v_cmp_gt_f32_e32 vcc, s47, v80
	s_nop 1
	v_cndmask_b32_e32 v80, v80, v81, vcc
	v_rsq_f32_e32 v84, v80
	v_lshlrev_b64 v[80:81], 6, v[96:97]
	v_lshl_add_u64 v[80:81], s[10:11], 0, v[80:81]
	v_mul_f32_e32 v85, 0x45800000, v84
	v_cndmask_b32_e32 v84, v84, v85, vcc
	v_pk_mul_f32 v[78:79], v[78:79], v[84:85] op_sel_hi:[1,0]
	v_pk_mul_f32 v[76:77], v[76:77], v[84:85] op_sel_hi:[1,0]
	v_pk_mul_f32 v[74:75], v[74:75], v[84:85] op_sel_hi:[1,0]
	v_pk_mul_f32 v[72:73], v[72:73], v[84:85] op_sel_hi:[1,0]
	v_pk_mul_f32 v[70:71], v[70:71], v[84:85] op_sel_hi:[1,0]
	v_pk_mul_f32 v[68:69], v[68:69], v[84:85] op_sel_hi:[1,0]
	v_pk_mul_f32 v[86:87], v[66:67], v[84:85] op_sel_hi:[1,0]
	v_pk_mul_f32 v[84:85], v[64:65], v[84:85] op_sel_hi:[1,0]
	v_cvt_pk_bf16_f32 v64, v76, v77
	v_cvt_pk_bf16_f32 v65, v78, v79
	v_cvt_pk_bf16_f32 v66, v72, v73
	v_cvt_pk_bf16_f32 v67, v74, v75
	global_store_dwordx4 v[82:83], v[64:67], off
	s_nop 1
	v_cvt_pk_bf16_f32 v64, v68, v69
	v_cvt_pk_bf16_f32 v65, v70, v71
	v_cvt_pk_bf16_f32 v66, v84, v85
	v_cvt_pk_bf16_f32 v67, v86, v87
	global_store_dwordx4 v[82:83], v[64:67], off offset:256
	v_bfe_u32 v72, v206, 4, 2
	v_lshlrev_b32_e32 v72, 4, v72
	v_mov_b32_e32 v73, 0
	v_lshl_add_u64 v[68:69], v[80:81], 0, v[72:73]
	global_load_dwordx4 v[64:67], v[68:69], off
	s_nop 0
	v_add_u32_e32 v80, 0x90, v146
	v_ashrrev_i32_e32 v81, 31, v80
	v_lshlrev_b64 v[82:83], 12, v[96:97]
	s_waitcnt vmcnt(0)
	v_add_f32_e32 v68, v64, v65
	v_add_f32_e32 v69, v66, v67
	v_add_f32_e32 v68, v68, v69
	ds_swizzle_b32 v69, v68 offset:swizzle(SWAP,16)
	s_waitcnt lgkmcnt(0)
	v_add_f32_e32 v68, v68, v69
	v_mov_b32_e32 v69, v68
	s_nop 1
	v_permlane32_swap_b32_e32 v68, v69
	v_add_f32_e32 v76, v68, v69
	s_nop 0
	v_lshl_add_u64 v[66:67], v[144:145], 0, v[82:83]
	v_mov_b32_e32 v64, v76
	v_fmamk_f32 v64, v64, 0x3a800000, v154
	v_mul_f32_e32 v65, 0x4b800000, v64
	v_cmp_gt_f32_e32 vcc, s47, v64
	s_nop 1
	v_cndmask_b32_e32 v64, v64, v65, vcc
	v_rsq_f32_e32 v68, v64
	v_lshlrev_b64 v[64:65], 6, v[80:81]
	v_lshl_add_u64 v[64:65], s[10:11], 0, v[64:65]
	v_mul_f32_e32 v69, 0x45800000, v68
	v_cndmask_b32_e32 v68, v68, v69, vcc
	v_pk_mul_f32 v[62:63], v[62:63], v[68:69] op_sel_hi:[1,0]
	v_pk_mul_f32 v[60:61], v[60:61], v[68:69] op_sel_hi:[1,0]
	v_pk_mul_f32 v[58:59], v[58:59], v[68:69] op_sel_hi:[1,0]
	v_pk_mul_f32 v[56:57], v[56:57], v[68:69] op_sel_hi:[1,0]
	v_pk_mul_f32 v[54:55], v[54:55], v[68:69] op_sel_hi:[1,0]
	v_pk_mul_f32 v[52:53], v[52:53], v[68:69] op_sel_hi:[1,0]
	v_pk_mul_f32 v[70:71], v[50:51], v[68:69] op_sel_hi:[1,0]
	v_pk_mul_f32 v[68:69], v[48:49], v[68:69] op_sel_hi:[1,0]
	v_cvt_pk_bf16_f32 v48, v60, v61
	v_cvt_pk_bf16_f32 v49, v62, v63
	v_cvt_pk_bf16_f32 v50, v56, v57
	v_cvt_pk_bf16_f32 v51, v58, v59
	global_store_dwordx4 v[66:67], v[48:51], off
	s_nop 1
	v_cvt_pk_bf16_f32 v48, v52, v53
	v_cvt_pk_bf16_f32 v49, v54, v55
	v_cvt_pk_bf16_f32 v50, v68, v69
	v_cvt_pk_bf16_f32 v51, v70, v71
	global_store_dwordx4 v[66:67], v[48:51], off offset:256
	v_bfe_u32 v56, v206, 4, 2
	v_lshlrev_b32_e32 v56, 4, v56
	v_mov_b32_e32 v57, 0
	v_lshl_add_u64 v[52:53], v[64:65], 0, v[56:57]
	global_load_dwordx4 v[48:51], v[52:53], off
	s_nop 0
	v_add_u32_e32 v64, 0xa0, v146
	v_ashrrev_i32_e32 v65, 31, v64
	v_lshlrev_b64 v[66:67], 12, v[80:81]
	s_waitcnt vmcnt(0)
	v_add_f32_e32 v52, v48, v49
	v_add_f32_e32 v53, v50, v51
	v_add_f32_e32 v52, v52, v53
	ds_swizzle_b32 v53, v52 offset:swizzle(SWAP,16)
	s_waitcnt lgkmcnt(0)
	v_add_f32_e32 v52, v52, v53
	v_mov_b32_e32 v53, v52
	s_nop 1
	v_permlane32_swap_b32_e32 v52, v53
	v_add_f32_e32 v60, v52, v53
	s_nop 0
	v_lshl_add_u64 v[50:51], v[144:145], 0, v[66:67]
	v_mov_b32_e32 v48, v60
	v_fmamk_f32 v48, v48, 0x3a800000, v154
	v_mul_f32_e32 v49, 0x4b800000, v48
	v_cmp_gt_f32_e32 vcc, s47, v48
	s_nop 1
	v_cndmask_b32_e32 v48, v48, v49, vcc
	v_rsq_f32_e32 v52, v48
	v_lshlrev_b64 v[48:49], 6, v[64:65]
	v_lshl_add_u64 v[48:49], s[10:11], 0, v[48:49]
	v_mul_f32_e32 v53, 0x45800000, v52
	v_cndmask_b32_e32 v52, v52, v53, vcc
	v_pk_mul_f32 v[46:47], v[46:47], v[52:53] op_sel_hi:[1,0]
	v_pk_mul_f32 v[44:45], v[44:45], v[52:53] op_sel_hi:[1,0]
	v_pk_mul_f32 v[42:43], v[42:43], v[52:53] op_sel_hi:[1,0]
	v_pk_mul_f32 v[40:41], v[40:41], v[52:53] op_sel_hi:[1,0]
	v_pk_mul_f32 v[38:39], v[38:39], v[52:53] op_sel_hi:[1,0]
	v_pk_mul_f32 v[36:37], v[36:37], v[52:53] op_sel_hi:[1,0]
	v_pk_mul_f32 v[54:55], v[34:35], v[52:53] op_sel_hi:[1,0]
	v_pk_mul_f32 v[52:53], v[32:33], v[52:53] op_sel_hi:[1,0]
	v_cvt_pk_bf16_f32 v32, v44, v45
	v_cvt_pk_bf16_f32 v33, v46, v47
	v_cvt_pk_bf16_f32 v34, v40, v41
	v_cvt_pk_bf16_f32 v35, v42, v43
	global_store_dwordx4 v[50:51], v[32:35], off
	s_nop 1
	v_cvt_pk_bf16_f32 v32, v36, v37
	v_cvt_pk_bf16_f32 v33, v38, v39
	v_cvt_pk_bf16_f32 v34, v52, v53
	v_cvt_pk_bf16_f32 v35, v54, v55
	global_store_dwordx4 v[50:51], v[32:35], off offset:256
	v_bfe_u32 v40, v206, 4, 2
	v_lshlrev_b32_e32 v40, 4, v40
	v_mov_b32_e32 v41, 0
	v_lshl_add_u64 v[36:37], v[48:49], 0, v[40:41]
	global_load_dwordx4 v[32:35], v[36:37], off
	s_nop 0
	v_add_u32_e32 v48, 0xb0, v146
	v_ashrrev_i32_e32 v49, 31, v48
	v_lshlrev_b64 v[50:51], 12, v[64:65]
	s_waitcnt vmcnt(0)
	v_add_f32_e32 v36, v32, v33
	v_add_f32_e32 v37, v34, v35
	v_add_f32_e32 v36, v36, v37
	ds_swizzle_b32 v37, v36 offset:swizzle(SWAP,16)
	s_waitcnt lgkmcnt(0)
	v_add_f32_e32 v36, v36, v37
	v_mov_b32_e32 v37, v36
	s_nop 1
	v_permlane32_swap_b32_e32 v36, v37
	v_add_f32_e32 v44, v36, v37
	s_nop 0
	v_lshl_add_u64 v[34:35], v[144:145], 0, v[50:51]
	v_mov_b32_e32 v32, v44
	v_fmamk_f32 v32, v32, 0x3a800000, v154
	v_mul_f32_e32 v33, 0x4b800000, v32
	v_cmp_gt_f32_e32 vcc, s47, v32
	s_nop 1
	v_cndmask_b32_e32 v32, v32, v33, vcc
	v_rsq_f32_e32 v36, v32
	v_lshlrev_b64 v[32:33], 6, v[48:49]
	v_lshl_add_u64 v[32:33], s[10:11], 0, v[32:33]
	v_mul_f32_e32 v37, 0x45800000, v36
	v_cndmask_b32_e32 v36, v36, v37, vcc
	v_pk_mul_f32 v[30:31], v[30:31], v[36:37] op_sel_hi:[1,0]
	v_pk_mul_f32 v[28:29], v[28:29], v[36:37] op_sel_hi:[1,0]
	v_pk_mul_f32 v[26:27], v[26:27], v[36:37] op_sel_hi:[1,0]
	v_pk_mul_f32 v[24:25], v[24:25], v[36:37] op_sel_hi:[1,0]
	v_pk_mul_f32 v[22:23], v[22:23], v[36:37] op_sel_hi:[1,0]
	v_pk_mul_f32 v[20:21], v[20:21], v[36:37] op_sel_hi:[1,0]
	v_pk_mul_f32 v[38:39], v[18:19], v[36:37] op_sel_hi:[1,0]
	v_pk_mul_f32 v[36:37], v[16:17], v[36:37] op_sel_hi:[1,0]
	v_cvt_pk_bf16_f32 v16, v28, v29
	v_cvt_pk_bf16_f32 v17, v30, v31
	v_cvt_pk_bf16_f32 v18, v24, v25
	v_cvt_pk_bf16_f32 v19, v26, v27
	global_store_dwordx4 v[34:35], v[16:19], off
	s_andn2_b64 vcc, exec, s[4:5]
	s_mov_b64 s[4:5], -1
	v_cvt_pk_bf16_f32 v16, v20, v21
	v_cvt_pk_bf16_f32 v17, v22, v23
	v_cvt_pk_bf16_f32 v18, v36, v37
	v_cvt_pk_bf16_f32 v19, v38, v39
	global_store_dwordx4 v[34:35], v[16:19], off offset:256
	v_bfe_u32 v24, v206, 4, 2
	v_lshlrev_b32_e32 v24, 4, v24
	v_mov_b32_e32 v25, 0
	v_lshl_add_u64 v[20:21], v[32:33], 0, v[24:25]
	global_load_dwordx4 v[16:19], v[20:21], off
	s_nop 0
	s_waitcnt vmcnt(0)
	v_add_f32_e32 v20, v16, v17
	v_add_f32_e32 v21, v18, v19
	v_add_f32_e32 v20, v20, v21
	ds_swizzle_b32 v21, v20 offset:swizzle(SWAP,16)
	s_waitcnt lgkmcnt(0)
	v_add_f32_e32 v20, v20, v21
	v_mov_b32_e32 v21, v20
	s_nop 1
	v_permlane32_swap_b32_e32 v20, v21
	v_add_f32_e32 v28, v20, v21
	s_nop 0
	s_nop 0
	v_mov_b32_e32 v16, v28
	v_fmamk_f32 v16, v16, 0x3a800000, v154
	v_mul_f32_e32 v17, 0x4b800000, v16
	v_cmp_gt_f32_e64 s[6:7], s47, v16
	s_nop 1
	v_cndmask_b32_e64 v16, v16, v17, s[6:7]
	v_rsq_f32_e32 v18, v16
	v_lshlrev_b64 v[16:17], 12, v[48:49]
	v_lshl_add_u64 v[16:17], v[144:145], 0, v[16:17]
	v_mul_f32_e32 v19, 0x45800000, v18
	v_cndmask_b32_e64 v18, v18, v19, s[6:7]
	v_pk_mul_f32 v[14:15], v[14:15], v[18:19] op_sel_hi:[1,0]
	v_pk_mul_f32 v[12:13], v[12:13], v[18:19] op_sel_hi:[1,0]
	v_pk_mul_f32 v[10:11], v[10:11], v[18:19] op_sel_hi:[1,0]
	v_pk_mul_f32 v[8:9], v[8:9], v[18:19] op_sel_hi:[1,0]
	v_pk_mul_f32 v[6:7], v[6:7], v[18:19] op_sel_hi:[1,0]
	v_pk_mul_f32 v[4:5], v[4:5], v[18:19] op_sel_hi:[1,0]
	v_pk_mul_f32 v[20:21], v[2:3], v[18:19] op_sel_hi:[1,0]
	v_pk_mul_f32 v[18:19], v[0:1], v[18:19] op_sel_hi:[1,0]
	v_cvt_pk_bf16_f32 v0, v12, v13
	v_cvt_pk_bf16_f32 v1, v14, v15
	v_cvt_pk_bf16_f32 v2, v8, v9
	v_cvt_pk_bf16_f32 v3, v10, v11
	global_store_dwordx4 v[16:17], v[0:3], off
	s_nop 1
	v_cvt_pk_bf16_f32 v0, v4, v5
	v_cvt_pk_bf16_f32 v1, v6, v7
	v_cvt_pk_bf16_f32 v2, v18, v19
	v_cvt_pk_bf16_f32 v3, v20, v21
	global_store_dwordx4 v[16:17], v[0:3], off offset:256
	s_cbranch_vccnz .LBB0_980
	s_andn2_b64 vcc, exec, s[2:3]
	s_cbranch_vccnz .LBB0_979
	s_barrier
	s_branch .LBB0_979

.LBB0_1368:
	v_lshl_add_u32 v146, s6, 8, v148
	v_ashrrev_i32_e32 v147, 31, v146
	v_lshlrev_b64 v[144:145], 6, v[146:147]
	v_lshl_add_u64 v[144:145], s[10:11], 0, v[144:145]
	v_bfe_u32 v164, v206, 4, 2
	v_lshlrev_b32_e32 v164, 4, v164
	v_mov_b32_e32 v165, 0
	v_lshl_add_u64 v[160:161], v[144:145], 0, v[164:165]
	global_load_dwordx4 v[156:159], v[160:161], off
	v_lshlrev_b64 v[174:175], 13, v[146:147]
	v_lshl_or_b32 v144, s7, 8, v150
	v_ashrrev_i32_e32 v145, 31, v144
	v_or_b32_e32 v172, 16, v146
	v_lshl_add_u64 v[144:145], v[144:145], 1, s[8:9]
	v_ashrrev_i32_e32 v173, 31, v172
	s_waitcnt vmcnt(0)
	v_add_f32_e32 v160, v156, v157
	v_add_f32_e32 v161, v158, v159
	v_add_f32_e32 v160, v160, v161
	ds_swizzle_b32 v161, v160 offset:swizzle(SWAP,16)
	s_waitcnt lgkmcnt(0)
	v_add_f32_e32 v160, v160, v161
	v_mov_b32_e32 v161, v160
	s_nop 1
	v_permlane32_swap_b32_e32 v160, v161
	v_add_f32_e32 v168, v160, v161
	s_nop 0
	v_lshlrev_b64 v[158:159], 6, v[172:173]
	v_mov_b32_e32 v147, v168
	v_fmamk_f32 v147, v147, 0x3a800000, v154
	v_mul_f32_e32 v155, 0x4b800000, v147
	v_cmp_gt_f32_e32 vcc, s48, v147
	v_lshl_add_u64 v[156:157], v[144:145], 0, v[174:175]
	v_lshl_add_u64 v[158:159], s[10:11], 0, v[158:159]
	v_cndmask_b32_e32 v147, v147, v155, vcc
	v_rsq_f32_e32 v147, v147
	s_nop 0
	v_mul_f32_e32 v155, 0x45800000, v147
	v_cndmask_b32_e32 v160, v147, v155, vcc
	v_pk_mul_f32 v[126:127], v[126:127], v[160:161] op_sel_hi:[1,0]
	v_pk_mul_f32 v[124:125], v[124:125], v[160:161] op_sel_hi:[1,0]
	v_pk_mul_f32 v[122:123], v[122:123], v[160:161] op_sel_hi:[1,0]
	v_pk_mul_f32 v[120:121], v[120:121], v[160:161] op_sel_hi:[1,0]
	v_pk_mul_f32 v[114:115], v[114:115], v[160:161] op_sel_hi:[1,0]
	v_pk_mul_f32 v[112:113], v[112:113], v[160:161] op_sel_hi:[1,0]
	v_pk_mul_f32 v[118:119], v[118:119], v[160:161] op_sel_hi:[1,0]
	v_pk_mul_f32 v[116:117], v[116:117], v[160:161] op_sel_hi:[1,0]
	v_max_f32_e32 v124, 0, v124
	v_max_f32_e32 v120, 0, v120
	v_max_f32_e32 v125, 0, v125
	v_max_f32_e32 v121, 0, v121
	v_max_f32_e32 v126, 0, v126
	v_max_f32_e32 v122, 0, v122
	v_max_f32_e32 v127, 0, v127
	v_max_f32_e32 v123, 0, v123
	v_max_f32_e32 v112, 0, v112
	v_max_f32_e32 v113, 0, v113
	v_max_f32_e32 v114, 0, v114
	v_max_f32_e32 v115, 0, v115
	v_max_f32_e32 v116, 0, v116
	v_max_f32_e32 v117, 0, v117
	v_max_f32_e32 v118, 0, v118
	v_max_f32_e32 v119, 0, v119
	v_mul_f32_e32 v124, v124, v124
	v_mul_f32_e32 v120, v120, v120
	v_mul_f32_e32 v125, v125, v125
	v_mul_f32_e32 v121, v121, v121
	v_mul_f32_e32 v126, v126, v126
	v_mul_f32_e32 v122, v122, v122
	v_mul_f32_e32 v127, v127, v127
	v_mul_f32_e32 v123, v123, v123
	v_mul_f32_e32 v147, v112, v112
	v_mul_f32_e32 v155, v113, v113
	v_mul_f32_e32 v160, v114, v114
	v_mul_f32_e32 v161, v115, v115
	v_cvt_pk_bf16_f32 v112, v124, v125
	v_cvt_pk_bf16_f32 v113, v126, v127
	v_cvt_pk_bf16_f32 v114, v120, v121
	v_cvt_pk_bf16_f32 v115, v122, v123
	v_mul_f32_e32 v116, v116, v116
	v_mul_f32_e32 v117, v117, v117
	v_mul_f32_e32 v118, v118, v118
	v_mul_f32_e32 v119, v119, v119
	global_store_dwordx4 v[156:157], v[112:115], off
	s_nop 1
	v_cvt_pk_bf16_f32 v112, v116, v117
	v_cvt_pk_bf16_f32 v113, v118, v119
	v_cvt_pk_bf16_f32 v114, v147, v155
	v_cvt_pk_bf16_f32 v115, v160, v161
	global_store_dwordx4 v[156:157], v[112:115], off offset:256
	v_bfe_u32 v120, v206, 4, 2
	v_lshlrev_b32_e32 v120, 4, v120
	v_mov_b32_e32 v121, 0
	v_lshl_add_u64 v[116:117], v[158:159], 0, v[120:121]
	global_load_dwordx4 v[112:115], v[116:117], off
	s_nop 0
	v_or_b32_e32 v156, 32, v146
	v_ashrrev_i32_e32 v157, 31, v156
	v_lshlrev_b64 v[158:159], 13, v[172:173]
	s_waitcnt vmcnt(0)
	v_add_f32_e32 v116, v112, v113
	v_add_f32_e32 v117, v114, v115
	v_add_f32_e32 v116, v116, v117
	ds_swizzle_b32 v117, v116 offset:swizzle(SWAP,16)
	s_waitcnt lgkmcnt(0)
	v_add_f32_e32 v116, v116, v117
	v_mov_b32_e32 v117, v116
	s_nop 1
	v_permlane32_swap_b32_e32 v116, v117
	v_add_f32_e32 v124, v116, v117
	s_nop 0
	v_lshl_add_u64 v[114:115], v[144:145], 0, v[158:159]
	v_mov_b32_e32 v112, v124
	v_fmamk_f32 v112, v112, 0x3a800000, v154
	v_mul_f32_e32 v113, 0x4b800000, v112
	v_cmp_gt_f32_e32 vcc, s48, v112
	s_nop 1
	v_cndmask_b32_e32 v112, v112, v113, vcc
	v_rsq_f32_e32 v116, v112
	v_lshlrev_b64 v[112:113], 6, v[156:157]
	v_lshl_add_u64 v[112:113], s[10:11], 0, v[112:113]
	v_mul_f32_e32 v117, 0x45800000, v116
	v_cndmask_b32_e32 v116, v116, v117, vcc
	v_pk_mul_f32 v[110:111], v[110:111], v[116:117] op_sel_hi:[1,0]
	v_pk_mul_f32 v[108:109], v[108:109], v[116:117] op_sel_hi:[1,0]
	v_pk_mul_f32 v[106:107], v[106:107], v[116:117] op_sel_hi:[1,0]
	v_pk_mul_f32 v[104:105], v[104:105], v[116:117] op_sel_hi:[1,0]
	v_pk_mul_f32 v[98:99], v[98:99], v[116:117] op_sel_hi:[1,0]
	v_pk_mul_f32 v[96:97], v[96:97], v[116:117] op_sel_hi:[1,0]
	v_pk_mul_f32 v[102:103], v[102:103], v[116:117] op_sel_hi:[1,0]
	v_pk_mul_f32 v[100:101], v[100:101], v[116:117] op_sel_hi:[1,0]
	v_max_f32_e32 v108, 0, v108
	v_max_f32_e32 v104, 0, v104
	v_max_f32_e32 v109, 0, v109
	v_max_f32_e32 v105, 0, v105
	v_max_f32_e32 v110, 0, v110
	v_max_f32_e32 v106, 0, v106
	v_max_f32_e32 v111, 0, v111
	v_max_f32_e32 v107, 0, v107
	v_max_f32_e32 v96, 0, v96
	v_max_f32_e32 v97, 0, v97
	v_max_f32_e32 v98, 0, v98
	v_max_f32_e32 v99, 0, v99
	v_max_f32_e32 v100, 0, v100
	v_max_f32_e32 v101, 0, v101
	v_max_f32_e32 v102, 0, v102
	v_max_f32_e32 v103, 0, v103
	v_mul_f32_e32 v108, v108, v108
	v_mul_f32_e32 v104, v104, v104
	v_mul_f32_e32 v109, v109, v109
	v_mul_f32_e32 v105, v105, v105
	v_mul_f32_e32 v110, v110, v110
	v_mul_f32_e32 v106, v106, v106
	v_mul_f32_e32 v111, v111, v111
	v_mul_f32_e32 v107, v107, v107
	v_mul_f32_e32 v116, v96, v96
	v_mul_f32_e32 v117, v97, v97
	v_mul_f32_e32 v118, v98, v98
	v_mul_f32_e32 v119, v99, v99
	v_cvt_pk_bf16_f32 v96, v108, v109
	v_cvt_pk_bf16_f32 v97, v110, v111
	v_cvt_pk_bf16_f32 v98, v104, v105
	v_cvt_pk_bf16_f32 v99, v106, v107
	v_mul_f32_e32 v100, v100, v100
	v_mul_f32_e32 v101, v101, v101
	v_mul_f32_e32 v102, v102, v102
	v_mul_f32_e32 v103, v103, v103
	global_store_dwordx4 v[114:115], v[96:99], off
	s_nop 1
	v_cvt_pk_bf16_f32 v96, v100, v101
	v_cvt_pk_bf16_f32 v97, v102, v103
	v_cvt_pk_bf16_f32 v98, v116, v117
	v_cvt_pk_bf16_f32 v99, v118, v119
	global_store_dwordx4 v[114:115], v[96:99], off offset:256
	v_bfe_u32 v104, v206, 4, 2
	v_lshlrev_b32_e32 v104, 4, v104
	v_mov_b32_e32 v105, 0
	v_lshl_add_u64 v[100:101], v[112:113], 0, v[104:105]
	global_load_dwordx4 v[96:99], v[100:101], off
	s_nop 0
	v_or_b32_e32 v112, 48, v146
	v_ashrrev_i32_e32 v113, 31, v112
	v_lshlrev_b64 v[114:115], 13, v[156:157]
	s_waitcnt vmcnt(0)
	v_add_f32_e32 v100, v96, v97
	v_add_f32_e32 v101, v98, v99
	v_add_f32_e32 v100, v100, v101
	ds_swizzle_b32 v101, v100 offset:swizzle(SWAP,16)
	s_waitcnt lgkmcnt(0)
	v_add_f32_e32 v100, v100, v101
	v_mov_b32_e32 v101, v100
	s_nop 1
	v_permlane32_swap_b32_e32 v100, v101
	v_add_f32_e32 v108, v100, v101
	s_nop 0
	v_lshl_add_u64 v[98:99], v[144:145], 0, v[114:115]
	v_mov_b32_e32 v96, v108
	v_fmamk_f32 v96, v96, 0x3a800000, v154
	v_mul_f32_e32 v97, 0x4b800000, v96
	v_cmp_gt_f32_e32 vcc, s48, v96
	s_nop 1
	v_cndmask_b32_e32 v96, v96, v97, vcc
	v_rsq_f32_e32 v100, v96
	v_lshlrev_b64 v[96:97], 6, v[112:113]
	v_lshl_add_u64 v[96:97], s[10:11], 0, v[96:97]
	v_mul_f32_e32 v101, 0x45800000, v100
	v_cndmask_b32_e32 v100, v100, v101, vcc
	v_pk_mul_f32 v[94:95], v[94:95], v[100:101] op_sel_hi:[1,0]
	v_pk_mul_f32 v[92:93], v[92:93], v[100:101] op_sel_hi:[1,0]
	v_pk_mul_f32 v[90:91], v[90:91], v[100:101] op_sel_hi:[1,0]
	v_pk_mul_f32 v[88:89], v[88:89], v[100:101] op_sel_hi:[1,0]
	v_pk_mul_f32 v[82:83], v[82:83], v[100:101] op_sel_hi:[1,0]
	v_pk_mul_f32 v[80:81], v[80:81], v[100:101] op_sel_hi:[1,0]
	v_pk_mul_f32 v[86:87], v[86:87], v[100:101] op_sel_hi:[1,0]
	v_pk_mul_f32 v[84:85], v[84:85], v[100:101] op_sel_hi:[1,0]
	v_max_f32_e32 v92, 0, v92
	v_max_f32_e32 v88, 0, v88
	v_max_f32_e32 v93, 0, v93
	v_max_f32_e32 v89, 0, v89
	v_max_f32_e32 v94, 0, v94
	v_max_f32_e32 v90, 0, v90
	v_max_f32_e32 v95, 0, v95
	v_max_f32_e32 v91, 0, v91
	v_max_f32_e32 v80, 0, v80
	v_max_f32_e32 v81, 0, v81
	v_max_f32_e32 v82, 0, v82
	v_max_f32_e32 v83, 0, v83
	v_max_f32_e32 v84, 0, v84
	v_max_f32_e32 v85, 0, v85
	v_max_f32_e32 v86, 0, v86
	v_max_f32_e32 v87, 0, v87
	v_mul_f32_e32 v92, v92, v92
	v_mul_f32_e32 v88, v88, v88
	v_mul_f32_e32 v93, v93, v93
	v_mul_f32_e32 v89, v89, v89
	v_mul_f32_e32 v94, v94, v94
	v_mul_f32_e32 v90, v90, v90
	v_mul_f32_e32 v95, v95, v95
	v_mul_f32_e32 v91, v91, v91
	v_mul_f32_e32 v100, v80, v80
	v_mul_f32_e32 v101, v81, v81
	v_mul_f32_e32 v102, v82, v82
	v_mul_f32_e32 v103, v83, v83
	v_cvt_pk_bf16_f32 v80, v92, v93
	v_cvt_pk_bf16_f32 v81, v94, v95
	v_cvt_pk_bf16_f32 v82, v88, v89
	v_cvt_pk_bf16_f32 v83, v90, v91
	v_mul_f32_e32 v84, v84, v84
	v_mul_f32_e32 v85, v85, v85
	v_mul_f32_e32 v86, v86, v86
	v_mul_f32_e32 v87, v87, v87
	global_store_dwordx4 v[98:99], v[80:83], off
	s_nop 1
	v_cvt_pk_bf16_f32 v80, v84, v85
	v_cvt_pk_bf16_f32 v81, v86, v87
	v_cvt_pk_bf16_f32 v82, v100, v101
	v_cvt_pk_bf16_f32 v83, v102, v103
	global_store_dwordx4 v[98:99], v[80:83], off offset:256
	v_bfe_u32 v88, v206, 4, 2
	v_lshlrev_b32_e32 v88, 4, v88
	v_mov_b32_e32 v89, 0
	v_lshl_add_u64 v[84:85], v[96:97], 0, v[88:89]
	global_load_dwordx4 v[80:83], v[84:85], off
	s_nop 0
	v_add_u32_e32 v96, 0x80, v146
	v_ashrrev_i32_e32 v97, 31, v96
	v_lshlrev_b64 v[98:99], 13, v[112:113]
	s_waitcnt vmcnt(0)
	v_add_f32_e32 v84, v80, v81
	v_add_f32_e32 v85, v82, v83
	v_add_f32_e32 v84, v84, v85
	ds_swizzle_b32 v85, v84 offset:swizzle(SWAP,16)
	s_waitcnt lgkmcnt(0)
	v_add_f32_e32 v84, v84, v85
	v_mov_b32_e32 v85, v84
	s_nop 1
	v_permlane32_swap_b32_e32 v84, v85
	v_add_f32_e32 v92, v84, v85
	s_nop 0
	v_lshl_add_u64 v[82:83], v[144:145], 0, v[98:99]
	v_mov_b32_e32 v80, v92
	v_fmamk_f32 v80, v80, 0x3a800000, v154
	v_mul_f32_e32 v81, 0x4b800000, v80
	v_cmp_gt_f32_e32 vcc, s48, v80
	s_nop 1
	v_cndmask_b32_e32 v80, v80, v81, vcc
	v_rsq_f32_e32 v84, v80
	v_lshlrev_b64 v[80:81], 6, v[96:97]
	v_lshl_add_u64 v[80:81], s[10:11], 0, v[80:81]
	v_mul_f32_e32 v85, 0x45800000, v84
	v_cndmask_b32_e32 v84, v84, v85, vcc
	v_pk_mul_f32 v[78:79], v[78:79], v[84:85] op_sel_hi:[1,0]
	v_pk_mul_f32 v[76:77], v[76:77], v[84:85] op_sel_hi:[1,0]
	v_pk_mul_f32 v[74:75], v[74:75], v[84:85] op_sel_hi:[1,0]
	v_pk_mul_f32 v[72:73], v[72:73], v[84:85] op_sel_hi:[1,0]
	v_pk_mul_f32 v[66:67], v[66:67], v[84:85] op_sel_hi:[1,0]
	v_pk_mul_f32 v[64:65], v[64:65], v[84:85] op_sel_hi:[1,0]
	v_pk_mul_f32 v[70:71], v[70:71], v[84:85] op_sel_hi:[1,0]
	v_pk_mul_f32 v[68:69], v[68:69], v[84:85] op_sel_hi:[1,0]
	v_max_f32_e32 v76, 0, v76
	v_max_f32_e32 v72, 0, v72
	v_max_f32_e32 v77, 0, v77
	v_max_f32_e32 v73, 0, v73
	v_max_f32_e32 v78, 0, v78
	v_max_f32_e32 v74, 0, v74
	v_max_f32_e32 v79, 0, v79
	v_max_f32_e32 v75, 0, v75
	v_max_f32_e32 v64, 0, v64
	v_max_f32_e32 v65, 0, v65
	v_max_f32_e32 v66, 0, v66
	v_max_f32_e32 v67, 0, v67
	v_max_f32_e32 v68, 0, v68
	v_max_f32_e32 v69, 0, v69
	v_max_f32_e32 v70, 0, v70
	v_max_f32_e32 v71, 0, v71
	v_mul_f32_e32 v76, v76, v76
	v_mul_f32_e32 v72, v72, v72
	v_mul_f32_e32 v77, v77, v77
	v_mul_f32_e32 v73, v73, v73
	v_mul_f32_e32 v78, v78, v78
	v_mul_f32_e32 v74, v74, v74
	v_mul_f32_e32 v79, v79, v79
	v_mul_f32_e32 v75, v75, v75
	v_mul_f32_e32 v84, v64, v64
	v_mul_f32_e32 v85, v65, v65
	v_mul_f32_e32 v86, v66, v66
	v_mul_f32_e32 v87, v67, v67
	v_cvt_pk_bf16_f32 v64, v76, v77
	v_cvt_pk_bf16_f32 v65, v78, v79
	v_cvt_pk_bf16_f32 v66, v72, v73
	v_cvt_pk_bf16_f32 v67, v74, v75
	v_mul_f32_e32 v68, v68, v68
	v_mul_f32_e32 v69, v69, v69
	v_mul_f32_e32 v70, v70, v70
	v_mul_f32_e32 v71, v71, v71
	global_store_dwordx4 v[82:83], v[64:67], off
	s_nop 1
	v_cvt_pk_bf16_f32 v64, v68, v69
	v_cvt_pk_bf16_f32 v65, v70, v71
	v_cvt_pk_bf16_f32 v66, v84, v85
	v_cvt_pk_bf16_f32 v67, v86, v87
	global_store_dwordx4 v[82:83], v[64:67], off offset:256
	v_bfe_u32 v72, v206, 4, 2
	v_lshlrev_b32_e32 v72, 4, v72
	v_mov_b32_e32 v73, 0
	v_lshl_add_u64 v[68:69], v[80:81], 0, v[72:73]
	global_load_dwordx4 v[64:67], v[68:69], off
	s_nop 0
	v_add_u32_e32 v80, 0x90, v146
	v_ashrrev_i32_e32 v81, 31, v80
	v_lshlrev_b64 v[82:83], 13, v[96:97]
	s_waitcnt vmcnt(0)
	v_add_f32_e32 v68, v64, v65
	v_add_f32_e32 v69, v66, v67
	v_add_f32_e32 v68, v68, v69
	ds_swizzle_b32 v69, v68 offset:swizzle(SWAP,16)
	s_waitcnt lgkmcnt(0)
	v_add_f32_e32 v68, v68, v69
	v_mov_b32_e32 v69, v68
	s_nop 1
	v_permlane32_swap_b32_e32 v68, v69
	v_add_f32_e32 v76, v68, v69
	s_nop 0
	v_lshl_add_u64 v[66:67], v[144:145], 0, v[82:83]
	v_mov_b32_e32 v64, v76
	v_fmamk_f32 v64, v64, 0x3a800000, v154
	v_mul_f32_e32 v65, 0x4b800000, v64
	v_cmp_gt_f32_e32 vcc, s48, v64
	s_nop 1
	v_cndmask_b32_e32 v64, v64, v65, vcc
	v_rsq_f32_e32 v68, v64
	v_lshlrev_b64 v[64:65], 6, v[80:81]
	v_lshl_add_u64 v[64:65], s[10:11], 0, v[64:65]
	v_mul_f32_e32 v69, 0x45800000, v68
	v_cndmask_b32_e32 v68, v68, v69, vcc
	v_pk_mul_f32 v[62:63], v[62:63], v[68:69] op_sel_hi:[1,0]
	v_pk_mul_f32 v[60:61], v[60:61], v[68:69] op_sel_hi:[1,0]
	v_pk_mul_f32 v[58:59], v[58:59], v[68:69] op_sel_hi:[1,0]
	v_pk_mul_f32 v[56:57], v[56:57], v[68:69] op_sel_hi:[1,0]
	v_pk_mul_f32 v[50:51], v[50:51], v[68:69] op_sel_hi:[1,0]
	v_pk_mul_f32 v[48:49], v[48:49], v[68:69] op_sel_hi:[1,0]
	v_pk_mul_f32 v[54:55], v[54:55], v[68:69] op_sel_hi:[1,0]
	v_pk_mul_f32 v[52:53], v[52:53], v[68:69] op_sel_hi:[1,0]
	v_max_f32_e32 v60, 0, v60
	v_max_f32_e32 v56, 0, v56
	v_max_f32_e32 v61, 0, v61
	v_max_f32_e32 v57, 0, v57
	v_max_f32_e32 v62, 0, v62
	v_max_f32_e32 v58, 0, v58
	v_max_f32_e32 v63, 0, v63
	v_max_f32_e32 v59, 0, v59
	v_max_f32_e32 v48, 0, v48
	v_max_f32_e32 v49, 0, v49
	v_max_f32_e32 v50, 0, v50
	v_max_f32_e32 v51, 0, v51
	v_max_f32_e32 v52, 0, v52
	v_max_f32_e32 v53, 0, v53
	v_max_f32_e32 v54, 0, v54
	v_max_f32_e32 v55, 0, v55
	v_mul_f32_e32 v60, v60, v60
	v_mul_f32_e32 v56, v56, v56
	v_mul_f32_e32 v61, v61, v61
	v_mul_f32_e32 v57, v57, v57
	v_mul_f32_e32 v62, v62, v62
	v_mul_f32_e32 v58, v58, v58
	v_mul_f32_e32 v63, v63, v63
	v_mul_f32_e32 v59, v59, v59
	v_mul_f32_e32 v68, v48, v48
	v_mul_f32_e32 v69, v49, v49
	v_mul_f32_e32 v70, v50, v50
	v_mul_f32_e32 v71, v51, v51
	v_cvt_pk_bf16_f32 v48, v60, v61
	v_cvt_pk_bf16_f32 v49, v62, v63
	v_cvt_pk_bf16_f32 v50, v56, v57
	v_cvt_pk_bf16_f32 v51, v58, v59
	v_mul_f32_e32 v52, v52, v52
	v_mul_f32_e32 v53, v53, v53
	v_mul_f32_e32 v54, v54, v54
	v_mul_f32_e32 v55, v55, v55
	global_store_dwordx4 v[66:67], v[48:51], off
	s_nop 1
	v_cvt_pk_bf16_f32 v48, v52, v53
	v_cvt_pk_bf16_f32 v49, v54, v55
	v_cvt_pk_bf16_f32 v50, v68, v69
	v_cvt_pk_bf16_f32 v51, v70, v71
	global_store_dwordx4 v[66:67], v[48:51], off offset:256
	v_bfe_u32 v56, v206, 4, 2
	v_lshlrev_b32_e32 v56, 4, v56
	v_mov_b32_e32 v57, 0
	v_lshl_add_u64 v[52:53], v[64:65], 0, v[56:57]
	global_load_dwordx4 v[48:51], v[52:53], off
	s_nop 0
	v_add_u32_e32 v64, 0xa0, v146
	v_ashrrev_i32_e32 v65, 31, v64
	v_lshlrev_b64 v[66:67], 13, v[80:81]
	s_waitcnt vmcnt(0)
	v_add_f32_e32 v52, v48, v49
	v_add_f32_e32 v53, v50, v51
	v_add_f32_e32 v52, v52, v53
	ds_swizzle_b32 v53, v52 offset:swizzle(SWAP,16)
	s_waitcnt lgkmcnt(0)
	v_add_f32_e32 v52, v52, v53
	v_mov_b32_e32 v53, v52
	s_nop 1
	v_permlane32_swap_b32_e32 v52, v53
	v_add_f32_e32 v60, v52, v53
	s_nop 0
	v_lshl_add_u64 v[50:51], v[144:145], 0, v[66:67]
	v_mov_b32_e32 v48, v60
	v_fmamk_f32 v48, v48, 0x3a800000, v154
	v_mul_f32_e32 v49, 0x4b800000, v48
	v_cmp_gt_f32_e32 vcc, s48, v48
	s_nop 1
	v_cndmask_b32_e32 v48, v48, v49, vcc
	v_rsq_f32_e32 v52, v48
	v_lshlrev_b64 v[48:49], 6, v[64:65]
	v_lshl_add_u64 v[48:49], s[10:11], 0, v[48:49]
	v_mul_f32_e32 v53, 0x45800000, v52
	v_cndmask_b32_e32 v52, v52, v53, vcc
	v_pk_mul_f32 v[46:47], v[46:47], v[52:53] op_sel_hi:[1,0]
	v_pk_mul_f32 v[44:45], v[44:45], v[52:53] op_sel_hi:[1,0]
	v_pk_mul_f32 v[42:43], v[42:43], v[52:53] op_sel_hi:[1,0]
	v_pk_mul_f32 v[40:41], v[40:41], v[52:53] op_sel_hi:[1,0]
	v_pk_mul_f32 v[34:35], v[34:35], v[52:53] op_sel_hi:[1,0]
	v_pk_mul_f32 v[32:33], v[32:33], v[52:53] op_sel_hi:[1,0]
	v_pk_mul_f32 v[38:39], v[38:39], v[52:53] op_sel_hi:[1,0]
	v_pk_mul_f32 v[36:37], v[36:37], v[52:53] op_sel_hi:[1,0]
	v_max_f32_e32 v44, 0, v44
	v_max_f32_e32 v40, 0, v40
	v_max_f32_e32 v45, 0, v45
	v_max_f32_e32 v41, 0, v41
	v_max_f32_e32 v46, 0, v46
	v_max_f32_e32 v42, 0, v42
	v_max_f32_e32 v47, 0, v47
	v_max_f32_e32 v43, 0, v43
	v_max_f32_e32 v32, 0, v32
	v_max_f32_e32 v33, 0, v33
	v_max_f32_e32 v34, 0, v34
	v_max_f32_e32 v35, 0, v35
	v_max_f32_e32 v36, 0, v36
	v_max_f32_e32 v37, 0, v37
	v_max_f32_e32 v38, 0, v38
	v_max_f32_e32 v39, 0, v39
	v_mul_f32_e32 v44, v44, v44
	v_mul_f32_e32 v40, v40, v40
	v_mul_f32_e32 v45, v45, v45
	v_mul_f32_e32 v41, v41, v41
	v_mul_f32_e32 v46, v46, v46
	v_mul_f32_e32 v42, v42, v42
	v_mul_f32_e32 v47, v47, v47
	v_mul_f32_e32 v43, v43, v43
	v_mul_f32_e32 v52, v32, v32
	v_mul_f32_e32 v53, v33, v33
	v_mul_f32_e32 v54, v34, v34
	v_mul_f32_e32 v55, v35, v35
	v_cvt_pk_bf16_f32 v32, v44, v45
	v_cvt_pk_bf16_f32 v33, v46, v47
	v_cvt_pk_bf16_f32 v34, v40, v41
	v_cvt_pk_bf16_f32 v35, v42, v43
	v_mul_f32_e32 v36, v36, v36
	v_mul_f32_e32 v37, v37, v37
	v_mul_f32_e32 v38, v38, v38
	v_mul_f32_e32 v39, v39, v39
	global_store_dwordx4 v[50:51], v[32:35], off
	s_nop 1
	v_cvt_pk_bf16_f32 v32, v36, v37
	v_cvt_pk_bf16_f32 v33, v38, v39
	v_cvt_pk_bf16_f32 v34, v52, v53
	v_cvt_pk_bf16_f32 v35, v54, v55
	global_store_dwordx4 v[50:51], v[32:35], off offset:256
	v_bfe_u32 v40, v206, 4, 2
	v_lshlrev_b32_e32 v40, 4, v40
	v_mov_b32_e32 v41, 0
	v_lshl_add_u64 v[36:37], v[48:49], 0, v[40:41]
	global_load_dwordx4 v[32:35], v[36:37], off
	s_nop 0
	v_add_u32_e32 v48, 0xb0, v146
	v_ashrrev_i32_e32 v49, 31, v48
	v_lshlrev_b64 v[50:51], 13, v[64:65]
	s_waitcnt vmcnt(0)
	v_add_f32_e32 v36, v32, v33
	v_add_f32_e32 v37, v34, v35
	v_add_f32_e32 v36, v36, v37
	ds_swizzle_b32 v37, v36 offset:swizzle(SWAP,16)
	s_waitcnt lgkmcnt(0)
	v_add_f32_e32 v36, v36, v37
	v_mov_b32_e32 v37, v36
	s_nop 1
	v_permlane32_swap_b32_e32 v36, v37
	v_add_f32_e32 v44, v36, v37
	s_nop 0
	v_lshl_add_u64 v[34:35], v[144:145], 0, v[50:51]
	v_mov_b32_e32 v32, v44
	v_fmamk_f32 v32, v32, 0x3a800000, v154
	v_mul_f32_e32 v33, 0x4b800000, v32
	v_cmp_gt_f32_e32 vcc, s48, v32
	s_nop 1
	v_cndmask_b32_e32 v32, v32, v33, vcc
	v_rsq_f32_e32 v36, v32
	v_lshlrev_b64 v[32:33], 6, v[48:49]
	v_lshl_add_u64 v[32:33], s[10:11], 0, v[32:33]
	v_mul_f32_e32 v37, 0x45800000, v36
	v_cndmask_b32_e32 v36, v36, v37, vcc
	v_pk_mul_f32 v[30:31], v[30:31], v[36:37] op_sel_hi:[1,0]
	v_pk_mul_f32 v[28:29], v[28:29], v[36:37] op_sel_hi:[1,0]
	v_pk_mul_f32 v[26:27], v[26:27], v[36:37] op_sel_hi:[1,0]
	v_pk_mul_f32 v[24:25], v[24:25], v[36:37] op_sel_hi:[1,0]
	v_pk_mul_f32 v[18:19], v[18:19], v[36:37] op_sel_hi:[1,0]
	v_pk_mul_f32 v[16:17], v[16:17], v[36:37] op_sel_hi:[1,0]
	v_pk_mul_f32 v[22:23], v[22:23], v[36:37] op_sel_hi:[1,0]
	v_pk_mul_f32 v[20:21], v[20:21], v[36:37] op_sel_hi:[1,0]
	v_max_f32_e32 v28, 0, v28
	v_max_f32_e32 v24, 0, v24
	v_max_f32_e32 v29, 0, v29
	v_max_f32_e32 v25, 0, v25
	v_max_f32_e32 v30, 0, v30
	v_max_f32_e32 v26, 0, v26
	v_max_f32_e32 v31, 0, v31
	v_max_f32_e32 v27, 0, v27
	v_max_f32_e32 v16, 0, v16
	v_max_f32_e32 v17, 0, v17
	v_max_f32_e32 v18, 0, v18
	v_max_f32_e32 v19, 0, v19
	v_max_f32_e32 v20, 0, v20
	v_max_f32_e32 v21, 0, v21
	v_max_f32_e32 v22, 0, v22
	v_max_f32_e32 v23, 0, v23
	v_mul_f32_e32 v28, v28, v28
	v_mul_f32_e32 v24, v24, v24
	v_mul_f32_e32 v29, v29, v29
	v_mul_f32_e32 v25, v25, v25
	v_mul_f32_e32 v30, v30, v30
	v_mul_f32_e32 v26, v26, v26
	v_mul_f32_e32 v31, v31, v31
	v_mul_f32_e32 v27, v27, v27
	v_mul_f32_e32 v36, v16, v16
	v_mul_f32_e32 v37, v17, v17
	v_mul_f32_e32 v38, v18, v18
	v_mul_f32_e32 v39, v19, v19
	v_cvt_pk_bf16_f32 v16, v28, v29
	v_cvt_pk_bf16_f32 v17, v30, v31
	v_cvt_pk_bf16_f32 v18, v24, v25
	v_cvt_pk_bf16_f32 v19, v26, v27
	v_mul_f32_e32 v20, v20, v20
	v_mul_f32_e32 v21, v21, v21
	v_mul_f32_e32 v22, v22, v22
	v_mul_f32_e32 v23, v23, v23
	global_store_dwordx4 v[34:35], v[16:19], off
	s_andn2_b64 vcc, exec, s[4:5]
	s_mov_b64 s[4:5], -1
	v_cvt_pk_bf16_f32 v16, v20, v21
	v_cvt_pk_bf16_f32 v17, v22, v23
	v_cvt_pk_bf16_f32 v18, v36, v37
	v_cvt_pk_bf16_f32 v19, v38, v39
	global_store_dwordx4 v[34:35], v[16:19], off offset:256
	v_bfe_u32 v24, v206, 4, 2
	v_lshlrev_b32_e32 v24, 4, v24
	v_mov_b32_e32 v25, 0
	v_lshl_add_u64 v[20:21], v[32:33], 0, v[24:25]
	global_load_dwordx4 v[16:19], v[20:21], off
	s_nop 0
	s_waitcnt vmcnt(0)
	v_add_f32_e32 v20, v16, v17
	v_add_f32_e32 v21, v18, v19
	v_add_f32_e32 v20, v20, v21
	ds_swizzle_b32 v21, v20 offset:swizzle(SWAP,16)
	s_waitcnt lgkmcnt(0)
	v_add_f32_e32 v20, v20, v21
	v_mov_b32_e32 v21, v20
	s_nop 1
	v_permlane32_swap_b32_e32 v20, v21
	v_add_f32_e32 v28, v20, v21
	s_nop 0
	s_nop 0
	v_mov_b32_e32 v16, v28
	v_fmamk_f32 v16, v16, 0x3a800000, v154
	v_mul_f32_e32 v17, 0x4b800000, v16
	v_cmp_gt_f32_e64 s[6:7], s48, v16
	s_nop 1
	v_cndmask_b32_e64 v16, v16, v17, s[6:7]
	v_rsq_f32_e32 v18, v16
	v_lshlrev_b64 v[16:17], 13, v[48:49]
	v_lshl_add_u64 v[16:17], v[144:145], 0, v[16:17]
	v_mul_f32_e32 v19, 0x45800000, v18
	v_cndmask_b32_e64 v18, v18, v19, s[6:7]
	v_pk_mul_f32 v[14:15], v[14:15], v[18:19] op_sel_hi:[1,0]
	v_pk_mul_f32 v[12:13], v[12:13], v[18:19] op_sel_hi:[1,0]
	v_pk_mul_f32 v[10:11], v[10:11], v[18:19] op_sel_hi:[1,0]
	v_pk_mul_f32 v[8:9], v[8:9], v[18:19] op_sel_hi:[1,0]
	v_pk_mul_f32 v[2:3], v[2:3], v[18:19] op_sel_hi:[1,0]
	v_pk_mul_f32 v[0:1], v[0:1], v[18:19] op_sel_hi:[1,0]
	v_pk_mul_f32 v[6:7], v[6:7], v[18:19] op_sel_hi:[1,0]
	v_pk_mul_f32 v[4:5], v[4:5], v[18:19] op_sel_hi:[1,0]
	v_max_f32_e32 v12, 0, v12
	v_max_f32_e32 v8, 0, v8
	v_max_f32_e32 v13, 0, v13
	v_max_f32_e32 v9, 0, v9
	v_max_f32_e32 v14, 0, v14
	v_max_f32_e32 v10, 0, v10
	v_max_f32_e32 v15, 0, v15
	v_max_f32_e32 v11, 0, v11
	v_max_f32_e32 v0, 0, v0
	v_max_f32_e32 v1, 0, v1
	v_max_f32_e32 v2, 0, v2
	v_max_f32_e32 v3, 0, v3
	v_max_f32_e32 v4, 0, v4
	v_max_f32_e32 v5, 0, v5
	v_max_f32_e32 v6, 0, v6
	v_max_f32_e32 v7, 0, v7
	v_mul_f32_e32 v12, v12, v12
	v_mul_f32_e32 v8, v8, v8
	v_mul_f32_e32 v13, v13, v13
	v_mul_f32_e32 v9, v9, v9
	v_mul_f32_e32 v14, v14, v14
	v_mul_f32_e32 v10, v10, v10
	v_mul_f32_e32 v15, v15, v15
	v_mul_f32_e32 v11, v11, v11
	v_mul_f32_e32 v18, v0, v0
	v_mul_f32_e32 v19, v1, v1
	v_mul_f32_e32 v20, v2, v2
	v_mul_f32_e32 v21, v3, v3
	v_cvt_pk_bf16_f32 v0, v12, v13
	v_cvt_pk_bf16_f32 v1, v14, v15
	v_cvt_pk_bf16_f32 v2, v8, v9
	v_cvt_pk_bf16_f32 v3, v10, v11
	v_mul_f32_e32 v4, v4, v4
	v_mul_f32_e32 v5, v5, v5
	v_mul_f32_e32 v6, v6, v6
	v_mul_f32_e32 v7, v7, v7
	global_store_dwordx4 v[16:17], v[0:3], off
	s_nop 1
	v_cvt_pk_bf16_f32 v0, v4, v5
	v_cvt_pk_bf16_f32 v1, v6, v7
	v_cvt_pk_bf16_f32 v2, v18, v19
	v_cvt_pk_bf16_f32 v3, v20, v21
	global_store_dwordx4 v[16:17], v[0:3], off offset:256
	s_cbranch_vccnz .LBB0_1357
	s_andn2_b64 vcc, exec, s[2:3]
	s_cbranch_vccnz .LBB0_1356
	s_barrier
	s_branch .LBB0_1356

.LBB0_1564:
	v_lshl_add_u32 v142, s14, 8, v148
	v_ashrrev_i32_e32 v143, 31, v142
	v_lshlrev_b64 v[144:145], 6, v[142:143]
	v_lshl_add_u64 v[146:147], s[18:19], 0, v[144:145]
	v_bfe_u32 v164, v206, 4, 2
	v_lshlrev_b32_e32 v164, 4, v164
	v_mov_b32_e32 v165, 0
	v_lshl_add_u64 v[160:161], v[146:147], 0, v[164:165]
	global_load_dwordx4 v[156:159], v[160:161], off
	v_lshl_or_b32 v140, s2, 8, v150
	v_ashrrev_i32_e32 v141, 31, v140
	v_lshlrev_b64 v[146:147], 10, v[142:143]
	v_lshl_add_u64 v[146:147], v[146:147], 0, v[140:141]
	v_lshlrev_b64 v[146:147], 1, v[146:147]
	v_lshl_add_u64 v[172:173], s[20:21], 0, v[146:147]
	v_lshl_add_u64 v[174:175], s[12:13], 0, v[146:147]
	global_load_dwordx2 v[172:173], v[172:173], off
	v_or_b32_e32 v176, 32, v146
	global_load_dwordx2 v[174:175], v[174:175], off
	v_mov_b32_e32 v177, v147
	v_lshl_add_u64 v[178:179], s[12:13], 0, v[176:177]
	s_lshl_b32 s36, s2, 2
	s_ashr_i32 s37, s36, 31
	s_waitcnt vmcnt(0)
	v_add_f32_e32 v160, v156, v157
	v_add_f32_e32 v161, v158, v159
	v_add_f32_e32 v160, v160, v161
	ds_swizzle_b32 v161, v160 offset:swizzle(SWAP,16)
	s_waitcnt lgkmcnt(0)
	v_add_f32_e32 v160, v160, v161
	v_mov_b32_e32 v161, v160
	s_nop 1
	v_permlane32_swap_b32_e32 v160, v161
	v_add_f32_e32 v168, v160, v161
	v_lshlrev_b32_e32 v162, 16, v173
	v_lshlrev_b32_e32 v158, 16, v172
	v_mov_b32_e32 v143, v168
	v_fmamk_f32 v143, v143, 0x3a800000, v154
	v_mul_f32_e32 v155, 0x4b800000, v143
	v_cmp_gt_f32_e32 vcc, s56, v143
	v_and_b32_e32 v159, 0xffff0000, v172
	v_lshlrev_b32_e32 v156, 16, v174
	v_cndmask_b32_e32 v143, v143, v155, vcc
	v_rsq_f32_e32 v143, v143
	v_and_b32_e32 v157, 0xffff0000, v174
	v_and_b32_e32 v163, 0xffff0000, v173
	v_lshlrev_b32_e32 v160, 16, v175
	v_mul_f32_e32 v155, 0x45800000, v143
	v_cndmask_b32_e32 v143, v143, v155, vcc
	v_mul_f32_e32 v124, v124, v143
	v_mul_f32_e32 v125, v125, v143
	v_mul_f32_e32 v126, v126, v143
	v_mul_f32_e32 v127, v127, v143
	v_mul_f32_e32 v124, 0xbfb8aa3b, v124
	v_mul_f32_e32 v125, 0xbfb8aa3b, v125
	v_mul_f32_e32 v126, 0xbfb8aa3b, v126
	v_mul_f32_e32 v127, 0xbfb8aa3b, v127
	v_exp_f32_e32 v124, v124
	v_exp_f32_e32 v125, v125
	v_exp_f32_e32 v126, v126
	v_exp_f32_e32 v127, v127
	v_add_f32_e32 v124, 1.0, v124
	v_add_f32_e32 v125, 1.0, v125
	v_add_f32_e32 v126, 1.0, v126
	v_add_f32_e32 v127, 1.0, v127
	v_rcp_f32_e32 v124, v124
	v_rcp_f32_e32 v125, v125
	v_rcp_f32_e32 v126, v126
	v_rcp_f32_e32 v127, v127
	v_and_b32_e32 v161, 0xffff0000, v175
	v_pk_fma_f32 v[156:157], v[124:125], v[158:159], v[156:157]
	v_lshl_add_u64 v[124:125], s[8:9], 0, v[146:147]
	v_pk_fma_f32 v[126:127], v[126:127], v[162:163], v[160:161]
	v_cvt_pk_bf16_f32 v158, v156, v157
	v_lshl_add_u64 v[162:163], s[20:21], 0, v[176:177]
	v_cvt_pk_bf16_f32 v159, v126, v127
	global_store_dwordx2 v[124:125], v[158:159], off
	global_load_dwordx2 v[160:161], v[178:179], off
	v_mul_f32_e32 v120, v120, v143
	global_load_dwordx2 v[158:159], v[162:163], off
	v_mul_f32_e32 v121, v121, v143
	v_mul_f32_e32 v122, v122, v143
	v_mul_f32_e32 v123, v123, v143
	v_mul_f32_e32 v120, 0xbfb8aa3b, v120
	v_mul_f32_e32 v121, 0xbfb8aa3b, v121
	v_mul_f32_e32 v122, 0xbfb8aa3b, v122
	v_mul_f32_e32 v123, 0xbfb8aa3b, v123
	v_exp_f32_e32 v120, v120
	v_exp_f32_e32 v121, v121
	v_exp_f32_e32 v122, v122
	v_exp_f32_e32 v123, v123
	v_add_f32_e32 v120, 1.0, v120
	v_add_f32_e32 v121, 1.0, v121
	v_add_f32_e32 v122, 1.0, v122
	v_add_f32_e32 v123, 1.0, v123
	v_rcp_f32_e32 v120, v120
	v_rcp_f32_e32 v121, v121
	v_rcp_f32_e32 v122, v122
	v_rcp_f32_e32 v123, v123
	v_or_b32_e32 v162, 0x100, v146
	v_mov_b32_e32 v163, v147
	v_lshl_add_u64 v[164:165], s[12:13], 0, v[162:163]
	v_lshl_add_u64 v[162:163], s[20:21], 0, v[162:163]
	v_mul_f32_e32 v116, v116, v143
	v_mul_f32_e32 v117, v117, v143
	v_mul_f32_e32 v118, v118, v143
	v_mul_f32_e32 v119, v119, v143
	v_mul_f32_e32 v116, 0xbfb8aa3b, v116
	v_mul_f32_e32 v117, 0xbfb8aa3b, v117
	v_mul_f32_e32 v118, 0xbfb8aa3b, v118
	v_mul_f32_e32 v119, 0xbfb8aa3b, v119
	v_exp_f32_e32 v116, v116
	v_exp_f32_e32 v117, v117
	v_exp_f32_e32 v118, v118
	v_exp_f32_e32 v119, v119
	v_add_f32_e32 v116, 1.0, v116
	v_add_f32_e32 v117, 1.0, v117
	v_add_f32_e32 v118, 1.0, v118
	v_add_f32_e32 v119, 1.0, v119
	v_rcp_f32_e32 v116, v116
	v_rcp_f32_e32 v117, v117
	v_rcp_f32_e32 v118, v118
	v_rcp_f32_e32 v119, v119
	v_or_b32_e32 v146, 0x120, v146
	v_mul_f32_e32 v112, v112, v143
	v_mul_f32_e32 v113, v113, v143
	v_mul_f32_e32 v114, v114, v143
	v_mul_f32_e32 v115, v115, v143
	v_mul_f32_e32 v112, 0xbfb8aa3b, v112
	v_mul_f32_e32 v113, 0xbfb8aa3b, v113
	v_mul_f32_e32 v114, 0xbfb8aa3b, v114
	v_mul_f32_e32 v115, 0xbfb8aa3b, v115
	v_exp_f32_e32 v112, v112
	v_exp_f32_e32 v113, v113
	v_exp_f32_e32 v114, v114
	v_exp_f32_e32 v115, v115
	v_add_f32_e32 v112, 1.0, v112
	v_add_f32_e32 v113, 1.0, v113
	v_add_f32_e32 v114, 1.0, v114
	v_add_f32_e32 v115, 1.0, v115
	v_mul_f32_e32 v143, v157, v157
	v_mul_f32_e32 v127, v127, v127
	v_rcp_f32_e32 v112, v112
	v_rcp_f32_e32 v113, v113
	v_rcp_f32_e32 v114, v114
	v_rcp_f32_e32 v115, v115
	v_fmac_f32_e32 v143, v156, v156
	v_fmac_f32_e32 v127, v126, v126
	v_add_f32_e32 v126, v143, v127
	s_waitcnt vmcnt(1)
	v_lshlrev_b32_e32 v166, 16, v160
	v_and_b32_e32 v167, 0xffff0000, v160
	v_lshlrev_b32_e32 v160, 16, v161
	v_and_b32_e32 v161, 0xffff0000, v161
	s_waitcnt vmcnt(0)
	v_lshlrev_b32_e32 v168, 16, v158
	v_and_b32_e32 v169, 0xffff0000, v158
	v_lshlrev_b32_e32 v158, 16, v159
	v_and_b32_e32 v159, 0xffff0000, v159
	v_pk_fma_f32 v[122:123], v[122:123], v[158:159], v[160:161]
	v_pk_fma_f32 v[120:121], v[120:121], v[168:169], v[166:167]
	s_nop 0
	v_cvt_pk_bf16_f32 v158, v120, v121
	v_cvt_pk_bf16_f32 v159, v122, v123
	global_store_dwordx2 v[124:125], v[158:159], off offset:32
	global_load_dwordx2 v[160:161], v[164:165], off
	v_mul_f32_e32 v121, v121, v121
	global_load_dwordx2 v[158:159], v[162:163], off
	v_lshl_add_u64 v[162:163], s[12:13], 0, v[146:147]
	v_lshl_add_u64 v[146:147], s[20:21], 0, v[146:147]
	v_mul_f32_e32 v123, v123, v123
	v_fmac_f32_e32 v121, v120, v120
	v_fmac_f32_e32 v123, v122, v122
	v_add_f32_e32 v120, v121, v123
	v_add_f32_e32 v120, v126, v120
	s_waitcnt vmcnt(1)
	v_lshlrev_b32_e32 v164, 16, v160
	v_and_b32_e32 v165, 0xffff0000, v160
	v_lshlrev_b32_e32 v160, 16, v161
	v_and_b32_e32 v161, 0xffff0000, v161
	s_waitcnt vmcnt(0)
	v_lshlrev_b32_e32 v166, 16, v158
	v_and_b32_e32 v167, 0xffff0000, v158
	v_lshlrev_b32_e32 v158, 16, v159
	v_and_b32_e32 v159, 0xffff0000, v159
	v_pk_fma_f32 v[118:119], v[118:119], v[158:159], v[160:161]
	v_pk_fma_f32 v[116:117], v[116:117], v[166:167], v[164:165]
	s_nop 0
	v_cvt_pk_bf16_f32 v158, v116, v117
	v_cvt_pk_bf16_f32 v159, v118, v119
	global_store_dwordx2 v[124:125], v[158:159], off offset:256
	global_load_dwordx2 v[160:161], v[162:163], off
	v_mul_f32_e32 v117, v117, v117
	global_load_dwordx2 v[146:147], v[146:147], off
	v_mul_f32_e32 v119, v119, v119
	v_fmac_f32_e32 v117, v116, v116
	v_fmac_f32_e32 v119, v118, v118
	v_add_f32_e32 v116, v117, v119
	v_add_f32_e32 v126, v116, v120
	s_waitcnt vmcnt(1)
	v_lshlrev_b32_e32 v116, 16, v160
	v_and_b32_e32 v117, 0xffff0000, v160
	v_lshlrev_b32_e32 v118, 16, v161
	v_and_b32_e32 v119, 0xffff0000, v161
	s_waitcnt vmcnt(0)
	v_lshlrev_b32_e32 v120, 16, v146
	v_and_b32_e32 v121, 0xffff0000, v146
	v_lshlrev_b32_e32 v122, 16, v147
	v_and_b32_e32 v123, 0xffff0000, v147
	v_pk_fma_f32 v[114:115], v[114:115], v[122:123], v[118:119]
	v_pk_fma_f32 v[112:113], v[112:113], v[120:121], v[116:117]
	v_mul_f32_e32 v117, v115, v115
	v_mul_f32_e32 v116, v113, v113
	v_fmac_f32_e32 v116, v112, v112
	v_fmac_f32_e32 v117, v114, v114
	v_add_f32_e32 v116, v116, v117
	v_add_f32_e32 v116, v126, v116
	ds_swizzle_b32 v117, v116 offset:swizzle(SWAP,16)
	v_cvt_pk_bf16_f32 v112, v112, v113
	v_cvt_pk_bf16_f32 v113, v114, v115
	global_store_dwordx2 v[124:125], v[112:113], off offset:288
	s_waitcnt lgkmcnt(0)
	v_add_f32_e32 v112, v116, v117
	v_mov_b32_e32 v113, v112
	s_nop 1
	v_permlane32_swap_b32_e32 v112, v113
	s_and_saveexec_b64 s[2:3], s[4:5]
	s_cbranch_execz .LBB0_1566
	v_add_f32_e32 v114, v112, v113
	v_lshl_add_u64 v[112:113], s[10:11], 0, v[144:145]
	v_lshl_add_u64 v[112:113], s[36:37], 2, v[112:113]
	s_lshl_b32 s14, s50, 2
	v_lshl_add_u64 v[112:113], v[112:113], 0, s[14:15]
	global_store_dword v[112:113], v114, off
.LBB0_1566:
	s_or_b64 exec, exec, s[2:3]
	v_or_b32_e32 v114, 16, v142
	v_ashrrev_i32_e32 v115, 31, v114
	v_lshlrev_b64 v[112:113], 6, v[114:115]
	v_lshl_add_u64 v[144:145], s[18:19], 0, v[112:113]
	v_bfe_u32 v124, v206, 4, 2
	v_lshlrev_b32_e32 v124, 4, v124
	v_mov_b32_e32 v125, 0
	v_lshl_add_u64 v[120:121], v[144:145], 0, v[124:125]
	global_load_dwordx4 v[116:119], v[120:121], off
	s_nop 0
	v_lshlrev_b64 v[114:115], 10, v[114:115]
	v_lshl_add_u64 v[114:115], v[114:115], 0, v[140:141]
	v_lshlrev_b64 v[114:115], 1, v[114:115]
	v_lshl_add_u64 v[156:157], s[20:21], 0, v[114:115]
	v_lshl_add_u64 v[158:159], s[12:13], 0, v[114:115]
	global_load_dwordx2 v[156:157], v[156:157], off
	v_or_b32_e32 v160, 32, v114
	global_load_dwordx2 v[158:159], v[158:159], off
	v_mov_b32_e32 v161, v115
	v_lshl_add_u64 v[162:163], s[12:13], 0, v[160:161]
	s_waitcnt vmcnt(0)
	v_add_f32_e32 v120, v116, v117
	v_add_f32_e32 v121, v118, v119
	v_add_f32_e32 v120, v120, v121
	ds_swizzle_b32 v121, v120 offset:swizzle(SWAP,16)
	s_waitcnt lgkmcnt(0)
	v_add_f32_e32 v120, v120, v121
	v_mov_b32_e32 v121, v120
	s_nop 1
	v_permlane32_swap_b32_e32 v120, v121
	v_add_f32_e32 v144, v120, v121
	v_lshlrev_b32_e32 v122, 16, v157
	v_lshlrev_b32_e32 v118, 16, v156
	v_mov_b32_e32 v116, v144
	v_fmamk_f32 v116, v116, 0x3a800000, v154
	v_mul_f32_e32 v117, 0x4b800000, v116
	v_cmp_gt_f32_e32 vcc, s56, v116
	v_and_b32_e32 v119, 0xffff0000, v156
	v_and_b32_e32 v123, 0xffff0000, v157
	v_cndmask_b32_e32 v116, v116, v117, vcc
	v_rsq_f32_e32 v120, v116
	s_waitcnt vmcnt(0)
	v_lshlrev_b32_e32 v116, 16, v158
	v_and_b32_e32 v117, 0xffff0000, v158
	v_mul_f32_e32 v121, 0x45800000, v120
	v_cndmask_b32_e32 v143, v120, v121, vcc
	v_mul_f32_e32 v108, v108, v143
	v_mul_f32_e32 v109, v109, v143
	v_mul_f32_e32 v110, v110, v143
	v_mul_f32_e32 v111, v111, v143
	v_mul_f32_e32 v108, 0xbfb8aa3b, v108
	v_mul_f32_e32 v109, 0xbfb8aa3b, v109
	v_mul_f32_e32 v110, 0xbfb8aa3b, v110
	v_mul_f32_e32 v111, 0xbfb8aa3b, v111
	v_exp_f32_e32 v108, v108
	v_exp_f32_e32 v109, v109
	v_exp_f32_e32 v110, v110
	v_exp_f32_e32 v111, v111
	v_add_f32_e32 v108, 1.0, v108
	v_add_f32_e32 v109, 1.0, v109
	v_add_f32_e32 v110, 1.0, v110
	v_add_f32_e32 v111, 1.0, v111
	v_rcp_f32_e32 v108, v108
	v_rcp_f32_e32 v109, v109
	v_rcp_f32_e32 v110, v110
	v_rcp_f32_e32 v111, v111
	v_lshlrev_b32_e32 v120, 16, v159
	v_and_b32_e32 v121, 0xffff0000, v159
	v_pk_fma_f32 v[116:117], v[108:109], v[118:119], v[116:117]
	v_lshl_add_u64 v[108:109], s[8:9], 0, v[114:115]
	v_pk_fma_f32 v[110:111], v[110:111], v[122:123], v[120:121]
	v_cvt_pk_bf16_f32 v118, v116, v117
	v_lshl_add_u64 v[122:123], s[20:21], 0, v[160:161]
	v_cvt_pk_bf16_f32 v119, v110, v111
	global_store_dwordx2 v[108:109], v[118:119], off
	global_load_dwordx2 v[120:121], v[162:163], off
	v_mul_f32_e32 v104, v104, v143
	global_load_dwordx2 v[118:119], v[122:123], off
	v_mul_f32_e32 v105, v105, v143
	v_mul_f32_e32 v106, v106, v143
	v_mul_f32_e32 v107, v107, v143
	v_mul_f32_e32 v104, 0xbfb8aa3b, v104
	v_mul_f32_e32 v105, 0xbfb8aa3b, v105
	v_mul_f32_e32 v106, 0xbfb8aa3b, v106
	v_mul_f32_e32 v107, 0xbfb8aa3b, v107
	v_exp_f32_e32 v104, v104
	v_exp_f32_e32 v105, v105
	v_exp_f32_e32 v106, v106
	v_exp_f32_e32 v107, v107
	v_add_f32_e32 v104, 1.0, v104
	v_add_f32_e32 v105, 1.0, v105
	v_add_f32_e32 v106, 1.0, v106
	v_add_f32_e32 v107, 1.0, v107
	v_rcp_f32_e32 v104, v104
	v_rcp_f32_e32 v105, v105
	v_rcp_f32_e32 v106, v106
	v_rcp_f32_e32 v107, v107
	v_or_b32_e32 v122, 0x100, v114
	v_mov_b32_e32 v123, v115
	v_lshl_add_u64 v[124:125], s[12:13], 0, v[122:123]
	v_lshl_add_u64 v[122:123], s[20:21], 0, v[122:123]
	v_mul_f32_e32 v100, v100, v143
	v_mul_f32_e32 v101, v101, v143
	v_mul_f32_e32 v102, v102, v143
	v_mul_f32_e32 v103, v103, v143
	v_mul_f32_e32 v100, 0xbfb8aa3b, v100
	v_mul_f32_e32 v101, 0xbfb8aa3b, v101
	v_mul_f32_e32 v102, 0xbfb8aa3b, v102
	v_mul_f32_e32 v103, 0xbfb8aa3b, v103
	v_exp_f32_e32 v100, v100
	v_exp_f32_e32 v101, v101
	v_exp_f32_e32 v102, v102
	v_exp_f32_e32 v103, v103
	v_add_f32_e32 v100, 1.0, v100
	v_add_f32_e32 v101, 1.0, v101
	v_add_f32_e32 v102, 1.0, v102
	v_add_f32_e32 v103, 1.0, v103
	v_rcp_f32_e32 v100, v100
	v_rcp_f32_e32 v101, v101
	v_rcp_f32_e32 v102, v102
	v_rcp_f32_e32 v103, v103
	v_or_b32_e32 v114, 0x120, v114
	v_mul_f32_e32 v96, v96, v143
	v_mul_f32_e32 v97, v97, v143
	v_mul_f32_e32 v98, v98, v143
	v_mul_f32_e32 v99, v99, v143
	v_mul_f32_e32 v96, 0xbfb8aa3b, v96
	v_mul_f32_e32 v97, 0xbfb8aa3b, v97
	v_mul_f32_e32 v98, 0xbfb8aa3b, v98
	v_mul_f32_e32 v99, 0xbfb8aa3b, v99
	v_exp_f32_e32 v96, v96
	v_exp_f32_e32 v97, v97
	v_exp_f32_e32 v98, v98
	v_exp_f32_e32 v99, v99
	v_add_f32_e32 v96, 1.0, v96
	v_add_f32_e32 v97, 1.0, v97
	v_add_f32_e32 v98, 1.0, v98
	v_add_f32_e32 v99, 1.0, v99
	v_mul_f32_e32 v117, v117, v117
	v_mul_f32_e32 v111, v111, v111
	v_rcp_f32_e32 v96, v96
	v_rcp_f32_e32 v97, v97
	v_rcp_f32_e32 v98, v98
	v_rcp_f32_e32 v99, v99
	v_fmac_f32_e32 v117, v116, v116
	v_fmac_f32_e32 v111, v110, v110
	v_add_f32_e32 v110, v117, v111
	s_waitcnt vmcnt(1)
	v_lshlrev_b32_e32 v126, 16, v120
	v_and_b32_e32 v127, 0xffff0000, v120
	v_lshlrev_b32_e32 v120, 16, v121
	v_and_b32_e32 v121, 0xffff0000, v121
	s_waitcnt vmcnt(0)
	v_lshlrev_b32_e32 v144, 16, v118
	v_and_b32_e32 v145, 0xffff0000, v118
	v_lshlrev_b32_e32 v118, 16, v119
	v_and_b32_e32 v119, 0xffff0000, v119
	v_pk_fma_f32 v[106:107], v[106:107], v[118:119], v[120:121]
	v_pk_fma_f32 v[104:105], v[104:105], v[144:145], v[126:127]
	s_nop 0
	v_cvt_pk_bf16_f32 v118, v104, v105
	v_cvt_pk_bf16_f32 v119, v106, v107
	global_store_dwordx2 v[108:109], v[118:119], off offset:32
	global_load_dwordx2 v[120:121], v[124:125], off
	v_mul_f32_e32 v105, v105, v105
	global_load_dwordx2 v[118:119], v[122:123], off
	v_lshl_add_u64 v[122:123], s[12:13], 0, v[114:115]
	v_lshl_add_u64 v[114:115], s[20:21], 0, v[114:115]
	v_mul_f32_e32 v107, v107, v107
	v_fmac_f32_e32 v105, v104, v104
	v_fmac_f32_e32 v107, v106, v106
	v_add_f32_e32 v104, v105, v107
	v_add_f32_e32 v104, v110, v104
	s_waitcnt vmcnt(1)
	v_lshlrev_b32_e32 v124, 16, v120
	v_and_b32_e32 v125, 0xffff0000, v120
	v_lshlrev_b32_e32 v120, 16, v121
	v_and_b32_e32 v121, 0xffff0000, v121
	s_waitcnt vmcnt(0)
	v_lshlrev_b32_e32 v126, 16, v118
	v_and_b32_e32 v127, 0xffff0000, v118
	v_lshlrev_b32_e32 v118, 16, v119
	v_and_b32_e32 v119, 0xffff0000, v119
	v_pk_fma_f32 v[102:103], v[102:103], v[118:119], v[120:121]
	v_pk_fma_f32 v[100:101], v[100:101], v[126:127], v[124:125]
	s_nop 0
	v_cvt_pk_bf16_f32 v118, v100, v101
	v_cvt_pk_bf16_f32 v119, v102, v103
	global_store_dwordx2 v[108:109], v[118:119], off offset:256
	global_load_dwordx2 v[120:121], v[122:123], off
	v_mul_f32_e32 v101, v101, v101
	global_load_dwordx2 v[114:115], v[114:115], off
	v_mul_f32_e32 v103, v103, v103
	v_fmac_f32_e32 v101, v100, v100
	v_fmac_f32_e32 v103, v102, v102
	v_add_f32_e32 v100, v101, v103
	v_add_f32_e32 v110, v100, v104
	s_waitcnt vmcnt(1)
	v_lshlrev_b32_e32 v100, 16, v120
	v_and_b32_e32 v101, 0xffff0000, v120
	v_lshlrev_b32_e32 v102, 16, v121
	v_and_b32_e32 v103, 0xffff0000, v121
	s_waitcnt vmcnt(0)
	v_lshlrev_b32_e32 v104, 16, v114
	v_and_b32_e32 v105, 0xffff0000, v114
	v_lshlrev_b32_e32 v106, 16, v115
	v_and_b32_e32 v107, 0xffff0000, v115
	v_pk_fma_f32 v[98:99], v[98:99], v[106:107], v[102:103]
	v_pk_fma_f32 v[96:97], v[96:97], v[104:105], v[100:101]
	v_mul_f32_e32 v101, v99, v99
	v_mul_f32_e32 v100, v97, v97
	v_fmac_f32_e32 v100, v96, v96
	v_fmac_f32_e32 v101, v98, v98
	v_add_f32_e32 v100, v100, v101
	v_add_f32_e32 v100, v110, v100
	ds_swizzle_b32 v101, v100 offset:swizzle(SWAP,16)
	v_cvt_pk_bf16_f32 v96, v96, v97
	v_cvt_pk_bf16_f32 v97, v98, v99
	global_store_dwordx2 v[108:109], v[96:97], off offset:288
	s_waitcnt lgkmcnt(0)
	v_add_f32_e32 v96, v100, v101
	v_mov_b32_e32 v97, v96
	s_nop 1
	v_permlane32_swap_b32_e32 v96, v97
	s_and_saveexec_b64 s[2:3], s[4:5]
	s_cbranch_execz .LBB0_1568
	v_add_f32_e32 v98, v96, v97
	v_lshl_add_u64 v[96:97], s[10:11], 0, v[112:113]
	v_lshl_add_u64 v[96:97], s[36:37], 2, v[96:97]
	s_lshl_b32 s14, s50, 2
	v_lshl_add_u64 v[96:97], v[96:97], 0, s[14:15]
	global_store_dword v[96:97], v98, off
.LBB0_1568:
	s_or_b64 exec, exec, s[2:3]
	v_or_b32_e32 v98, 32, v142
	v_ashrrev_i32_e32 v99, 31, v98
	v_lshlrev_b64 v[96:97], 6, v[98:99]
	v_lshl_add_u64 v[112:113], s[18:19], 0, v[96:97]
	v_bfe_u32 v108, v206, 4, 2
	v_lshlrev_b32_e32 v108, 4, v108
	v_mov_b32_e32 v109, 0
	v_lshl_add_u64 v[104:105], v[112:113], 0, v[108:109]
	global_load_dwordx4 v[100:103], v[104:105], off
	s_nop 0
	v_lshlrev_b64 v[98:99], 10, v[98:99]
	v_lshl_add_u64 v[98:99], v[98:99], 0, v[140:141]
	v_lshlrev_b64 v[98:99], 1, v[98:99]
	v_lshl_add_u64 v[116:117], s[20:21], 0, v[98:99]
	v_lshl_add_u64 v[118:119], s[12:13], 0, v[98:99]
	global_load_dwordx2 v[116:117], v[116:117], off
	v_or_b32_e32 v120, 32, v98
	global_load_dwordx2 v[118:119], v[118:119], off
	v_mov_b32_e32 v121, v99
	v_lshl_add_u64 v[122:123], s[12:13], 0, v[120:121]
	s_waitcnt vmcnt(0)
	v_add_f32_e32 v104, v100, v101
	v_add_f32_e32 v105, v102, v103
	v_add_f32_e32 v104, v104, v105
	ds_swizzle_b32 v105, v104 offset:swizzle(SWAP,16)
	s_waitcnt lgkmcnt(0)
	v_add_f32_e32 v104, v104, v105
	v_mov_b32_e32 v105, v104
	s_nop 1
	v_permlane32_swap_b32_e32 v104, v105
	v_add_f32_e32 v112, v104, v105
	v_lshlrev_b32_e32 v106, 16, v117
	v_lshlrev_b32_e32 v102, 16, v116
	v_mov_b32_e32 v100, v112
	v_fmamk_f32 v100, v100, 0x3a800000, v154
	v_mul_f32_e32 v101, 0x4b800000, v100
	v_cmp_gt_f32_e32 vcc, s56, v100
	v_and_b32_e32 v103, 0xffff0000, v116
	v_and_b32_e32 v107, 0xffff0000, v117
	v_cndmask_b32_e32 v100, v100, v101, vcc
	v_rsq_f32_e32 v104, v100
	s_waitcnt vmcnt(0)
	v_lshlrev_b32_e32 v100, 16, v118
	v_and_b32_e32 v101, 0xffff0000, v118
	v_mul_f32_e32 v105, 0x45800000, v104
	v_cndmask_b32_e32 v114, v104, v105, vcc
	v_mul_f32_e32 v92, v92, v114
	v_mul_f32_e32 v93, v93, v114
	v_mul_f32_e32 v94, v94, v114
	v_mul_f32_e32 v95, v95, v114
	v_mul_f32_e32 v92, 0xbfb8aa3b, v92
	v_mul_f32_e32 v93, 0xbfb8aa3b, v93
	v_mul_f32_e32 v94, 0xbfb8aa3b, v94
	v_mul_f32_e32 v95, 0xbfb8aa3b, v95
	v_exp_f32_e32 v92, v92
	v_exp_f32_e32 v93, v93
	v_exp_f32_e32 v94, v94
	v_exp_f32_e32 v95, v95
	v_add_f32_e32 v92, 1.0, v92
	v_add_f32_e32 v93, 1.0, v93
	v_add_f32_e32 v94, 1.0, v94
	v_add_f32_e32 v95, 1.0, v95
	v_rcp_f32_e32 v92, v92
	v_rcp_f32_e32 v93, v93
	v_rcp_f32_e32 v94, v94
	v_rcp_f32_e32 v95, v95
	v_lshlrev_b32_e32 v104, 16, v119
	v_and_b32_e32 v105, 0xffff0000, v119
	v_pk_fma_f32 v[100:101], v[92:93], v[102:103], v[100:101]
	v_lshl_add_u64 v[92:93], s[8:9], 0, v[98:99]
	v_pk_fma_f32 v[94:95], v[94:95], v[106:107], v[104:105]
	v_cvt_pk_bf16_f32 v102, v100, v101
	v_lshl_add_u64 v[106:107], s[20:21], 0, v[120:121]
	v_cvt_pk_bf16_f32 v103, v94, v95
	global_store_dwordx2 v[92:93], v[102:103], off
	global_load_dwordx2 v[104:105], v[122:123], off
	v_mul_f32_e32 v88, v88, v114
	global_load_dwordx2 v[102:103], v[106:107], off
	v_mul_f32_e32 v89, v89, v114
	v_mul_f32_e32 v90, v90, v114
	v_mul_f32_e32 v91, v91, v114
	v_mul_f32_e32 v88, 0xbfb8aa3b, v88
	v_mul_f32_e32 v89, 0xbfb8aa3b, v89
	v_mul_f32_e32 v90, 0xbfb8aa3b, v90
	v_mul_f32_e32 v91, 0xbfb8aa3b, v91
	v_exp_f32_e32 v88, v88
	v_exp_f32_e32 v89, v89
	v_exp_f32_e32 v90, v90
	v_exp_f32_e32 v91, v91
	v_add_f32_e32 v88, 1.0, v88
	v_add_f32_e32 v89, 1.0, v89
	v_add_f32_e32 v90, 1.0, v90
	v_add_f32_e32 v91, 1.0, v91
	v_rcp_f32_e32 v88, v88
	v_rcp_f32_e32 v89, v89
	v_rcp_f32_e32 v90, v90
	v_rcp_f32_e32 v91, v91
	v_or_b32_e32 v106, 0x100, v98
	v_mov_b32_e32 v107, v99
	v_lshl_add_u64 v[108:109], s[12:13], 0, v[106:107]
	v_lshl_add_u64 v[106:107], s[20:21], 0, v[106:107]
	v_mul_f32_e32 v84, v84, v114
	v_mul_f32_e32 v85, v85, v114
	v_mul_f32_e32 v86, v86, v114
	v_mul_f32_e32 v87, v87, v114
	v_mul_f32_e32 v84, 0xbfb8aa3b, v84
	v_mul_f32_e32 v85, 0xbfb8aa3b, v85
	v_mul_f32_e32 v86, 0xbfb8aa3b, v86
	v_mul_f32_e32 v87, 0xbfb8aa3b, v87
	v_exp_f32_e32 v84, v84
	v_exp_f32_e32 v85, v85
	v_exp_f32_e32 v86, v86
	v_exp_f32_e32 v87, v87
	v_add_f32_e32 v84, 1.0, v84
	v_add_f32_e32 v85, 1.0, v85
	v_add_f32_e32 v86, 1.0, v86
	v_add_f32_e32 v87, 1.0, v87
	v_rcp_f32_e32 v84, v84
	v_rcp_f32_e32 v85, v85
	v_rcp_f32_e32 v86, v86
	v_rcp_f32_e32 v87, v87
	v_or_b32_e32 v98, 0x120, v98
	v_mul_f32_e32 v80, v80, v114
	v_mul_f32_e32 v81, v81, v114
	v_mul_f32_e32 v82, v82, v114
	v_mul_f32_e32 v83, v83, v114
	v_mul_f32_e32 v80, 0xbfb8aa3b, v80
	v_mul_f32_e32 v81, 0xbfb8aa3b, v81
	v_mul_f32_e32 v82, 0xbfb8aa3b, v82
	v_mul_f32_e32 v83, 0xbfb8aa3b, v83
	v_exp_f32_e32 v80, v80
	v_exp_f32_e32 v81, v81
	v_exp_f32_e32 v82, v82
	v_exp_f32_e32 v83, v83
	v_add_f32_e32 v80, 1.0, v80
	v_add_f32_e32 v81, 1.0, v81
	v_add_f32_e32 v82, 1.0, v82
	v_add_f32_e32 v83, 1.0, v83
	v_mul_f32_e32 v101, v101, v101
	v_mul_f32_e32 v95, v95, v95
	v_rcp_f32_e32 v80, v80
	v_rcp_f32_e32 v81, v81
	v_rcp_f32_e32 v82, v82
	v_rcp_f32_e32 v83, v83
	v_fmac_f32_e32 v101, v100, v100
	v_fmac_f32_e32 v95, v94, v94
	v_add_f32_e32 v94, v101, v95
	s_waitcnt vmcnt(1)
	v_lshlrev_b32_e32 v110, 16, v104
	v_and_b32_e32 v111, 0xffff0000, v104
	v_lshlrev_b32_e32 v104, 16, v105
	v_and_b32_e32 v105, 0xffff0000, v105
	s_waitcnt vmcnt(0)
	v_lshlrev_b32_e32 v112, 16, v102
	v_and_b32_e32 v113, 0xffff0000, v102
	v_lshlrev_b32_e32 v102, 16, v103
	v_and_b32_e32 v103, 0xffff0000, v103
	v_pk_fma_f32 v[90:91], v[90:91], v[102:103], v[104:105]
	v_pk_fma_f32 v[88:89], v[88:89], v[112:113], v[110:111]
	s_nop 0
	v_cvt_pk_bf16_f32 v102, v88, v89
	v_cvt_pk_bf16_f32 v103, v90, v91
	global_store_dwordx2 v[92:93], v[102:103], off offset:32
	global_load_dwordx2 v[104:105], v[108:109], off
	v_mul_f32_e32 v89, v89, v89
	global_load_dwordx2 v[102:103], v[106:107], off
	v_lshl_add_u64 v[106:107], s[12:13], 0, v[98:99]
	v_lshl_add_u64 v[98:99], s[20:21], 0, v[98:99]
	v_mul_f32_e32 v91, v91, v91
	v_fmac_f32_e32 v89, v88, v88
	v_fmac_f32_e32 v91, v90, v90
	v_add_f32_e32 v88, v89, v91
	v_add_f32_e32 v88, v94, v88
	s_waitcnt vmcnt(1)
	v_lshlrev_b32_e32 v108, 16, v104
	v_and_b32_e32 v109, 0xffff0000, v104
	v_lshlrev_b32_e32 v104, 16, v105
	v_and_b32_e32 v105, 0xffff0000, v105
	s_waitcnt vmcnt(0)
	v_lshlrev_b32_e32 v110, 16, v102
	v_and_b32_e32 v111, 0xffff0000, v102
	v_lshlrev_b32_e32 v102, 16, v103
	v_and_b32_e32 v103, 0xffff0000, v103
	v_pk_fma_f32 v[86:87], v[86:87], v[102:103], v[104:105]
	v_pk_fma_f32 v[84:85], v[84:85], v[110:111], v[108:109]
	s_nop 0
	v_cvt_pk_bf16_f32 v102, v84, v85
	v_cvt_pk_bf16_f32 v103, v86, v87
	global_store_dwordx2 v[92:93], v[102:103], off offset:256
	global_load_dwordx2 v[104:105], v[106:107], off
	v_mul_f32_e32 v85, v85, v85
	global_load_dwordx2 v[98:99], v[98:99], off
	v_mul_f32_e32 v87, v87, v87
	v_fmac_f32_e32 v85, v84, v84
	v_fmac_f32_e32 v87, v86, v86
	v_add_f32_e32 v84, v85, v87
	v_add_f32_e32 v94, v84, v88
	s_waitcnt vmcnt(1)
	v_lshlrev_b32_e32 v84, 16, v104
	v_and_b32_e32 v85, 0xffff0000, v104
	v_lshlrev_b32_e32 v86, 16, v105
	v_and_b32_e32 v87, 0xffff0000, v105
	s_waitcnt vmcnt(0)
	v_lshlrev_b32_e32 v88, 16, v98
	v_and_b32_e32 v89, 0xffff0000, v98
	v_lshlrev_b32_e32 v90, 16, v99
	v_and_b32_e32 v91, 0xffff0000, v99
	v_pk_fma_f32 v[82:83], v[82:83], v[90:91], v[86:87]
	v_pk_fma_f32 v[80:81], v[80:81], v[88:89], v[84:85]
	v_mul_f32_e32 v85, v83, v83
	v_mul_f32_e32 v84, v81, v81
	v_fmac_f32_e32 v84, v80, v80
	v_fmac_f32_e32 v85, v82, v82
	v_add_f32_e32 v84, v84, v85
	v_add_f32_e32 v84, v94, v84
	ds_swizzle_b32 v85, v84 offset:swizzle(SWAP,16)
	v_cvt_pk_bf16_f32 v80, v80, v81
	v_cvt_pk_bf16_f32 v81, v82, v83
	global_store_dwordx2 v[92:93], v[80:81], off offset:288
	s_waitcnt lgkmcnt(0)
	v_add_f32_e32 v80, v84, v85
	v_mov_b32_e32 v81, v80
	s_nop 1
	v_permlane32_swap_b32_e32 v80, v81
	s_and_saveexec_b64 s[2:3], s[4:5]
	s_cbranch_execz .LBB0_1570
	v_add_f32_e32 v82, v80, v81
	v_lshl_add_u64 v[80:81], s[10:11], 0, v[96:97]
	v_lshl_add_u64 v[80:81], s[36:37], 2, v[80:81]
	s_lshl_b32 s14, s50, 2
	v_lshl_add_u64 v[80:81], v[80:81], 0, s[14:15]
	global_store_dword v[80:81], v82, off
.LBB0_1570:
	s_or_b64 exec, exec, s[2:3]
	v_or_b32_e32 v82, 48, v142
	v_ashrrev_i32_e32 v83, 31, v82
	v_lshlrev_b64 v[80:81], 6, v[82:83]
	v_lshl_add_u64 v[96:97], s[18:19], 0, v[80:81]
	v_bfe_u32 v92, v206, 4, 2
	v_lshlrev_b32_e32 v92, 4, v92
	v_mov_b32_e32 v93, 0
	v_lshl_add_u64 v[88:89], v[96:97], 0, v[92:93]
	global_load_dwordx4 v[84:87], v[88:89], off
	s_nop 0
	v_lshlrev_b64 v[82:83], 10, v[82:83]
	v_lshl_add_u64 v[82:83], v[82:83], 0, v[140:141]
	v_lshlrev_b64 v[82:83], 1, v[82:83]
	v_lshl_add_u64 v[100:101], s[20:21], 0, v[82:83]
	v_lshl_add_u64 v[102:103], s[12:13], 0, v[82:83]
	global_load_dwordx2 v[100:101], v[100:101], off
	v_or_b32_e32 v104, 32, v82
	global_load_dwordx2 v[102:103], v[102:103], off
	v_mov_b32_e32 v105, v83
	v_lshl_add_u64 v[106:107], s[12:13], 0, v[104:105]
	s_waitcnt vmcnt(0)
	v_add_f32_e32 v88, v84, v85
	v_add_f32_e32 v89, v86, v87
	v_add_f32_e32 v88, v88, v89
	ds_swizzle_b32 v89, v88 offset:swizzle(SWAP,16)
	s_waitcnt lgkmcnt(0)
	v_add_f32_e32 v88, v88, v89
	v_mov_b32_e32 v89, v88
	s_nop 1
	v_permlane32_swap_b32_e32 v88, v89
	v_add_f32_e32 v96, v88, v89
	v_lshlrev_b32_e32 v90, 16, v101
	v_lshlrev_b32_e32 v86, 16, v100
	v_mov_b32_e32 v84, v96
	v_fmamk_f32 v84, v84, 0x3a800000, v154
	v_mul_f32_e32 v85, 0x4b800000, v84
	v_cmp_gt_f32_e32 vcc, s56, v84
	v_and_b32_e32 v87, 0xffff0000, v100
	v_and_b32_e32 v91, 0xffff0000, v101
	v_cndmask_b32_e32 v84, v84, v85, vcc
	v_rsq_f32_e32 v88, v84
	s_waitcnt vmcnt(0)
	v_lshlrev_b32_e32 v84, 16, v102
	v_and_b32_e32 v85, 0xffff0000, v102
	v_mul_f32_e32 v89, 0x45800000, v88
	v_cndmask_b32_e32 v98, v88, v89, vcc
	v_mul_f32_e32 v76, v76, v98
	v_mul_f32_e32 v77, v77, v98
	v_mul_f32_e32 v78, v78, v98
	v_mul_f32_e32 v79, v79, v98
	v_mul_f32_e32 v76, 0xbfb8aa3b, v76
	v_mul_f32_e32 v77, 0xbfb8aa3b, v77
	v_mul_f32_e32 v78, 0xbfb8aa3b, v78
	v_mul_f32_e32 v79, 0xbfb8aa3b, v79
	v_exp_f32_e32 v76, v76
	v_exp_f32_e32 v77, v77
	v_exp_f32_e32 v78, v78
	v_exp_f32_e32 v79, v79
	v_add_f32_e32 v76, 1.0, v76
	v_add_f32_e32 v77, 1.0, v77
	v_add_f32_e32 v78, 1.0, v78
	v_add_f32_e32 v79, 1.0, v79
	v_rcp_f32_e32 v76, v76
	v_rcp_f32_e32 v77, v77
	v_rcp_f32_e32 v78, v78
	v_rcp_f32_e32 v79, v79
	v_lshlrev_b32_e32 v88, 16, v103
	v_and_b32_e32 v89, 0xffff0000, v103
	v_pk_fma_f32 v[84:85], v[76:77], v[86:87], v[84:85]
	v_lshl_add_u64 v[76:77], s[8:9], 0, v[82:83]
	v_pk_fma_f32 v[78:79], v[78:79], v[90:91], v[88:89]
	v_cvt_pk_bf16_f32 v86, v84, v85
	v_lshl_add_u64 v[90:91], s[20:21], 0, v[104:105]
	v_cvt_pk_bf16_f32 v87, v78, v79
	global_store_dwordx2 v[76:77], v[86:87], off
	global_load_dwordx2 v[88:89], v[106:107], off
	v_mul_f32_e32 v72, v72, v98
	global_load_dwordx2 v[86:87], v[90:91], off
	v_mul_f32_e32 v73, v73, v98
	v_mul_f32_e32 v74, v74, v98
	v_mul_f32_e32 v75, v75, v98
	v_mul_f32_e32 v72, 0xbfb8aa3b, v72
	v_mul_f32_e32 v73, 0xbfb8aa3b, v73
	v_mul_f32_e32 v74, 0xbfb8aa3b, v74
	v_mul_f32_e32 v75, 0xbfb8aa3b, v75
	v_exp_f32_e32 v72, v72
	v_exp_f32_e32 v73, v73
	v_exp_f32_e32 v74, v74
	v_exp_f32_e32 v75, v75
	v_add_f32_e32 v72, 1.0, v72
	v_add_f32_e32 v73, 1.0, v73
	v_add_f32_e32 v74, 1.0, v74
	v_add_f32_e32 v75, 1.0, v75
	v_rcp_f32_e32 v72, v72
	v_rcp_f32_e32 v73, v73
	v_rcp_f32_e32 v74, v74
	v_rcp_f32_e32 v75, v75
	v_or_b32_e32 v90, 0x100, v82
	v_mov_b32_e32 v91, v83
	v_lshl_add_u64 v[92:93], s[12:13], 0, v[90:91]
	v_lshl_add_u64 v[90:91], s[20:21], 0, v[90:91]
	v_mul_f32_e32 v68, v68, v98
	v_mul_f32_e32 v69, v69, v98
	v_mul_f32_e32 v70, v70, v98
	v_mul_f32_e32 v71, v71, v98
	v_mul_f32_e32 v68, 0xbfb8aa3b, v68
	v_mul_f32_e32 v69, 0xbfb8aa3b, v69
	v_mul_f32_e32 v70, 0xbfb8aa3b, v70
	v_mul_f32_e32 v71, 0xbfb8aa3b, v71
	v_exp_f32_e32 v68, v68
	v_exp_f32_e32 v69, v69
	v_exp_f32_e32 v70, v70
	v_exp_f32_e32 v71, v71
	v_add_f32_e32 v68, 1.0, v68
	v_add_f32_e32 v69, 1.0, v69
	v_add_f32_e32 v70, 1.0, v70
	v_add_f32_e32 v71, 1.0, v71
	v_rcp_f32_e32 v68, v68
	v_rcp_f32_e32 v69, v69
	v_rcp_f32_e32 v70, v70
	v_rcp_f32_e32 v71, v71
	v_or_b32_e32 v82, 0x120, v82
	v_mul_f32_e32 v64, v64, v98
	v_mul_f32_e32 v65, v65, v98
	v_mul_f32_e32 v66, v66, v98
	v_mul_f32_e32 v67, v67, v98
	v_mul_f32_e32 v64, 0xbfb8aa3b, v64
	v_mul_f32_e32 v65, 0xbfb8aa3b, v65
	v_mul_f32_e32 v66, 0xbfb8aa3b, v66
	v_mul_f32_e32 v67, 0xbfb8aa3b, v67
	v_exp_f32_e32 v64, v64
	v_exp_f32_e32 v65, v65
	v_exp_f32_e32 v66, v66
	v_exp_f32_e32 v67, v67
	v_add_f32_e32 v64, 1.0, v64
	v_add_f32_e32 v65, 1.0, v65
	v_add_f32_e32 v66, 1.0, v66
	v_add_f32_e32 v67, 1.0, v67
	v_mul_f32_e32 v85, v85, v85
	v_mul_f32_e32 v79, v79, v79
	v_rcp_f32_e32 v64, v64
	v_rcp_f32_e32 v65, v65
	v_rcp_f32_e32 v66, v66
	v_rcp_f32_e32 v67, v67
	v_fmac_f32_e32 v85, v84, v84
	v_fmac_f32_e32 v79, v78, v78
	v_add_f32_e32 v78, v85, v79
	s_waitcnt vmcnt(1)
	v_lshlrev_b32_e32 v94, 16, v88
	v_and_b32_e32 v95, 0xffff0000, v88
	v_lshlrev_b32_e32 v88, 16, v89
	v_and_b32_e32 v89, 0xffff0000, v89
	s_waitcnt vmcnt(0)
	v_lshlrev_b32_e32 v96, 16, v86
	v_and_b32_e32 v97, 0xffff0000, v86
	v_lshlrev_b32_e32 v86, 16, v87
	v_and_b32_e32 v87, 0xffff0000, v87
	v_pk_fma_f32 v[74:75], v[74:75], v[86:87], v[88:89]
	v_pk_fma_f32 v[72:73], v[72:73], v[96:97], v[94:95]
	s_nop 0
	v_cvt_pk_bf16_f32 v86, v72, v73
	v_cvt_pk_bf16_f32 v87, v74, v75
	global_store_dwordx2 v[76:77], v[86:87], off offset:32
	global_load_dwordx2 v[88:89], v[92:93], off
	v_mul_f32_e32 v73, v73, v73
	global_load_dwordx2 v[86:87], v[90:91], off
	v_lshl_add_u64 v[90:91], s[12:13], 0, v[82:83]
	v_lshl_add_u64 v[82:83], s[20:21], 0, v[82:83]
	v_mul_f32_e32 v75, v75, v75
	v_fmac_f32_e32 v73, v72, v72
	v_fmac_f32_e32 v75, v74, v74
	v_add_f32_e32 v72, v73, v75
	v_add_f32_e32 v72, v78, v72
	s_waitcnt vmcnt(1)
	v_lshlrev_b32_e32 v92, 16, v88
	v_and_b32_e32 v93, 0xffff0000, v88
	v_lshlrev_b32_e32 v88, 16, v89
	v_and_b32_e32 v89, 0xffff0000, v89
	s_waitcnt vmcnt(0)
	v_lshlrev_b32_e32 v94, 16, v86
	v_and_b32_e32 v95, 0xffff0000, v86
	v_lshlrev_b32_e32 v86, 16, v87
	v_and_b32_e32 v87, 0xffff0000, v87
	v_pk_fma_f32 v[70:71], v[70:71], v[86:87], v[88:89]
	v_pk_fma_f32 v[68:69], v[68:69], v[94:95], v[92:93]
	s_nop 0
	v_cvt_pk_bf16_f32 v86, v68, v69
	v_cvt_pk_bf16_f32 v87, v70, v71
	global_store_dwordx2 v[76:77], v[86:87], off offset:256
	global_load_dwordx2 v[88:89], v[90:91], off
	v_mul_f32_e32 v69, v69, v69
	global_load_dwordx2 v[82:83], v[82:83], off
	v_mul_f32_e32 v71, v71, v71
	v_fmac_f32_e32 v69, v68, v68
	v_fmac_f32_e32 v71, v70, v70
	v_add_f32_e32 v68, v69, v71
	v_add_f32_e32 v78, v68, v72
	s_waitcnt vmcnt(1)
	v_lshlrev_b32_e32 v68, 16, v88
	v_and_b32_e32 v69, 0xffff0000, v88
	v_lshlrev_b32_e32 v70, 16, v89
	v_and_b32_e32 v71, 0xffff0000, v89
	s_waitcnt vmcnt(0)
	v_lshlrev_b32_e32 v72, 16, v82
	v_and_b32_e32 v73, 0xffff0000, v82
	v_lshlrev_b32_e32 v74, 16, v83
	v_and_b32_e32 v75, 0xffff0000, v83
	v_pk_fma_f32 v[66:67], v[66:67], v[74:75], v[70:71]
	v_pk_fma_f32 v[64:65], v[64:65], v[72:73], v[68:69]
	v_mul_f32_e32 v69, v67, v67
	v_mul_f32_e32 v68, v65, v65
	v_fmac_f32_e32 v68, v64, v64
	v_fmac_f32_e32 v69, v66, v66
	v_add_f32_e32 v68, v68, v69
	v_add_f32_e32 v68, v78, v68
	ds_swizzle_b32 v69, v68 offset:swizzle(SWAP,16)
	v_cvt_pk_bf16_f32 v64, v64, v65
	v_cvt_pk_bf16_f32 v65, v66, v67
	global_store_dwordx2 v[76:77], v[64:65], off offset:288
	s_waitcnt lgkmcnt(0)
	v_add_f32_e32 v64, v68, v69
	v_mov_b32_e32 v65, v64
	s_nop 1
	v_permlane32_swap_b32_e32 v64, v65
	s_and_saveexec_b64 s[2:3], s[4:5]
	s_cbranch_execz .LBB0_1572
	v_add_f32_e32 v66, v64, v65
	v_lshl_add_u64 v[64:65], s[10:11], 0, v[80:81]
	v_lshl_add_u64 v[64:65], s[36:37], 2, v[64:65]
	s_lshl_b32 s14, s50, 2
	v_lshl_add_u64 v[64:65], v[64:65], 0, s[14:15]
	global_store_dword v[64:65], v66, off
.LBB0_1572:
	s_or_b64 exec, exec, s[2:3]
	v_add_u32_e32 v66, 0x80, v142
	v_ashrrev_i32_e32 v67, 31, v66
	v_lshlrev_b64 v[64:65], 6, v[66:67]
	v_lshl_add_u64 v[80:81], s[18:19], 0, v[64:65]
	v_bfe_u32 v76, v206, 4, 2
	v_lshlrev_b32_e32 v76, 4, v76
	v_mov_b32_e32 v77, 0
	v_lshl_add_u64 v[72:73], v[80:81], 0, v[76:77]
	global_load_dwordx4 v[68:71], v[72:73], off
	s_nop 0
	v_lshlrev_b64 v[66:67], 10, v[66:67]
	v_lshl_add_u64 v[66:67], v[66:67], 0, v[140:141]
	v_lshlrev_b64 v[66:67], 1, v[66:67]
	v_lshl_add_u64 v[84:85], s[20:21], 0, v[66:67]
	v_lshl_add_u64 v[86:87], s[12:13], 0, v[66:67]
	global_load_dwordx2 v[84:85], v[84:85], off
	v_or_b32_e32 v88, 32, v66
	global_load_dwordx2 v[86:87], v[86:87], off
	v_mov_b32_e32 v89, v67
	v_lshl_add_u64 v[90:91], s[12:13], 0, v[88:89]
	s_waitcnt vmcnt(0)
	v_add_f32_e32 v72, v68, v69
	v_add_f32_e32 v73, v70, v71
	v_add_f32_e32 v72, v72, v73
	ds_swizzle_b32 v73, v72 offset:swizzle(SWAP,16)
	s_waitcnt lgkmcnt(0)
	v_add_f32_e32 v72, v72, v73
	v_mov_b32_e32 v73, v72
	s_nop 1
	v_permlane32_swap_b32_e32 v72, v73
	v_add_f32_e32 v80, v72, v73
	v_lshlrev_b32_e32 v74, 16, v85
	v_lshlrev_b32_e32 v70, 16, v84
	v_mov_b32_e32 v68, v80
	v_fmamk_f32 v68, v68, 0x3a800000, v154
	v_mul_f32_e32 v69, 0x4b800000, v68
	v_cmp_gt_f32_e32 vcc, s56, v68
	v_and_b32_e32 v71, 0xffff0000, v84
	v_and_b32_e32 v75, 0xffff0000, v85
	v_cndmask_b32_e32 v68, v68, v69, vcc
	v_rsq_f32_e32 v72, v68
	s_waitcnt vmcnt(0)
	v_lshlrev_b32_e32 v68, 16, v86
	v_and_b32_e32 v69, 0xffff0000, v86
	v_mul_f32_e32 v73, 0x45800000, v72
	v_cndmask_b32_e32 v82, v72, v73, vcc
	v_mul_f32_e32 v60, v60, v82
	v_mul_f32_e32 v61, v61, v82
	v_mul_f32_e32 v62, v62, v82
	v_mul_f32_e32 v63, v63, v82
	v_mul_f32_e32 v60, 0xbfb8aa3b, v60
	v_mul_f32_e32 v61, 0xbfb8aa3b, v61
	v_mul_f32_e32 v62, 0xbfb8aa3b, v62
	v_mul_f32_e32 v63, 0xbfb8aa3b, v63
	v_exp_f32_e32 v60, v60
	v_exp_f32_e32 v61, v61
	v_exp_f32_e32 v62, v62
	v_exp_f32_e32 v63, v63
	v_add_f32_e32 v60, 1.0, v60
	v_add_f32_e32 v61, 1.0, v61
	v_add_f32_e32 v62, 1.0, v62
	v_add_f32_e32 v63, 1.0, v63
	v_rcp_f32_e32 v60, v60
	v_rcp_f32_e32 v61, v61
	v_rcp_f32_e32 v62, v62
	v_rcp_f32_e32 v63, v63
	v_lshlrev_b32_e32 v72, 16, v87
	v_and_b32_e32 v73, 0xffff0000, v87
	v_pk_fma_f32 v[68:69], v[60:61], v[70:71], v[68:69]
	v_lshl_add_u64 v[60:61], s[8:9], 0, v[66:67]
	v_pk_fma_f32 v[62:63], v[62:63], v[74:75], v[72:73]
	v_cvt_pk_bf16_f32 v70, v68, v69
	v_lshl_add_u64 v[74:75], s[20:21], 0, v[88:89]
	v_cvt_pk_bf16_f32 v71, v62, v63
	global_store_dwordx2 v[60:61], v[70:71], off
	global_load_dwordx2 v[72:73], v[90:91], off
	v_mul_f32_e32 v56, v56, v82
	global_load_dwordx2 v[70:71], v[74:75], off
	v_mul_f32_e32 v57, v57, v82
	v_mul_f32_e32 v58, v58, v82
	v_mul_f32_e32 v59, v59, v82
	v_mul_f32_e32 v56, 0xbfb8aa3b, v56
	v_mul_f32_e32 v57, 0xbfb8aa3b, v57
	v_mul_f32_e32 v58, 0xbfb8aa3b, v58
	v_mul_f32_e32 v59, 0xbfb8aa3b, v59
	v_exp_f32_e32 v56, v56
	v_exp_f32_e32 v57, v57
	v_exp_f32_e32 v58, v58
	v_exp_f32_e32 v59, v59
	v_add_f32_e32 v56, 1.0, v56
	v_add_f32_e32 v57, 1.0, v57
	v_add_f32_e32 v58, 1.0, v58
	v_add_f32_e32 v59, 1.0, v59
	v_rcp_f32_e32 v56, v56
	v_rcp_f32_e32 v57, v57
	v_rcp_f32_e32 v58, v58
	v_rcp_f32_e32 v59, v59
	v_or_b32_e32 v74, 0x100, v66
	v_mov_b32_e32 v75, v67
	v_lshl_add_u64 v[76:77], s[12:13], 0, v[74:75]
	v_lshl_add_u64 v[74:75], s[20:21], 0, v[74:75]
	v_mul_f32_e32 v52, v52, v82
	v_mul_f32_e32 v53, v53, v82
	v_mul_f32_e32 v54, v54, v82
	v_mul_f32_e32 v55, v55, v82
	v_mul_f32_e32 v52, 0xbfb8aa3b, v52
	v_mul_f32_e32 v53, 0xbfb8aa3b, v53
	v_mul_f32_e32 v54, 0xbfb8aa3b, v54
	v_mul_f32_e32 v55, 0xbfb8aa3b, v55
	v_exp_f32_e32 v52, v52
	v_exp_f32_e32 v53, v53
	v_exp_f32_e32 v54, v54
	v_exp_f32_e32 v55, v55
	v_add_f32_e32 v52, 1.0, v52
	v_add_f32_e32 v53, 1.0, v53
	v_add_f32_e32 v54, 1.0, v54
	v_add_f32_e32 v55, 1.0, v55
	v_rcp_f32_e32 v52, v52
	v_rcp_f32_e32 v53, v53
	v_rcp_f32_e32 v54, v54
	v_rcp_f32_e32 v55, v55
	v_or_b32_e32 v66, 0x120, v66
	v_mul_f32_e32 v48, v48, v82
	v_mul_f32_e32 v49, v49, v82
	v_mul_f32_e32 v50, v50, v82
	v_mul_f32_e32 v51, v51, v82
	v_mul_f32_e32 v48, 0xbfb8aa3b, v48
	v_mul_f32_e32 v49, 0xbfb8aa3b, v49
	v_mul_f32_e32 v50, 0xbfb8aa3b, v50
	v_mul_f32_e32 v51, 0xbfb8aa3b, v51
	v_exp_f32_e32 v48, v48
	v_exp_f32_e32 v49, v49
	v_exp_f32_e32 v50, v50
	v_exp_f32_e32 v51, v51
	v_add_f32_e32 v48, 1.0, v48
	v_add_f32_e32 v49, 1.0, v49
	v_add_f32_e32 v50, 1.0, v50
	v_add_f32_e32 v51, 1.0, v51
	v_mul_f32_e32 v69, v69, v69
	v_mul_f32_e32 v63, v63, v63
	v_rcp_f32_e32 v48, v48
	v_rcp_f32_e32 v49, v49
	v_rcp_f32_e32 v50, v50
	v_rcp_f32_e32 v51, v51
	v_fmac_f32_e32 v69, v68, v68
	v_fmac_f32_e32 v63, v62, v62
	v_add_f32_e32 v62, v69, v63
	s_waitcnt vmcnt(1)
	v_lshlrev_b32_e32 v78, 16, v72
	v_and_b32_e32 v79, 0xffff0000, v72
	v_lshlrev_b32_e32 v72, 16, v73
	v_and_b32_e32 v73, 0xffff0000, v73
	s_waitcnt vmcnt(0)
	v_lshlrev_b32_e32 v80, 16, v70
	v_and_b32_e32 v81, 0xffff0000, v70
	v_lshlrev_b32_e32 v70, 16, v71
	v_and_b32_e32 v71, 0xffff0000, v71
	v_pk_fma_f32 v[58:59], v[58:59], v[70:71], v[72:73]
	v_pk_fma_f32 v[56:57], v[56:57], v[80:81], v[78:79]
	s_nop 0
	v_cvt_pk_bf16_f32 v70, v56, v57
	v_cvt_pk_bf16_f32 v71, v58, v59
	global_store_dwordx2 v[60:61], v[70:71], off offset:32
	global_load_dwordx2 v[72:73], v[76:77], off
	v_mul_f32_e32 v57, v57, v57
	global_load_dwordx2 v[70:71], v[74:75], off
	v_lshl_add_u64 v[74:75], s[12:13], 0, v[66:67]
	v_lshl_add_u64 v[66:67], s[20:21], 0, v[66:67]
	v_mul_f32_e32 v59, v59, v59
	v_fmac_f32_e32 v57, v56, v56
	v_fmac_f32_e32 v59, v58, v58
	v_add_f32_e32 v56, v57, v59
	v_add_f32_e32 v56, v62, v56
	s_waitcnt vmcnt(1)
	v_lshlrev_b32_e32 v76, 16, v72
	v_and_b32_e32 v77, 0xffff0000, v72
	v_lshlrev_b32_e32 v72, 16, v73
	v_and_b32_e32 v73, 0xffff0000, v73
	s_waitcnt vmcnt(0)
	v_lshlrev_b32_e32 v78, 16, v70
	v_and_b32_e32 v79, 0xffff0000, v70
	v_lshlrev_b32_e32 v70, 16, v71
	v_and_b32_e32 v71, 0xffff0000, v71
	v_pk_fma_f32 v[54:55], v[54:55], v[70:71], v[72:73]
	v_pk_fma_f32 v[52:53], v[52:53], v[78:79], v[76:77]
	s_nop 0
	v_cvt_pk_bf16_f32 v70, v52, v53
	v_cvt_pk_bf16_f32 v71, v54, v55
	global_store_dwordx2 v[60:61], v[70:71], off offset:256
	global_load_dwordx2 v[72:73], v[74:75], off
	v_mul_f32_e32 v53, v53, v53
	global_load_dwordx2 v[66:67], v[66:67], off
	v_mul_f32_e32 v55, v55, v55
	v_fmac_f32_e32 v53, v52, v52
	v_fmac_f32_e32 v55, v54, v54
	v_add_f32_e32 v52, v53, v55
	v_add_f32_e32 v62, v52, v56
	s_waitcnt vmcnt(1)
	v_lshlrev_b32_e32 v52, 16, v72
	v_and_b32_e32 v53, 0xffff0000, v72
	v_lshlrev_b32_e32 v54, 16, v73
	v_and_b32_e32 v55, 0xffff0000, v73
	s_waitcnt vmcnt(0)
	v_lshlrev_b32_e32 v56, 16, v66
	v_and_b32_e32 v57, 0xffff0000, v66
	v_lshlrev_b32_e32 v58, 16, v67
	v_and_b32_e32 v59, 0xffff0000, v67
	v_pk_fma_f32 v[50:51], v[50:51], v[58:59], v[54:55]
	v_pk_fma_f32 v[48:49], v[48:49], v[56:57], v[52:53]
	v_mul_f32_e32 v53, v51, v51
	v_mul_f32_e32 v52, v49, v49
	v_fmac_f32_e32 v52, v48, v48
	v_fmac_f32_e32 v53, v50, v50
	v_add_f32_e32 v52, v52, v53
	v_add_f32_e32 v52, v62, v52
	ds_swizzle_b32 v53, v52 offset:swizzle(SWAP,16)
	v_cvt_pk_bf16_f32 v48, v48, v49
	v_cvt_pk_bf16_f32 v49, v50, v51
	global_store_dwordx2 v[60:61], v[48:49], off offset:288
	s_waitcnt lgkmcnt(0)
	v_add_f32_e32 v48, v52, v53
	v_mov_b32_e32 v49, v48
	s_nop 1
	v_permlane32_swap_b32_e32 v48, v49
	s_and_saveexec_b64 s[2:3], s[4:5]
	s_cbranch_execz .LBB0_1574
	v_add_f32_e32 v50, v48, v49
	v_lshl_add_u64 v[48:49], s[10:11], 0, v[64:65]
	v_lshl_add_u64 v[48:49], s[36:37], 2, v[48:49]
	s_lshl_b32 s14, s50, 2
	v_lshl_add_u64 v[48:49], v[48:49], 0, s[14:15]
	global_store_dword v[48:49], v50, off
.LBB0_1574:
	s_or_b64 exec, exec, s[2:3]
	v_add_u32_e32 v50, 0x90, v142
	v_ashrrev_i32_e32 v51, 31, v50
	v_lshlrev_b64 v[48:49], 6, v[50:51]
	v_lshl_add_u64 v[64:65], s[18:19], 0, v[48:49]
	v_bfe_u32 v60, v206, 4, 2
	v_lshlrev_b32_e32 v60, 4, v60
	v_mov_b32_e32 v61, 0
	v_lshl_add_u64 v[56:57], v[64:65], 0, v[60:61]
	global_load_dwordx4 v[52:55], v[56:57], off
	s_nop 0
	v_lshlrev_b64 v[50:51], 10, v[50:51]
	v_lshl_add_u64 v[50:51], v[50:51], 0, v[140:141]
	v_lshlrev_b64 v[50:51], 1, v[50:51]
	v_lshl_add_u64 v[68:69], s[20:21], 0, v[50:51]
	v_lshl_add_u64 v[70:71], s[12:13], 0, v[50:51]
	global_load_dwordx2 v[68:69], v[68:69], off
	v_or_b32_e32 v72, 32, v50
	global_load_dwordx2 v[70:71], v[70:71], off
	v_mov_b32_e32 v73, v51
	v_lshl_add_u64 v[74:75], s[12:13], 0, v[72:73]
	s_waitcnt vmcnt(0)
	v_add_f32_e32 v56, v52, v53
	v_add_f32_e32 v57, v54, v55
	v_add_f32_e32 v56, v56, v57
	ds_swizzle_b32 v57, v56 offset:swizzle(SWAP,16)
	s_waitcnt lgkmcnt(0)
	v_add_f32_e32 v56, v56, v57
	v_mov_b32_e32 v57, v56
	s_nop 1
	v_permlane32_swap_b32_e32 v56, v57
	v_add_f32_e32 v64, v56, v57
	v_lshlrev_b32_e32 v58, 16, v69
	v_lshlrev_b32_e32 v54, 16, v68
	v_mov_b32_e32 v52, v64
	v_fmamk_f32 v52, v52, 0x3a800000, v154
	v_mul_f32_e32 v53, 0x4b800000, v52
	v_cmp_gt_f32_e32 vcc, s56, v52
	v_and_b32_e32 v55, 0xffff0000, v68
	v_and_b32_e32 v59, 0xffff0000, v69
	v_cndmask_b32_e32 v52, v52, v53, vcc
	v_rsq_f32_e32 v56, v52
	s_waitcnt vmcnt(0)
	v_lshlrev_b32_e32 v52, 16, v70
	v_and_b32_e32 v53, 0xffff0000, v70
	v_mul_f32_e32 v57, 0x45800000, v56
	v_cndmask_b32_e32 v66, v56, v57, vcc
	v_mul_f32_e32 v44, v44, v66
	v_mul_f32_e32 v45, v45, v66
	v_mul_f32_e32 v46, v46, v66
	v_mul_f32_e32 v47, v47, v66
	v_mul_f32_e32 v44, 0xbfb8aa3b, v44
	v_mul_f32_e32 v45, 0xbfb8aa3b, v45
	v_mul_f32_e32 v46, 0xbfb8aa3b, v46
	v_mul_f32_e32 v47, 0xbfb8aa3b, v47
	v_exp_f32_e32 v44, v44
	v_exp_f32_e32 v45, v45
	v_exp_f32_e32 v46, v46
	v_exp_f32_e32 v47, v47
	v_add_f32_e32 v44, 1.0, v44
	v_add_f32_e32 v45, 1.0, v45
	v_add_f32_e32 v46, 1.0, v46
	v_add_f32_e32 v47, 1.0, v47
	v_rcp_f32_e32 v44, v44
	v_rcp_f32_e32 v45, v45
	v_rcp_f32_e32 v46, v46
	v_rcp_f32_e32 v47, v47
	v_lshlrev_b32_e32 v56, 16, v71
	v_and_b32_e32 v57, 0xffff0000, v71
	v_pk_fma_f32 v[52:53], v[44:45], v[54:55], v[52:53]
	v_lshl_add_u64 v[44:45], s[8:9], 0, v[50:51]
	v_pk_fma_f32 v[46:47], v[46:47], v[58:59], v[56:57]
	v_cvt_pk_bf16_f32 v54, v52, v53
	v_lshl_add_u64 v[58:59], s[20:21], 0, v[72:73]
	v_cvt_pk_bf16_f32 v55, v46, v47
	global_store_dwordx2 v[44:45], v[54:55], off
	global_load_dwordx2 v[56:57], v[74:75], off
	v_mul_f32_e32 v40, v40, v66
	global_load_dwordx2 v[54:55], v[58:59], off
	v_mul_f32_e32 v41, v41, v66
	v_mul_f32_e32 v42, v42, v66
	v_mul_f32_e32 v43, v43, v66
	v_mul_f32_e32 v40, 0xbfb8aa3b, v40
	v_mul_f32_e32 v41, 0xbfb8aa3b, v41
	v_mul_f32_e32 v42, 0xbfb8aa3b, v42
	v_mul_f32_e32 v43, 0xbfb8aa3b, v43
	v_exp_f32_e32 v40, v40
	v_exp_f32_e32 v41, v41
	v_exp_f32_e32 v42, v42
	v_exp_f32_e32 v43, v43
	v_add_f32_e32 v40, 1.0, v40
	v_add_f32_e32 v41, 1.0, v41
	v_add_f32_e32 v42, 1.0, v42
	v_add_f32_e32 v43, 1.0, v43
	v_rcp_f32_e32 v40, v40
	v_rcp_f32_e32 v41, v41
	v_rcp_f32_e32 v42, v42
	v_rcp_f32_e32 v43, v43
	v_or_b32_e32 v58, 0x100, v50
	v_mov_b32_e32 v59, v51
	v_lshl_add_u64 v[60:61], s[12:13], 0, v[58:59]
	v_lshl_add_u64 v[58:59], s[20:21], 0, v[58:59]
	v_mul_f32_e32 v36, v36, v66
	v_mul_f32_e32 v37, v37, v66
	v_mul_f32_e32 v38, v38, v66
	v_mul_f32_e32 v39, v39, v66
	v_mul_f32_e32 v36, 0xbfb8aa3b, v36
	v_mul_f32_e32 v37, 0xbfb8aa3b, v37
	v_mul_f32_e32 v38, 0xbfb8aa3b, v38
	v_mul_f32_e32 v39, 0xbfb8aa3b, v39
	v_exp_f32_e32 v36, v36
	v_exp_f32_e32 v37, v37
	v_exp_f32_e32 v38, v38
	v_exp_f32_e32 v39, v39
	v_add_f32_e32 v36, 1.0, v36
	v_add_f32_e32 v37, 1.0, v37
	v_add_f32_e32 v38, 1.0, v38
	v_add_f32_e32 v39, 1.0, v39
	v_rcp_f32_e32 v36, v36
	v_rcp_f32_e32 v37, v37
	v_rcp_f32_e32 v38, v38
	v_rcp_f32_e32 v39, v39
	v_or_b32_e32 v50, 0x120, v50
	v_mul_f32_e32 v32, v32, v66
	v_mul_f32_e32 v33, v33, v66
	v_mul_f32_e32 v34, v34, v66
	v_mul_f32_e32 v35, v35, v66
	v_mul_f32_e32 v32, 0xbfb8aa3b, v32
	v_mul_f32_e32 v33, 0xbfb8aa3b, v33
	v_mul_f32_e32 v34, 0xbfb8aa3b, v34
	v_mul_f32_e32 v35, 0xbfb8aa3b, v35
	v_exp_f32_e32 v32, v32
	v_exp_f32_e32 v33, v33
	v_exp_f32_e32 v34, v34
	v_exp_f32_e32 v35, v35
	v_add_f32_e32 v32, 1.0, v32
	v_add_f32_e32 v33, 1.0, v33
	v_add_f32_e32 v34, 1.0, v34
	v_add_f32_e32 v35, 1.0, v35
	v_mul_f32_e32 v53, v53, v53
	v_mul_f32_e32 v47, v47, v47
	v_rcp_f32_e32 v32, v32
	v_rcp_f32_e32 v33, v33
	v_rcp_f32_e32 v34, v34
	v_rcp_f32_e32 v35, v35
	v_fmac_f32_e32 v53, v52, v52
	v_fmac_f32_e32 v47, v46, v46
	v_add_f32_e32 v46, v53, v47
	s_waitcnt vmcnt(1)
	v_lshlrev_b32_e32 v62, 16, v56
	v_and_b32_e32 v63, 0xffff0000, v56
	v_lshlrev_b32_e32 v56, 16, v57
	v_and_b32_e32 v57, 0xffff0000, v57
	s_waitcnt vmcnt(0)
	v_lshlrev_b32_e32 v64, 16, v54
	v_and_b32_e32 v65, 0xffff0000, v54
	v_lshlrev_b32_e32 v54, 16, v55
	v_and_b32_e32 v55, 0xffff0000, v55
	v_pk_fma_f32 v[42:43], v[42:43], v[54:55], v[56:57]
	v_pk_fma_f32 v[40:41], v[40:41], v[64:65], v[62:63]
	s_nop 0
	v_cvt_pk_bf16_f32 v54, v40, v41
	v_cvt_pk_bf16_f32 v55, v42, v43
	global_store_dwordx2 v[44:45], v[54:55], off offset:32
	global_load_dwordx2 v[56:57], v[60:61], off
	v_mul_f32_e32 v41, v41, v41
	global_load_dwordx2 v[54:55], v[58:59], off
	v_lshl_add_u64 v[58:59], s[12:13], 0, v[50:51]
	v_lshl_add_u64 v[50:51], s[20:21], 0, v[50:51]
	v_mul_f32_e32 v43, v43, v43
	v_fmac_f32_e32 v41, v40, v40
	v_fmac_f32_e32 v43, v42, v42
	v_add_f32_e32 v40, v41, v43
	v_add_f32_e32 v40, v46, v40
	s_waitcnt vmcnt(1)
	v_lshlrev_b32_e32 v60, 16, v56
	v_and_b32_e32 v61, 0xffff0000, v56
	v_lshlrev_b32_e32 v56, 16, v57
	v_and_b32_e32 v57, 0xffff0000, v57
	s_waitcnt vmcnt(0)
	v_lshlrev_b32_e32 v62, 16, v54
	v_and_b32_e32 v63, 0xffff0000, v54
	v_lshlrev_b32_e32 v54, 16, v55
	v_and_b32_e32 v55, 0xffff0000, v55
	v_pk_fma_f32 v[38:39], v[38:39], v[54:55], v[56:57]
	v_pk_fma_f32 v[36:37], v[36:37], v[62:63], v[60:61]
	s_nop 0
	v_cvt_pk_bf16_f32 v54, v36, v37
	v_cvt_pk_bf16_f32 v55, v38, v39
	global_store_dwordx2 v[44:45], v[54:55], off offset:256
	global_load_dwordx2 v[56:57], v[58:59], off
	v_mul_f32_e32 v37, v37, v37
	global_load_dwordx2 v[50:51], v[50:51], off
	v_mul_f32_e32 v39, v39, v39
	v_fmac_f32_e32 v37, v36, v36
	v_fmac_f32_e32 v39, v38, v38
	v_add_f32_e32 v36, v37, v39
	v_add_f32_e32 v46, v36, v40
	s_waitcnt vmcnt(1)
	v_lshlrev_b32_e32 v36, 16, v56
	v_and_b32_e32 v37, 0xffff0000, v56
	v_lshlrev_b32_e32 v38, 16, v57
	v_and_b32_e32 v39, 0xffff0000, v57
	s_waitcnt vmcnt(0)
	v_lshlrev_b32_e32 v40, 16, v50
	v_and_b32_e32 v41, 0xffff0000, v50
	v_lshlrev_b32_e32 v42, 16, v51
	v_and_b32_e32 v43, 0xffff0000, v51
	v_pk_fma_f32 v[34:35], v[34:35], v[42:43], v[38:39]
	v_pk_fma_f32 v[32:33], v[32:33], v[40:41], v[36:37]
	v_mul_f32_e32 v37, v35, v35
	v_mul_f32_e32 v36, v33, v33
	v_fmac_f32_e32 v36, v32, v32
	v_fmac_f32_e32 v37, v34, v34
	v_add_f32_e32 v36, v36, v37
	v_add_f32_e32 v36, v46, v36
	ds_swizzle_b32 v37, v36 offset:swizzle(SWAP,16)
	v_cvt_pk_bf16_f32 v32, v32, v33
	v_cvt_pk_bf16_f32 v33, v34, v35
	global_store_dwordx2 v[44:45], v[32:33], off offset:288
	s_waitcnt lgkmcnt(0)
	v_add_f32_e32 v32, v36, v37
	v_mov_b32_e32 v33, v32
	s_nop 1
	v_permlane32_swap_b32_e32 v32, v33
	s_and_saveexec_b64 s[2:3], s[4:5]
	s_cbranch_execz .LBB0_1576
	v_add_f32_e32 v34, v32, v33
	v_lshl_add_u64 v[32:33], s[10:11], 0, v[48:49]
	v_lshl_add_u64 v[32:33], s[36:37], 2, v[32:33]
	s_lshl_b32 s14, s50, 2
	v_lshl_add_u64 v[32:33], v[32:33], 0, s[14:15]
	global_store_dword v[32:33], v34, off
.LBB0_1576:
	s_or_b64 exec, exec, s[2:3]
	v_add_u32_e32 v34, 0xa0, v142
	v_ashrrev_i32_e32 v35, 31, v34
	v_lshlrev_b64 v[32:33], 6, v[34:35]
	v_lshl_add_u64 v[48:49], s[18:19], 0, v[32:33]
	v_bfe_u32 v44, v206, 4, 2
	v_lshlrev_b32_e32 v44, 4, v44
	v_mov_b32_e32 v45, 0
	v_lshl_add_u64 v[40:41], v[48:49], 0, v[44:45]
	global_load_dwordx4 v[36:39], v[40:41], off
	s_nop 0
	v_lshlrev_b64 v[34:35], 10, v[34:35]
	v_lshl_add_u64 v[34:35], v[34:35], 0, v[140:141]
	v_lshlrev_b64 v[34:35], 1, v[34:35]
	v_lshl_add_u64 v[52:53], s[20:21], 0, v[34:35]
	v_lshl_add_u64 v[54:55], s[12:13], 0, v[34:35]
	global_load_dwordx2 v[52:53], v[52:53], off
	v_or_b32_e32 v56, 32, v34
	global_load_dwordx2 v[54:55], v[54:55], off
	v_mov_b32_e32 v57, v35
	v_lshl_add_u64 v[58:59], s[12:13], 0, v[56:57]
	s_waitcnt vmcnt(0)
	v_add_f32_e32 v40, v36, v37
	v_add_f32_e32 v41, v38, v39
	v_add_f32_e32 v40, v40, v41
	ds_swizzle_b32 v41, v40 offset:swizzle(SWAP,16)
	s_waitcnt lgkmcnt(0)
	v_add_f32_e32 v40, v40, v41
	v_mov_b32_e32 v41, v40
	s_nop 1
	v_permlane32_swap_b32_e32 v40, v41
	v_add_f32_e32 v48, v40, v41
	v_lshlrev_b32_e32 v42, 16, v53
	v_lshlrev_b32_e32 v38, 16, v52
	v_mov_b32_e32 v36, v48
	v_fmamk_f32 v36, v36, 0x3a800000, v154
	v_mul_f32_e32 v37, 0x4b800000, v36
	v_cmp_gt_f32_e32 vcc, s56, v36
	v_and_b32_e32 v39, 0xffff0000, v52
	v_and_b32_e32 v43, 0xffff0000, v53
	v_cndmask_b32_e32 v36, v36, v37, vcc
	v_rsq_f32_e32 v40, v36
	s_waitcnt vmcnt(0)
	v_lshlrev_b32_e32 v36, 16, v54
	v_and_b32_e32 v37, 0xffff0000, v54
	v_mul_f32_e32 v41, 0x45800000, v40
	v_cndmask_b32_e32 v50, v40, v41, vcc
	v_mul_f32_e32 v28, v28, v50
	v_mul_f32_e32 v29, v29, v50
	v_mul_f32_e32 v30, v30, v50
	v_mul_f32_e32 v31, v31, v50
	v_mul_f32_e32 v28, 0xbfb8aa3b, v28
	v_mul_f32_e32 v29, 0xbfb8aa3b, v29
	v_mul_f32_e32 v30, 0xbfb8aa3b, v30
	v_mul_f32_e32 v31, 0xbfb8aa3b, v31
	v_exp_f32_e32 v28, v28
	v_exp_f32_e32 v29, v29
	v_exp_f32_e32 v30, v30
	v_exp_f32_e32 v31, v31
	v_add_f32_e32 v28, 1.0, v28
	v_add_f32_e32 v29, 1.0, v29
	v_add_f32_e32 v30, 1.0, v30
	v_add_f32_e32 v31, 1.0, v31
	v_rcp_f32_e32 v28, v28
	v_rcp_f32_e32 v29, v29
	v_rcp_f32_e32 v30, v30
	v_rcp_f32_e32 v31, v31
	v_lshlrev_b32_e32 v40, 16, v55
	v_and_b32_e32 v41, 0xffff0000, v55
	v_pk_fma_f32 v[36:37], v[28:29], v[38:39], v[36:37]
	v_lshl_add_u64 v[28:29], s[8:9], 0, v[34:35]
	v_pk_fma_f32 v[30:31], v[30:31], v[42:43], v[40:41]
	v_cvt_pk_bf16_f32 v38, v36, v37
	v_lshl_add_u64 v[42:43], s[20:21], 0, v[56:57]
	v_cvt_pk_bf16_f32 v39, v30, v31
	global_store_dwordx2 v[28:29], v[38:39], off
	global_load_dwordx2 v[40:41], v[58:59], off
	v_mul_f32_e32 v24, v24, v50
	global_load_dwordx2 v[38:39], v[42:43], off
	v_mul_f32_e32 v25, v25, v50
	v_mul_f32_e32 v26, v26, v50
	v_mul_f32_e32 v27, v27, v50
	v_mul_f32_e32 v24, 0xbfb8aa3b, v24
	v_mul_f32_e32 v25, 0xbfb8aa3b, v25
	v_mul_f32_e32 v26, 0xbfb8aa3b, v26
	v_mul_f32_e32 v27, 0xbfb8aa3b, v27
	v_exp_f32_e32 v24, v24
	v_exp_f32_e32 v25, v25
	v_exp_f32_e32 v26, v26
	v_exp_f32_e32 v27, v27
	v_add_f32_e32 v24, 1.0, v24
	v_add_f32_e32 v25, 1.0, v25
	v_add_f32_e32 v26, 1.0, v26
	v_add_f32_e32 v27, 1.0, v27
	v_rcp_f32_e32 v24, v24
	v_rcp_f32_e32 v25, v25
	v_rcp_f32_e32 v26, v26
	v_rcp_f32_e32 v27, v27
	v_or_b32_e32 v42, 0x100, v34
	v_mov_b32_e32 v43, v35
	v_lshl_add_u64 v[44:45], s[12:13], 0, v[42:43]
	v_lshl_add_u64 v[42:43], s[20:21], 0, v[42:43]
	v_mul_f32_e32 v20, v20, v50
	v_mul_f32_e32 v21, v21, v50
	v_mul_f32_e32 v22, v22, v50
	v_mul_f32_e32 v23, v23, v50
	v_mul_f32_e32 v20, 0xbfb8aa3b, v20
	v_mul_f32_e32 v21, 0xbfb8aa3b, v21
	v_mul_f32_e32 v22, 0xbfb8aa3b, v22
	v_mul_f32_e32 v23, 0xbfb8aa3b, v23
	v_exp_f32_e32 v20, v20
	v_exp_f32_e32 v21, v21
	v_exp_f32_e32 v22, v22
	v_exp_f32_e32 v23, v23
	v_add_f32_e32 v20, 1.0, v20
	v_add_f32_e32 v21, 1.0, v21
	v_add_f32_e32 v22, 1.0, v22
	v_add_f32_e32 v23, 1.0, v23
	v_rcp_f32_e32 v20, v20
	v_rcp_f32_e32 v21, v21
	v_rcp_f32_e32 v22, v22
	v_rcp_f32_e32 v23, v23
	v_or_b32_e32 v34, 0x120, v34
	v_mul_f32_e32 v16, v16, v50
	v_mul_f32_e32 v17, v17, v50
	v_mul_f32_e32 v18, v18, v50
	v_mul_f32_e32 v19, v19, v50
	v_mul_f32_e32 v16, 0xbfb8aa3b, v16
	v_mul_f32_e32 v17, 0xbfb8aa3b, v17
	v_mul_f32_e32 v18, 0xbfb8aa3b, v18
	v_mul_f32_e32 v19, 0xbfb8aa3b, v19
	v_exp_f32_e32 v16, v16
	v_exp_f32_e32 v17, v17
	v_exp_f32_e32 v18, v18
	v_exp_f32_e32 v19, v19
	v_add_f32_e32 v16, 1.0, v16
	v_add_f32_e32 v17, 1.0, v17
	v_add_f32_e32 v18, 1.0, v18
	v_add_f32_e32 v19, 1.0, v19
	v_mul_f32_e32 v37, v37, v37
	v_mul_f32_e32 v31, v31, v31
	v_rcp_f32_e32 v16, v16
	v_rcp_f32_e32 v17, v17
	v_rcp_f32_e32 v18, v18
	v_rcp_f32_e32 v19, v19
	v_fmac_f32_e32 v37, v36, v36
	v_fmac_f32_e32 v31, v30, v30
	v_add_f32_e32 v30, v37, v31
	s_waitcnt vmcnt(1)
	v_lshlrev_b32_e32 v46, 16, v40
	v_and_b32_e32 v47, 0xffff0000, v40
	v_lshlrev_b32_e32 v40, 16, v41
	v_and_b32_e32 v41, 0xffff0000, v41
	s_waitcnt vmcnt(0)
	v_lshlrev_b32_e32 v48, 16, v38
	v_and_b32_e32 v49, 0xffff0000, v38
	v_lshlrev_b32_e32 v38, 16, v39
	v_and_b32_e32 v39, 0xffff0000, v39
	v_pk_fma_f32 v[26:27], v[26:27], v[38:39], v[40:41]
	v_pk_fma_f32 v[24:25], v[24:25], v[48:49], v[46:47]
	s_nop 0
	v_cvt_pk_bf16_f32 v38, v24, v25
	v_cvt_pk_bf16_f32 v39, v26, v27
	global_store_dwordx2 v[28:29], v[38:39], off offset:32
	global_load_dwordx2 v[40:41], v[44:45], off
	v_mul_f32_e32 v25, v25, v25
	global_load_dwordx2 v[38:39], v[42:43], off
	v_lshl_add_u64 v[42:43], s[12:13], 0, v[34:35]
	v_lshl_add_u64 v[34:35], s[20:21], 0, v[34:35]
	v_mul_f32_e32 v27, v27, v27
	v_fmac_f32_e32 v25, v24, v24
	v_fmac_f32_e32 v27, v26, v26
	v_add_f32_e32 v24, v25, v27
	v_add_f32_e32 v24, v30, v24
	s_waitcnt vmcnt(1)
	v_lshlrev_b32_e32 v44, 16, v40
	v_and_b32_e32 v45, 0xffff0000, v40
	v_lshlrev_b32_e32 v40, 16, v41
	v_and_b32_e32 v41, 0xffff0000, v41
	s_waitcnt vmcnt(0)
	v_lshlrev_b32_e32 v46, 16, v38
	v_and_b32_e32 v47, 0xffff0000, v38
	v_lshlrev_b32_e32 v38, 16, v39
	v_and_b32_e32 v39, 0xffff0000, v39
	v_pk_fma_f32 v[22:23], v[22:23], v[38:39], v[40:41]
	v_pk_fma_f32 v[20:21], v[20:21], v[46:47], v[44:45]
	s_nop 0
	v_cvt_pk_bf16_f32 v38, v20, v21
	v_cvt_pk_bf16_f32 v39, v22, v23
	global_store_dwordx2 v[28:29], v[38:39], off offset:256
	global_load_dwordx2 v[40:41], v[42:43], off
	v_mul_f32_e32 v21, v21, v21
	global_load_dwordx2 v[34:35], v[34:35], off
	v_mul_f32_e32 v23, v23, v23
	v_fmac_f32_e32 v21, v20, v20
	v_fmac_f32_e32 v23, v22, v22
	v_add_f32_e32 v20, v21, v23
	v_add_f32_e32 v30, v20, v24
	s_waitcnt vmcnt(1)
	v_lshlrev_b32_e32 v20, 16, v40
	v_and_b32_e32 v21, 0xffff0000, v40
	v_lshlrev_b32_e32 v22, 16, v41
	v_and_b32_e32 v23, 0xffff0000, v41
	s_waitcnt vmcnt(0)
	v_lshlrev_b32_e32 v24, 16, v34
	v_and_b32_e32 v25, 0xffff0000, v34
	v_lshlrev_b32_e32 v26, 16, v35
	v_and_b32_e32 v27, 0xffff0000, v35
	v_pk_fma_f32 v[18:19], v[18:19], v[26:27], v[22:23]
	v_pk_fma_f32 v[16:17], v[16:17], v[24:25], v[20:21]
	v_mul_f32_e32 v21, v19, v19
	v_mul_f32_e32 v20, v17, v17
	v_fmac_f32_e32 v20, v16, v16
	v_fmac_f32_e32 v21, v18, v18
	v_add_f32_e32 v20, v20, v21
	v_add_f32_e32 v20, v30, v20
	ds_swizzle_b32 v21, v20 offset:swizzle(SWAP,16)
	v_cvt_pk_bf16_f32 v16, v16, v17
	v_cvt_pk_bf16_f32 v17, v18, v19
	global_store_dwordx2 v[28:29], v[16:17], off offset:288
	s_waitcnt lgkmcnt(0)
	v_add_f32_e32 v16, v20, v21
	v_mov_b32_e32 v17, v16
	s_nop 1
	v_permlane32_swap_b32_e32 v16, v17
	s_and_saveexec_b64 s[2:3], s[4:5]
	s_cbranch_execz .LBB0_1578
	v_add_f32_e32 v18, v16, v17
	v_lshl_add_u64 v[16:17], s[10:11], 0, v[32:33]
	v_lshl_add_u64 v[16:17], s[36:37], 2, v[16:17]
	s_lshl_b32 s14, s50, 2
	v_lshl_add_u64 v[16:17], v[16:17], 0, s[14:15]
	global_store_dword v[16:17], v18, off
.LBB0_1578:
	s_or_b64 exec, exec, s[2:3]
	v_add_u32_e32 v18, 0xb0, v142
	v_ashrrev_i32_e32 v19, 31, v18
	v_lshlrev_b64 v[16:17], 6, v[18:19]
	v_lshl_add_u64 v[32:33], s[18:19], 0, v[16:17]
	v_bfe_u32 v28, v206, 4, 2
	v_lshlrev_b32_e32 v28, 4, v28
	v_mov_b32_e32 v29, 0
	v_lshl_add_u64 v[24:25], v[32:33], 0, v[28:29]
	global_load_dwordx4 v[20:23], v[24:25], off
	s_nop 0
	v_lshlrev_b64 v[18:19], 10, v[18:19]
	v_lshl_add_u64 v[18:19], v[18:19], 0, v[140:141]
	v_lshlrev_b64 v[18:19], 1, v[18:19]
	v_lshl_add_u64 v[36:37], s[20:21], 0, v[18:19]
	v_lshl_add_u64 v[38:39], s[12:13], 0, v[18:19]
	global_load_dwordx2 v[36:37], v[36:37], off
	v_or_b32_e32 v40, 32, v18
	global_load_dwordx2 v[38:39], v[38:39], off
	v_mov_b32_e32 v41, v19
	v_lshl_add_u64 v[42:43], s[12:13], 0, v[40:41]
	s_waitcnt vmcnt(0)
	v_add_f32_e32 v24, v20, v21
	v_add_f32_e32 v25, v22, v23
	v_add_f32_e32 v24, v24, v25
	ds_swizzle_b32 v25, v24 offset:swizzle(SWAP,16)
	s_waitcnt lgkmcnt(0)
	v_add_f32_e32 v24, v24, v25
	v_mov_b32_e32 v25, v24
	s_nop 1
	v_permlane32_swap_b32_e32 v24, v25
	v_add_f32_e32 v32, v24, v25
	v_lshlrev_b32_e32 v26, 16, v37
	v_lshlrev_b32_e32 v22, 16, v36
	v_mov_b32_e32 v20, v32
	v_fmamk_f32 v20, v20, 0x3a800000, v154
	v_mul_f32_e32 v21, 0x4b800000, v20
	v_cmp_gt_f32_e32 vcc, s56, v20
	v_and_b32_e32 v23, 0xffff0000, v36
	v_and_b32_e32 v27, 0xffff0000, v37
	v_cndmask_b32_e32 v20, v20, v21, vcc
	v_rsq_f32_e32 v24, v20
	s_waitcnt vmcnt(0)
	v_lshlrev_b32_e32 v20, 16, v38
	v_and_b32_e32 v21, 0xffff0000, v38
	v_mul_f32_e32 v25, 0x45800000, v24
	v_cndmask_b32_e32 v34, v24, v25, vcc
	v_mul_f32_e32 v12, v12, v34
	v_mul_f32_e32 v13, v13, v34
	v_mul_f32_e32 v14, v14, v34
	v_mul_f32_e32 v15, v15, v34
	v_mul_f32_e32 v12, 0xbfb8aa3b, v12
	v_mul_f32_e32 v13, 0xbfb8aa3b, v13
	v_mul_f32_e32 v14, 0xbfb8aa3b, v14
	v_mul_f32_e32 v15, 0xbfb8aa3b, v15
	v_exp_f32_e32 v12, v12
	v_exp_f32_e32 v13, v13
	v_exp_f32_e32 v14, v14
	v_exp_f32_e32 v15, v15
	v_add_f32_e32 v12, 1.0, v12
	v_add_f32_e32 v13, 1.0, v13
	v_add_f32_e32 v14, 1.0, v14
	v_add_f32_e32 v15, 1.0, v15
	v_rcp_f32_e32 v12, v12
	v_rcp_f32_e32 v13, v13
	v_rcp_f32_e32 v14, v14
	v_rcp_f32_e32 v15, v15
	v_lshlrev_b32_e32 v24, 16, v39
	v_and_b32_e32 v25, 0xffff0000, v39
	v_pk_fma_f32 v[20:21], v[12:13], v[22:23], v[20:21]
	v_lshl_add_u64 v[12:13], s[8:9], 0, v[18:19]
	v_pk_fma_f32 v[14:15], v[14:15], v[26:27], v[24:25]
	v_cvt_pk_bf16_f32 v22, v20, v21
	v_lshl_add_u64 v[26:27], s[20:21], 0, v[40:41]
	v_cvt_pk_bf16_f32 v23, v14, v15
	global_store_dwordx2 v[12:13], v[22:23], off
	global_load_dwordx2 v[24:25], v[42:43], off
	v_mul_f32_e32 v8, v8, v34
	global_load_dwordx2 v[22:23], v[26:27], off
	v_mul_f32_e32 v9, v9, v34
	v_mul_f32_e32 v10, v10, v34
	v_mul_f32_e32 v11, v11, v34
	v_mul_f32_e32 v8, 0xbfb8aa3b, v8
	v_mul_f32_e32 v9, 0xbfb8aa3b, v9
	v_mul_f32_e32 v10, 0xbfb8aa3b, v10
	v_mul_f32_e32 v11, 0xbfb8aa3b, v11
	v_exp_f32_e32 v8, v8
	v_exp_f32_e32 v9, v9
	v_exp_f32_e32 v10, v10
	v_exp_f32_e32 v11, v11
	v_add_f32_e32 v8, 1.0, v8
	v_add_f32_e32 v9, 1.0, v9
	v_add_f32_e32 v10, 1.0, v10
	v_add_f32_e32 v11, 1.0, v11
	v_rcp_f32_e32 v8, v8
	v_rcp_f32_e32 v9, v9
	v_rcp_f32_e32 v10, v10
	v_rcp_f32_e32 v11, v11
	v_or_b32_e32 v26, 0x100, v18
	v_mov_b32_e32 v27, v19
	v_lshl_add_u64 v[28:29], s[12:13], 0, v[26:27]
	v_lshl_add_u64 v[26:27], s[20:21], 0, v[26:27]
	v_mul_f32_e32 v4, v4, v34
	v_mul_f32_e32 v5, v5, v34
	v_mul_f32_e32 v6, v6, v34
	v_mul_f32_e32 v7, v7, v34
	v_mul_f32_e32 v4, 0xbfb8aa3b, v4
	v_mul_f32_e32 v5, 0xbfb8aa3b, v5
	v_mul_f32_e32 v6, 0xbfb8aa3b, v6
	v_mul_f32_e32 v7, 0xbfb8aa3b, v7
	v_exp_f32_e32 v4, v4
	v_exp_f32_e32 v5, v5
	v_exp_f32_e32 v6, v6
	v_exp_f32_e32 v7, v7
	v_add_f32_e32 v4, 1.0, v4
	v_add_f32_e32 v5, 1.0, v5
	v_add_f32_e32 v6, 1.0, v6
	v_add_f32_e32 v7, 1.0, v7
	v_rcp_f32_e32 v4, v4
	v_rcp_f32_e32 v5, v5
	v_rcp_f32_e32 v6, v6
	v_rcp_f32_e32 v7, v7
	v_or_b32_e32 v18, 0x120, v18
	v_mul_f32_e32 v0, v0, v34
	v_mul_f32_e32 v1, v1, v34
	v_mul_f32_e32 v2, v2, v34
	v_mul_f32_e32 v3, v3, v34
	v_mul_f32_e32 v0, 0xbfb8aa3b, v0
	v_mul_f32_e32 v1, 0xbfb8aa3b, v1
	v_mul_f32_e32 v2, 0xbfb8aa3b, v2
	v_mul_f32_e32 v3, 0xbfb8aa3b, v3
	v_exp_f32_e32 v0, v0
	v_exp_f32_e32 v1, v1
	v_exp_f32_e32 v2, v2
	v_exp_f32_e32 v3, v3
	v_add_f32_e32 v0, 1.0, v0
	v_add_f32_e32 v1, 1.0, v1
	v_add_f32_e32 v2, 1.0, v2
	v_add_f32_e32 v3, 1.0, v3
	v_mul_f32_e32 v21, v21, v21
	v_mul_f32_e32 v15, v15, v15
	v_rcp_f32_e32 v0, v0
	v_rcp_f32_e32 v1, v1
	v_rcp_f32_e32 v2, v2
	v_rcp_f32_e32 v3, v3
	v_fmac_f32_e32 v21, v20, v20
	v_fmac_f32_e32 v15, v14, v14
	v_add_f32_e32 v14, v21, v15
	s_waitcnt vmcnt(1)
	v_lshlrev_b32_e32 v30, 16, v24
	v_and_b32_e32 v31, 0xffff0000, v24
	v_lshlrev_b32_e32 v24, 16, v25
	v_and_b32_e32 v25, 0xffff0000, v25
	s_waitcnt vmcnt(0)
	v_lshlrev_b32_e32 v32, 16, v22
	v_and_b32_e32 v33, 0xffff0000, v22
	v_lshlrev_b32_e32 v22, 16, v23
	v_and_b32_e32 v23, 0xffff0000, v23
	v_pk_fma_f32 v[10:11], v[10:11], v[22:23], v[24:25]
	v_pk_fma_f32 v[8:9], v[8:9], v[32:33], v[30:31]
	s_nop 0
	v_cvt_pk_bf16_f32 v22, v8, v9
	v_cvt_pk_bf16_f32 v23, v10, v11
	global_store_dwordx2 v[12:13], v[22:23], off offset:32
	global_load_dwordx2 v[24:25], v[28:29], off
	v_mul_f32_e32 v9, v9, v9
	global_load_dwordx2 v[22:23], v[26:27], off
	v_lshl_add_u64 v[26:27], s[12:13], 0, v[18:19]
	v_lshl_add_u64 v[18:19], s[20:21], 0, v[18:19]
	v_mul_f32_e32 v11, v11, v11
	v_fmac_f32_e32 v9, v8, v8
	v_fmac_f32_e32 v11, v10, v10
	v_add_f32_e32 v8, v9, v11
	v_add_f32_e32 v8, v14, v8
	s_waitcnt vmcnt(1)
	v_lshlrev_b32_e32 v28, 16, v24
	v_and_b32_e32 v29, 0xffff0000, v24
	v_lshlrev_b32_e32 v24, 16, v25
	v_and_b32_e32 v25, 0xffff0000, v25
	s_waitcnt vmcnt(0)
	v_lshlrev_b32_e32 v30, 16, v22
	v_and_b32_e32 v31, 0xffff0000, v22
	v_lshlrev_b32_e32 v22, 16, v23
	v_and_b32_e32 v23, 0xffff0000, v23
	v_pk_fma_f32 v[6:7], v[6:7], v[22:23], v[24:25]
	v_pk_fma_f32 v[4:5], v[4:5], v[30:31], v[28:29]
	s_nop 0
	v_cvt_pk_bf16_f32 v22, v4, v5
	v_cvt_pk_bf16_f32 v23, v6, v7
	global_store_dwordx2 v[12:13], v[22:23], off offset:256
	global_load_dwordx2 v[24:25], v[26:27], off
	v_mul_f32_e32 v5, v5, v5
	global_load_dwordx2 v[18:19], v[18:19], off
	v_mul_f32_e32 v7, v7, v7
	v_fmac_f32_e32 v5, v4, v4
	v_fmac_f32_e32 v7, v6, v6
	v_add_f32_e32 v4, v5, v7
	v_add_f32_e32 v14, v4, v8
	s_waitcnt vmcnt(1)
	v_lshlrev_b32_e32 v4, 16, v24
	v_and_b32_e32 v5, 0xffff0000, v24
	v_lshlrev_b32_e32 v6, 16, v25
	v_and_b32_e32 v7, 0xffff0000, v25
	s_waitcnt vmcnt(0)
	v_lshlrev_b32_e32 v8, 16, v18
	v_and_b32_e32 v9, 0xffff0000, v18
	v_lshlrev_b32_e32 v10, 16, v19
	v_and_b32_e32 v11, 0xffff0000, v19
	v_pk_fma_f32 v[2:3], v[2:3], v[10:11], v[6:7]
	v_pk_fma_f32 v[0:1], v[0:1], v[8:9], v[4:5]
	v_mul_f32_e32 v5, v3, v3
	v_mul_f32_e32 v4, v1, v1
	v_fmac_f32_e32 v4, v0, v0
	v_fmac_f32_e32 v5, v2, v2
	v_add_f32_e32 v4, v4, v5
	v_add_f32_e32 v4, v14, v4
	ds_swizzle_b32 v5, v4 offset:swizzle(SWAP,16)
	v_cvt_pk_bf16_f32 v0, v0, v1
	v_cvt_pk_bf16_f32 v1, v2, v3
	global_store_dwordx2 v[12:13], v[0:1], off offset:288
	s_waitcnt lgkmcnt(0)
	v_add_f32_e32 v0, v4, v5
	v_mov_b32_e32 v1, v0
	s_nop 1
	v_permlane32_swap_b32_e32 v0, v1
	s_and_saveexec_b64 s[2:3], s[4:5]
	s_cbranch_execz .LBB0_1580
	v_add_f32_e32 v2, v0, v1
	v_lshl_add_u64 v[0:1], s[10:11], 0, v[16:17]
	v_lshl_add_u64 v[0:1], s[36:37], 2, v[0:1]
	s_lshl_b32 s14, s50, 2
	v_lshl_add_u64 v[0:1], v[0:1], 0, s[14:15]
	global_store_dword v[0:1], v2, off

.LBB0_1649:
	v_lshl_add_u32 v146, s6, 8, v148
	v_ashrrev_i32_e32 v147, 31, v146
	v_lshlrev_b64 v[144:145], 6, v[146:147]
	v_lshl_add_u64 v[144:145], s[10:11], 0, v[144:145]
	v_bfe_u32 v164, v206, 4, 2
	v_lshlrev_b32_e32 v164, 4, v164
	v_mov_b32_e32 v165, 0
	v_lshl_add_u64 v[160:161], v[144:145], 0, v[164:165]
	global_load_dwordx4 v[156:159], v[160:161], off
	v_or_b32_e32 v172, 16, v146
	v_ashrrev_i32_e32 v173, 31, v172
	s_lshr_b32 s17, s7, 31
	v_lshlrev_b64 v[144:145], 6, v[172:173]
	s_add_i32 s17, s7, s17
	v_lshl_add_u64 v[176:177], s[10:11], 0, v[144:145]
	s_ashr_i32 s24, s17, 1
	s_ashr_i32 s25, s24, 31
	s_lshl_b32 s6, s7, 8
	s_lshl_b64 s[26:27], s[24:25], 25
	s_add_u32 s26, s43, s26
	s_addc_u32 s27, s44, s27
	s_lshl_b32 s17, s24, 9
	s_lshl_b32 s7, 1, s7
	s_sub_i32 s6, s6, s17
	s_and_b32 s7, s7, 0xc3
	s_cmp_eq_u32 s7, 0
	v_or_b32_e32 v144, s6, v150
	s_cselect_b64 s[6:7], -1, 0
	v_lshlrev_b64 v[174:175], 10, v[146:147]
	v_cndmask_b32_e64 v147, v155, 1.0, s[6:7]
	s_waitcnt vmcnt(0)
	v_add_f32_e32 v160, v156, v157
	v_add_f32_e32 v161, v158, v159
	v_add_f32_e32 v160, v160, v161
	ds_swizzle_b32 v161, v160 offset:swizzle(SWAP,16)
	s_waitcnt lgkmcnt(0)
	v_add_f32_e32 v160, v160, v161
	v_mov_b32_e32 v161, v160
	s_nop 1
	v_permlane32_swap_b32_e32 v160, v161
	v_add_f32_e32 v168, v160, v161
	s_nop 0
	s_nop 0
	v_mov_b32_e32 v145, v168
	v_fmamk_f32 v145, v145, 0x3a800000, v154
	v_mul_f32_e32 v156, 0x4b800000, v145
	v_cmp_gt_f32_e32 vcc, s49, v145
	s_nop 1
	v_cndmask_b32_e32 v145, v145, v156, vcc
	v_rsq_f32_e32 v158, v145
	v_ashrrev_i32_e32 v145, 31, v144
	v_lshl_add_u64 v[144:145], v[144:145], 1, s[26:27]
	v_lshl_add_u64 v[156:157], v[144:145], 0, v[174:175]
	v_mul_f32_e32 v159, 0x45800000, v158
	v_cndmask_b32_e32 v158, v158, v159, vcc
	v_mul_f32_e32 v158, v147, v158
	v_pk_mul_f32 v[126:127], v[126:127], v[158:159] op_sel_hi:[1,0]
	v_pk_mul_f32 v[124:125], v[124:125], v[158:159] op_sel_hi:[1,0]
	v_pk_mul_f32 v[122:123], v[122:123], v[158:159] op_sel_hi:[1,0]
	v_pk_mul_f32 v[120:121], v[120:121], v[158:159] op_sel_hi:[1,0]
	v_pk_mul_f32 v[118:119], v[118:119], v[158:159] op_sel_hi:[1,0]
	v_pk_mul_f32 v[116:117], v[116:117], v[158:159] op_sel_hi:[1,0]
	v_pk_mul_f32 v[160:161], v[114:115], v[158:159] op_sel_hi:[1,0]
	v_pk_mul_f32 v[158:159], v[112:113], v[158:159] op_sel_hi:[1,0]
	v_cvt_pk_bf16_f32 v112, v124, v125
	v_cvt_pk_bf16_f32 v113, v126, v127
	v_cvt_pk_bf16_f32 v114, v120, v121
	v_cvt_pk_bf16_f32 v115, v122, v123
	global_store_dwordx4 v[156:157], v[112:115], off
	s_nop 1
	v_cvt_pk_bf16_f32 v112, v116, v117
	v_cvt_pk_bf16_f32 v113, v118, v119
	v_cvt_pk_bf16_f32 v114, v158, v159
	v_cvt_pk_bf16_f32 v115, v160, v161
	global_store_dwordx4 v[156:157], v[112:115], off offset:256
	v_bfe_u32 v120, v206, 4, 2
	v_lshlrev_b32_e32 v120, 4, v120
	v_mov_b32_e32 v121, 0
	v_lshl_add_u64 v[116:117], v[176:177], 0, v[120:121]
	global_load_dwordx4 v[112:115], v[116:117], off
	s_nop 0
	v_or_b32_e32 v156, 32, v146
	v_ashrrev_i32_e32 v157, 31, v156
	v_lshlrev_b64 v[158:159], 10, v[172:173]
	s_waitcnt vmcnt(0)
	v_add_f32_e32 v116, v112, v113
	v_add_f32_e32 v117, v114, v115
	v_add_f32_e32 v116, v116, v117
	ds_swizzle_b32 v117, v116 offset:swizzle(SWAP,16)
	s_waitcnt lgkmcnt(0)
	v_add_f32_e32 v116, v116, v117
	v_mov_b32_e32 v117, v116
	s_nop 1
	v_permlane32_swap_b32_e32 v116, v117
	v_add_f32_e32 v124, v116, v117
	s_nop 0
	v_lshl_add_u64 v[114:115], v[144:145], 0, v[158:159]
	v_mov_b32_e32 v112, v124
	v_fmamk_f32 v112, v112, 0x3a800000, v154
	v_mul_f32_e32 v113, 0x4b800000, v112
	v_cmp_gt_f32_e32 vcc, s49, v112
	s_nop 1
	v_cndmask_b32_e32 v112, v112, v113, vcc
	v_rsq_f32_e32 v116, v112
	v_lshlrev_b64 v[112:113], 6, v[156:157]
	v_lshl_add_u64 v[112:113], s[10:11], 0, v[112:113]
	v_mul_f32_e32 v117, 0x45800000, v116
	v_cndmask_b32_e32 v116, v116, v117, vcc
	v_mul_f32_e32 v116, v147, v116
	v_pk_mul_f32 v[110:111], v[110:111], v[116:117] op_sel_hi:[1,0]
	v_pk_mul_f32 v[108:109], v[108:109], v[116:117] op_sel_hi:[1,0]
	v_pk_mul_f32 v[106:107], v[106:107], v[116:117] op_sel_hi:[1,0]
	v_pk_mul_f32 v[104:105], v[104:105], v[116:117] op_sel_hi:[1,0]
	v_pk_mul_f32 v[102:103], v[102:103], v[116:117] op_sel_hi:[1,0]
	v_pk_mul_f32 v[100:101], v[100:101], v[116:117] op_sel_hi:[1,0]
	v_pk_mul_f32 v[118:119], v[98:99], v[116:117] op_sel_hi:[1,0]
	v_pk_mul_f32 v[116:117], v[96:97], v[116:117] op_sel_hi:[1,0]
	v_cvt_pk_bf16_f32 v96, v108, v109
	v_cvt_pk_bf16_f32 v97, v110, v111
	v_cvt_pk_bf16_f32 v98, v104, v105
	v_cvt_pk_bf16_f32 v99, v106, v107
	global_store_dwordx4 v[114:115], v[96:99], off
	s_nop 1
	v_cvt_pk_bf16_f32 v96, v100, v101
	v_cvt_pk_bf16_f32 v97, v102, v103
	v_cvt_pk_bf16_f32 v98, v116, v117
	v_cvt_pk_bf16_f32 v99, v118, v119
	global_store_dwordx4 v[114:115], v[96:99], off offset:256
	v_bfe_u32 v104, v206, 4, 2
	v_lshlrev_b32_e32 v104, 4, v104
	v_mov_b32_e32 v105, 0
	v_lshl_add_u64 v[100:101], v[112:113], 0, v[104:105]
	global_load_dwordx4 v[96:99], v[100:101], off
	s_nop 0
	v_or_b32_e32 v112, 48, v146
	v_ashrrev_i32_e32 v113, 31, v112
	v_lshlrev_b64 v[114:115], 10, v[156:157]
	s_waitcnt vmcnt(0)
	v_add_f32_e32 v100, v96, v97
	v_add_f32_e32 v101, v98, v99
	v_add_f32_e32 v100, v100, v101
	ds_swizzle_b32 v101, v100 offset:swizzle(SWAP,16)
	s_waitcnt lgkmcnt(0)
	v_add_f32_e32 v100, v100, v101
	v_mov_b32_e32 v101, v100
	s_nop 1
	v_permlane32_swap_b32_e32 v100, v101
	v_add_f32_e32 v108, v100, v101
	s_nop 0
	v_lshl_add_u64 v[98:99], v[144:145], 0, v[114:115]
	v_mov_b32_e32 v96, v108
	v_fmamk_f32 v96, v96, 0x3a800000, v154
	v_mul_f32_e32 v97, 0x4b800000, v96
	v_cmp_gt_f32_e32 vcc, s49, v96
	s_nop 1
	v_cndmask_b32_e32 v96, v96, v97, vcc
	v_rsq_f32_e32 v100, v96
	v_lshlrev_b64 v[96:97], 6, v[112:113]
	v_lshl_add_u64 v[96:97], s[10:11], 0, v[96:97]
	v_mul_f32_e32 v101, 0x45800000, v100
	v_cndmask_b32_e32 v100, v100, v101, vcc
	v_mul_f32_e32 v100, v147, v100
	v_pk_mul_f32 v[94:95], v[94:95], v[100:101] op_sel_hi:[1,0]
	v_pk_mul_f32 v[92:93], v[92:93], v[100:101] op_sel_hi:[1,0]
	v_pk_mul_f32 v[90:91], v[90:91], v[100:101] op_sel_hi:[1,0]
	v_pk_mul_f32 v[88:89], v[88:89], v[100:101] op_sel_hi:[1,0]
	v_pk_mul_f32 v[86:87], v[86:87], v[100:101] op_sel_hi:[1,0]
	v_pk_mul_f32 v[84:85], v[84:85], v[100:101] op_sel_hi:[1,0]
	v_pk_mul_f32 v[102:103], v[82:83], v[100:101] op_sel_hi:[1,0]
	v_pk_mul_f32 v[100:101], v[80:81], v[100:101] op_sel_hi:[1,0]
	v_cvt_pk_bf16_f32 v80, v92, v93
	v_cvt_pk_bf16_f32 v81, v94, v95
	v_cvt_pk_bf16_f32 v82, v88, v89
	v_cvt_pk_bf16_f32 v83, v90, v91
	global_store_dwordx4 v[98:99], v[80:83], off
	s_nop 1
	v_cvt_pk_bf16_f32 v80, v84, v85
	v_cvt_pk_bf16_f32 v81, v86, v87
	v_cvt_pk_bf16_f32 v82, v100, v101
	v_cvt_pk_bf16_f32 v83, v102, v103
	global_store_dwordx4 v[98:99], v[80:83], off offset:256
	v_bfe_u32 v88, v206, 4, 2
	v_lshlrev_b32_e32 v88, 4, v88
	v_mov_b32_e32 v89, 0
	v_lshl_add_u64 v[84:85], v[96:97], 0, v[88:89]
	global_load_dwordx4 v[80:83], v[84:85], off
	s_nop 0
	v_add_u32_e32 v96, 0x80, v146
	v_ashrrev_i32_e32 v97, 31, v96
	v_lshlrev_b64 v[98:99], 10, v[112:113]
	s_waitcnt vmcnt(0)
	v_add_f32_e32 v84, v80, v81
	v_add_f32_e32 v85, v82, v83
	v_add_f32_e32 v84, v84, v85
	ds_swizzle_b32 v85, v84 offset:swizzle(SWAP,16)
	s_waitcnt lgkmcnt(0)
	v_add_f32_e32 v84, v84, v85
	v_mov_b32_e32 v85, v84
	s_nop 1
	v_permlane32_swap_b32_e32 v84, v85
	v_add_f32_e32 v92, v84, v85
	s_nop 0
	v_lshl_add_u64 v[82:83], v[144:145], 0, v[98:99]
	v_mov_b32_e32 v80, v92
	v_fmamk_f32 v80, v80, 0x3a800000, v154
	v_mul_f32_e32 v81, 0x4b800000, v80
	v_cmp_gt_f32_e32 vcc, s49, v80
	s_nop 1
	v_cndmask_b32_e32 v80, v80, v81, vcc
	v_rsq_f32_e32 v84, v80
	v_lshlrev_b64 v[80:81], 6, v[96:97]
	v_lshl_add_u64 v[80:81], s[10:11], 0, v[80:81]
	v_mul_f32_e32 v85, 0x45800000, v84
	v_cndmask_b32_e32 v84, v84, v85, vcc
	v_mul_f32_e32 v84, v147, v84
	v_pk_mul_f32 v[78:79], v[78:79], v[84:85] op_sel_hi:[1,0]
	v_pk_mul_f32 v[76:77], v[76:77], v[84:85] op_sel_hi:[1,0]
	v_pk_mul_f32 v[74:75], v[74:75], v[84:85] op_sel_hi:[1,0]
	v_pk_mul_f32 v[72:73], v[72:73], v[84:85] op_sel_hi:[1,0]
	v_pk_mul_f32 v[70:71], v[70:71], v[84:85] op_sel_hi:[1,0]
	v_pk_mul_f32 v[68:69], v[68:69], v[84:85] op_sel_hi:[1,0]
	v_pk_mul_f32 v[86:87], v[66:67], v[84:85] op_sel_hi:[1,0]
	v_pk_mul_f32 v[84:85], v[64:65], v[84:85] op_sel_hi:[1,0]
	v_cvt_pk_bf16_f32 v64, v76, v77
	v_cvt_pk_bf16_f32 v65, v78, v79
	v_cvt_pk_bf16_f32 v66, v72, v73
	v_cvt_pk_bf16_f32 v67, v74, v75
	global_store_dwordx4 v[82:83], v[64:67], off
	s_nop 1
	v_cvt_pk_bf16_f32 v64, v68, v69
	v_cvt_pk_bf16_f32 v65, v70, v71
	v_cvt_pk_bf16_f32 v66, v84, v85
	v_cvt_pk_bf16_f32 v67, v86, v87
	global_store_dwordx4 v[82:83], v[64:67], off offset:256
	v_bfe_u32 v72, v206, 4, 2
	v_lshlrev_b32_e32 v72, 4, v72
	v_mov_b32_e32 v73, 0
	v_lshl_add_u64 v[68:69], v[80:81], 0, v[72:73]
	global_load_dwordx4 v[64:67], v[68:69], off
	s_nop 0
	v_add_u32_e32 v80, 0x90, v146
	v_ashrrev_i32_e32 v81, 31, v80
	v_lshlrev_b64 v[82:83], 10, v[96:97]
	s_waitcnt vmcnt(0)
	v_add_f32_e32 v68, v64, v65
	v_add_f32_e32 v69, v66, v67
	v_add_f32_e32 v68, v68, v69
	ds_swizzle_b32 v69, v68 offset:swizzle(SWAP,16)
	s_waitcnt lgkmcnt(0)
	v_add_f32_e32 v68, v68, v69
	v_mov_b32_e32 v69, v68
	s_nop 1
	v_permlane32_swap_b32_e32 v68, v69
	v_add_f32_e32 v76, v68, v69
	s_nop 0
	v_lshl_add_u64 v[66:67], v[144:145], 0, v[82:83]
	v_mov_b32_e32 v64, v76
	v_fmamk_f32 v64, v64, 0x3a800000, v154
	v_mul_f32_e32 v65, 0x4b800000, v64
	v_cmp_gt_f32_e32 vcc, s49, v64
	s_nop 1
	v_cndmask_b32_e32 v64, v64, v65, vcc
	v_rsq_f32_e32 v68, v64
	v_lshlrev_b64 v[64:65], 6, v[80:81]
	v_lshl_add_u64 v[64:65], s[10:11], 0, v[64:65]
	v_mul_f32_e32 v69, 0x45800000, v68
	v_cndmask_b32_e32 v68, v68, v69, vcc
	v_mul_f32_e32 v68, v147, v68
	v_pk_mul_f32 v[62:63], v[62:63], v[68:69] op_sel_hi:[1,0]
	v_pk_mul_f32 v[60:61], v[60:61], v[68:69] op_sel_hi:[1,0]
	v_pk_mul_f32 v[58:59], v[58:59], v[68:69] op_sel_hi:[1,0]
	v_pk_mul_f32 v[56:57], v[56:57], v[68:69] op_sel_hi:[1,0]
	v_pk_mul_f32 v[54:55], v[54:55], v[68:69] op_sel_hi:[1,0]
	v_pk_mul_f32 v[52:53], v[52:53], v[68:69] op_sel_hi:[1,0]
	v_pk_mul_f32 v[70:71], v[50:51], v[68:69] op_sel_hi:[1,0]
	v_pk_mul_f32 v[68:69], v[48:49], v[68:69] op_sel_hi:[1,0]
	v_cvt_pk_bf16_f32 v48, v60, v61
	v_cvt_pk_bf16_f32 v49, v62, v63
	v_cvt_pk_bf16_f32 v50, v56, v57
	v_cvt_pk_bf16_f32 v51, v58, v59
	global_store_dwordx4 v[66:67], v[48:51], off
	s_nop 1
	v_cvt_pk_bf16_f32 v48, v52, v53
	v_cvt_pk_bf16_f32 v49, v54, v55
	v_cvt_pk_bf16_f32 v50, v68, v69
	v_cvt_pk_bf16_f32 v51, v70, v71
	global_store_dwordx4 v[66:67], v[48:51], off offset:256
	v_bfe_u32 v56, v206, 4, 2
	v_lshlrev_b32_e32 v56, 4, v56
	v_mov_b32_e32 v57, 0
	v_lshl_add_u64 v[52:53], v[64:65], 0, v[56:57]
	global_load_dwordx4 v[48:51], v[52:53], off
	s_nop 0
	v_add_u32_e32 v64, 0xa0, v146
	v_ashrrev_i32_e32 v65, 31, v64
	v_lshlrev_b64 v[66:67], 10, v[80:81]
	s_waitcnt vmcnt(0)
	v_add_f32_e32 v52, v48, v49
	v_add_f32_e32 v53, v50, v51
	v_add_f32_e32 v52, v52, v53
	ds_swizzle_b32 v53, v52 offset:swizzle(SWAP,16)
	s_waitcnt lgkmcnt(0)
	v_add_f32_e32 v52, v52, v53
	v_mov_b32_e32 v53, v52
	s_nop 1
	v_permlane32_swap_b32_e32 v52, v53
	v_add_f32_e32 v60, v52, v53
	s_nop 0
	v_lshl_add_u64 v[50:51], v[144:145], 0, v[66:67]
	v_mov_b32_e32 v48, v60
	v_fmamk_f32 v48, v48, 0x3a800000, v154
	v_mul_f32_e32 v49, 0x4b800000, v48
	v_cmp_gt_f32_e32 vcc, s49, v48
	s_nop 1
	v_cndmask_b32_e32 v48, v48, v49, vcc
	v_rsq_f32_e32 v52, v48
	v_lshlrev_b64 v[48:49], 6, v[64:65]
	v_lshl_add_u64 v[48:49], s[10:11], 0, v[48:49]
	v_mul_f32_e32 v53, 0x45800000, v52
	v_cndmask_b32_e32 v52, v52, v53, vcc
	v_mul_f32_e32 v52, v147, v52
	v_pk_mul_f32 v[46:47], v[46:47], v[52:53] op_sel_hi:[1,0]
	v_pk_mul_f32 v[44:45], v[44:45], v[52:53] op_sel_hi:[1,0]
	v_pk_mul_f32 v[42:43], v[42:43], v[52:53] op_sel_hi:[1,0]
	v_pk_mul_f32 v[40:41], v[40:41], v[52:53] op_sel_hi:[1,0]
	v_pk_mul_f32 v[38:39], v[38:39], v[52:53] op_sel_hi:[1,0]
	v_pk_mul_f32 v[36:37], v[36:37], v[52:53] op_sel_hi:[1,0]
	v_pk_mul_f32 v[54:55], v[34:35], v[52:53] op_sel_hi:[1,0]
	v_pk_mul_f32 v[52:53], v[32:33], v[52:53] op_sel_hi:[1,0]
	v_cvt_pk_bf16_f32 v32, v44, v45
	v_cvt_pk_bf16_f32 v33, v46, v47
	v_cvt_pk_bf16_f32 v34, v40, v41
	v_cvt_pk_bf16_f32 v35, v42, v43
	global_store_dwordx4 v[50:51], v[32:35], off
	s_nop 1
	v_cvt_pk_bf16_f32 v32, v36, v37
	v_cvt_pk_bf16_f32 v33, v38, v39
	v_cvt_pk_bf16_f32 v34, v52, v53
	v_cvt_pk_bf16_f32 v35, v54, v55
	global_store_dwordx4 v[50:51], v[32:35], off offset:256
	v_bfe_u32 v40, v206, 4, 2
	v_lshlrev_b32_e32 v40, 4, v40
	v_mov_b32_e32 v41, 0
	v_lshl_add_u64 v[36:37], v[48:49], 0, v[40:41]
	global_load_dwordx4 v[32:35], v[36:37], off
	s_nop 0
	v_add_u32_e32 v48, 0xb0, v146
	v_ashrrev_i32_e32 v49, 31, v48
	v_lshlrev_b64 v[50:51], 10, v[64:65]
	s_waitcnt vmcnt(0)
	v_add_f32_e32 v36, v32, v33
	v_add_f32_e32 v37, v34, v35
	v_add_f32_e32 v36, v36, v37
	ds_swizzle_b32 v37, v36 offset:swizzle(SWAP,16)
	s_waitcnt lgkmcnt(0)
	v_add_f32_e32 v36, v36, v37
	v_mov_b32_e32 v37, v36
	s_nop 1
	v_permlane32_swap_b32_e32 v36, v37
	v_add_f32_e32 v44, v36, v37
	s_nop 0
	v_lshl_add_u64 v[34:35], v[144:145], 0, v[50:51]
	v_mov_b32_e32 v32, v44
	v_fmamk_f32 v32, v32, 0x3a800000, v154
	v_mul_f32_e32 v33, 0x4b800000, v32
	v_cmp_gt_f32_e32 vcc, s49, v32
	s_nop 1
	v_cndmask_b32_e32 v32, v32, v33, vcc
	v_rsq_f32_e32 v36, v32
	v_lshlrev_b64 v[32:33], 6, v[48:49]
	v_lshl_add_u64 v[32:33], s[10:11], 0, v[32:33]
	v_mul_f32_e32 v37, 0x45800000, v36
	v_cndmask_b32_e32 v36, v36, v37, vcc
	v_mul_f32_e32 v36, v147, v36
	v_pk_mul_f32 v[30:31], v[30:31], v[36:37] op_sel_hi:[1,0]
	v_pk_mul_f32 v[28:29], v[28:29], v[36:37] op_sel_hi:[1,0]
	v_pk_mul_f32 v[26:27], v[26:27], v[36:37] op_sel_hi:[1,0]
	v_pk_mul_f32 v[24:25], v[24:25], v[36:37] op_sel_hi:[1,0]
	v_pk_mul_f32 v[22:23], v[22:23], v[36:37] op_sel_hi:[1,0]
	v_pk_mul_f32 v[20:21], v[20:21], v[36:37] op_sel_hi:[1,0]
	v_pk_mul_f32 v[38:39], v[18:19], v[36:37] op_sel_hi:[1,0]
	v_pk_mul_f32 v[36:37], v[16:17], v[36:37] op_sel_hi:[1,0]
	v_cvt_pk_bf16_f32 v16, v28, v29
	v_cvt_pk_bf16_f32 v17, v30, v31
	v_cvt_pk_bf16_f32 v18, v24, v25
	v_cvt_pk_bf16_f32 v19, v26, v27
	global_store_dwordx4 v[34:35], v[16:19], off
	s_andn2_b64 vcc, exec, s[4:5]
	s_mov_b64 s[4:5], -1
	v_cvt_pk_bf16_f32 v16, v20, v21
	v_cvt_pk_bf16_f32 v17, v22, v23
	v_cvt_pk_bf16_f32 v18, v36, v37
	v_cvt_pk_bf16_f32 v19, v38, v39
	global_store_dwordx4 v[34:35], v[16:19], off offset:256
	v_bfe_u32 v24, v206, 4, 2
	v_lshlrev_b32_e32 v24, 4, v24
	v_mov_b32_e32 v25, 0
	v_lshl_add_u64 v[20:21], v[32:33], 0, v[24:25]
	global_load_dwordx4 v[16:19], v[20:21], off
	s_nop 0
	s_waitcnt vmcnt(0)
	v_add_f32_e32 v20, v16, v17
	v_add_f32_e32 v21, v18, v19
	v_add_f32_e32 v20, v20, v21
	ds_swizzle_b32 v21, v20 offset:swizzle(SWAP,16)
	s_waitcnt lgkmcnt(0)
	v_add_f32_e32 v20, v20, v21
	v_mov_b32_e32 v21, v20
	s_nop 1
	v_permlane32_swap_b32_e32 v20, v21
	v_add_f32_e32 v28, v20, v21
	s_nop 0
	s_nop 0
	v_mov_b32_e32 v16, v28
	v_fmamk_f32 v16, v16, 0x3a800000, v154
	v_mul_f32_e32 v17, 0x4b800000, v16
	v_cmp_gt_f32_e64 s[6:7], s49, v16
	s_nop 1
	v_cndmask_b32_e64 v16, v16, v17, s[6:7]
	v_rsq_f32_e32 v18, v16
	v_lshlrev_b64 v[16:17], 10, v[48:49]
	v_lshl_add_u64 v[16:17], v[144:145], 0, v[16:17]
	v_mul_f32_e32 v19, 0x45800000, v18
	v_cndmask_b32_e64 v18, v18, v19, s[6:7]
	v_mul_f32_e32 v18, v147, v18
	v_pk_mul_f32 v[14:15], v[14:15], v[18:19] op_sel_hi:[1,0]
	v_pk_mul_f32 v[12:13], v[12:13], v[18:19] op_sel_hi:[1,0]
	v_pk_mul_f32 v[10:11], v[10:11], v[18:19] op_sel_hi:[1,0]
	v_pk_mul_f32 v[8:9], v[8:9], v[18:19] op_sel_hi:[1,0]
	v_pk_mul_f32 v[6:7], v[6:7], v[18:19] op_sel_hi:[1,0]
	v_pk_mul_f32 v[4:5], v[4:5], v[18:19] op_sel_hi:[1,0]
	v_pk_mul_f32 v[20:21], v[2:3], v[18:19] op_sel_hi:[1,0]
	v_pk_mul_f32 v[18:19], v[0:1], v[18:19] op_sel_hi:[1,0]
	v_cvt_pk_bf16_f32 v0, v12, v13
	v_cvt_pk_bf16_f32 v1, v14, v15
	v_cvt_pk_bf16_f32 v2, v8, v9
	v_cvt_pk_bf16_f32 v3, v10, v11
	global_store_dwordx4 v[16:17], v[0:3], off
	s_nop 1
	v_cvt_pk_bf16_f32 v0, v4, v5
	v_cvt_pk_bf16_f32 v1, v6, v7
	v_cvt_pk_bf16_f32 v2, v18, v19
	v_cvt_pk_bf16_f32 v3, v20, v21
	global_store_dwordx4 v[16:17], v[0:3], off offset:256
	s_cbranch_vccnz .LBB0_1642
	s_andn2_b64 vcc, exec, s[2:3]
	s_cbranch_vccnz .LBB0_1641
	s_barrier
	s_branch .LBB0_1641

.LBB0_3044:
	v_lshl_add_u32 v142, s12, 8, v148
	v_ashrrev_i32_e32 v143, 31, v142
	v_lshlrev_b64 v[144:145], 6, v[142:143]
	v_lshl_add_u64 v[146:147], s[18:19], 0, v[144:145]
	v_bfe_u32 v164, v206, 4, 2
	v_lshlrev_b32_e32 v164, 4, v164
	v_mov_b32_e32 v165, 0
	v_lshl_add_u64 v[160:161], v[146:147], 0, v[164:165]
	global_load_dwordx4 v[156:159], v[160:161], off
	v_lshl_or_b32 v140, s2, 8, v150
	v_ashrrev_i32_e32 v141, 31, v140
	v_lshlrev_b64 v[146:147], 10, v[142:143]
	v_lshl_add_u64 v[146:147], v[146:147], 0, v[140:141]
	v_lshlrev_b64 v[146:147], 1, v[146:147]
	v_lshl_add_u64 v[172:173], s[20:21], 0, v[146:147]
	v_lshl_add_u64 v[174:175], s[8:9], 0, v[146:147]
	global_load_dwordx2 v[172:173], v[172:173], off
	v_or_b32_e32 v176, 32, v146
	global_load_dwordx2 v[174:175], v[174:175], off
	v_mov_b32_e32 v177, v147
	v_lshl_add_u64 v[178:179], s[20:21], 0, v[176:177]
	s_lshl_b32 s36, s2, 2
	s_ashr_i32 s37, s36, 31
	s_waitcnt vmcnt(0)
	v_add_f32_e32 v160, v156, v157
	v_add_f32_e32 v161, v158, v159
	v_add_f32_e32 v160, v160, v161
	ds_swizzle_b32 v161, v160 offset:swizzle(SWAP,16)
	s_waitcnt lgkmcnt(0)
	v_add_f32_e32 v160, v160, v161
	v_mov_b32_e32 v161, v160
	s_nop 1
	v_permlane32_swap_b32_e32 v160, v161
	v_add_f32_e32 v168, v160, v161
	v_lshlrev_b32_e32 v162, 16, v173
	v_and_b32_e32 v163, 0xffff0000, v173
	v_mov_b32_e32 v143, v168
	v_fmamk_f32 v143, v143, 0x3a800000, v154
	v_mul_f32_e32 v155, 0x4b800000, v143
	v_cmp_gt_f32_e32 vcc, s56, v143
	v_lshlrev_b32_e32 v160, 16, v175
	v_and_b32_e32 v161, 0xffff0000, v175
	v_cndmask_b32_e32 v143, v143, v155, vcc
	v_rsq_f32_e32 v143, v143
	v_lshlrev_b32_e32 v158, 16, v172
	v_and_b32_e32 v159, 0xffff0000, v172
	v_lshlrev_b32_e32 v156, 16, v174
	v_mul_f32_e32 v155, 0x45800000, v143
	v_cndmask_b32_e32 v143, v143, v155, vcc
	v_mul_f32_e32 v124, v124, v143
	v_mul_f32_e32 v125, v125, v143
	v_mul_f32_e32 v126, v126, v143
	v_mul_f32_e32 v127, v127, v143
	v_mul_f32_e32 v124, 0xbfb8aa3b, v124
	v_mul_f32_e32 v125, 0xbfb8aa3b, v125
	v_mul_f32_e32 v126, 0xbfb8aa3b, v126
	v_mul_f32_e32 v127, 0xbfb8aa3b, v127
	v_exp_f32_e32 v124, v124
	v_exp_f32_e32 v125, v125
	v_exp_f32_e32 v126, v126
	v_exp_f32_e32 v127, v127
	v_add_f32_e32 v124, 1.0, v124
	v_add_f32_e32 v155, 1.0, v125
	v_add_f32_e32 v125, 1.0, v126
	v_add_f32_e32 v127, 1.0, v127
	v_rcp_f32_e32 v126, v124
	v_rcp_f32_e32 v124, v125
	v_rcp_f32_e32 v125, v127
	v_rcp_f32_e32 v127, v155
	v_and_b32_e32 v157, 0xffff0000, v174
	v_mul_f32_e32 v120, v120, v143
	v_pk_fma_f32 v[124:125], v[124:125], v[162:163], v[160:161]
	v_lshl_add_u64 v[160:161], s[16:17], 0, v[146:147]
	v_pk_fma_f32 v[126:127], v[126:127], v[158:159], v[156:157]
	v_lshl_add_u64 v[162:163], s[8:9], 0, v[176:177]
	v_cvt_pk_bf16_f32 v156, v126, v127
	v_cvt_pk_bf16_f32 v157, v124, v125
	global_store_dwordx2 v[160:161], v[156:157], off
	global_load_dwordx2 v[158:159], v[178:179], off
	v_mul_f32_e32 v121, v121, v143
	global_load_dwordx2 v[156:157], v[162:163], off
	v_mul_f32_e32 v122, v122, v143
	v_mul_f32_e32 v123, v123, v143
	v_mul_f32_e32 v120, 0xbfb8aa3b, v120
	v_mul_f32_e32 v121, 0xbfb8aa3b, v121
	v_mul_f32_e32 v122, 0xbfb8aa3b, v122
	v_mul_f32_e32 v123, 0xbfb8aa3b, v123
	v_exp_f32_e32 v120, v120
	v_exp_f32_e32 v121, v121
	v_exp_f32_e32 v122, v122
	v_exp_f32_e32 v123, v123
	v_add_f32_e32 v120, 1.0, v120
	v_add_f32_e32 v121, 1.0, v121
	v_add_f32_e32 v122, 1.0, v122
	v_add_f32_e32 v123, 1.0, v123
	v_rcp_f32_e32 v120, v120
	v_rcp_f32_e32 v121, v121
	v_rcp_f32_e32 v122, v122
	v_rcp_f32_e32 v123, v123
	v_or_b32_e32 v160, 0x100, v146
	v_mov_b32_e32 v161, v147
	v_lshl_add_u64 v[162:163], s[20:21], 0, v[160:161]
	v_mul_f32_e32 v116, v116, v143
	v_mul_f32_e32 v117, v117, v143
	v_mul_f32_e32 v118, v118, v143
	v_mul_f32_e32 v119, v119, v143
	v_mul_f32_e32 v116, 0xbfb8aa3b, v116
	v_mul_f32_e32 v117, 0xbfb8aa3b, v117
	v_mul_f32_e32 v118, 0xbfb8aa3b, v118
	v_mul_f32_e32 v119, 0xbfb8aa3b, v119
	v_exp_f32_e32 v116, v116
	v_exp_f32_e32 v117, v117
	v_exp_f32_e32 v118, v118
	v_exp_f32_e32 v119, v119
	v_add_f32_e32 v116, 1.0, v116
	v_add_f32_e32 v117, 1.0, v117
	v_add_f32_e32 v118, 1.0, v118
	v_add_f32_e32 v119, 1.0, v119
	v_rcp_f32_e32 v116, v116
	v_rcp_f32_e32 v117, v117
	v_rcp_f32_e32 v118, v118
	v_rcp_f32_e32 v119, v119
	v_or_b32_e32 v146, 0x120, v146
	v_mul_f32_e32 v112, v112, v143
	v_mul_f32_e32 v113, v113, v143
	v_mul_f32_e32 v114, v114, v143
	v_mul_f32_e32 v115, v115, v143
	v_mul_f32_e32 v112, 0xbfb8aa3b, v112
	v_mul_f32_e32 v113, 0xbfb8aa3b, v113
	v_mul_f32_e32 v114, 0xbfb8aa3b, v114
	v_mul_f32_e32 v115, 0xbfb8aa3b, v115
	v_exp_f32_e32 v112, v112
	v_exp_f32_e32 v113, v113
	v_exp_f32_e32 v114, v114
	v_exp_f32_e32 v115, v115
	v_add_f32_e32 v112, 1.0, v112
	v_add_f32_e32 v113, 1.0, v113
	v_add_f32_e32 v114, 1.0, v114
	v_add_f32_e32 v115, 1.0, v115
	v_mul_f32_e32 v127, v127, v127
	v_mul_f32_e32 v125, v125, v125
	v_rcp_f32_e32 v112, v112
	v_rcp_f32_e32 v113, v113
	v_rcp_f32_e32 v114, v114
	v_rcp_f32_e32 v115, v115
	v_fmac_f32_e32 v127, v126, v126
	v_fmac_f32_e32 v125, v124, v124
	v_add_f32_e32 v124, v127, v125
	s_waitcnt vmcnt(1)
	v_lshlrev_b32_e32 v164, 16, v158
	v_and_b32_e32 v165, 0xffff0000, v158
	v_lshlrev_b32_e32 v158, 16, v159
	v_and_b32_e32 v159, 0xffff0000, v159
	s_waitcnt vmcnt(0)
	v_lshlrev_b32_e32 v166, 16, v156
	v_and_b32_e32 v167, 0xffff0000, v156
	v_lshlrev_b32_e32 v156, 16, v157
	v_and_b32_e32 v157, 0xffff0000, v157
	v_pk_fma_f32 v[122:123], v[122:123], v[158:159], v[156:157]
	v_pk_fma_f32 v[120:121], v[120:121], v[164:165], v[166:167]
	v_lshl_add_u64 v[164:165], s[8:9], 0, v[160:161]
	v_cvt_pk_bf16_f32 v156, v120, v121
	v_cvt_pk_bf16_f32 v157, v122, v123
	global_load_dwordx2 v[158:159], v[162:163], off
	v_lshl_add_u64 v[162:163], s[16:17], 0, v[176:177]
	global_store_dwordx2 v[162:163], v[156:157], off
	global_load_dwordx2 v[156:157], v[164:165], off
	v_lshl_add_u64 v[162:163], s[20:21], 0, v[146:147]
	v_lshl_add_u64 v[160:161], s[16:17], 0, v[160:161]
	v_mul_f32_e32 v121, v121, v121
	v_mul_f32_e32 v123, v123, v123
	v_fmac_f32_e32 v121, v120, v120
	v_fmac_f32_e32 v123, v122, v122
	v_add_f32_e32 v120, v121, v123
	v_add_f32_e32 v120, v124, v120
	s_waitcnt vmcnt(2)
	v_lshlrev_b32_e32 v164, 16, v158
	v_and_b32_e32 v165, 0xffff0000, v158
	v_lshlrev_b32_e32 v158, 16, v159
	v_and_b32_e32 v159, 0xffff0000, v159
	s_waitcnt vmcnt(0)
	v_lshlrev_b32_e32 v166, 16, v156
	v_and_b32_e32 v167, 0xffff0000, v156
	v_lshlrev_b32_e32 v156, 16, v157
	v_and_b32_e32 v157, 0xffff0000, v157
	v_pk_fma_f32 v[118:119], v[118:119], v[158:159], v[156:157]
	v_pk_fma_f32 v[116:117], v[116:117], v[164:165], v[166:167]
	s_nop 0
	v_cvt_pk_bf16_f32 v156, v116, v117
	v_cvt_pk_bf16_f32 v157, v118, v119
	global_load_dwordx2 v[158:159], v[162:163], off
	v_lshl_add_u64 v[162:163], s[8:9], 0, v[146:147]
	global_store_dwordx2 v[160:161], v[156:157], off
	global_load_dwordx2 v[156:157], v[162:163], off
	v_mul_f32_e32 v117, v117, v117
	v_mul_f32_e32 v119, v119, v119
	v_fmac_f32_e32 v117, v116, v116
	v_fmac_f32_e32 v119, v118, v118
	v_add_f32_e32 v116, v117, v119
	v_add_f32_e32 v124, v116, v120
	s_waitcnt vmcnt(2)
	v_lshlrev_b32_e32 v116, 16, v158
	v_and_b32_e32 v117, 0xffff0000, v158
	v_lshlrev_b32_e32 v118, 16, v159
	v_and_b32_e32 v119, 0xffff0000, v159
	s_waitcnt vmcnt(0)
	v_lshlrev_b32_e32 v120, 16, v156
	v_and_b32_e32 v121, 0xffff0000, v156
	v_lshlrev_b32_e32 v122, 16, v157
	v_and_b32_e32 v123, 0xffff0000, v157
	v_pk_fma_f32 v[114:115], v[114:115], v[118:119], v[122:123]
	v_pk_fma_f32 v[112:113], v[112:113], v[116:117], v[120:121]
	v_mul_f32_e32 v117, v115, v115
	v_mul_f32_e32 v116, v113, v113
	v_fmac_f32_e32 v116, v112, v112
	v_fmac_f32_e32 v117, v114, v114
	v_add_f32_e32 v116, v116, v117
	v_add_f32_e32 v118, v124, v116
	ds_swizzle_b32 v119, v118 offset:swizzle(SWAP,16)
	v_lshl_add_u64 v[116:117], s[16:17], 0, v[146:147]
	v_cvt_pk_bf16_f32 v112, v112, v113
	v_cvt_pk_bf16_f32 v113, v114, v115
	global_store_dwordx2 v[116:117], v[112:113], off
	s_waitcnt lgkmcnt(0)
	v_add_f32_e32 v112, v118, v119
	v_mov_b32_e32 v113, v112
	s_nop 1
	v_permlane32_swap_b32_e32 v112, v113
	s_and_saveexec_b64 s[2:3], s[4:5]
	s_cbranch_execz .LBB0_3046
	v_add_f32_e32 v114, v112, v113
	v_lshl_add_u64 v[112:113], s[10:11], 0, v[144:145]
	v_lshl_add_u64 v[112:113], s[36:37], 2, v[112:113]
	s_lshl_b32 s12, s50, 2
	v_lshl_add_u64 v[112:113], v[112:113], 0, s[12:13]
	global_store_dword v[112:113], v114, off
.LBB0_3046:
	s_or_b64 exec, exec, s[2:3]
	v_or_b32_e32 v114, 16, v142
	v_ashrrev_i32_e32 v115, 31, v114
	v_lshlrev_b64 v[112:113], 6, v[114:115]
	v_lshl_add_u64 v[144:145], s[18:19], 0, v[112:113]
	v_bfe_u32 v124, v206, 4, 2
	v_lshlrev_b32_e32 v124, 4, v124
	v_mov_b32_e32 v125, 0
	v_lshl_add_u64 v[120:121], v[144:145], 0, v[124:125]
	global_load_dwordx4 v[116:119], v[120:121], off
	s_nop 0
	v_lshlrev_b64 v[114:115], 10, v[114:115]
	v_lshl_add_u64 v[114:115], v[114:115], 0, v[140:141]
	v_lshlrev_b64 v[114:115], 1, v[114:115]
	v_lshl_add_u64 v[156:157], s[20:21], 0, v[114:115]
	v_lshl_add_u64 v[158:159], s[8:9], 0, v[114:115]
	global_load_dwordx2 v[156:157], v[156:157], off
	v_or_b32_e32 v160, 32, v114
	global_load_dwordx2 v[158:159], v[158:159], off
	v_mov_b32_e32 v161, v115
	v_lshl_add_u64 v[162:163], s[20:21], 0, v[160:161]
	s_waitcnt vmcnt(0)
	v_add_f32_e32 v120, v116, v117
	v_add_f32_e32 v121, v118, v119
	v_add_f32_e32 v120, v120, v121
	ds_swizzle_b32 v121, v120 offset:swizzle(SWAP,16)
	s_waitcnt lgkmcnt(0)
	v_add_f32_e32 v120, v120, v121
	v_mov_b32_e32 v121, v120
	s_nop 1
	v_permlane32_swap_b32_e32 v120, v121
	v_add_f32_e32 v144, v120, v121
	v_lshlrev_b32_e32 v122, 16, v157
	v_and_b32_e32 v123, 0xffff0000, v157
	v_mov_b32_e32 v116, v144
	v_fmamk_f32 v116, v116, 0x3a800000, v154
	v_mul_f32_e32 v117, 0x4b800000, v116
	v_cmp_gt_f32_e32 vcc, s56, v116
	v_lshlrev_b32_e32 v118, 16, v156
	v_and_b32_e32 v119, 0xffff0000, v156
	v_cndmask_b32_e32 v116, v116, v117, vcc
	v_rsq_f32_e32 v120, v116
	s_waitcnt vmcnt(0)
	v_lshlrev_b32_e32 v116, 16, v158
	v_and_b32_e32 v117, 0xffff0000, v158
	v_mul_f32_e32 v121, 0x45800000, v120
	v_cndmask_b32_e32 v143, v120, v121, vcc
	v_mul_f32_e32 v108, v108, v143
	v_mul_f32_e32 v109, v109, v143
	v_mul_f32_e32 v110, v110, v143
	v_mul_f32_e32 v111, v111, v143
	v_mul_f32_e32 v108, 0xbfb8aa3b, v108
	v_mul_f32_e32 v109, 0xbfb8aa3b, v109
	v_mul_f32_e32 v110, 0xbfb8aa3b, v110
	v_mul_f32_e32 v111, 0xbfb8aa3b, v111
	v_exp_f32_e32 v108, v108
	v_exp_f32_e32 v109, v109
	v_exp_f32_e32 v110, v110
	v_exp_f32_e32 v111, v111
	v_add_f32_e32 v108, 1.0, v108
	v_add_f32_e32 v120, 1.0, v109
	v_add_f32_e32 v109, 1.0, v110
	v_add_f32_e32 v111, 1.0, v111
	v_rcp_f32_e32 v110, v108
	v_rcp_f32_e32 v108, v109
	v_rcp_f32_e32 v109, v111
	v_rcp_f32_e32 v111, v120
	v_lshlrev_b32_e32 v120, 16, v159
	v_and_b32_e32 v121, 0xffff0000, v159
	v_pk_fma_f32 v[108:109], v[108:109], v[122:123], v[120:121]
	v_lshl_add_u64 v[120:121], s[16:17], 0, v[114:115]
	v_pk_fma_f32 v[110:111], v[110:111], v[118:119], v[116:117]
	v_lshl_add_u64 v[122:123], s[8:9], 0, v[160:161]
	v_cvt_pk_bf16_f32 v116, v110, v111
	v_cvt_pk_bf16_f32 v117, v108, v109
	global_store_dwordx2 v[120:121], v[116:117], off
	global_load_dwordx2 v[118:119], v[162:163], off
	v_mul_f32_e32 v104, v104, v143
	global_load_dwordx2 v[116:117], v[122:123], off
	v_mul_f32_e32 v105, v105, v143
	v_mul_f32_e32 v106, v106, v143
	v_mul_f32_e32 v107, v107, v143
	v_mul_f32_e32 v104, 0xbfb8aa3b, v104
	v_mul_f32_e32 v105, 0xbfb8aa3b, v105
	v_mul_f32_e32 v106, 0xbfb8aa3b, v106
	v_mul_f32_e32 v107, 0xbfb8aa3b, v107
	v_exp_f32_e32 v104, v104
	v_exp_f32_e32 v105, v105
	v_exp_f32_e32 v106, v106
	v_exp_f32_e32 v107, v107
	v_add_f32_e32 v104, 1.0, v104
	v_add_f32_e32 v105, 1.0, v105
	v_add_f32_e32 v106, 1.0, v106
	v_add_f32_e32 v107, 1.0, v107
	v_rcp_f32_e32 v104, v104
	v_rcp_f32_e32 v105, v105
	v_rcp_f32_e32 v106, v106
	v_rcp_f32_e32 v107, v107
	v_or_b32_e32 v120, 0x100, v114
	v_mov_b32_e32 v121, v115
	v_lshl_add_u64 v[122:123], s[20:21], 0, v[120:121]
	v_mul_f32_e32 v100, v100, v143
	v_mul_f32_e32 v101, v101, v143
	v_mul_f32_e32 v102, v102, v143
	v_mul_f32_e32 v103, v103, v143
	v_mul_f32_e32 v100, 0xbfb8aa3b, v100
	v_mul_f32_e32 v101, 0xbfb8aa3b, v101
	v_mul_f32_e32 v102, 0xbfb8aa3b, v102
	v_mul_f32_e32 v103, 0xbfb8aa3b, v103
	v_exp_f32_e32 v100, v100
	v_exp_f32_e32 v101, v101
	v_exp_f32_e32 v102, v102
	v_exp_f32_e32 v103, v103
	v_add_f32_e32 v100, 1.0, v100
	v_add_f32_e32 v101, 1.0, v101
	v_add_f32_e32 v102, 1.0, v102
	v_add_f32_e32 v103, 1.0, v103
	v_rcp_f32_e32 v100, v100
	v_rcp_f32_e32 v101, v101
	v_rcp_f32_e32 v102, v102
	v_rcp_f32_e32 v103, v103
	v_or_b32_e32 v114, 0x120, v114
	v_mul_f32_e32 v96, v96, v143
	v_mul_f32_e32 v97, v97, v143
	v_mul_f32_e32 v98, v98, v143
	v_mul_f32_e32 v99, v99, v143
	v_mul_f32_e32 v96, 0xbfb8aa3b, v96
	v_mul_f32_e32 v97, 0xbfb8aa3b, v97
	v_mul_f32_e32 v98, 0xbfb8aa3b, v98
	v_mul_f32_e32 v99, 0xbfb8aa3b, v99
	v_exp_f32_e32 v96, v96
	v_exp_f32_e32 v97, v97
	v_exp_f32_e32 v98, v98
	v_exp_f32_e32 v99, v99
	v_add_f32_e32 v96, 1.0, v96
	v_add_f32_e32 v97, 1.0, v97
	v_add_f32_e32 v98, 1.0, v98
	v_add_f32_e32 v99, 1.0, v99
	v_mul_f32_e32 v111, v111, v111
	v_mul_f32_e32 v109, v109, v109
	v_rcp_f32_e32 v96, v96
	v_rcp_f32_e32 v97, v97
	v_rcp_f32_e32 v98, v98
	v_rcp_f32_e32 v99, v99
	v_fmac_f32_e32 v111, v110, v110
	v_fmac_f32_e32 v109, v108, v108
	v_add_f32_e32 v108, v111, v109
	s_waitcnt vmcnt(1)
	v_lshlrev_b32_e32 v124, 16, v118
	v_and_b32_e32 v125, 0xffff0000, v118
	v_lshlrev_b32_e32 v118, 16, v119
	v_and_b32_e32 v119, 0xffff0000, v119
	s_waitcnt vmcnt(0)
	v_lshlrev_b32_e32 v126, 16, v116
	v_and_b32_e32 v127, 0xffff0000, v116
	v_lshlrev_b32_e32 v116, 16, v117
	v_and_b32_e32 v117, 0xffff0000, v117
	v_pk_fma_f32 v[106:107], v[106:107], v[118:119], v[116:117]
	v_pk_fma_f32 v[104:105], v[104:105], v[124:125], v[126:127]
	v_lshl_add_u64 v[124:125], s[8:9], 0, v[120:121]
	v_cvt_pk_bf16_f32 v116, v104, v105
	v_cvt_pk_bf16_f32 v117, v106, v107
	global_load_dwordx2 v[118:119], v[122:123], off
	v_lshl_add_u64 v[122:123], s[16:17], 0, v[160:161]
	global_store_dwordx2 v[122:123], v[116:117], off
	global_load_dwordx2 v[116:117], v[124:125], off
	v_lshl_add_u64 v[122:123], s[20:21], 0, v[114:115]
	v_lshl_add_u64 v[120:121], s[16:17], 0, v[120:121]
	v_mul_f32_e32 v105, v105, v105
	v_mul_f32_e32 v107, v107, v107
	v_fmac_f32_e32 v105, v104, v104
	v_fmac_f32_e32 v107, v106, v106
	v_add_f32_e32 v104, v105, v107
	v_add_f32_e32 v104, v108, v104
	s_waitcnt vmcnt(2)
	v_lshlrev_b32_e32 v124, 16, v118
	v_and_b32_e32 v125, 0xffff0000, v118
	v_lshlrev_b32_e32 v118, 16, v119
	v_and_b32_e32 v119, 0xffff0000, v119
	s_waitcnt vmcnt(0)
	v_lshlrev_b32_e32 v126, 16, v116
	v_and_b32_e32 v127, 0xffff0000, v116
	v_lshlrev_b32_e32 v116, 16, v117
	v_and_b32_e32 v117, 0xffff0000, v117
	v_pk_fma_f32 v[102:103], v[102:103], v[118:119], v[116:117]
	v_pk_fma_f32 v[100:101], v[100:101], v[124:125], v[126:127]
	s_nop 0
	v_cvt_pk_bf16_f32 v116, v100, v101
	v_cvt_pk_bf16_f32 v117, v102, v103
	global_load_dwordx2 v[118:119], v[122:123], off
	v_lshl_add_u64 v[122:123], s[8:9], 0, v[114:115]
	global_store_dwordx2 v[120:121], v[116:117], off
	global_load_dwordx2 v[116:117], v[122:123], off
	v_mul_f32_e32 v101, v101, v101
	v_mul_f32_e32 v103, v103, v103
	v_fmac_f32_e32 v101, v100, v100
	v_fmac_f32_e32 v103, v102, v102
	v_add_f32_e32 v100, v101, v103
	v_add_f32_e32 v108, v100, v104
	s_waitcnt vmcnt(2)
	v_lshlrev_b32_e32 v100, 16, v118
	v_and_b32_e32 v101, 0xffff0000, v118
	v_lshlrev_b32_e32 v102, 16, v119
	v_and_b32_e32 v103, 0xffff0000, v119
	s_waitcnt vmcnt(0)
	v_lshlrev_b32_e32 v104, 16, v116
	v_and_b32_e32 v105, 0xffff0000, v116
	v_lshlrev_b32_e32 v106, 16, v117
	v_and_b32_e32 v107, 0xffff0000, v117
	v_pk_fma_f32 v[98:99], v[98:99], v[102:103], v[106:107]
	v_pk_fma_f32 v[96:97], v[96:97], v[100:101], v[104:105]
	v_mul_f32_e32 v101, v99, v99
	v_mul_f32_e32 v100, v97, v97
	v_fmac_f32_e32 v100, v96, v96
	v_fmac_f32_e32 v101, v98, v98
	v_add_f32_e32 v100, v100, v101
	v_add_f32_e32 v102, v108, v100
	ds_swizzle_b32 v103, v102 offset:swizzle(SWAP,16)
	v_lshl_add_u64 v[100:101], s[16:17], 0, v[114:115]
	v_cvt_pk_bf16_f32 v96, v96, v97
	v_cvt_pk_bf16_f32 v97, v98, v99
	global_store_dwordx2 v[100:101], v[96:97], off
	s_waitcnt lgkmcnt(0)
	v_add_f32_e32 v96, v102, v103
	v_mov_b32_e32 v97, v96
	s_nop 1
	v_permlane32_swap_b32_e32 v96, v97
	s_and_saveexec_b64 s[2:3], s[4:5]
	s_cbranch_execz .LBB0_3048
	v_add_f32_e32 v98, v96, v97
	v_lshl_add_u64 v[96:97], s[10:11], 0, v[112:113]
	v_lshl_add_u64 v[96:97], s[36:37], 2, v[96:97]
	s_lshl_b32 s12, s50, 2
	v_lshl_add_u64 v[96:97], v[96:97], 0, s[12:13]
	global_store_dword v[96:97], v98, off
.LBB0_3048:
	s_or_b64 exec, exec, s[2:3]
	v_or_b32_e32 v98, 32, v142
	v_ashrrev_i32_e32 v99, 31, v98
	v_lshlrev_b64 v[96:97], 6, v[98:99]
	v_lshl_add_u64 v[112:113], s[18:19], 0, v[96:97]
	v_bfe_u32 v108, v206, 4, 2
	v_lshlrev_b32_e32 v108, 4, v108
	v_mov_b32_e32 v109, 0
	v_lshl_add_u64 v[104:105], v[112:113], 0, v[108:109]
	global_load_dwordx4 v[100:103], v[104:105], off
	s_nop 0
	v_lshlrev_b64 v[98:99], 10, v[98:99]
	v_lshl_add_u64 v[98:99], v[98:99], 0, v[140:141]
	v_lshlrev_b64 v[98:99], 1, v[98:99]
	v_lshl_add_u64 v[116:117], s[20:21], 0, v[98:99]
	v_lshl_add_u64 v[118:119], s[8:9], 0, v[98:99]
	global_load_dwordx2 v[116:117], v[116:117], off
	v_or_b32_e32 v120, 32, v98
	global_load_dwordx2 v[118:119], v[118:119], off
	v_mov_b32_e32 v121, v99
	v_lshl_add_u64 v[122:123], s[20:21], 0, v[120:121]
	s_waitcnt vmcnt(0)
	v_add_f32_e32 v104, v100, v101
	v_add_f32_e32 v105, v102, v103
	v_add_f32_e32 v104, v104, v105
	ds_swizzle_b32 v105, v104 offset:swizzle(SWAP,16)
	s_waitcnt lgkmcnt(0)
	v_add_f32_e32 v104, v104, v105
	v_mov_b32_e32 v105, v104
	s_nop 1
	v_permlane32_swap_b32_e32 v104, v105
	v_add_f32_e32 v112, v104, v105
	v_lshlrev_b32_e32 v106, 16, v117
	v_and_b32_e32 v107, 0xffff0000, v117
	v_mov_b32_e32 v100, v112
	v_fmamk_f32 v100, v100, 0x3a800000, v154
	v_mul_f32_e32 v101, 0x4b800000, v100
	v_cmp_gt_f32_e32 vcc, s56, v100
	v_lshlrev_b32_e32 v102, 16, v116
	v_and_b32_e32 v103, 0xffff0000, v116
	v_cndmask_b32_e32 v100, v100, v101, vcc
	v_rsq_f32_e32 v104, v100
	s_waitcnt vmcnt(0)
	v_lshlrev_b32_e32 v100, 16, v118
	v_and_b32_e32 v101, 0xffff0000, v118
	v_mul_f32_e32 v105, 0x45800000, v104
	v_cndmask_b32_e32 v112, v104, v105, vcc
	v_mul_f32_e32 v92, v92, v112
	v_mul_f32_e32 v93, v93, v112
	v_mul_f32_e32 v94, v94, v112
	v_mul_f32_e32 v95, v95, v112
	v_mul_f32_e32 v92, 0xbfb8aa3b, v92
	v_mul_f32_e32 v93, 0xbfb8aa3b, v93
	v_mul_f32_e32 v94, 0xbfb8aa3b, v94
	v_mul_f32_e32 v95, 0xbfb8aa3b, v95
	v_exp_f32_e32 v92, v92
	v_exp_f32_e32 v93, v93
	v_exp_f32_e32 v94, v94
	v_exp_f32_e32 v95, v95
	v_add_f32_e32 v92, 1.0, v92
	v_add_f32_e32 v104, 1.0, v93
	v_add_f32_e32 v93, 1.0, v94
	v_add_f32_e32 v95, 1.0, v95
	v_rcp_f32_e32 v94, v92
	v_rcp_f32_e32 v92, v93
	v_rcp_f32_e32 v93, v95
	v_rcp_f32_e32 v95, v104
	v_lshlrev_b32_e32 v104, 16, v119
	v_and_b32_e32 v105, 0xffff0000, v119
	v_pk_fma_f32 v[92:93], v[92:93], v[106:107], v[104:105]
	v_lshl_add_u64 v[104:105], s[16:17], 0, v[98:99]
	v_pk_fma_f32 v[94:95], v[94:95], v[102:103], v[100:101]
	v_lshl_add_u64 v[106:107], s[8:9], 0, v[120:121]
	v_cvt_pk_bf16_f32 v100, v94, v95
	v_cvt_pk_bf16_f32 v101, v92, v93
	global_store_dwordx2 v[104:105], v[100:101], off
	global_load_dwordx2 v[102:103], v[122:123], off
	v_mul_f32_e32 v88, v88, v112
	global_load_dwordx2 v[100:101], v[106:107], off
	v_mul_f32_e32 v89, v89, v112
	v_mul_f32_e32 v90, v90, v112
	v_mul_f32_e32 v91, v91, v112
	v_mul_f32_e32 v88, 0xbfb8aa3b, v88
	v_mul_f32_e32 v89, 0xbfb8aa3b, v89
	v_mul_f32_e32 v90, 0xbfb8aa3b, v90
	v_mul_f32_e32 v91, 0xbfb8aa3b, v91
	v_exp_f32_e32 v88, v88
	v_exp_f32_e32 v89, v89
	v_exp_f32_e32 v90, v90
	v_exp_f32_e32 v91, v91
	v_add_f32_e32 v88, 1.0, v88
	v_add_f32_e32 v89, 1.0, v89
	v_add_f32_e32 v90, 1.0, v90
	v_add_f32_e32 v91, 1.0, v91
	v_rcp_f32_e32 v88, v88
	v_rcp_f32_e32 v89, v89
	v_rcp_f32_e32 v90, v90
	v_rcp_f32_e32 v91, v91
	v_or_b32_e32 v104, 0x100, v98
	v_mov_b32_e32 v105, v99
	v_lshl_add_u64 v[106:107], s[20:21], 0, v[104:105]
	v_mul_f32_e32 v84, v84, v112
	v_mul_f32_e32 v85, v85, v112
	v_mul_f32_e32 v86, v86, v112
	v_mul_f32_e32 v87, v87, v112
	v_mul_f32_e32 v84, 0xbfb8aa3b, v84
	v_mul_f32_e32 v85, 0xbfb8aa3b, v85
	v_mul_f32_e32 v86, 0xbfb8aa3b, v86
	v_mul_f32_e32 v87, 0xbfb8aa3b, v87
	v_exp_f32_e32 v84, v84
	v_exp_f32_e32 v85, v85
	v_exp_f32_e32 v86, v86
	v_exp_f32_e32 v87, v87
	v_add_f32_e32 v84, 1.0, v84
	v_add_f32_e32 v85, 1.0, v85
	v_add_f32_e32 v86, 1.0, v86
	v_add_f32_e32 v87, 1.0, v87
	v_rcp_f32_e32 v84, v84
	v_rcp_f32_e32 v85, v85
	v_rcp_f32_e32 v86, v86
	v_rcp_f32_e32 v87, v87
	v_or_b32_e32 v98, 0x120, v98
	v_mul_f32_e32 v80, v80, v112
	v_mul_f32_e32 v81, v81, v112
	v_mul_f32_e32 v82, v82, v112
	v_mul_f32_e32 v83, v83, v112
	v_mul_f32_e32 v80, 0xbfb8aa3b, v80
	v_mul_f32_e32 v81, 0xbfb8aa3b, v81
	v_mul_f32_e32 v82, 0xbfb8aa3b, v82
	v_mul_f32_e32 v83, 0xbfb8aa3b, v83
	v_exp_f32_e32 v80, v80
	v_exp_f32_e32 v81, v81
	v_exp_f32_e32 v82, v82
	v_exp_f32_e32 v83, v83
	v_add_f32_e32 v80, 1.0, v80
	v_add_f32_e32 v81, 1.0, v81
	v_add_f32_e32 v82, 1.0, v82
	v_add_f32_e32 v83, 1.0, v83
	v_mul_f32_e32 v95, v95, v95
	v_mul_f32_e32 v93, v93, v93
	v_rcp_f32_e32 v80, v80
	v_rcp_f32_e32 v81, v81
	v_rcp_f32_e32 v82, v82
	v_rcp_f32_e32 v83, v83
	v_fmac_f32_e32 v95, v94, v94
	v_fmac_f32_e32 v93, v92, v92
	v_add_f32_e32 v92, v95, v93
	s_waitcnt vmcnt(1)
	v_lshlrev_b32_e32 v108, 16, v102
	v_and_b32_e32 v109, 0xffff0000, v102
	v_lshlrev_b32_e32 v102, 16, v103
	v_and_b32_e32 v103, 0xffff0000, v103
	s_waitcnt vmcnt(0)
	v_lshlrev_b32_e32 v110, 16, v100
	v_and_b32_e32 v111, 0xffff0000, v100
	v_lshlrev_b32_e32 v100, 16, v101
	v_and_b32_e32 v101, 0xffff0000, v101
	v_pk_fma_f32 v[90:91], v[90:91], v[102:103], v[100:101]
	v_pk_fma_f32 v[88:89], v[88:89], v[108:109], v[110:111]
	v_lshl_add_u64 v[108:109], s[8:9], 0, v[104:105]
	v_cvt_pk_bf16_f32 v100, v88, v89
	v_cvt_pk_bf16_f32 v101, v90, v91
	global_load_dwordx2 v[102:103], v[106:107], off
	v_lshl_add_u64 v[106:107], s[16:17], 0, v[120:121]
	global_store_dwordx2 v[106:107], v[100:101], off
	global_load_dwordx2 v[100:101], v[108:109], off
	v_lshl_add_u64 v[106:107], s[20:21], 0, v[98:99]
	v_lshl_add_u64 v[104:105], s[16:17], 0, v[104:105]
	v_mul_f32_e32 v89, v89, v89
	v_mul_f32_e32 v91, v91, v91
	v_fmac_f32_e32 v89, v88, v88
	v_fmac_f32_e32 v91, v90, v90
	v_add_f32_e32 v88, v89, v91
	v_add_f32_e32 v88, v92, v88
	s_waitcnt vmcnt(2)
	v_lshlrev_b32_e32 v108, 16, v102
	v_and_b32_e32 v109, 0xffff0000, v102
	v_lshlrev_b32_e32 v102, 16, v103
	v_and_b32_e32 v103, 0xffff0000, v103
	s_waitcnt vmcnt(0)
	v_lshlrev_b32_e32 v110, 16, v100
	v_and_b32_e32 v111, 0xffff0000, v100
	v_lshlrev_b32_e32 v100, 16, v101
	v_and_b32_e32 v101, 0xffff0000, v101
	v_pk_fma_f32 v[86:87], v[86:87], v[102:103], v[100:101]
	v_pk_fma_f32 v[84:85], v[84:85], v[108:109], v[110:111]
	s_nop 0
	v_cvt_pk_bf16_f32 v100, v84, v85
	v_cvt_pk_bf16_f32 v101, v86, v87
	global_load_dwordx2 v[102:103], v[106:107], off
	v_lshl_add_u64 v[106:107], s[8:9], 0, v[98:99]
	global_store_dwordx2 v[104:105], v[100:101], off
	global_load_dwordx2 v[100:101], v[106:107], off
	v_mul_f32_e32 v85, v85, v85
	v_mul_f32_e32 v87, v87, v87
	v_fmac_f32_e32 v85, v84, v84
	v_fmac_f32_e32 v87, v86, v86
	v_add_f32_e32 v84, v85, v87
	v_add_f32_e32 v92, v84, v88
	s_waitcnt vmcnt(2)
	v_lshlrev_b32_e32 v84, 16, v102
	v_and_b32_e32 v85, 0xffff0000, v102
	v_lshlrev_b32_e32 v86, 16, v103
	v_and_b32_e32 v87, 0xffff0000, v103
	s_waitcnt vmcnt(0)
	v_lshlrev_b32_e32 v88, 16, v100
	v_and_b32_e32 v89, 0xffff0000, v100
	v_lshlrev_b32_e32 v90, 16, v101
	v_and_b32_e32 v91, 0xffff0000, v101
	v_pk_fma_f32 v[82:83], v[82:83], v[86:87], v[90:91]
	v_pk_fma_f32 v[80:81], v[80:81], v[84:85], v[88:89]
	v_mul_f32_e32 v85, v83, v83
	v_mul_f32_e32 v84, v81, v81
	v_fmac_f32_e32 v84, v80, v80
	v_fmac_f32_e32 v85, v82, v82
	v_add_f32_e32 v84, v84, v85
	v_add_f32_e32 v86, v92, v84
	ds_swizzle_b32 v87, v86 offset:swizzle(SWAP,16)
	v_lshl_add_u64 v[84:85], s[16:17], 0, v[98:99]
	v_cvt_pk_bf16_f32 v80, v80, v81
	v_cvt_pk_bf16_f32 v81, v82, v83
	global_store_dwordx2 v[84:85], v[80:81], off
	s_waitcnt lgkmcnt(0)
	v_add_f32_e32 v80, v86, v87
	v_mov_b32_e32 v81, v80
	s_nop 1
	v_permlane32_swap_b32_e32 v80, v81
	s_and_saveexec_b64 s[2:3], s[4:5]
	s_cbranch_execz .LBB0_3050
	v_add_f32_e32 v82, v80, v81
	v_lshl_add_u64 v[80:81], s[10:11], 0, v[96:97]
	v_lshl_add_u64 v[80:81], s[36:37], 2, v[80:81]
	s_lshl_b32 s12, s50, 2
	v_lshl_add_u64 v[80:81], v[80:81], 0, s[12:13]
	global_store_dword v[80:81], v82, off
.LBB0_3050:
	s_or_b64 exec, exec, s[2:3]
	v_or_b32_e32 v82, 48, v142
	v_ashrrev_i32_e32 v83, 31, v82
	v_lshlrev_b64 v[80:81], 6, v[82:83]
	v_lshl_add_u64 v[96:97], s[18:19], 0, v[80:81]
	v_bfe_u32 v92, v206, 4, 2
	v_lshlrev_b32_e32 v92, 4, v92
	v_mov_b32_e32 v93, 0
	v_lshl_add_u64 v[88:89], v[96:97], 0, v[92:93]
	global_load_dwordx4 v[84:87], v[88:89], off
	s_nop 0
	v_lshlrev_b64 v[82:83], 10, v[82:83]
	v_lshl_add_u64 v[82:83], v[82:83], 0, v[140:141]
	v_lshlrev_b64 v[82:83], 1, v[82:83]
	v_lshl_add_u64 v[100:101], s[20:21], 0, v[82:83]
	v_lshl_add_u64 v[102:103], s[8:9], 0, v[82:83]
	global_load_dwordx2 v[100:101], v[100:101], off
	v_or_b32_e32 v104, 32, v82
	global_load_dwordx2 v[102:103], v[102:103], off
	v_mov_b32_e32 v105, v83
	v_lshl_add_u64 v[106:107], s[20:21], 0, v[104:105]
	s_waitcnt vmcnt(0)
	v_add_f32_e32 v88, v84, v85
	v_add_f32_e32 v89, v86, v87
	v_add_f32_e32 v88, v88, v89
	ds_swizzle_b32 v89, v88 offset:swizzle(SWAP,16)
	s_waitcnt lgkmcnt(0)
	v_add_f32_e32 v88, v88, v89
	v_mov_b32_e32 v89, v88
	s_nop 1
	v_permlane32_swap_b32_e32 v88, v89
	v_add_f32_e32 v96, v88, v89
	v_lshlrev_b32_e32 v90, 16, v101
	v_and_b32_e32 v91, 0xffff0000, v101
	v_mov_b32_e32 v84, v96
	v_fmamk_f32 v84, v84, 0x3a800000, v154
	v_mul_f32_e32 v85, 0x4b800000, v84
	v_cmp_gt_f32_e32 vcc, s56, v84
	v_lshlrev_b32_e32 v86, 16, v100
	v_and_b32_e32 v87, 0xffff0000, v100
	v_cndmask_b32_e32 v84, v84, v85, vcc
	v_rsq_f32_e32 v88, v84
	s_waitcnt vmcnt(0)
	v_lshlrev_b32_e32 v84, 16, v102
	v_and_b32_e32 v85, 0xffff0000, v102
	v_mul_f32_e32 v89, 0x45800000, v88
	v_cndmask_b32_e32 v96, v88, v89, vcc
	v_mul_f32_e32 v76, v76, v96
	v_mul_f32_e32 v77, v77, v96
	v_mul_f32_e32 v78, v78, v96
	v_mul_f32_e32 v79, v79, v96
	v_mul_f32_e32 v76, 0xbfb8aa3b, v76
	v_mul_f32_e32 v77, 0xbfb8aa3b, v77
	v_mul_f32_e32 v78, 0xbfb8aa3b, v78
	v_mul_f32_e32 v79, 0xbfb8aa3b, v79
	v_exp_f32_e32 v76, v76
	v_exp_f32_e32 v77, v77
	v_exp_f32_e32 v78, v78
	v_exp_f32_e32 v79, v79
	v_add_f32_e32 v76, 1.0, v76
	v_add_f32_e32 v88, 1.0, v77
	v_add_f32_e32 v77, 1.0, v78
	v_add_f32_e32 v79, 1.0, v79
	v_rcp_f32_e32 v78, v76
	v_rcp_f32_e32 v76, v77
	v_rcp_f32_e32 v77, v79
	v_rcp_f32_e32 v79, v88
	v_lshlrev_b32_e32 v88, 16, v103
	v_and_b32_e32 v89, 0xffff0000, v103
	v_pk_fma_f32 v[76:77], v[76:77], v[90:91], v[88:89]
	v_lshl_add_u64 v[88:89], s[16:17], 0, v[82:83]
	v_pk_fma_f32 v[78:79], v[78:79], v[86:87], v[84:85]
	v_lshl_add_u64 v[90:91], s[8:9], 0, v[104:105]
	v_cvt_pk_bf16_f32 v84, v78, v79
	v_cvt_pk_bf16_f32 v85, v76, v77
	global_store_dwordx2 v[88:89], v[84:85], off
	global_load_dwordx2 v[86:87], v[106:107], off
	v_mul_f32_e32 v72, v72, v96
	global_load_dwordx2 v[84:85], v[90:91], off
	v_mul_f32_e32 v73, v73, v96
	v_mul_f32_e32 v74, v74, v96
	v_mul_f32_e32 v75, v75, v96
	v_mul_f32_e32 v72, 0xbfb8aa3b, v72
	v_mul_f32_e32 v73, 0xbfb8aa3b, v73
	v_mul_f32_e32 v74, 0xbfb8aa3b, v74
	v_mul_f32_e32 v75, 0xbfb8aa3b, v75
	v_exp_f32_e32 v72, v72
	v_exp_f32_e32 v73, v73
	v_exp_f32_e32 v74, v74
	v_exp_f32_e32 v75, v75
	v_add_f32_e32 v72, 1.0, v72
	v_add_f32_e32 v73, 1.0, v73
	v_add_f32_e32 v74, 1.0, v74
	v_add_f32_e32 v75, 1.0, v75
	v_rcp_f32_e32 v72, v72
	v_rcp_f32_e32 v73, v73
	v_rcp_f32_e32 v74, v74
	v_rcp_f32_e32 v75, v75
	v_or_b32_e32 v88, 0x100, v82
	v_mov_b32_e32 v89, v83
	v_lshl_add_u64 v[90:91], s[20:21], 0, v[88:89]
	v_mul_f32_e32 v68, v68, v96
	v_mul_f32_e32 v69, v69, v96
	v_mul_f32_e32 v70, v70, v96
	v_mul_f32_e32 v71, v71, v96
	v_mul_f32_e32 v68, 0xbfb8aa3b, v68
	v_mul_f32_e32 v69, 0xbfb8aa3b, v69
	v_mul_f32_e32 v70, 0xbfb8aa3b, v70
	v_mul_f32_e32 v71, 0xbfb8aa3b, v71
	v_exp_f32_e32 v68, v68
	v_exp_f32_e32 v69, v69
	v_exp_f32_e32 v70, v70
	v_exp_f32_e32 v71, v71
	v_add_f32_e32 v68, 1.0, v68
	v_add_f32_e32 v69, 1.0, v69
	v_add_f32_e32 v70, 1.0, v70
	v_add_f32_e32 v71, 1.0, v71
	v_rcp_f32_e32 v68, v68
	v_rcp_f32_e32 v69, v69
	v_rcp_f32_e32 v70, v70
	v_rcp_f32_e32 v71, v71
	v_or_b32_e32 v82, 0x120, v82
	v_mul_f32_e32 v64, v64, v96
	v_mul_f32_e32 v65, v65, v96
	v_mul_f32_e32 v66, v66, v96
	v_mul_f32_e32 v67, v67, v96
	v_mul_f32_e32 v64, 0xbfb8aa3b, v64
	v_mul_f32_e32 v65, 0xbfb8aa3b, v65
	v_mul_f32_e32 v66, 0xbfb8aa3b, v66
	v_mul_f32_e32 v67, 0xbfb8aa3b, v67
	v_exp_f32_e32 v64, v64
	v_exp_f32_e32 v65, v65
	v_exp_f32_e32 v66, v66
	v_exp_f32_e32 v67, v67
	v_add_f32_e32 v64, 1.0, v64
	v_add_f32_e32 v65, 1.0, v65
	v_add_f32_e32 v66, 1.0, v66
	v_add_f32_e32 v67, 1.0, v67
	v_mul_f32_e32 v79, v79, v79
	v_mul_f32_e32 v77, v77, v77
	v_rcp_f32_e32 v64, v64
	v_rcp_f32_e32 v65, v65
	v_rcp_f32_e32 v66, v66
	v_rcp_f32_e32 v67, v67
	v_fmac_f32_e32 v79, v78, v78
	v_fmac_f32_e32 v77, v76, v76
	v_add_f32_e32 v76, v79, v77
	s_waitcnt vmcnt(1)
	v_lshlrev_b32_e32 v92, 16, v86
	v_and_b32_e32 v93, 0xffff0000, v86
	v_lshlrev_b32_e32 v86, 16, v87
	v_and_b32_e32 v87, 0xffff0000, v87
	s_waitcnt vmcnt(0)
	v_lshlrev_b32_e32 v94, 16, v84
	v_and_b32_e32 v95, 0xffff0000, v84
	v_lshlrev_b32_e32 v84, 16, v85
	v_and_b32_e32 v85, 0xffff0000, v85
	v_pk_fma_f32 v[74:75], v[74:75], v[86:87], v[84:85]
	v_pk_fma_f32 v[72:73], v[72:73], v[92:93], v[94:95]
	v_lshl_add_u64 v[92:93], s[8:9], 0, v[88:89]
	v_cvt_pk_bf16_f32 v84, v72, v73
	v_cvt_pk_bf16_f32 v85, v74, v75
	global_load_dwordx2 v[86:87], v[90:91], off
	v_lshl_add_u64 v[90:91], s[16:17], 0, v[104:105]
	global_store_dwordx2 v[90:91], v[84:85], off
	global_load_dwordx2 v[84:85], v[92:93], off
	v_lshl_add_u64 v[90:91], s[20:21], 0, v[82:83]
	v_lshl_add_u64 v[88:89], s[16:17], 0, v[88:89]
	v_mul_f32_e32 v73, v73, v73
	v_mul_f32_e32 v75, v75, v75
	v_fmac_f32_e32 v73, v72, v72
	v_fmac_f32_e32 v75, v74, v74
	v_add_f32_e32 v72, v73, v75
	v_add_f32_e32 v72, v76, v72
	s_waitcnt vmcnt(2)
	v_lshlrev_b32_e32 v92, 16, v86
	v_and_b32_e32 v93, 0xffff0000, v86
	v_lshlrev_b32_e32 v86, 16, v87
	v_and_b32_e32 v87, 0xffff0000, v87
	s_waitcnt vmcnt(0)
	v_lshlrev_b32_e32 v94, 16, v84
	v_and_b32_e32 v95, 0xffff0000, v84
	v_lshlrev_b32_e32 v84, 16, v85
	v_and_b32_e32 v85, 0xffff0000, v85
	v_pk_fma_f32 v[70:71], v[70:71], v[86:87], v[84:85]
	v_pk_fma_f32 v[68:69], v[68:69], v[92:93], v[94:95]
	s_nop 0
	v_cvt_pk_bf16_f32 v84, v68, v69
	v_cvt_pk_bf16_f32 v85, v70, v71
	global_load_dwordx2 v[86:87], v[90:91], off
	v_lshl_add_u64 v[90:91], s[8:9], 0, v[82:83]
	global_store_dwordx2 v[88:89], v[84:85], off
	global_load_dwordx2 v[84:85], v[90:91], off
	v_mul_f32_e32 v69, v69, v69
	v_mul_f32_e32 v71, v71, v71
	v_fmac_f32_e32 v69, v68, v68
	v_fmac_f32_e32 v71, v70, v70
	v_add_f32_e32 v68, v69, v71
	v_add_f32_e32 v76, v68, v72
	s_waitcnt vmcnt(2)
	v_lshlrev_b32_e32 v68, 16, v86
	v_and_b32_e32 v69, 0xffff0000, v86
	v_lshlrev_b32_e32 v70, 16, v87
	v_and_b32_e32 v71, 0xffff0000, v87
	s_waitcnt vmcnt(0)
	v_lshlrev_b32_e32 v72, 16, v84
	v_and_b32_e32 v73, 0xffff0000, v84
	v_lshlrev_b32_e32 v74, 16, v85
	v_and_b32_e32 v75, 0xffff0000, v85
	v_pk_fma_f32 v[66:67], v[66:67], v[70:71], v[74:75]
	v_pk_fma_f32 v[64:65], v[64:65], v[68:69], v[72:73]
	v_mul_f32_e32 v69, v67, v67
	v_mul_f32_e32 v68, v65, v65
	v_fmac_f32_e32 v68, v64, v64
	v_fmac_f32_e32 v69, v66, v66
	v_add_f32_e32 v68, v68, v69
	v_add_f32_e32 v70, v76, v68
	ds_swizzle_b32 v71, v70 offset:swizzle(SWAP,16)
	v_lshl_add_u64 v[68:69], s[16:17], 0, v[82:83]
	v_cvt_pk_bf16_f32 v64, v64, v65
	v_cvt_pk_bf16_f32 v65, v66, v67
	global_store_dwordx2 v[68:69], v[64:65], off
	s_waitcnt lgkmcnt(0)
	v_add_f32_e32 v64, v70, v71
	v_mov_b32_e32 v65, v64
	s_nop 1
	v_permlane32_swap_b32_e32 v64, v65
	s_and_saveexec_b64 s[2:3], s[4:5]
	s_cbranch_execz .LBB0_3052
	v_add_f32_e32 v66, v64, v65
	v_lshl_add_u64 v[64:65], s[10:11], 0, v[80:81]
	v_lshl_add_u64 v[64:65], s[36:37], 2, v[64:65]
	s_lshl_b32 s12, s50, 2
	v_lshl_add_u64 v[64:65], v[64:65], 0, s[12:13]
	global_store_dword v[64:65], v66, off
.LBB0_3052:
	s_or_b64 exec, exec, s[2:3]
	v_add_u32_e32 v66, 0x80, v142
	v_ashrrev_i32_e32 v67, 31, v66
	v_lshlrev_b64 v[64:65], 6, v[66:67]
	v_lshl_add_u64 v[80:81], s[18:19], 0, v[64:65]
	v_bfe_u32 v76, v206, 4, 2
	v_lshlrev_b32_e32 v76, 4, v76
	v_mov_b32_e32 v77, 0
	v_lshl_add_u64 v[72:73], v[80:81], 0, v[76:77]
	global_load_dwordx4 v[68:71], v[72:73], off
	s_nop 0
	v_lshlrev_b64 v[66:67], 10, v[66:67]
	v_lshl_add_u64 v[66:67], v[66:67], 0, v[140:141]
	v_lshlrev_b64 v[66:67], 1, v[66:67]
	v_lshl_add_u64 v[84:85], s[20:21], 0, v[66:67]
	v_lshl_add_u64 v[86:87], s[8:9], 0, v[66:67]
	global_load_dwordx2 v[84:85], v[84:85], off
	v_or_b32_e32 v88, 32, v66
	global_load_dwordx2 v[86:87], v[86:87], off
	v_mov_b32_e32 v89, v67
	v_lshl_add_u64 v[90:91], s[20:21], 0, v[88:89]
	s_waitcnt vmcnt(0)
	v_add_f32_e32 v72, v68, v69
	v_add_f32_e32 v73, v70, v71
	v_add_f32_e32 v72, v72, v73
	ds_swizzle_b32 v73, v72 offset:swizzle(SWAP,16)
	s_waitcnt lgkmcnt(0)
	v_add_f32_e32 v72, v72, v73
	v_mov_b32_e32 v73, v72
	s_nop 1
	v_permlane32_swap_b32_e32 v72, v73
	v_add_f32_e32 v80, v72, v73
	v_lshlrev_b32_e32 v74, 16, v85
	v_and_b32_e32 v75, 0xffff0000, v85
	v_mov_b32_e32 v68, v80
	v_fmamk_f32 v68, v68, 0x3a800000, v154
	v_mul_f32_e32 v69, 0x4b800000, v68
	v_cmp_gt_f32_e32 vcc, s56, v68
	v_lshlrev_b32_e32 v70, 16, v84
	v_and_b32_e32 v71, 0xffff0000, v84
	v_cndmask_b32_e32 v68, v68, v69, vcc
	v_rsq_f32_e32 v72, v68
	s_waitcnt vmcnt(0)
	v_lshlrev_b32_e32 v68, 16, v86
	v_and_b32_e32 v69, 0xffff0000, v86
	v_mul_f32_e32 v73, 0x45800000, v72
	v_cndmask_b32_e32 v80, v72, v73, vcc
	v_mul_f32_e32 v60, v60, v80
	v_mul_f32_e32 v61, v61, v80
	v_mul_f32_e32 v62, v62, v80
	v_mul_f32_e32 v63, v63, v80
	v_mul_f32_e32 v60, 0xbfb8aa3b, v60
	v_mul_f32_e32 v61, 0xbfb8aa3b, v61
	v_mul_f32_e32 v62, 0xbfb8aa3b, v62
	v_mul_f32_e32 v63, 0xbfb8aa3b, v63
	v_exp_f32_e32 v60, v60
	v_exp_f32_e32 v61, v61
	v_exp_f32_e32 v62, v62
	v_exp_f32_e32 v63, v63
	v_add_f32_e32 v60, 1.0, v60
	v_add_f32_e32 v72, 1.0, v61
	v_add_f32_e32 v61, 1.0, v62
	v_add_f32_e32 v63, 1.0, v63
	v_rcp_f32_e32 v62, v60
	v_rcp_f32_e32 v60, v61
	v_rcp_f32_e32 v61, v63
	v_rcp_f32_e32 v63, v72
	v_lshlrev_b32_e32 v72, 16, v87
	v_and_b32_e32 v73, 0xffff0000, v87
	v_pk_fma_f32 v[60:61], v[60:61], v[74:75], v[72:73]
	v_lshl_add_u64 v[72:73], s[16:17], 0, v[66:67]
	v_pk_fma_f32 v[62:63], v[62:63], v[70:71], v[68:69]
	v_lshl_add_u64 v[74:75], s[8:9], 0, v[88:89]
	v_cvt_pk_bf16_f32 v68, v62, v63
	v_cvt_pk_bf16_f32 v69, v60, v61
	global_store_dwordx2 v[72:73], v[68:69], off
	global_load_dwordx2 v[70:71], v[90:91], off
	v_mul_f32_e32 v56, v56, v80
	global_load_dwordx2 v[68:69], v[74:75], off
	v_mul_f32_e32 v57, v57, v80
	v_mul_f32_e32 v58, v58, v80
	v_mul_f32_e32 v59, v59, v80
	v_mul_f32_e32 v56, 0xbfb8aa3b, v56
	v_mul_f32_e32 v57, 0xbfb8aa3b, v57
	v_mul_f32_e32 v58, 0xbfb8aa3b, v58
	v_mul_f32_e32 v59, 0xbfb8aa3b, v59
	v_exp_f32_e32 v56, v56
	v_exp_f32_e32 v57, v57
	v_exp_f32_e32 v58, v58
	v_exp_f32_e32 v59, v59
	v_add_f32_e32 v56, 1.0, v56
	v_add_f32_e32 v57, 1.0, v57
	v_add_f32_e32 v58, 1.0, v58
	v_add_f32_e32 v59, 1.0, v59
	v_rcp_f32_e32 v56, v56
	v_rcp_f32_e32 v57, v57
	v_rcp_f32_e32 v58, v58
	v_rcp_f32_e32 v59, v59
	v_or_b32_e32 v72, 0x100, v66
	v_mov_b32_e32 v73, v67
	v_lshl_add_u64 v[74:75], s[20:21], 0, v[72:73]
	v_mul_f32_e32 v52, v52, v80
	v_mul_f32_e32 v53, v53, v80
	v_mul_f32_e32 v54, v54, v80
	v_mul_f32_e32 v55, v55, v80
	v_mul_f32_e32 v52, 0xbfb8aa3b, v52
	v_mul_f32_e32 v53, 0xbfb8aa3b, v53
	v_mul_f32_e32 v54, 0xbfb8aa3b, v54
	v_mul_f32_e32 v55, 0xbfb8aa3b, v55
	v_exp_f32_e32 v52, v52
	v_exp_f32_e32 v53, v53
	v_exp_f32_e32 v54, v54
	v_exp_f32_e32 v55, v55
	v_add_f32_e32 v52, 1.0, v52
	v_add_f32_e32 v53, 1.0, v53
	v_add_f32_e32 v54, 1.0, v54
	v_add_f32_e32 v55, 1.0, v55
	v_rcp_f32_e32 v52, v52
	v_rcp_f32_e32 v53, v53
	v_rcp_f32_e32 v54, v54
	v_rcp_f32_e32 v55, v55
	v_or_b32_e32 v66, 0x120, v66
	v_mul_f32_e32 v48, v48, v80
	v_mul_f32_e32 v49, v49, v80
	v_mul_f32_e32 v50, v50, v80
	v_mul_f32_e32 v51, v51, v80
	v_mul_f32_e32 v48, 0xbfb8aa3b, v48
	v_mul_f32_e32 v49, 0xbfb8aa3b, v49
	v_mul_f32_e32 v50, 0xbfb8aa3b, v50
	v_mul_f32_e32 v51, 0xbfb8aa3b, v51
	v_exp_f32_e32 v48, v48
	v_exp_f32_e32 v49, v49
	v_exp_f32_e32 v50, v50
	v_exp_f32_e32 v51, v51
	v_add_f32_e32 v48, 1.0, v48
	v_add_f32_e32 v49, 1.0, v49
	v_add_f32_e32 v50, 1.0, v50
	v_add_f32_e32 v51, 1.0, v51
	v_mul_f32_e32 v63, v63, v63
	v_mul_f32_e32 v61, v61, v61
	v_rcp_f32_e32 v48, v48
	v_rcp_f32_e32 v49, v49
	v_rcp_f32_e32 v50, v50
	v_rcp_f32_e32 v51, v51
	v_fmac_f32_e32 v63, v62, v62
	v_fmac_f32_e32 v61, v60, v60
	v_add_f32_e32 v60, v63, v61
	s_waitcnt vmcnt(1)
	v_lshlrev_b32_e32 v76, 16, v70
	v_and_b32_e32 v77, 0xffff0000, v70
	v_lshlrev_b32_e32 v70, 16, v71
	v_and_b32_e32 v71, 0xffff0000, v71
	s_waitcnt vmcnt(0)
	v_lshlrev_b32_e32 v78, 16, v68
	v_and_b32_e32 v79, 0xffff0000, v68
	v_lshlrev_b32_e32 v68, 16, v69
	v_and_b32_e32 v69, 0xffff0000, v69
	v_pk_fma_f32 v[58:59], v[58:59], v[70:71], v[68:69]
	v_pk_fma_f32 v[56:57], v[56:57], v[76:77], v[78:79]
	v_lshl_add_u64 v[76:77], s[8:9], 0, v[72:73]
	v_cvt_pk_bf16_f32 v68, v56, v57
	v_cvt_pk_bf16_f32 v69, v58, v59
	global_load_dwordx2 v[70:71], v[74:75], off
	v_lshl_add_u64 v[74:75], s[16:17], 0, v[88:89]
	global_store_dwordx2 v[74:75], v[68:69], off
	global_load_dwordx2 v[68:69], v[76:77], off
	v_lshl_add_u64 v[74:75], s[20:21], 0, v[66:67]
	v_lshl_add_u64 v[72:73], s[16:17], 0, v[72:73]
	v_mul_f32_e32 v57, v57, v57
	v_mul_f32_e32 v59, v59, v59
	v_fmac_f32_e32 v57, v56, v56
	v_fmac_f32_e32 v59, v58, v58
	v_add_f32_e32 v56, v57, v59
	v_add_f32_e32 v56, v60, v56
	s_waitcnt vmcnt(2)
	v_lshlrev_b32_e32 v76, 16, v70
	v_and_b32_e32 v77, 0xffff0000, v70
	v_lshlrev_b32_e32 v70, 16, v71
	v_and_b32_e32 v71, 0xffff0000, v71
	s_waitcnt vmcnt(0)
	v_lshlrev_b32_e32 v78, 16, v68
	v_and_b32_e32 v79, 0xffff0000, v68
	v_lshlrev_b32_e32 v68, 16, v69
	v_and_b32_e32 v69, 0xffff0000, v69
	v_pk_fma_f32 v[54:55], v[54:55], v[70:71], v[68:69]
	v_pk_fma_f32 v[52:53], v[52:53], v[76:77], v[78:79]
	s_nop 0
	v_cvt_pk_bf16_f32 v68, v52, v53
	v_cvt_pk_bf16_f32 v69, v54, v55
	global_load_dwordx2 v[70:71], v[74:75], off
	v_lshl_add_u64 v[74:75], s[8:9], 0, v[66:67]
	global_store_dwordx2 v[72:73], v[68:69], off
	global_load_dwordx2 v[68:69], v[74:75], off
	v_mul_f32_e32 v53, v53, v53
	v_mul_f32_e32 v55, v55, v55
	v_fmac_f32_e32 v53, v52, v52
	v_fmac_f32_e32 v55, v54, v54
	v_add_f32_e32 v52, v53, v55
	v_add_f32_e32 v60, v52, v56
	s_waitcnt vmcnt(2)
	v_lshlrev_b32_e32 v52, 16, v70
	v_and_b32_e32 v53, 0xffff0000, v70
	v_lshlrev_b32_e32 v54, 16, v71
	v_and_b32_e32 v55, 0xffff0000, v71
	s_waitcnt vmcnt(0)
	v_lshlrev_b32_e32 v56, 16, v68
	v_and_b32_e32 v57, 0xffff0000, v68
	v_lshlrev_b32_e32 v58, 16, v69
	v_and_b32_e32 v59, 0xffff0000, v69
	v_pk_fma_f32 v[50:51], v[50:51], v[54:55], v[58:59]
	v_pk_fma_f32 v[48:49], v[48:49], v[52:53], v[56:57]
	v_mul_f32_e32 v53, v51, v51
	v_mul_f32_e32 v52, v49, v49
	v_fmac_f32_e32 v52, v48, v48
	v_fmac_f32_e32 v53, v50, v50
	v_add_f32_e32 v52, v52, v53
	v_add_f32_e32 v54, v60, v52
	ds_swizzle_b32 v55, v54 offset:swizzle(SWAP,16)
	v_lshl_add_u64 v[52:53], s[16:17], 0, v[66:67]
	v_cvt_pk_bf16_f32 v48, v48, v49
	v_cvt_pk_bf16_f32 v49, v50, v51
	global_store_dwordx2 v[52:53], v[48:49], off
	s_waitcnt lgkmcnt(0)
	v_add_f32_e32 v48, v54, v55
	v_mov_b32_e32 v49, v48
	s_nop 1
	v_permlane32_swap_b32_e32 v48, v49
	s_and_saveexec_b64 s[2:3], s[4:5]
	s_cbranch_execz .LBB0_3054
	v_add_f32_e32 v50, v48, v49
	v_lshl_add_u64 v[48:49], s[10:11], 0, v[64:65]
	v_lshl_add_u64 v[48:49], s[36:37], 2, v[48:49]
	s_lshl_b32 s12, s50, 2
	v_lshl_add_u64 v[48:49], v[48:49], 0, s[12:13]
	global_store_dword v[48:49], v50, off
.LBB0_3054:
	s_or_b64 exec, exec, s[2:3]
	v_add_u32_e32 v50, 0x90, v142
	v_ashrrev_i32_e32 v51, 31, v50
	v_lshlrev_b64 v[48:49], 6, v[50:51]
	v_lshl_add_u64 v[64:65], s[18:19], 0, v[48:49]
	v_bfe_u32 v60, v206, 4, 2
	v_lshlrev_b32_e32 v60, 4, v60
	v_mov_b32_e32 v61, 0
	v_lshl_add_u64 v[56:57], v[64:65], 0, v[60:61]
	global_load_dwordx4 v[52:55], v[56:57], off
	s_nop 0
	v_lshlrev_b64 v[50:51], 10, v[50:51]
	v_lshl_add_u64 v[50:51], v[50:51], 0, v[140:141]
	v_lshlrev_b64 v[50:51], 1, v[50:51]
	v_lshl_add_u64 v[68:69], s[20:21], 0, v[50:51]
	v_lshl_add_u64 v[70:71], s[8:9], 0, v[50:51]
	global_load_dwordx2 v[68:69], v[68:69], off
	v_or_b32_e32 v72, 32, v50
	global_load_dwordx2 v[70:71], v[70:71], off
	v_mov_b32_e32 v73, v51
	v_lshl_add_u64 v[74:75], s[20:21], 0, v[72:73]
	s_waitcnt vmcnt(0)
	v_add_f32_e32 v56, v52, v53
	v_add_f32_e32 v57, v54, v55
	v_add_f32_e32 v56, v56, v57
	ds_swizzle_b32 v57, v56 offset:swizzle(SWAP,16)
	s_waitcnt lgkmcnt(0)
	v_add_f32_e32 v56, v56, v57
	v_mov_b32_e32 v57, v56
	s_nop 1
	v_permlane32_swap_b32_e32 v56, v57
	v_add_f32_e32 v64, v56, v57
	v_lshlrev_b32_e32 v58, 16, v69
	v_and_b32_e32 v59, 0xffff0000, v69
	v_mov_b32_e32 v52, v64
	v_fmamk_f32 v52, v52, 0x3a800000, v154
	v_mul_f32_e32 v53, 0x4b800000, v52
	v_cmp_gt_f32_e32 vcc, s56, v52
	v_lshlrev_b32_e32 v54, 16, v68
	v_and_b32_e32 v55, 0xffff0000, v68
	v_cndmask_b32_e32 v52, v52, v53, vcc
	v_rsq_f32_e32 v56, v52
	s_waitcnt vmcnt(0)
	v_lshlrev_b32_e32 v52, 16, v70
	v_and_b32_e32 v53, 0xffff0000, v70
	v_mul_f32_e32 v57, 0x45800000, v56
	v_cndmask_b32_e32 v64, v56, v57, vcc
	v_mul_f32_e32 v44, v44, v64
	v_mul_f32_e32 v45, v45, v64
	v_mul_f32_e32 v46, v46, v64
	v_mul_f32_e32 v47, v47, v64
	v_mul_f32_e32 v44, 0xbfb8aa3b, v44
	v_mul_f32_e32 v45, 0xbfb8aa3b, v45
	v_mul_f32_e32 v46, 0xbfb8aa3b, v46
	v_mul_f32_e32 v47, 0xbfb8aa3b, v47
	v_exp_f32_e32 v44, v44
	v_exp_f32_e32 v45, v45
	v_exp_f32_e32 v46, v46
	v_exp_f32_e32 v47, v47
	v_add_f32_e32 v44, 1.0, v44
	v_add_f32_e32 v56, 1.0, v45
	v_add_f32_e32 v45, 1.0, v46
	v_add_f32_e32 v47, 1.0, v47
	v_rcp_f32_e32 v46, v44
	v_rcp_f32_e32 v44, v45
	v_rcp_f32_e32 v45, v47
	v_rcp_f32_e32 v47, v56
	v_lshlrev_b32_e32 v56, 16, v71
	v_and_b32_e32 v57, 0xffff0000, v71
	v_pk_fma_f32 v[44:45], v[44:45], v[58:59], v[56:57]
	v_lshl_add_u64 v[56:57], s[16:17], 0, v[50:51]
	v_pk_fma_f32 v[46:47], v[46:47], v[54:55], v[52:53]
	v_lshl_add_u64 v[58:59], s[8:9], 0, v[72:73]
	v_cvt_pk_bf16_f32 v52, v46, v47
	v_cvt_pk_bf16_f32 v53, v44, v45
	global_store_dwordx2 v[56:57], v[52:53], off
	global_load_dwordx2 v[54:55], v[74:75], off
	v_mul_f32_e32 v40, v40, v64
	global_load_dwordx2 v[52:53], v[58:59], off
	v_mul_f32_e32 v41, v41, v64
	v_mul_f32_e32 v42, v42, v64
	v_mul_f32_e32 v43, v43, v64
	v_mul_f32_e32 v40, 0xbfb8aa3b, v40
	v_mul_f32_e32 v41, 0xbfb8aa3b, v41
	v_mul_f32_e32 v42, 0xbfb8aa3b, v42
	v_mul_f32_e32 v43, 0xbfb8aa3b, v43
	v_exp_f32_e32 v40, v40
	v_exp_f32_e32 v41, v41
	v_exp_f32_e32 v42, v42
	v_exp_f32_e32 v43, v43
	v_add_f32_e32 v40, 1.0, v40
	v_add_f32_e32 v41, 1.0, v41
	v_add_f32_e32 v42, 1.0, v42
	v_add_f32_e32 v43, 1.0, v43
	v_rcp_f32_e32 v40, v40
	v_rcp_f32_e32 v41, v41
	v_rcp_f32_e32 v42, v42
	v_rcp_f32_e32 v43, v43
	v_or_b32_e32 v56, 0x100, v50
	v_mov_b32_e32 v57, v51
	v_lshl_add_u64 v[58:59], s[20:21], 0, v[56:57]
	v_mul_f32_e32 v36, v36, v64
	v_mul_f32_e32 v37, v37, v64
	v_mul_f32_e32 v38, v38, v64
	v_mul_f32_e32 v39, v39, v64
	v_mul_f32_e32 v36, 0xbfb8aa3b, v36
	v_mul_f32_e32 v37, 0xbfb8aa3b, v37
	v_mul_f32_e32 v38, 0xbfb8aa3b, v38
	v_mul_f32_e32 v39, 0xbfb8aa3b, v39
	v_exp_f32_e32 v36, v36
	v_exp_f32_e32 v37, v37
	v_exp_f32_e32 v38, v38
	v_exp_f32_e32 v39, v39
	v_add_f32_e32 v36, 1.0, v36
	v_add_f32_e32 v37, 1.0, v37
	v_add_f32_e32 v38, 1.0, v38
	v_add_f32_e32 v39, 1.0, v39
	v_rcp_f32_e32 v36, v36
	v_rcp_f32_e32 v37, v37
	v_rcp_f32_e32 v38, v38
	v_rcp_f32_e32 v39, v39
	v_or_b32_e32 v50, 0x120, v50
	v_mul_f32_e32 v32, v32, v64
	v_mul_f32_e32 v33, v33, v64
	v_mul_f32_e32 v34, v34, v64
	v_mul_f32_e32 v35, v35, v64
	v_mul_f32_e32 v32, 0xbfb8aa3b, v32
	v_mul_f32_e32 v33, 0xbfb8aa3b, v33
	v_mul_f32_e32 v34, 0xbfb8aa3b, v34
	v_mul_f32_e32 v35, 0xbfb8aa3b, v35
	v_exp_f32_e32 v32, v32
	v_exp_f32_e32 v33, v33
	v_exp_f32_e32 v34, v34
	v_exp_f32_e32 v35, v35
	v_add_f32_e32 v32, 1.0, v32
	v_add_f32_e32 v33, 1.0, v33
	v_add_f32_e32 v34, 1.0, v34
	v_add_f32_e32 v35, 1.0, v35
	v_mul_f32_e32 v47, v47, v47
	v_mul_f32_e32 v45, v45, v45
	v_rcp_f32_e32 v32, v32
	v_rcp_f32_e32 v33, v33
	v_rcp_f32_e32 v34, v34
	v_rcp_f32_e32 v35, v35
	v_fmac_f32_e32 v47, v46, v46
	v_fmac_f32_e32 v45, v44, v44
	v_add_f32_e32 v44, v47, v45
	s_waitcnt vmcnt(1)
	v_lshlrev_b32_e32 v60, 16, v54
	v_and_b32_e32 v61, 0xffff0000, v54
	v_lshlrev_b32_e32 v54, 16, v55
	v_and_b32_e32 v55, 0xffff0000, v55
	s_waitcnt vmcnt(0)
	v_lshlrev_b32_e32 v62, 16, v52
	v_and_b32_e32 v63, 0xffff0000, v52
	v_lshlrev_b32_e32 v52, 16, v53
	v_and_b32_e32 v53, 0xffff0000, v53
	v_pk_fma_f32 v[42:43], v[42:43], v[54:55], v[52:53]
	v_pk_fma_f32 v[40:41], v[40:41], v[60:61], v[62:63]
	v_lshl_add_u64 v[60:61], s[8:9], 0, v[56:57]
	v_cvt_pk_bf16_f32 v52, v40, v41
	v_cvt_pk_bf16_f32 v53, v42, v43
	global_load_dwordx2 v[54:55], v[58:59], off
	v_lshl_add_u64 v[58:59], s[16:17], 0, v[72:73]
	global_store_dwordx2 v[58:59], v[52:53], off
	global_load_dwordx2 v[52:53], v[60:61], off
	v_lshl_add_u64 v[58:59], s[20:21], 0, v[50:51]
	v_lshl_add_u64 v[56:57], s[16:17], 0, v[56:57]
	v_mul_f32_e32 v41, v41, v41
	v_mul_f32_e32 v43, v43, v43
	v_fmac_f32_e32 v41, v40, v40
	v_fmac_f32_e32 v43, v42, v42
	v_add_f32_e32 v40, v41, v43
	v_add_f32_e32 v40, v44, v40
	s_waitcnt vmcnt(2)
	v_lshlrev_b32_e32 v60, 16, v54
	v_and_b32_e32 v61, 0xffff0000, v54
	v_lshlrev_b32_e32 v54, 16, v55
	v_and_b32_e32 v55, 0xffff0000, v55
	s_waitcnt vmcnt(0)
	v_lshlrev_b32_e32 v62, 16, v52
	v_and_b32_e32 v63, 0xffff0000, v52
	v_lshlrev_b32_e32 v52, 16, v53
	v_and_b32_e32 v53, 0xffff0000, v53
	v_pk_fma_f32 v[38:39], v[38:39], v[54:55], v[52:53]
	v_pk_fma_f32 v[36:37], v[36:37], v[60:61], v[62:63]
	s_nop 0
	v_cvt_pk_bf16_f32 v52, v36, v37
	v_cvt_pk_bf16_f32 v53, v38, v39
	global_load_dwordx2 v[54:55], v[58:59], off
	v_lshl_add_u64 v[58:59], s[8:9], 0, v[50:51]
	global_store_dwordx2 v[56:57], v[52:53], off
	global_load_dwordx2 v[52:53], v[58:59], off
	v_mul_f32_e32 v37, v37, v37
	v_mul_f32_e32 v39, v39, v39
	v_fmac_f32_e32 v37, v36, v36
	v_fmac_f32_e32 v39, v38, v38
	v_add_f32_e32 v36, v37, v39
	v_add_f32_e32 v44, v36, v40
	s_waitcnt vmcnt(2)
	v_lshlrev_b32_e32 v36, 16, v54
	v_and_b32_e32 v37, 0xffff0000, v54
	v_lshlrev_b32_e32 v38, 16, v55
	v_and_b32_e32 v39, 0xffff0000, v55
	s_waitcnt vmcnt(0)
	v_lshlrev_b32_e32 v40, 16, v52
	v_and_b32_e32 v41, 0xffff0000, v52
	v_lshlrev_b32_e32 v42, 16, v53
	v_and_b32_e32 v43, 0xffff0000, v53
	v_pk_fma_f32 v[34:35], v[34:35], v[38:39], v[42:43]
	v_pk_fma_f32 v[32:33], v[32:33], v[36:37], v[40:41]
	v_mul_f32_e32 v37, v35, v35
	v_mul_f32_e32 v36, v33, v33
	v_fmac_f32_e32 v36, v32, v32
	v_fmac_f32_e32 v37, v34, v34
	v_add_f32_e32 v36, v36, v37
	v_add_f32_e32 v38, v44, v36
	ds_swizzle_b32 v39, v38 offset:swizzle(SWAP,16)
	v_lshl_add_u64 v[36:37], s[16:17], 0, v[50:51]
	v_cvt_pk_bf16_f32 v32, v32, v33
	v_cvt_pk_bf16_f32 v33, v34, v35
	global_store_dwordx2 v[36:37], v[32:33], off
	s_waitcnt lgkmcnt(0)
	v_add_f32_e32 v32, v38, v39
	v_mov_b32_e32 v33, v32
	s_nop 1
	v_permlane32_swap_b32_e32 v32, v33
	s_and_saveexec_b64 s[2:3], s[4:5]
	s_cbranch_execz .LBB0_3056
	v_add_f32_e32 v34, v32, v33
	v_lshl_add_u64 v[32:33], s[10:11], 0, v[48:49]
	v_lshl_add_u64 v[32:33], s[36:37], 2, v[32:33]
	s_lshl_b32 s12, s50, 2
	v_lshl_add_u64 v[32:33], v[32:33], 0, s[12:13]
	global_store_dword v[32:33], v34, off
.LBB0_3056:
	s_or_b64 exec, exec, s[2:3]
	v_add_u32_e32 v34, 0xa0, v142
	v_ashrrev_i32_e32 v35, 31, v34
	v_lshlrev_b64 v[32:33], 6, v[34:35]
	v_lshl_add_u64 v[48:49], s[18:19], 0, v[32:33]
	v_bfe_u32 v44, v206, 4, 2
	v_lshlrev_b32_e32 v44, 4, v44
	v_mov_b32_e32 v45, 0
	v_lshl_add_u64 v[40:41], v[48:49], 0, v[44:45]
	global_load_dwordx4 v[36:39], v[40:41], off
	s_nop 0
	v_lshlrev_b64 v[34:35], 10, v[34:35]
	v_lshl_add_u64 v[34:35], v[34:35], 0, v[140:141]
	v_lshlrev_b64 v[34:35], 1, v[34:35]
	v_lshl_add_u64 v[52:53], s[20:21], 0, v[34:35]
	v_lshl_add_u64 v[54:55], s[8:9], 0, v[34:35]
	global_load_dwordx2 v[52:53], v[52:53], off
	v_or_b32_e32 v56, 32, v34
	global_load_dwordx2 v[54:55], v[54:55], off
	v_mov_b32_e32 v57, v35
	v_lshl_add_u64 v[58:59], s[20:21], 0, v[56:57]
	s_waitcnt vmcnt(0)
	v_add_f32_e32 v40, v36, v37
	v_add_f32_e32 v41, v38, v39
	v_add_f32_e32 v40, v40, v41
	ds_swizzle_b32 v41, v40 offset:swizzle(SWAP,16)
	s_waitcnt lgkmcnt(0)
	v_add_f32_e32 v40, v40, v41
	v_mov_b32_e32 v41, v40
	s_nop 1
	v_permlane32_swap_b32_e32 v40, v41
	v_add_f32_e32 v48, v40, v41
	v_lshlrev_b32_e32 v42, 16, v53
	v_and_b32_e32 v43, 0xffff0000, v53
	v_mov_b32_e32 v36, v48
	v_fmamk_f32 v36, v36, 0x3a800000, v154
	v_mul_f32_e32 v37, 0x4b800000, v36
	v_cmp_gt_f32_e32 vcc, s56, v36
	v_lshlrev_b32_e32 v38, 16, v52
	v_and_b32_e32 v39, 0xffff0000, v52
	v_cndmask_b32_e32 v36, v36, v37, vcc
	v_rsq_f32_e32 v40, v36
	s_waitcnt vmcnt(0)
	v_lshlrev_b32_e32 v36, 16, v54
	v_and_b32_e32 v37, 0xffff0000, v54
	v_mul_f32_e32 v41, 0x45800000, v40
	v_cndmask_b32_e32 v48, v40, v41, vcc
	v_mul_f32_e32 v28, v28, v48
	v_mul_f32_e32 v29, v29, v48
	v_mul_f32_e32 v30, v30, v48
	v_mul_f32_e32 v31, v31, v48
	v_mul_f32_e32 v28, 0xbfb8aa3b, v28
	v_mul_f32_e32 v29, 0xbfb8aa3b, v29
	v_mul_f32_e32 v30, 0xbfb8aa3b, v30
	v_mul_f32_e32 v31, 0xbfb8aa3b, v31
	v_exp_f32_e32 v28, v28
	v_exp_f32_e32 v29, v29
	v_exp_f32_e32 v30, v30
	v_exp_f32_e32 v31, v31
	v_add_f32_e32 v28, 1.0, v28
	v_add_f32_e32 v40, 1.0, v29
	v_add_f32_e32 v29, 1.0, v30
	v_add_f32_e32 v31, 1.0, v31
	v_rcp_f32_e32 v30, v28
	v_rcp_f32_e32 v28, v29
	v_rcp_f32_e32 v29, v31
	v_rcp_f32_e32 v31, v40
	v_lshlrev_b32_e32 v40, 16, v55
	v_and_b32_e32 v41, 0xffff0000, v55
	v_pk_fma_f32 v[28:29], v[28:29], v[42:43], v[40:41]
	v_lshl_add_u64 v[40:41], s[16:17], 0, v[34:35]
	v_pk_fma_f32 v[30:31], v[30:31], v[38:39], v[36:37]
	v_lshl_add_u64 v[42:43], s[8:9], 0, v[56:57]
	v_cvt_pk_bf16_f32 v36, v30, v31
	v_cvt_pk_bf16_f32 v37, v28, v29
	global_store_dwordx2 v[40:41], v[36:37], off
	global_load_dwordx2 v[38:39], v[58:59], off
	v_mul_f32_e32 v24, v24, v48
	global_load_dwordx2 v[36:37], v[42:43], off
	v_mul_f32_e32 v25, v25, v48
	v_mul_f32_e32 v26, v26, v48
	v_mul_f32_e32 v27, v27, v48
	v_mul_f32_e32 v24, 0xbfb8aa3b, v24
	v_mul_f32_e32 v25, 0xbfb8aa3b, v25
	v_mul_f32_e32 v26, 0xbfb8aa3b, v26
	v_mul_f32_e32 v27, 0xbfb8aa3b, v27
	v_exp_f32_e32 v24, v24
	v_exp_f32_e32 v25, v25
	v_exp_f32_e32 v26, v26
	v_exp_f32_e32 v27, v27
	v_add_f32_e32 v24, 1.0, v24
	v_add_f32_e32 v25, 1.0, v25
	v_add_f32_e32 v26, 1.0, v26
	v_add_f32_e32 v27, 1.0, v27
	v_rcp_f32_e32 v24, v24
	v_rcp_f32_e32 v25, v25
	v_rcp_f32_e32 v26, v26
	v_rcp_f32_e32 v27, v27
	v_or_b32_e32 v40, 0x100, v34
	v_mov_b32_e32 v41, v35
	v_lshl_add_u64 v[42:43], s[20:21], 0, v[40:41]
	v_mul_f32_e32 v20, v20, v48
	v_mul_f32_e32 v21, v21, v48
	v_mul_f32_e32 v22, v22, v48
	v_mul_f32_e32 v23, v23, v48
	v_mul_f32_e32 v20, 0xbfb8aa3b, v20
	v_mul_f32_e32 v21, 0xbfb8aa3b, v21
	v_mul_f32_e32 v22, 0xbfb8aa3b, v22
	v_mul_f32_e32 v23, 0xbfb8aa3b, v23
	v_exp_f32_e32 v20, v20
	v_exp_f32_e32 v21, v21
	v_exp_f32_e32 v22, v22
	v_exp_f32_e32 v23, v23
	v_add_f32_e32 v20, 1.0, v20
	v_add_f32_e32 v21, 1.0, v21
	v_add_f32_e32 v22, 1.0, v22
	v_add_f32_e32 v23, 1.0, v23
	v_rcp_f32_e32 v20, v20
	v_rcp_f32_e32 v21, v21
	v_rcp_f32_e32 v22, v22
	v_rcp_f32_e32 v23, v23
	v_or_b32_e32 v34, 0x120, v34
	v_mul_f32_e32 v16, v16, v48
	v_mul_f32_e32 v17, v17, v48
	v_mul_f32_e32 v18, v18, v48
	v_mul_f32_e32 v19, v19, v48
	v_mul_f32_e32 v16, 0xbfb8aa3b, v16
	v_mul_f32_e32 v17, 0xbfb8aa3b, v17
	v_mul_f32_e32 v18, 0xbfb8aa3b, v18
	v_mul_f32_e32 v19, 0xbfb8aa3b, v19
	v_exp_f32_e32 v16, v16
	v_exp_f32_e32 v17, v17
	v_exp_f32_e32 v18, v18
	v_exp_f32_e32 v19, v19
	v_add_f32_e32 v16, 1.0, v16
	v_add_f32_e32 v17, 1.0, v17
	v_add_f32_e32 v18, 1.0, v18
	v_add_f32_e32 v19, 1.0, v19
	v_mul_f32_e32 v31, v31, v31
	v_mul_f32_e32 v29, v29, v29
	v_rcp_f32_e32 v16, v16
	v_rcp_f32_e32 v17, v17
	v_rcp_f32_e32 v18, v18
	v_rcp_f32_e32 v19, v19
	v_fmac_f32_e32 v31, v30, v30
	v_fmac_f32_e32 v29, v28, v28
	v_add_f32_e32 v28, v31, v29
	s_waitcnt vmcnt(1)
	v_lshlrev_b32_e32 v44, 16, v38
	v_and_b32_e32 v45, 0xffff0000, v38
	v_lshlrev_b32_e32 v38, 16, v39
	v_and_b32_e32 v39, 0xffff0000, v39
	s_waitcnt vmcnt(0)
	v_lshlrev_b32_e32 v46, 16, v36
	v_and_b32_e32 v47, 0xffff0000, v36
	v_lshlrev_b32_e32 v36, 16, v37
	v_and_b32_e32 v37, 0xffff0000, v37
	v_pk_fma_f32 v[26:27], v[26:27], v[38:39], v[36:37]
	v_pk_fma_f32 v[24:25], v[24:25], v[44:45], v[46:47]
	v_lshl_add_u64 v[44:45], s[8:9], 0, v[40:41]
	v_cvt_pk_bf16_f32 v36, v24, v25
	v_cvt_pk_bf16_f32 v37, v26, v27
	global_load_dwordx2 v[38:39], v[42:43], off
	v_lshl_add_u64 v[42:43], s[16:17], 0, v[56:57]
	global_store_dwordx2 v[42:43], v[36:37], off
	global_load_dwordx2 v[36:37], v[44:45], off
	v_lshl_add_u64 v[42:43], s[20:21], 0, v[34:35]
	v_lshl_add_u64 v[40:41], s[16:17], 0, v[40:41]
	v_mul_f32_e32 v25, v25, v25
	v_mul_f32_e32 v27, v27, v27
	v_fmac_f32_e32 v25, v24, v24
	v_fmac_f32_e32 v27, v26, v26
	v_add_f32_e32 v24, v25, v27
	v_add_f32_e32 v24, v28, v24
	s_waitcnt vmcnt(2)
	v_lshlrev_b32_e32 v44, 16, v38
	v_and_b32_e32 v45, 0xffff0000, v38
	v_lshlrev_b32_e32 v38, 16, v39
	v_and_b32_e32 v39, 0xffff0000, v39
	s_waitcnt vmcnt(0)
	v_lshlrev_b32_e32 v46, 16, v36
	v_and_b32_e32 v47, 0xffff0000, v36
	v_lshlrev_b32_e32 v36, 16, v37
	v_and_b32_e32 v37, 0xffff0000, v37
	v_pk_fma_f32 v[22:23], v[22:23], v[38:39], v[36:37]
	v_pk_fma_f32 v[20:21], v[20:21], v[44:45], v[46:47]
	s_nop 0
	v_cvt_pk_bf16_f32 v36, v20, v21
	v_cvt_pk_bf16_f32 v37, v22, v23
	global_load_dwordx2 v[38:39], v[42:43], off
	v_lshl_add_u64 v[42:43], s[8:9], 0, v[34:35]
	global_store_dwordx2 v[40:41], v[36:37], off
	global_load_dwordx2 v[36:37], v[42:43], off
	v_mul_f32_e32 v21, v21, v21
	v_mul_f32_e32 v23, v23, v23
	v_fmac_f32_e32 v21, v20, v20
	v_fmac_f32_e32 v23, v22, v22
	v_add_f32_e32 v20, v21, v23
	v_add_f32_e32 v28, v20, v24
	s_waitcnt vmcnt(2)
	v_lshlrev_b32_e32 v20, 16, v38
	v_and_b32_e32 v21, 0xffff0000, v38
	v_lshlrev_b32_e32 v22, 16, v39
	v_and_b32_e32 v23, 0xffff0000, v39
	s_waitcnt vmcnt(0)
	v_lshlrev_b32_e32 v24, 16, v36
	v_and_b32_e32 v25, 0xffff0000, v36
	v_lshlrev_b32_e32 v26, 16, v37
	v_and_b32_e32 v27, 0xffff0000, v37
	v_pk_fma_f32 v[18:19], v[18:19], v[22:23], v[26:27]
	v_pk_fma_f32 v[16:17], v[16:17], v[20:21], v[24:25]
	v_mul_f32_e32 v21, v19, v19
	v_mul_f32_e32 v20, v17, v17
	v_fmac_f32_e32 v20, v16, v16
	v_fmac_f32_e32 v21, v18, v18
	v_add_f32_e32 v20, v20, v21
	v_add_f32_e32 v22, v28, v20
	ds_swizzle_b32 v23, v22 offset:swizzle(SWAP,16)
	v_lshl_add_u64 v[20:21], s[16:17], 0, v[34:35]
	v_cvt_pk_bf16_f32 v16, v16, v17
	v_cvt_pk_bf16_f32 v17, v18, v19
	global_store_dwordx2 v[20:21], v[16:17], off
	s_waitcnt lgkmcnt(0)
	v_add_f32_e32 v16, v22, v23
	v_mov_b32_e32 v17, v16
	s_nop 1
	v_permlane32_swap_b32_e32 v16, v17
	s_and_saveexec_b64 s[2:3], s[4:5]
	s_cbranch_execz .LBB0_3058
	v_add_f32_e32 v18, v16, v17
	v_lshl_add_u64 v[16:17], s[10:11], 0, v[32:33]
	v_lshl_add_u64 v[16:17], s[36:37], 2, v[16:17]
	s_lshl_b32 s12, s50, 2
	v_lshl_add_u64 v[16:17], v[16:17], 0, s[12:13]
	global_store_dword v[16:17], v18, off
.LBB0_3058:
	s_or_b64 exec, exec, s[2:3]
	v_add_u32_e32 v18, 0xb0, v142
	v_ashrrev_i32_e32 v19, 31, v18
	v_lshlrev_b64 v[16:17], 6, v[18:19]
	v_lshl_add_u64 v[32:33], s[18:19], 0, v[16:17]
	v_bfe_u32 v28, v206, 4, 2
	v_lshlrev_b32_e32 v28, 4, v28
	v_mov_b32_e32 v29, 0
	v_lshl_add_u64 v[24:25], v[32:33], 0, v[28:29]
	global_load_dwordx4 v[20:23], v[24:25], off
	s_nop 0
	v_lshlrev_b64 v[18:19], 10, v[18:19]
	v_lshl_add_u64 v[18:19], v[18:19], 0, v[140:141]
	v_lshlrev_b64 v[18:19], 1, v[18:19]
	v_lshl_add_u64 v[36:37], s[20:21], 0, v[18:19]
	v_lshl_add_u64 v[38:39], s[8:9], 0, v[18:19]
	global_load_dwordx2 v[36:37], v[36:37], off
	v_or_b32_e32 v40, 32, v18
	global_load_dwordx2 v[38:39], v[38:39], off
	v_mov_b32_e32 v41, v19
	v_lshl_add_u64 v[42:43], s[20:21], 0, v[40:41]
	s_waitcnt vmcnt(0)
	v_add_f32_e32 v24, v20, v21
	v_add_f32_e32 v25, v22, v23
	v_add_f32_e32 v24, v24, v25
	ds_swizzle_b32 v25, v24 offset:swizzle(SWAP,16)
	s_waitcnt lgkmcnt(0)
	v_add_f32_e32 v24, v24, v25
	v_mov_b32_e32 v25, v24
	s_nop 1
	v_permlane32_swap_b32_e32 v24, v25
	v_add_f32_e32 v32, v24, v25
	v_lshlrev_b32_e32 v26, 16, v37
	v_and_b32_e32 v27, 0xffff0000, v37
	v_mov_b32_e32 v20, v32
	v_fmamk_f32 v20, v20, 0x3a800000, v154
	v_mul_f32_e32 v21, 0x4b800000, v20
	v_cmp_gt_f32_e32 vcc, s56, v20
	v_lshlrev_b32_e32 v22, 16, v36
	v_and_b32_e32 v23, 0xffff0000, v36
	v_cndmask_b32_e32 v20, v20, v21, vcc
	v_rsq_f32_e32 v24, v20
	s_waitcnt vmcnt(0)
	v_lshlrev_b32_e32 v20, 16, v38
	v_and_b32_e32 v21, 0xffff0000, v38
	v_mul_f32_e32 v25, 0x45800000, v24
	v_cndmask_b32_e32 v32, v24, v25, vcc
	v_mul_f32_e32 v12, v12, v32
	v_mul_f32_e32 v13, v13, v32
	v_mul_f32_e32 v14, v14, v32
	v_mul_f32_e32 v15, v15, v32
	v_mul_f32_e32 v12, 0xbfb8aa3b, v12
	v_mul_f32_e32 v13, 0xbfb8aa3b, v13
	v_mul_f32_e32 v14, 0xbfb8aa3b, v14
	v_mul_f32_e32 v15, 0xbfb8aa3b, v15
	v_exp_f32_e32 v12, v12
	v_exp_f32_e32 v13, v13
	v_exp_f32_e32 v14, v14
	v_exp_f32_e32 v15, v15
	v_add_f32_e32 v12, 1.0, v12
	v_add_f32_e32 v24, 1.0, v13
	v_add_f32_e32 v13, 1.0, v14
	v_add_f32_e32 v15, 1.0, v15
	v_rcp_f32_e32 v14, v12
	v_rcp_f32_e32 v12, v13
	v_rcp_f32_e32 v13, v15
	v_rcp_f32_e32 v15, v24
	v_lshlrev_b32_e32 v24, 16, v39
	v_and_b32_e32 v25, 0xffff0000, v39
	v_pk_fma_f32 v[12:13], v[12:13], v[26:27], v[24:25]
	v_lshl_add_u64 v[24:25], s[16:17], 0, v[18:19]
	v_pk_fma_f32 v[14:15], v[14:15], v[22:23], v[20:21]
	v_lshl_add_u64 v[26:27], s[8:9], 0, v[40:41]
	v_cvt_pk_bf16_f32 v20, v14, v15
	v_cvt_pk_bf16_f32 v21, v12, v13
	global_store_dwordx2 v[24:25], v[20:21], off
	global_load_dwordx2 v[22:23], v[42:43], off
	v_mul_f32_e32 v8, v8, v32
	global_load_dwordx2 v[20:21], v[26:27], off
	v_mul_f32_e32 v9, v9, v32
	v_mul_f32_e32 v10, v10, v32
	v_mul_f32_e32 v11, v11, v32
	v_mul_f32_e32 v8, 0xbfb8aa3b, v8
	v_mul_f32_e32 v9, 0xbfb8aa3b, v9
	v_mul_f32_e32 v10, 0xbfb8aa3b, v10
	v_mul_f32_e32 v11, 0xbfb8aa3b, v11
	v_exp_f32_e32 v8, v8
	v_exp_f32_e32 v9, v9
	v_exp_f32_e32 v10, v10
	v_exp_f32_e32 v11, v11
	v_add_f32_e32 v8, 1.0, v8
	v_add_f32_e32 v9, 1.0, v9
	v_add_f32_e32 v10, 1.0, v10
	v_add_f32_e32 v11, 1.0, v11
	v_rcp_f32_e32 v8, v8
	v_rcp_f32_e32 v9, v9
	v_rcp_f32_e32 v10, v10
	v_rcp_f32_e32 v11, v11
	v_or_b32_e32 v24, 0x100, v18
	v_mov_b32_e32 v25, v19
	v_lshl_add_u64 v[26:27], s[20:21], 0, v[24:25]
	v_mul_f32_e32 v4, v4, v32
	v_mul_f32_e32 v5, v5, v32
	v_mul_f32_e32 v6, v6, v32
	v_mul_f32_e32 v7, v7, v32
	v_mul_f32_e32 v4, 0xbfb8aa3b, v4
	v_mul_f32_e32 v5, 0xbfb8aa3b, v5
	v_mul_f32_e32 v6, 0xbfb8aa3b, v6
	v_mul_f32_e32 v7, 0xbfb8aa3b, v7
	v_exp_f32_e32 v4, v4
	v_exp_f32_e32 v5, v5
	v_exp_f32_e32 v6, v6
	v_exp_f32_e32 v7, v7
	v_add_f32_e32 v4, 1.0, v4
	v_add_f32_e32 v5, 1.0, v5
	v_add_f32_e32 v6, 1.0, v6
	v_add_f32_e32 v7, 1.0, v7
	v_rcp_f32_e32 v4, v4
	v_rcp_f32_e32 v5, v5
	v_rcp_f32_e32 v6, v6
	v_rcp_f32_e32 v7, v7
	v_or_b32_e32 v18, 0x120, v18
	v_mul_f32_e32 v0, v0, v32
	v_mul_f32_e32 v1, v1, v32
	v_mul_f32_e32 v2, v2, v32
	v_mul_f32_e32 v3, v3, v32
	v_mul_f32_e32 v0, 0xbfb8aa3b, v0
	v_mul_f32_e32 v1, 0xbfb8aa3b, v1
	v_mul_f32_e32 v2, 0xbfb8aa3b, v2
	v_mul_f32_e32 v3, 0xbfb8aa3b, v3
	v_exp_f32_e32 v0, v0
	v_exp_f32_e32 v1, v1
	v_exp_f32_e32 v2, v2
	v_exp_f32_e32 v3, v3
	v_add_f32_e32 v0, 1.0, v0
	v_add_f32_e32 v1, 1.0, v1
	v_add_f32_e32 v2, 1.0, v2
	v_add_f32_e32 v3, 1.0, v3
	v_mul_f32_e32 v15, v15, v15
	v_mul_f32_e32 v13, v13, v13
	v_rcp_f32_e32 v0, v0
	v_rcp_f32_e32 v1, v1
	v_rcp_f32_e32 v2, v2
	v_rcp_f32_e32 v3, v3
	v_fmac_f32_e32 v15, v14, v14
	v_fmac_f32_e32 v13, v12, v12
	v_add_f32_e32 v12, v15, v13
	s_waitcnt vmcnt(1)
	v_lshlrev_b32_e32 v28, 16, v22
	v_and_b32_e32 v29, 0xffff0000, v22
	v_lshlrev_b32_e32 v22, 16, v23
	v_and_b32_e32 v23, 0xffff0000, v23
	s_waitcnt vmcnt(0)
	v_lshlrev_b32_e32 v30, 16, v20
	v_and_b32_e32 v31, 0xffff0000, v20
	v_lshlrev_b32_e32 v20, 16, v21
	v_and_b32_e32 v21, 0xffff0000, v21
	v_pk_fma_f32 v[10:11], v[10:11], v[22:23], v[20:21]
	v_pk_fma_f32 v[8:9], v[8:9], v[28:29], v[30:31]
	v_lshl_add_u64 v[28:29], s[8:9], 0, v[24:25]
	v_cvt_pk_bf16_f32 v20, v8, v9
	v_cvt_pk_bf16_f32 v21, v10, v11
	global_load_dwordx2 v[22:23], v[26:27], off
	v_lshl_add_u64 v[26:27], s[16:17], 0, v[40:41]
	global_store_dwordx2 v[26:27], v[20:21], off
	global_load_dwordx2 v[20:21], v[28:29], off
	v_lshl_add_u64 v[26:27], s[20:21], 0, v[18:19]
	v_lshl_add_u64 v[24:25], s[16:17], 0, v[24:25]
	v_mul_f32_e32 v9, v9, v9
	v_mul_f32_e32 v11, v11, v11
	v_fmac_f32_e32 v9, v8, v8
	v_fmac_f32_e32 v11, v10, v10
	v_add_f32_e32 v8, v9, v11
	v_add_f32_e32 v8, v12, v8
	s_waitcnt vmcnt(2)
	v_lshlrev_b32_e32 v28, 16, v22
	v_and_b32_e32 v29, 0xffff0000, v22
	v_lshlrev_b32_e32 v22, 16, v23
	v_and_b32_e32 v23, 0xffff0000, v23
	s_waitcnt vmcnt(0)
	v_lshlrev_b32_e32 v30, 16, v20
	v_and_b32_e32 v31, 0xffff0000, v20
	v_lshlrev_b32_e32 v20, 16, v21
	v_and_b32_e32 v21, 0xffff0000, v21
	v_pk_fma_f32 v[6:7], v[6:7], v[22:23], v[20:21]
	v_pk_fma_f32 v[4:5], v[4:5], v[28:29], v[30:31]
	s_nop 0
	v_cvt_pk_bf16_f32 v20, v4, v5
	v_cvt_pk_bf16_f32 v21, v6, v7
	global_load_dwordx2 v[22:23], v[26:27], off
	v_lshl_add_u64 v[26:27], s[8:9], 0, v[18:19]
	global_store_dwordx2 v[24:25], v[20:21], off
	global_load_dwordx2 v[20:21], v[26:27], off
	v_mul_f32_e32 v5, v5, v5
	v_mul_f32_e32 v7, v7, v7
	v_fmac_f32_e32 v5, v4, v4
	v_fmac_f32_e32 v7, v6, v6
	v_add_f32_e32 v4, v5, v7
	v_add_f32_e32 v12, v4, v8
	s_waitcnt vmcnt(2)
	v_lshlrev_b32_e32 v4, 16, v22
	v_and_b32_e32 v5, 0xffff0000, v22
	v_lshlrev_b32_e32 v6, 16, v23
	v_and_b32_e32 v7, 0xffff0000, v23
	s_waitcnt vmcnt(0)
	v_lshlrev_b32_e32 v8, 16, v20
	v_and_b32_e32 v9, 0xffff0000, v20
	v_lshlrev_b32_e32 v10, 16, v21
	v_and_b32_e32 v11, 0xffff0000, v21
	v_pk_fma_f32 v[2:3], v[2:3], v[6:7], v[10:11]
	v_pk_fma_f32 v[0:1], v[0:1], v[4:5], v[8:9]
	v_mul_f32_e32 v5, v3, v3
	v_mul_f32_e32 v4, v1, v1
	v_fmac_f32_e32 v4, v0, v0
	v_fmac_f32_e32 v5, v2, v2
	v_add_f32_e32 v4, v4, v5
	v_add_f32_e32 v6, v12, v4
	ds_swizzle_b32 v7, v6 offset:swizzle(SWAP,16)
	v_lshl_add_u64 v[4:5], s[16:17], 0, v[18:19]
	v_cvt_pk_bf16_f32 v0, v0, v1
	v_cvt_pk_bf16_f32 v1, v2, v3
	global_store_dwordx2 v[4:5], v[0:1], off
	s_waitcnt lgkmcnt(0)
	v_add_f32_e32 v0, v6, v7
	v_mov_b32_e32 v1, v0
	s_nop 1
	v_permlane32_swap_b32_e32 v0, v1
	s_and_saveexec_b64 s[2:3], s[4:5]
	s_cbranch_execz .LBB0_3060
	v_add_f32_e32 v2, v0, v1
	v_lshl_add_u64 v[0:1], s[10:11], 0, v[16:17]
	v_lshl_add_u64 v[0:1], s[36:37], 2, v[0:1]
	s_lshl_b32 s12, s50, 2
	v_lshl_add_u64 v[0:1], v[0:1], 0, s[12:13]
	global_store_dword v[0:1], v2, off
